# GEMM tile loops: MFMA fragment reads double-buffered in AGPRs and issued one k-step ahead (as the source intends), counted lgkmcnt waits
# speedup vs baseline: 1.0055x; 1.0055x over previous
.LBB0_94:
	s_ashr_i32 s0, s2, 31
	s_lshr_b32 s0, s0, 29
	s_add_i32 s0, s2, s0
	v_mov_b32_e32 v78, v133
	s_and_b32 s1, s0, 0x1fffff8
	s_lshl_b32 s0, s0, 5
	s_and_b32 s22, s0, 0xffffff00
	v_ashrrev_i32_e32 v6, 6, v78
	v_bfe_u32 v7, v78, 3, 3
	v_lshl_or_b32 v8, v6, 5, v7
	v_add_u32_e32 v0, s22, v8
	s_waitcnt lgkmcnt(0)
	v_ashrrev_i32_e32 v1, 31, v0
	v_lshlrev_b64 v[2:3], 11, v[0:1]
	v_bfe_u32 v1, v78, 4, 2
	v_readlane_b32 s20, v214, 4
	v_xor_b32_e32 v1, v1, v78
	v_readlane_b32 s21, v214, 5
	v_lshlrev_b32_e32 v1, 4, v1
	v_and_b32_e32 v64, 0x70, v1
	v_lshl_add_u64 v[2:3], s[20:21], 0, v[2:3]
	v_or_b32_e32 v1, 8, v8
	v_lshl_add_u64 v[66:67], v[2:3], 0, v[64:65]
	v_add_u32_e32 v2, s22, v1
	v_lshrrev_b32_e32 v1, 1, v1
	v_xor_b32_e32 v1, v1, v78
	v_ashrrev_i32_e32 v3, 31, v2
	v_lshlrev_b32_e32 v1, 4, v1
	v_or_b32_e32 v0, 16, v0
	v_lshlrev_b64 v[2:3], 11, v[2:3]
	v_and_b32_e32 v4, 0x70, v1
	v_ashrrev_i32_e32 v1, 31, v0
	v_lshl_add_u64 v[2:3], s[20:21], 0, v[2:3]
	v_mov_b32_e32 v5, v65
	v_lshlrev_b64 v[0:1], 11, v[0:1]
	v_lshl_add_u64 v[68:69], v[2:3], 0, v[4:5]
	v_lshl_add_u64 v[0:1], s[20:21], 0, v[0:1]
	v_or_b32_e32 v2, 24, v8
	v_lshl_add_u64 v[70:71], v[0:1], 0, v[64:65]
	v_add_u32_e32 v0, s22, v2
	v_lshrrev_b32_e32 v2, 1, v2
	v_ashrrev_i32_e32 v1, 31, v0
	v_xor_b32_e32 v2, v2, v78
	v_lshlrev_b64 v[0:1], 11, v[0:1]
	v_lshlrev_b32_e32 v2, 4, v2
	s_sub_i32 s1, s2, s1
	v_lshl_add_u64 v[0:1], s[20:21], 0, v[0:1]
	v_and_b32_e32 v2, 0x70, v2
	v_mov_b32_e32 v3, v65
	s_lshl_b32 s0, s1, 7
	v_lshl_add_u64 v[72:73], v[0:1], 0, v[2:3]
	v_lshl_or_b32 v2, v6, 4, v7
	v_add_u32_e32 v0, s0, v2
	v_lshlrev_b32_e32 v3, 12, v6
	v_ashrrev_i32_e32 v1, 31, v0
	v_add_u32_e32 v126, 0, v3
	v_lshlrev_b64 v[0:1], 11, v[0:1]
	s_waitcnt vmcnt(0)
	v_readfirstlane_b32 s38, v126
	v_add_u32_e32 v127, 0x400, v126
	v_lshl_add_u64 v[0:1], s[40:41], 0, v[0:1]
	v_or_b32_e32 v2, 8, v2
	s_waitcnt lgkmcnt(0)
	s_barrier
	s_mov_b32 m0, s38
	v_readfirstlane_b32 s39, v127
	v_add_u32_e32 v128, 0x800, v126
	v_lshlrev_b32_e32 v5, 11, v6
	v_and_b32_e32 v80, 1, v6
	v_lshl_add_u64 v[74:75], v[0:1], 0, v[64:65]
	v_add_u32_e32 v0, s0, v2
	v_lshrrev_b32_e32 v2, 1, v2
	global_load_lds_dwordx4 v[66:67], off
	s_mov_b32 m0, s39
	v_readfirstlane_b32 s48, v128
	v_add_u32_e32 v129, 0xc00, v126
	v_add_u32_e32 v6, 0, v5
	v_ashrrev_i32_e32 v1, 31, v0
	v_xor_b32_e32 v2, v2, v78
	global_load_lds_dwordx4 v[68:69], off
	s_mov_b32 m0, s48
	v_readfirstlane_b32 s49, v129
	v_add_u32_e32 v131, 0x8000, v6
	v_lshlrev_b64 v[0:1], 11, v[0:1]
	v_lshlrev_b32_e32 v2, 4, v2
	global_load_lds_dwordx4 v[70:71], off
	s_mov_b32 m0, s49
	v_readfirstlane_b32 s53, v131
	v_add_u32_e32 v130, 0x8400, v6
	v_lshl_add_u64 v[0:1], s[40:41], 0, v[0:1]
	v_and_b32_e32 v64, 0x70, v2
	global_load_lds_dwordx4 v[72:73], off
	s_mov_b32 m0, s53
	v_readfirstlane_b32 s54, v130
	v_add_u32_e32 v120, 0xc000, v126
	v_lshl_add_u64 v[76:77], v[0:1], 0, v[64:65]
	global_load_lds_dwordx4 v[74:75], off
	s_mov_b32 m0, s54
	s_mov_b64 s[20:21], 0x80
	v_readfirstlane_b32 s29, v120
	v_add_u32_e32 v121, 0xc400, v126
	global_load_lds_dwordx4 v[76:77], off
	v_lshl_add_u64 v[0:1], v[66:67], 0, s[20:21]
	s_mov_b32 m0, s29
	v_readfirstlane_b32 s33, v121
	v_add_u32_e32 v122, 0xc800, v126
	global_load_lds_dwordx4 v[0:1], off
	v_lshl_add_u64 v[0:1], v[68:69], 0, s[20:21]
	s_mov_b32 m0, s33
	v_readfirstlane_b32 s34, v122
	v_add_u32_e32 v123, 0xcc00, v126
	global_load_lds_dwordx4 v[0:1], off
	v_lshl_add_u64 v[0:1], v[70:71], 0, s[20:21]
	s_mov_b32 m0, s34
	v_readfirstlane_b32 s35, v123
	v_add_u32_e32 v124, s85, v5
	global_load_lds_dwordx4 v[0:1], off
	v_lshl_add_u64 v[0:1], v[72:73], 0, s[20:21]
	s_mov_b32 m0, s35
	v_readfirstlane_b32 s36, v124
	v_add_u32_e32 v125, 0x14400, v6
	global_load_lds_dwordx4 v[0:1], off
	v_lshl_add_u64 v[0:1], v[74:75], 0, s[20:21]
	s_mov_b32 m0, s36
	v_readfirstlane_b32 s37, v125
	global_load_lds_dwordx4 v[0:1], off
	v_lshl_add_u64 v[0:1], v[76:77], 0, s[20:21]
	s_mov_b32 m0, s37
	v_lshrrev_b32_e32 v2, 1, v78
	v_bfe_u32 v64, v78, 5, 1
	global_load_lds_dwordx4 v[0:1], off
	v_add_u32_e32 v114, s3, v3
	v_bitop3_b32 v0, v2, v64, 7 bitop3:0x6c
	s_waitcnt vmcnt(6)
	s_mov_b64 s[30:31], 0x100
	v_readfirstlane_b32 s1, v114
	v_add_u32_e32 v115, 0x400, v114
	v_lshlrev_b32_e32 v132, 4, v0
	s_waitcnt lgkmcnt(0)
	s_barrier
	v_lshl_add_u64 v[0:1], v[66:67], 0, s[30:31]
	s_mov_b32 m0, s1
	v_readfirstlane_b32 s20, v115
	v_add_u32_e32 v116, 0x800, v114
	global_load_lds_dwordx4 v[0:1], off
	v_lshl_add_u64 v[0:1], v[68:69], 0, s[30:31]
	s_mov_b32 m0, s20
	v_readfirstlane_b32 s21, v116
	v_add_u32_e32 v117, 0xc00, v114
	v_readlane_b32 s24, v212, 31
	v_and_b32_e32 v79, 31, v78
	global_load_lds_dwordx4 v[0:1], off
	v_lshl_add_u64 v[0:1], v[70:71], 0, s[30:31]
	s_mov_b32 m0, s21
	v_readfirstlane_b32 s23, v117
	v_add_u32_e32 v118, s24, v5
	v_add_u32_e32 v2, s3, v5
	v_lshlrev_b32_e32 v4, 7, v79
	global_load_lds_dwordx4 v[0:1], off
	v_lshl_add_u64 v[0:1], v[72:73], 0, s[30:31]
	s_mov_b32 m0, s23
	v_readfirstlane_b32 s24, v118
	v_add_u32_e32 v119, 0x8400, v2
	v_lshl_or_b32 v102, v80, 13, v4
	global_load_lds_dwordx4 v[0:1], off
	v_lshl_add_u64 v[0:1], v[74:75], 0, s[30:31]
	s_mov_b32 m0, s24
	v_readfirstlane_b32 s28, v119
	global_load_lds_dwordx4 v[0:1], off
	v_lshl_add_u64 v[0:1], v[76:77], 0, s[30:31]
	s_mov_b32 m0, s28
	v_add_u32_e32 v100, 0, v102
	global_load_lds_dwordx4 v[0:1], off
	v_add_u32_e32 v83, v100, v132
	v_ashrrev_i32_e32 v81, 7, v78
	ds_read_b128 a[0:3], v83 offset:32768
	ds_read_b128 a[4:7], v83 offset:36864
	v_lshl_or_b32 v134, v81, 13, v4
	v_add_u32_e32 v101, 0, v134
	v_add_u32_e32 v82, v101, v132
	ds_read_b128 a[8:11], v82
	ds_read_b128 a[12:15], v82 offset:4096
	v_lshrrev_b32_e32 v182, 6, v133
	s_nop 0
	v_readfirstlane_b32 s32, v182
	s_waitcnt lgkmcnt(1)
	v_mfma_f32_32x32x16_bf16 v[48:63], a[0:3], a[8:11], 0
	v_bfe_u32 v103, v78, 1, 3
	s_mov_b64 s[30:31], 0x180
	s_nop 0
	v_or_b32_e32 v143, 0x8000, v102
	v_or_b32_e32 v144, 0x9000, v102
	v_add_u32_e32 v145, s3, v134
	v_lshl_or_b32 v81, v81, 6, v79
	s_waitcnt vmcnt(12)
	v_mfma_f32_32x32x16_bf16 v[32:47], a[4:7], a[8:11], 0
	v_mul_lo_u32 v81, v81, s26
	s_mov_b64 s[80:81], 0x200
	s_waitcnt lgkmcnt(0)
	v_mfma_f32_32x32x16_bf16 v[16:31], a[0:3], a[12:15], 0
	v_bitop3_b32 v0, v64, v103, 2 bitop3:0x36
	v_lshlrev_b32_e32 v138, 4, v0
	v_add_u32_e32 v84, v101, v138
	ds_read_b128 a[28:31], v84 offset:4096
	s_nop 0
	s_nop 0
	ds_read_b128 a[24:27], v84
	s_nop 0
	v_add_u32_e32 v85, v100, v138
	ds_read_b128 a[20:23], v85 offset:36864
	s_nop 0
	s_nop 0
	ds_read_b128 a[16:19], v85 offset:32768
	s_nop 0
	s_nop 0
	s_nop 0
	s_nop 0
	s_nop 0
	s_nop 0
	v_mfma_f32_32x32x16_bf16 v[0:15], a[4:7], a[12:15], 0
	s_nop 0
	s_waitcnt lgkmcnt(0)
	v_mfma_f32_32x32x16_bf16 v[48:63], a[16:19], a[24:27], v[48:63]
	v_mfma_f32_32x32x16_bf16 v[32:47], a[20:23], a[24:27], v[32:47]
	v_mfma_f32_32x32x16_bf16 v[16:31], a[16:19], a[28:31], v[16:31]
	v_bitop3_b32 v86, v64, v103, 4 bitop3:0x36
	v_lshlrev_b32_e32 v139, 4, v86
	v_add_u32_e32 v86, v101, v139
	ds_read_b128 a[12:15], v86 offset:4096
	s_nop 0
	s_nop 0
	ds_read_b128 a[8:11], v86
	s_nop 0
	v_add_u32_e32 v87, v100, v139
	ds_read_b128 a[4:7], v87 offset:36864
	s_nop 0
	s_nop 0
	ds_read_b128 a[0:3], v87 offset:32768
	s_nop 0
	s_nop 0
	s_nop 0
	v_mfma_f32_32x32x16_bf16 v[0:15], a[20:23], a[28:31], v[0:15]
	s_nop 0
	s_nop 0
	s_nop 0
	s_nop 0
	s_waitcnt lgkmcnt(0)
	v_mfma_f32_32x32x16_bf16 v[48:63], a[0:3], a[8:11], v[48:63]
	v_mfma_f32_32x32x16_bf16 v[32:47], a[4:7], a[8:11], v[32:47]
	v_mfma_f32_32x32x16_bf16 v[16:31], a[0:3], a[12:15], v[16:31]
	v_bitop3_b32 v88, v64, v103, 6 bitop3:0x36
	v_lshlrev_b32_e32 v142, 4, v88
	v_add_u32_e32 v88, v101, v142
	ds_read_b128 a[28:31], v88 offset:4096
	s_nop 0
	s_nop 0
	ds_read_b128 a[24:27], v88
	s_nop 0
	v_add_u32_e32 v89, v100, v142
	ds_read_b128 a[20:23], v89 offset:36864
	s_nop 0
	s_nop 0
	ds_read_b128 a[16:19], v89 offset:32768
	s_nop 0
	s_nop 0
	s_nop 0
	v_lshlrev_b32_e32 v64, 4, v64
	v_lshl_or_b32 v64, v80, 8, v64
	v_add3_u32 v64, 0, v81, v64
	v_mfma_f32_32x32x16_bf16 v[0:15], a[4:7], a[12:15], v[0:15]
	s_nop 0
	s_nop 0
	s_nop 0
	s_nop 0
	s_waitcnt lgkmcnt(0)
	v_mfma_f32_32x32x16_bf16 v[48:63], a[16:19], a[24:27], v[48:63]
	v_mfma_f32_32x32x16_bf16 v[32:47], a[20:23], a[24:27], v[32:47]
	s_waitcnt vmcnt(6)
	s_waitcnt lgkmcnt(0)
	s_barrier
	ds_read_b128 a[12:15], v82 offset:53248
	ds_read_b128 a[8:11], v82 offset:49152
	v_mfma_f32_32x32x16_bf16 v[16:31], a[16:19], a[28:31], v[16:31]
	v_lshl_add_u64 v[158:159], v[66:67], 0, s[30:31]
	s_nop 0
	v_lshl_add_u64 v[160:161], v[68:69], 0, s[30:31]
	s_nop 0
	s_nop 0
	s_nop 0
	v_lshl_add_u64 v[162:163], v[70:71], 0, s[30:31]
	s_nop 0
	v_mfma_f32_32x32x16_bf16 v[0:15], a[20:23], a[28:31], v[0:15]
	s_and_b32 m0, s32, 7
	s_lshl_b32 m0, m0, 12
	s_add_i32 m0, m0, 0x0
	s_nop 0
	global_load_lds_dwordx4 v[158:159], off
	s_nop 0
	v_lshl_add_u64 v[164:165], v[72:73], 0, s[30:31]
	s_nop 0
	s_nop 0
	s_nop 0
	v_lshl_add_u64 v[166:167], v[74:75], 0, s[30:31]
	s_nop 0
	s_nop 0
	s_nop 0
	v_lshl_add_u64 v[168:169], v[76:77], 0, s[30:31]
	s_nop 0
	s_add_i32 s30, 0, 0xc000
	v_add_u32_e32 v90, s30, v132
	v_add_u32_e32 v92, v90, v143
	v_add_u32_e32 v90, v90, v144
	ds_read_b128 a[4:7], v90
	ds_read_b128 a[0:3], v92
	s_nop 0
	s_nop 0
	s_nop 0
	s_nop 0
	s_nop 0
	s_nop 0
	s_nop 0
	s_nop 0
	v_add_u32_e32 v91, s30, v138
	v_add_u32_e32 v93, v91, v143
	ds_read_b128 a[16:19], v93
	v_add_u32_e32 v91, v91, v144
	ds_read_b128 a[20:23], v91
	ds_read_b128 a[24:27], v84 offset:49152
	ds_read_b128 a[28:31], v84 offset:53248
	s_waitcnt lgkmcnt(4)
	v_mfma_f32_32x32x16_bf16 v[48:63], a[0:3], a[8:11], v[48:63]
	s_nop 0
	s_nop 0
	s_nop 0
	s_nop 0
	v_mfma_f32_32x32x16_bf16 v[32:47], a[4:7], a[8:11], v[32:47]
	s_and_b32 m0, s32, 7
	s_lshl_b32 m0, m0, 12
	s_add_i32 m0, m0, 0x400
	s_nop 0
	global_load_lds_dwordx4 v[160:161], off
	v_mfma_f32_32x32x16_bf16 v[16:31], a[0:3], a[12:15], v[16:31]
	v_mfma_f32_32x32x16_bf16 v[0:15], a[4:7], a[12:15], v[0:15]
	s_and_b32 m0, s32, 7
	s_lshl_b32 m0, m0, 12
	s_add_i32 m0, m0, 0x800
	s_nop 0
	global_load_lds_dwordx4 v[162:163], off
	s_nop 0
	s_nop 0
	s_nop 0
	s_nop 0
	v_add_u32_e32 v94, s30, v139
	v_add_u32_e32 v95, v94, v143
	ds_read_b128 a[0:3], v95
	v_add_u32_e32 v94, v94, v144
	ds_read_b128 a[4:7], v94
	ds_read_b128 a[8:11], v86 offset:49152
	ds_read_b128 a[12:15], v86 offset:53248
	s_waitcnt lgkmcnt(5)
	v_mfma_f32_32x32x16_bf16 v[48:63], a[16:19], a[24:27], v[48:63]
	v_mfma_f32_32x32x16_bf16 v[32:47], a[20:23], a[24:27], v[32:47]
	s_and_b32 m0, s32, 7
	s_lshl_b32 m0, m0, 12
	s_add_i32 m0, m0, 0xc00
	s_nop 0
	global_load_lds_dwordx4 v[164:165], off
	s_waitcnt lgkmcnt(4)
	v_mfma_f32_32x32x16_bf16 v[16:31], a[16:19], a[28:31], v[16:31]
	s_nop 0
	s_nop 0
	s_nop 0
	v_mfma_f32_32x32x16_bf16 v[0:15], a[20:23], a[28:31], v[0:15]
	s_and_b32 m0, s32, 7
	s_lshl_b32 m0, m0, 11
	s_add_i32 m0, m0, 0x8000
	s_nop 0
	global_load_lds_dwordx4 v[166:167], off
	s_nop 0
	s_nop 0
	s_nop 0
	s_nop 0
	v_add_u32_e32 v96, s30, v142
	v_add_u32_e32 v97, v96, v143
	ds_read_b128 a[16:19], v97
	v_add_u32_e32 v96, v96, v144
	ds_read_b128 a[20:23], v96
	ds_read_b128 a[24:27], v88 offset:49152
	ds_read_b128 a[28:31], v88 offset:53248
	s_waitcnt lgkmcnt(5)
	v_mfma_f32_32x32x16_bf16 v[48:63], a[0:3], a[8:11], v[48:63]
	v_mfma_f32_32x32x16_bf16 v[32:47], a[4:7], a[8:11], v[32:47]
	s_and_b32 m0, s32, 7
	s_lshl_b32 m0, m0, 11
	s_add_i32 m0, m0, 0x8400
	s_nop 0
	global_load_lds_dwordx4 v[168:169], off
	s_waitcnt lgkmcnt(4)
	v_mfma_f32_32x32x16_bf16 v[16:31], a[0:3], a[12:15], v[16:31]
	s_nop 0
	s_nop 0
	s_nop 0
	s_mov_b64 s[30:31], 0x200
	v_mfma_f32_32x32x16_bf16 v[0:15], a[4:7], a[12:15], v[0:15]
	s_nop 0
	s_nop 0
	s_nop 0
	s_nop 0
	s_waitcnt lgkmcnt(1)
	v_mfma_f32_32x32x16_bf16 v[48:63], a[16:19], a[24:27], v[48:63]
	v_mfma_f32_32x32x16_bf16 v[32:47], a[20:23], a[24:27], v[32:47]
	s_waitcnt vmcnt(6)
	s_waitcnt lgkmcnt(0)
	s_barrier
	v_add_u32_e32 v100, v145, v132
	ds_read_b128 a[8:11], v100
	v_add_u32_e32 v101, s3, v132
	v_add_u32_e32 v99, v101, v144
	ds_read_b128 a[4:7], v99
	s_nop 0
	v_add_u32_e32 v98, v101, v143
	v_or_b32_e32 v132, 0x1000, v134
	v_add_u32_e32 v101, v101, v132
	ds_read_b128 a[12:15], v101
	ds_read_b128 a[0:3], v98
	v_mfma_f32_32x32x16_bf16 v[16:31], a[16:19], a[28:31], v[16:31]
	v_lshl_add_u64 v[170:171], v[66:67], 0, s[30:31]
	s_nop 0
	v_lshl_add_u64 v[172:173], v[68:69], 0, s[30:31]
	s_nop 0
	s_nop 0
	s_nop 0
	v_lshl_add_u64 v[174:175], v[70:71], 0, s[30:31]
	s_nop 0
	v_mfma_f32_32x32x16_bf16 v[0:15], a[20:23], a[28:31], v[0:15]
	s_and_b32 m0, s32, 7
	s_lshl_b32 m0, m0, 12
	s_add_i32 m0, m0, 0xc000
	s_nop 0
	global_load_lds_dwordx4 v[170:171], off
	s_nop 0
	v_lshl_add_u64 v[176:177], v[72:73], 0, s[30:31]
	s_nop 0
	s_nop 0
	s_nop 0
	v_lshl_add_u64 v[178:179], v[74:75], 0, s[30:31]
	s_nop 0
	s_nop 0
	s_nop 0
	v_lshl_add_u64 v[180:181], v[76:77], 0, s[30:31]
	s_nop 0
	s_mov_b64 s[30:31], 0x280
	s_nop 0
	s_nop 0
	s_nop 0
	s_nop 0
	s_nop 0
	s_nop 0
	s_nop 0
	s_nop 0
	v_add_u32_e32 v105, s3, v138
	v_add_u32_e32 v102, v105, v143
	ds_read_b128 a[16:19], v102
	v_add_u32_e32 v103, v105, v144
	ds_read_b128 a[20:23], v103
	v_add_u32_e32 v104, v145, v138
	ds_read_b128 a[24:27], v104
	v_add_u32_e32 v105, v105, v132
	ds_read_b128 a[28:31], v105
	s_waitcnt lgkmcnt(4)
	v_mfma_f32_32x32x16_bf16 v[48:63], a[0:3], a[8:11], v[48:63]
	s_nop 0
	v_mfma_f32_32x32x16_bf16 v[32:47], a[4:7], a[8:11], v[32:47]
	s_and_b32 m0, s32, 7
	s_lshl_b32 m0, m0, 12
	s_add_i32 m0, m0, 0xc400
	s_nop 0
	global_load_lds_dwordx4 v[172:173], off
	s_nop 0
	s_nop 0
	s_nop 0
	s_nop 0
	s_nop 0
	v_mfma_f32_32x32x16_bf16 v[16:31], a[0:3], a[12:15], v[16:31]
	s_nop 0
	v_mfma_f32_32x32x16_bf16 v[0:15], a[4:7], a[12:15], v[0:15]
	s_and_b32 m0, s32, 7
	s_lshl_b32 m0, m0, 12
	s_add_i32 m0, m0, 0xc800
	s_nop 0
	global_load_lds_dwordx4 v[174:175], off
	s_nop 0
	s_nop 0
	s_nop 0
	v_add_u32_e32 v109, s3, v139
	v_add_u32_e32 v106, v109, v143
	ds_read_b128 a[0:3], v106
	v_add_u32_e32 v107, v109, v144
	ds_read_b128 a[4:7], v107
	v_add_u32_e32 v108, v145, v139
	ds_read_b128 a[8:11], v108
	v_add_u32_e32 v109, v109, v132
	ds_read_b128 a[12:15], v109
	s_waitcnt lgkmcnt(5)
	v_mfma_f32_32x32x16_bf16 v[48:63], a[16:19], a[24:27], v[48:63]
	v_mfma_f32_32x32x16_bf16 v[32:47], a[20:23], a[24:27], v[32:47]
	s_and_b32 m0, s32, 7
	s_lshl_b32 m0, m0, 12
	s_add_i32 m0, m0, 0xcc00
	s_nop 0
	global_load_lds_dwordx4 v[176:177], off
	s_waitcnt lgkmcnt(4)
	v_mfma_f32_32x32x16_bf16 v[16:31], a[16:19], a[28:31], v[16:31]
	s_nop 0
	s_nop 0
	s_nop 0
	s_nop 0
	s_nop 0
	s_nop 0
	v_mfma_f32_32x32x16_bf16 v[0:15], a[20:23], a[28:31], v[0:15]
	s_and_b32 m0, s32, 7
	s_lshl_b32 m0, m0, 11
	s_add_i32 m0, m0, 0x14000
	s_nop 0
	global_load_lds_dwordx4 v[178:179], off
	s_nop 0
	s_nop 0
	s_nop 0
	v_add_u32_e32 v113, s3, v142
	v_add_u32_e32 v110, v113, v143
	ds_read_b128 a[16:19], v110
	v_add_u32_e32 v111, v113, v144
	ds_read_b128 a[20:23], v111
	v_add_u32_e32 v112, v145, v142
	ds_read_b128 a[24:27], v112
	v_add_u32_e32 v113, v113, v132
	ds_read_b128 a[28:31], v113
	s_waitcnt lgkmcnt(5)
	v_mfma_f32_32x32x16_bf16 v[48:63], a[0:3], a[8:11], v[48:63]
	v_mfma_f32_32x32x16_bf16 v[32:47], a[4:7], a[8:11], v[32:47]
	s_and_b32 m0, s32, 7
	s_lshl_b32 m0, m0, 11
	s_add_i32 m0, m0, 0x14400
	s_nop 0
	global_load_lds_dwordx4 v[180:181], off
	s_waitcnt lgkmcnt(4)
	v_mfma_f32_32x32x16_bf16 v[16:31], a[0:3], a[12:15], v[16:31]
	s_nop 0
	s_nop 0
	s_nop 0
	s_nop 0
	s_nop 0
	s_nop 0
	v_mfma_f32_32x32x16_bf16 v[0:15], a[4:7], a[12:15], v[0:15]
	s_nop 0
	s_nop 0
	s_nop 0
	s_waitcnt lgkmcnt(1)
	v_mfma_f32_32x32x16_bf16 v[48:63], a[16:19], a[24:27], v[48:63]
	v_mfma_f32_32x32x16_bf16 v[32:47], a[20:23], a[24:27], v[32:47]
	s_waitcnt vmcnt(6)
	s_waitcnt lgkmcnt(0)
	s_barrier
	ds_read_b128 a[12:15], v82 offset:4096
	ds_read_b128 a[8:11], v82
	ds_read_b128 a[4:7], v83 offset:36864
	ds_read_b128 a[0:3], v83 offset:32768
	v_mfma_f32_32x32x16_bf16 v[16:31], a[16:19], a[28:31], v[16:31]
	v_lshl_add_u64 v[158:159], v[66:67], 0, s[30:31]
	s_nop 0
	v_lshl_add_u64 v[160:161], v[68:69], 0, s[30:31]
	s_nop 0
	s_nop 0
	s_nop 0
	v_lshl_add_u64 v[162:163], v[70:71], 0, s[30:31]
	s_nop 0
	v_mfma_f32_32x32x16_bf16 v[0:15], a[20:23], a[28:31], v[0:15]
	s_and_b32 m0, s32, 7
	s_lshl_b32 m0, m0, 12
	s_add_i32 m0, m0, 0x18000
	s_nop 0
	global_load_lds_dwordx4 v[158:159], off
	s_nop 0
	v_lshl_add_u64 v[164:165], v[72:73], 0, s[30:31]
	s_nop 0
	s_nop 0
	s_nop 0
	v_lshl_add_u64 v[166:167], v[74:75], 0, s[30:31]
	s_nop 0
	s_nop 0
	s_nop 0
	v_lshl_add_u64 v[168:169], v[76:77], 0, s[30:31]
	s_nop 0
	s_mov_b64 s[30:31], 0x300
	s_nop 0
	s_nop 0
	s_nop 0
	s_nop 0
	s_nop 0
	ds_read_b128 a[16:19], v85 offset:32768
	ds_read_b128 a[20:23], v85 offset:36864
	ds_read_b128 a[24:27], v84
	ds_read_b128 a[28:31], v84 offset:4096
	s_waitcnt lgkmcnt(4)
	v_mfma_f32_32x32x16_bf16 v[48:63], a[0:3], a[8:11], v[48:63]
	s_nop 0
	v_readfirstlane_b32 s38, v114
	v_mfma_f32_32x32x16_bf16 v[32:47], a[4:7], a[8:11], v[32:47]
	s_and_b32 m0, s32, 7
	s_lshl_b32 m0, m0, 12
	s_add_i32 m0, m0, 0x18400
	s_nop 0
	global_load_lds_dwordx4 v[160:161], off
	v_mfma_f32_32x32x16_bf16 v[16:31], a[0:3], a[12:15], v[16:31]
	v_mfma_f32_32x32x16_bf16 v[0:15], a[4:7], a[12:15], v[0:15]
	s_and_b32 m0, s32, 7
	s_lshl_b32 m0, m0, 12
	s_add_i32 m0, m0, 0x18800
	s_nop 0
	global_load_lds_dwordx4 v[162:163], off
	s_nop 0
	s_nop 0
	s_nop 0
	s_nop 0
	ds_read_b128 a[0:3], v87 offset:32768
	ds_read_b128 a[4:7], v87 offset:36864
	ds_read_b128 a[8:11], v86
	ds_read_b128 a[12:15], v86 offset:4096
	s_waitcnt lgkmcnt(5)
	v_mfma_f32_32x32x16_bf16 v[48:63], a[16:19], a[24:27], v[48:63]
	v_mfma_f32_32x32x16_bf16 v[32:47], a[20:23], a[24:27], v[32:47]
	s_and_b32 m0, s32, 7
	s_lshl_b32 m0, m0, 12
	s_add_i32 m0, m0, 0x18c00
	s_nop 0
	global_load_lds_dwordx4 v[164:165], off
	s_waitcnt lgkmcnt(4)
	v_mfma_f32_32x32x16_bf16 v[16:31], a[16:19], a[28:31], v[16:31]
	v_mfma_f32_32x32x16_bf16 v[0:15], a[20:23], a[28:31], v[0:15]
	s_and_b32 m0, s32, 7
	s_lshl_b32 m0, m0, 11
	s_add_i32 m0, m0, 0x20000
	s_nop 0
	global_load_lds_dwordx4 v[166:167], off
	s_nop 0
	s_nop 0
	s_nop 0
	s_nop 0
	ds_read_b128 a[16:19], v89 offset:32768
	ds_read_b128 a[20:23], v89 offset:36864
	ds_read_b128 a[24:27], v88
	ds_read_b128 a[28:31], v88 offset:4096
	s_waitcnt lgkmcnt(5)
	v_mfma_f32_32x32x16_bf16 v[48:63], a[0:3], a[8:11], v[48:63]
	v_mfma_f32_32x32x16_bf16 v[32:47], a[4:7], a[8:11], v[32:47]
	s_and_b32 m0, s32, 7
	s_lshl_b32 m0, m0, 11
	s_add_i32 m0, m0, 0x20400
	s_nop 0
	global_load_lds_dwordx4 v[168:169], off
	s_waitcnt lgkmcnt(4)
	v_mfma_f32_32x32x16_bf16 v[16:31], a[0:3], a[12:15], v[16:31]
	v_mfma_f32_32x32x16_bf16 v[0:15], a[4:7], a[12:15], v[0:15]
	s_nop 0
	s_nop 0
	s_nop 0
	s_nop 0
	s_waitcnt lgkmcnt(1)
	v_mfma_f32_32x32x16_bf16 v[48:63], a[16:19], a[24:27], v[48:63]
	v_mfma_f32_32x32x16_bf16 v[32:47], a[20:23], a[24:27], v[32:47]
	s_waitcnt vmcnt(6)
	s_waitcnt lgkmcnt(0)
	s_barrier
	ds_read_b128 a[12:15], v82 offset:53248
	ds_read_b128 a[8:11], v82 offset:49152
	ds_read_b128 a[4:7], v90
	ds_read_b128 a[0:3], v92
	v_mfma_f32_32x32x16_bf16 v[16:31], a[16:19], a[28:31], v[16:31]
	v_lshl_add_u64 v[170:171], v[66:67], 0, s[30:31]
	s_nop 0
	v_lshl_add_u64 v[172:173], v[68:69], 0, s[30:31]
	s_nop 0
	v_readfirstlane_b32 s39, v115
	s_nop 0
	v_lshl_add_u64 v[174:175], v[70:71], 0, s[30:31]
	s_nop 0
	v_mfma_f32_32x32x16_bf16 v[0:15], a[20:23], a[28:31], v[0:15]
	s_and_b32 m0, s32, 7
	s_lshl_b32 m0, m0, 12
	s_add_i32 m0, m0, 0x0
	s_nop 0
	global_load_lds_dwordx4 v[170:171], off
	s_nop 0
	v_lshl_add_u64 v[176:177], v[72:73], 0, s[30:31]
	s_nop 0
	v_readfirstlane_b32 s48, v116
	s_nop 0
	v_lshl_add_u64 v[178:179], v[74:75], 0, s[30:31]
	s_nop 0
	v_readfirstlane_b32 s49, v117
	s_nop 0
	v_lshl_add_u64 v[180:181], v[76:77], 0, s[30:31]
	s_nop 0
	s_mov_b64 s[30:31], 0x380
	s_nop 0
	s_nop 0
	s_nop 0
	s_nop 0
	s_nop 0
	ds_read_b128 a[16:19], v93
	ds_read_b128 a[20:23], v91
	ds_read_b128 a[24:27], v84 offset:49152
	ds_read_b128 a[28:31], v84 offset:53248
	s_waitcnt lgkmcnt(4)
	v_mfma_f32_32x32x16_bf16 v[48:63], a[0:3], a[8:11], v[48:63]
	s_nop 0
	v_readfirstlane_b32 s53, v118
	v_readfirstlane_b32 s54, v119
	v_mfma_f32_32x32x16_bf16 v[32:47], a[4:7], a[8:11], v[32:47]
	s_and_b32 m0, s32, 7
	s_lshl_b32 m0, m0, 12
	s_add_i32 m0, m0, 0x400
	s_nop 0
	global_load_lds_dwordx4 v[172:173], off
	v_mfma_f32_32x32x16_bf16 v[16:31], a[0:3], a[12:15], v[16:31]
	v_mfma_f32_32x32x16_bf16 v[0:15], a[4:7], a[12:15], v[0:15]
	s_and_b32 m0, s32, 7
	s_lshl_b32 m0, m0, 12
	s_add_i32 m0, m0, 0x800
	s_nop 0
	global_load_lds_dwordx4 v[174:175], off
	s_nop 0
	s_nop 0
	s_nop 0
	s_nop 0
	ds_read_b128 a[0:3], v95
	ds_read_b128 a[4:7], v94
	ds_read_b128 a[8:11], v86 offset:49152
	ds_read_b128 a[12:15], v86 offset:53248
	s_waitcnt lgkmcnt(5)
	v_mfma_f32_32x32x16_bf16 v[48:63], a[16:19], a[24:27], v[48:63]
	v_mfma_f32_32x32x16_bf16 v[32:47], a[20:23], a[24:27], v[32:47]
	s_and_b32 m0, s32, 7
	s_lshl_b32 m0, m0, 12
	s_add_i32 m0, m0, 0xc00
	s_nop 0
	global_load_lds_dwordx4 v[176:177], off
	s_waitcnt lgkmcnt(4)
	v_mfma_f32_32x32x16_bf16 v[16:31], a[16:19], a[28:31], v[16:31]
	v_mfma_f32_32x32x16_bf16 v[0:15], a[20:23], a[28:31], v[0:15]
	s_and_b32 m0, s32, 7
	s_lshl_b32 m0, m0, 11
	s_add_i32 m0, m0, 0x8000
	s_nop 0
	global_load_lds_dwordx4 v[178:179], off
	s_nop 0
	s_nop 0
	s_nop 0
	s_nop 0
	ds_read_b128 a[16:19], v97
	ds_read_b128 a[20:23], v96
	ds_read_b128 a[24:27], v88 offset:49152
	ds_read_b128 a[28:31], v88 offset:53248
	s_waitcnt lgkmcnt(5)
	v_mfma_f32_32x32x16_bf16 v[48:63], a[0:3], a[8:11], v[48:63]
	v_mfma_f32_32x32x16_bf16 v[32:47], a[4:7], a[8:11], v[32:47]
	s_and_b32 m0, s32, 7
	s_lshl_b32 m0, m0, 11
	s_add_i32 m0, m0, 0x8400
	s_nop 0
	global_load_lds_dwordx4 v[180:181], off
	s_waitcnt lgkmcnt(4)
	v_mfma_f32_32x32x16_bf16 v[16:31], a[0:3], a[12:15], v[16:31]
	v_mfma_f32_32x32x16_bf16 v[0:15], a[4:7], a[12:15], v[0:15]
	s_nop 0
	s_nop 0
	s_nop 0
	s_nop 0
	s_waitcnt lgkmcnt(1)
	v_mfma_f32_32x32x16_bf16 v[48:63], a[16:19], a[24:27], v[48:63]
	v_mfma_f32_32x32x16_bf16 v[32:47], a[20:23], a[24:27], v[32:47]
	s_waitcnt vmcnt(6)
	s_waitcnt lgkmcnt(0)
	s_barrier
	ds_read_b128 a[12:15], v101
	ds_read_b128 a[8:11], v100
	ds_read_b128 a[4:7], v99
	ds_read_b128 a[0:3], v98
	v_mfma_f32_32x32x16_bf16 v[16:31], a[16:19], a[28:31], v[16:31]
	v_lshl_add_u64 v[158:159], v[66:67], 0, s[30:31]
	s_nop 0
	v_lshl_add_u64 v[160:161], v[68:69], 0, s[30:31]
	s_nop 0
	v_readfirstlane_b32 s33, v121
	s_nop 0
	v_lshl_add_u64 v[162:163], v[70:71], 0, s[30:31]
	s_nop 0
	v_mfma_f32_32x32x16_bf16 v[0:15], a[20:23], a[28:31], v[0:15]
	s_and_b32 m0, s32, 7
	s_lshl_b32 m0, m0, 12
	s_add_i32 m0, m0, 0xc000
	s_nop 0
	global_load_lds_dwordx4 v[158:159], off
	s_nop 0
	v_lshl_add_u64 v[164:165], v[72:73], 0, s[30:31]
	s_nop 0
	v_readfirstlane_b32 s34, v122
	s_nop 0
	v_lshl_add_u64 v[166:167], v[74:75], 0, s[30:31]
	s_nop 0
	v_readfirstlane_b32 s35, v123
	s_nop 0
	v_lshl_add_u64 v[168:169], v[76:77], 0, s[30:31]
	s_nop 0
	s_mov_b64 s[30:31], 0x400
	s_nop 0
	s_nop 0
	s_nop 0
	s_nop 0
	s_nop 0
	ds_read_b128 a[16:19], v102
	ds_read_b128 a[20:23], v103
	ds_read_b128 a[24:27], v104
	ds_read_b128 a[28:31], v105
	s_waitcnt lgkmcnt(4)
	v_mfma_f32_32x32x16_bf16 v[48:63], a[0:3], a[8:11], v[48:63]
	s_nop 0
	v_readfirstlane_b32 s1, v126
	v_readfirstlane_b32 s36, v124
	v_readfirstlane_b32 s37, v125
	v_mfma_f32_32x32x16_bf16 v[32:47], a[4:7], a[8:11], v[32:47]
	s_and_b32 m0, s32, 7
	s_lshl_b32 m0, m0, 12
	s_add_i32 m0, m0, 0xc400
	s_nop 0
	global_load_lds_dwordx4 v[160:161], off
	v_mfma_f32_32x32x16_bf16 v[16:31], a[0:3], a[12:15], v[16:31]
	v_mfma_f32_32x32x16_bf16 v[0:15], a[4:7], a[12:15], v[0:15]
	s_and_b32 m0, s32, 7
	s_lshl_b32 m0, m0, 12
	s_add_i32 m0, m0, 0xc800
	s_nop 0
	global_load_lds_dwordx4 v[162:163], off
	s_nop 0
	s_nop 0
	s_nop 0
	s_nop 0
	ds_read_b128 a[0:3], v106
	ds_read_b128 a[4:7], v107
	ds_read_b128 a[8:11], v108
	ds_read_b128 a[12:15], v109
	s_waitcnt lgkmcnt(5)
	v_mfma_f32_32x32x16_bf16 v[48:63], a[16:19], a[24:27], v[48:63]
	v_mfma_f32_32x32x16_bf16 v[32:47], a[20:23], a[24:27], v[32:47]
	s_and_b32 m0, s32, 7
	s_lshl_b32 m0, m0, 12
	s_add_i32 m0, m0, 0xcc00
	s_nop 0
	global_load_lds_dwordx4 v[164:165], off
	s_waitcnt lgkmcnt(4)
	v_mfma_f32_32x32x16_bf16 v[16:31], a[16:19], a[28:31], v[16:31]
	v_mfma_f32_32x32x16_bf16 v[0:15], a[20:23], a[28:31], v[0:15]
	s_and_b32 m0, s32, 7
	s_lshl_b32 m0, m0, 11
	s_add_i32 m0, m0, 0x14000
	s_nop 0
	global_load_lds_dwordx4 v[166:167], off
	s_nop 0
	s_nop 0
	s_nop 0
	s_nop 0
	ds_read_b128 a[16:19], v110
	ds_read_b128 a[20:23], v111
	ds_read_b128 a[24:27], v112
	ds_read_b128 a[28:31], v113
	s_waitcnt lgkmcnt(5)
	v_mfma_f32_32x32x16_bf16 v[48:63], a[0:3], a[8:11], v[48:63]
	v_mfma_f32_32x32x16_bf16 v[32:47], a[4:7], a[8:11], v[32:47]
	s_and_b32 m0, s32, 7
	s_lshl_b32 m0, m0, 11
	s_add_i32 m0, m0, 0x14400
	s_nop 0
	global_load_lds_dwordx4 v[168:169], off
	s_waitcnt lgkmcnt(4)
	v_mfma_f32_32x32x16_bf16 v[16:31], a[0:3], a[12:15], v[16:31]
	v_mfma_f32_32x32x16_bf16 v[0:15], a[4:7], a[12:15], v[0:15]
	s_nop 0
	s_nop 0
	s_nop 0
	s_nop 0
	s_waitcnt lgkmcnt(1)
	v_mfma_f32_32x32x16_bf16 v[48:63], a[16:19], a[24:27], v[48:63]
	v_mfma_f32_32x32x16_bf16 v[32:47], a[20:23], a[24:27], v[32:47]
	s_waitcnt vmcnt(6)
	s_waitcnt lgkmcnt(0)
	s_barrier
	ds_read_b128 a[12:15], v82 offset:4096
	ds_read_b128 a[8:11], v82
	ds_read_b128 a[4:7], v83 offset:36864
	ds_read_b128 a[0:3], v83 offset:32768
	v_mfma_f32_32x32x16_bf16 v[16:31], a[16:19], a[28:31], v[16:31]
	v_lshl_add_u64 v[170:171], v[66:67], 0, s[30:31]
	s_nop 0
	v_lshl_add_u64 v[172:173], v[68:69], 0, s[30:31]
	s_nop 0
	v_readfirstlane_b32 s20, v127
	s_nop 0
	v_lshl_add_u64 v[174:175], v[70:71], 0, s[30:31]
	s_nop 0
	v_mfma_f32_32x32x16_bf16 v[0:15], a[20:23], a[28:31], v[0:15]
	s_and_b32 m0, s32, 7
	s_lshl_b32 m0, m0, 12
	s_add_i32 m0, m0, 0x18000
	s_nop 0
	global_load_lds_dwordx4 v[170:171], off
	s_nop 0
	v_lshl_add_u64 v[176:177], v[72:73], 0, s[30:31]
	s_nop 0
	v_readfirstlane_b32 s21, v128
	s_nop 0
	v_lshl_add_u64 v[178:179], v[74:75], 0, s[30:31]
	s_nop 0
	v_readfirstlane_b32 s23, v129
	s_nop 0
	v_lshl_add_u64 v[180:181], v[76:77], 0, s[30:31]
	s_nop 0
	s_mov_b64 s[28:29], 0x480
	s_nop 0
	s_nop 0
	s_nop 0
	s_nop 0
	s_nop 0
	ds_read_b128 a[16:19], v85 offset:32768
	ds_read_b128 a[20:23], v85 offset:36864
	ds_read_b128 a[24:27], v84
	ds_read_b128 a[28:31], v84 offset:4096
	s_waitcnt lgkmcnt(4)
	v_mfma_f32_32x32x16_bf16 v[48:63], a[0:3], a[8:11], v[48:63]
	s_nop 0
	v_lshl_add_u64 v[162:163], v[70:71], 0, s[28:29]
	v_readfirstlane_b32 s24, v131
	s_mov_b64 s[30:31], 0x500
	v_mfma_f32_32x32x16_bf16 v[32:47], a[4:7], a[8:11], v[32:47]
	s_and_b32 m0, s32, 7
	s_lshl_b32 m0, m0, 12
	s_add_i32 m0, m0, 0x18400
	s_nop 0
	global_load_lds_dwordx4 v[172:173], off
	v_mfma_f32_32x32x16_bf16 v[16:31], a[0:3], a[12:15], v[16:31]
	v_mfma_f32_32x32x16_bf16 v[0:15], a[4:7], a[12:15], v[0:15]
	s_and_b32 m0, s32, 7
	s_lshl_b32 m0, m0, 12
	s_add_i32 m0, m0, 0x18800
	s_nop 0
	global_load_lds_dwordx4 v[174:175], off
	s_nop 0
	s_nop 0
	s_nop 0
	s_nop 0
	ds_read_b128 a[0:3], v87 offset:32768
	ds_read_b128 a[4:7], v87 offset:36864
	ds_read_b128 a[8:11], v86
	ds_read_b128 a[12:15], v86 offset:4096
	s_waitcnt lgkmcnt(5)
	v_mfma_f32_32x32x16_bf16 v[48:63], a[16:19], a[24:27], v[48:63]
	v_mfma_f32_32x32x16_bf16 v[32:47], a[20:23], a[24:27], v[32:47]
	s_and_b32 m0, s32, 7
	s_lshl_b32 m0, m0, 12
	s_add_i32 m0, m0, 0x18c00
	s_nop 0
	global_load_lds_dwordx4 v[176:177], off
	s_waitcnt lgkmcnt(4)
	v_mfma_f32_32x32x16_bf16 v[16:31], a[16:19], a[28:31], v[16:31]
	v_mfma_f32_32x32x16_bf16 v[0:15], a[20:23], a[28:31], v[0:15]
	s_and_b32 m0, s32, 7
	s_lshl_b32 m0, m0, 11
	s_add_i32 m0, m0, 0x20000
	s_nop 0
	global_load_lds_dwordx4 v[178:179], off
	s_nop 0
	s_nop 0
	s_nop 0
	s_nop 0
	ds_read_b128 a[16:19], v89 offset:32768
	ds_read_b128 a[20:23], v89 offset:36864
	ds_read_b128 a[24:27], v88
	ds_read_b128 a[28:31], v88 offset:4096
	s_waitcnt lgkmcnt(5)
	v_mfma_f32_32x32x16_bf16 v[48:63], a[0:3], a[8:11], v[48:63]
	v_mfma_f32_32x32x16_bf16 v[32:47], a[4:7], a[8:11], v[32:47]
	s_and_b32 m0, s32, 7
	s_lshl_b32 m0, m0, 11
	s_add_i32 m0, m0, 0x20400
	s_nop 0
	global_load_lds_dwordx4 v[180:181], off
	s_waitcnt lgkmcnt(4)
	v_mfma_f32_32x32x16_bf16 v[16:31], a[0:3], a[12:15], v[16:31]
	v_mfma_f32_32x32x16_bf16 v[0:15], a[4:7], a[12:15], v[0:15]
	s_nop 0
	s_nop 0
	s_nop 0
	s_nop 0
	s_waitcnt lgkmcnt(1)
	v_mfma_f32_32x32x16_bf16 v[48:63], a[16:19], a[24:27], v[48:63]
	v_mfma_f32_32x32x16_bf16 v[32:47], a[20:23], a[24:27], v[32:47]
	s_waitcnt vmcnt(6)
	s_waitcnt lgkmcnt(0)
	s_barrier
	ds_read_b128 a[12:15], v82 offset:53248
	ds_read_b128 a[8:11], v82 offset:49152
	ds_read_b128 a[4:7], v90
	ds_read_b128 a[0:3], v92
	v_mfma_f32_32x32x16_bf16 v[16:31], a[16:19], a[28:31], v[16:31]
	v_lshl_add_u64 v[158:159], v[66:67], 0, s[28:29]
	s_nop 0
	v_lshl_add_u64 v[160:161], v[68:69], 0, s[28:29]
	s_nop 0
	s_nop 0
	s_nop 0
	s_nop 0
	v_mfma_f32_32x32x16_bf16 v[0:15], a[20:23], a[28:31], v[0:15]
	s_and_b32 m0, s32, 7
	s_lshl_b32 m0, m0, 12
	s_add_i32 m0, m0, 0x0
	s_nop 0
	global_load_lds_dwordx4 v[158:159], off
	s_nop 0
	v_lshl_add_u64 v[164:165], v[72:73], 0, s[28:29]
	s_nop 0
	s_nop 0
	s_nop 0
	v_lshl_add_u64 v[166:167], v[74:75], 0, s[28:29]
	s_nop 0
	s_nop 0
	s_nop 0
	v_lshl_add_u64 v[168:169], v[76:77], 0, s[28:29]
	v_readfirstlane_b32 s28, v130
	s_nop 0
	v_readfirstlane_b32 s29, v120
	s_nop 0
	s_nop 0
	s_nop 0
	s_nop 0
	s_nop 0
	ds_read_b128 a[16:19], v93
	ds_read_b128 a[20:23], v91
	ds_read_b128 a[24:27], v84 offset:49152
	ds_read_b128 a[28:31], v84 offset:53248
	s_waitcnt lgkmcnt(4)
	v_mfma_f32_32x32x16_bf16 v[48:63], a[0:3], a[8:11], v[48:63]
	s_nop 0
	v_lshl_add_u64 v[174:175], v[70:71], 0, s[30:31]
	v_mfma_f32_32x32x16_bf16 v[32:47], a[4:7], a[8:11], v[32:47]
	s_and_b32 m0, s32, 7
	s_lshl_b32 m0, m0, 12
	s_add_i32 m0, m0, 0x400
	s_nop 0
	global_load_lds_dwordx4 v[160:161], off
	v_mfma_f32_32x32x16_bf16 v[16:31], a[0:3], a[12:15], v[16:31]
	v_mfma_f32_32x32x16_bf16 v[0:15], a[4:7], a[12:15], v[0:15]
	s_and_b32 m0, s32, 7
	s_lshl_b32 m0, m0, 12
	s_add_i32 m0, m0, 0x800
	s_nop 0
	global_load_lds_dwordx4 v[162:163], off
	s_nop 0
	s_nop 0
	s_nop 0
	s_nop 0
	ds_read_b128 a[0:3], v95
	ds_read_b128 a[4:7], v94
	ds_read_b128 a[8:11], v86 offset:49152
	ds_read_b128 a[12:15], v86 offset:53248
	s_waitcnt lgkmcnt(5)
	v_mfma_f32_32x32x16_bf16 v[48:63], a[16:19], a[24:27], v[48:63]
	v_mfma_f32_32x32x16_bf16 v[32:47], a[20:23], a[24:27], v[32:47]
	s_and_b32 m0, s32, 7
	s_lshl_b32 m0, m0, 12
	s_add_i32 m0, m0, 0xc00
	s_nop 0
	global_load_lds_dwordx4 v[164:165], off
	s_waitcnt lgkmcnt(4)
	v_mfma_f32_32x32x16_bf16 v[16:31], a[16:19], a[28:31], v[16:31]
	v_mfma_f32_32x32x16_bf16 v[0:15], a[20:23], a[28:31], v[0:15]
	s_and_b32 m0, s32, 7
	s_lshl_b32 m0, m0, 11
	s_add_i32 m0, m0, 0x8000
	s_nop 0
	global_load_lds_dwordx4 v[166:167], off
	s_nop 0
	s_nop 0
	s_nop 0
	s_nop 0
	ds_read_b128 a[16:19], v97
	ds_read_b128 a[20:23], v96
	ds_read_b128 a[24:27], v88 offset:49152
	ds_read_b128 a[28:31], v88 offset:53248
	s_waitcnt lgkmcnt(5)
	v_mfma_f32_32x32x16_bf16 v[48:63], a[0:3], a[8:11], v[48:63]
	v_mfma_f32_32x32x16_bf16 v[32:47], a[4:7], a[8:11], v[32:47]
	s_and_b32 m0, s32, 7
	s_lshl_b32 m0, m0, 11
	s_add_i32 m0, m0, 0x8400
	s_nop 0
	global_load_lds_dwordx4 v[168:169], off
	s_waitcnt lgkmcnt(4)
	v_mfma_f32_32x32x16_bf16 v[16:31], a[0:3], a[12:15], v[16:31]
	v_mfma_f32_32x32x16_bf16 v[0:15], a[4:7], a[12:15], v[0:15]
	s_nop 0
	s_nop 0
	s_nop 0
	s_nop 0
	s_waitcnt lgkmcnt(1)
	v_mfma_f32_32x32x16_bf16 v[48:63], a[16:19], a[24:27], v[48:63]
	v_mfma_f32_32x32x16_bf16 v[32:47], a[20:23], a[24:27], v[32:47]
	s_waitcnt vmcnt(6)
	s_waitcnt lgkmcnt(0)
	s_barrier
	ds_read_b128 a[12:15], v101
	ds_read_b128 a[8:11], v100
	ds_read_b128 a[4:7], v99
	ds_read_b128 a[0:3], v98
	v_mfma_f32_32x32x16_bf16 v[16:31], a[16:19], a[28:31], v[16:31]
	v_lshl_add_u64 v[170:171], v[66:67], 0, s[30:31]
	s_nop 0
	v_lshl_add_u64 v[172:173], v[68:69], 0, s[30:31]
	s_nop 0
	s_nop 0
	s_nop 0
	s_nop 0
	v_mfma_f32_32x32x16_bf16 v[0:15], a[20:23], a[28:31], v[0:15]
	s_and_b32 m0, s32, 7
	s_lshl_b32 m0, m0, 12
	s_add_i32 m0, m0, 0xc000
	s_nop 0
	global_load_lds_dwordx4 v[170:171], off
	s_nop 0
	v_lshl_add_u64 v[176:177], v[72:73], 0, s[30:31]
	s_nop 0
	s_nop 0
	s_nop 0
	v_lshl_add_u64 v[178:179], v[74:75], 0, s[30:31]
	s_nop 0
	s_nop 0
	s_nop 0
	v_lshl_add_u64 v[180:181], v[76:77], 0, s[30:31]
	s_nop 0
	s_mov_b64 s[30:31], 0x580
	s_nop 0
	s_nop 0
	s_nop 0
	s_nop 0
	s_nop 0
	ds_read_b128 a[16:19], v102
	ds_read_b128 a[20:23], v103
	ds_read_b128 a[24:27], v104
	ds_read_b128 a[28:31], v105
	s_waitcnt lgkmcnt(4)
	v_mfma_f32_32x32x16_bf16 v[48:63], a[0:3], a[8:11], v[48:63]
	s_nop 0
	v_lshl_add_u64 v[162:163], v[70:71], 0, s[30:31]
	v_mfma_f32_32x32x16_bf16 v[32:47], a[4:7], a[8:11], v[32:47]
	s_and_b32 m0, s32, 7
	s_lshl_b32 m0, m0, 12
	s_add_i32 m0, m0, 0xc400
	s_nop 0
	global_load_lds_dwordx4 v[172:173], off
	v_mfma_f32_32x32x16_bf16 v[16:31], a[0:3], a[12:15], v[16:31]
	v_mfma_f32_32x32x16_bf16 v[0:15], a[4:7], a[12:15], v[0:15]
	s_and_b32 m0, s32, 7
	s_lshl_b32 m0, m0, 12
	s_add_i32 m0, m0, 0xc800
	s_nop 0
	global_load_lds_dwordx4 v[174:175], off
	s_nop 0
	s_nop 0
	s_nop 0
	s_nop 0
	ds_read_b128 a[0:3], v106
	ds_read_b128 a[4:7], v107
	ds_read_b128 a[8:11], v108
	ds_read_b128 a[12:15], v109
	s_waitcnt lgkmcnt(5)
	v_mfma_f32_32x32x16_bf16 v[48:63], a[16:19], a[24:27], v[48:63]
	v_mfma_f32_32x32x16_bf16 v[32:47], a[20:23], a[24:27], v[32:47]
	s_and_b32 m0, s32, 7
	s_lshl_b32 m0, m0, 12
	s_add_i32 m0, m0, 0xcc00
	s_nop 0
	global_load_lds_dwordx4 v[176:177], off
	s_waitcnt lgkmcnt(4)
	v_mfma_f32_32x32x16_bf16 v[16:31], a[16:19], a[28:31], v[16:31]
	v_mfma_f32_32x32x16_bf16 v[0:15], a[20:23], a[28:31], v[0:15]
	s_and_b32 m0, s32, 7
	s_lshl_b32 m0, m0, 11
	s_add_i32 m0, m0, 0x14000
	s_nop 0
	global_load_lds_dwordx4 v[178:179], off
	s_nop 0
	s_nop 0
	s_nop 0
	s_nop 0
	ds_read_b128 a[16:19], v110
	ds_read_b128 a[20:23], v111
	ds_read_b128 a[24:27], v112
	ds_read_b128 a[28:31], v113
	s_waitcnt lgkmcnt(5)
	v_mfma_f32_32x32x16_bf16 v[48:63], a[0:3], a[8:11], v[48:63]
	v_mfma_f32_32x32x16_bf16 v[32:47], a[4:7], a[8:11], v[32:47]
	s_and_b32 m0, s32, 7
	s_lshl_b32 m0, m0, 11
	s_add_i32 m0, m0, 0x14400
	s_nop 0
	global_load_lds_dwordx4 v[180:181], off
	s_waitcnt lgkmcnt(4)
	v_mfma_f32_32x32x16_bf16 v[16:31], a[0:3], a[12:15], v[16:31]
	v_mfma_f32_32x32x16_bf16 v[0:15], a[4:7], a[12:15], v[0:15]
	s_nop 0
	s_nop 0
	s_nop 0
	s_nop 0
	s_waitcnt lgkmcnt(1)
	v_mfma_f32_32x32x16_bf16 v[48:63], a[16:19], a[24:27], v[48:63]
	v_mfma_f32_32x32x16_bf16 v[32:47], a[20:23], a[24:27], v[32:47]
	s_waitcnt vmcnt(6)
	s_waitcnt lgkmcnt(0)
	s_barrier
	ds_read_b128 a[12:15], v82 offset:4096
	ds_read_b128 a[8:11], v82
	ds_read_b128 a[4:7], v83 offset:36864
	ds_read_b128 a[0:3], v83 offset:32768
	v_mfma_f32_32x32x16_bf16 v[16:31], a[16:19], a[28:31], v[16:31]
	v_lshl_add_u64 v[158:159], v[66:67], 0, s[30:31]
	s_nop 0
	v_lshl_add_u64 v[160:161], v[68:69], 0, s[30:31]
	s_nop 0
	s_nop 0
	s_nop 0
	s_nop 0
	v_mfma_f32_32x32x16_bf16 v[0:15], a[20:23], a[28:31], v[0:15]
	s_and_b32 m0, s32, 7
	s_lshl_b32 m0, m0, 12
	s_add_i32 m0, m0, 0x18000
	s_nop 0
	global_load_lds_dwordx4 v[158:159], off
	s_nop 0
	v_lshl_add_u64 v[164:165], v[72:73], 0, s[30:31]
	s_nop 0
	s_nop 0
	s_nop 0
	v_lshl_add_u64 v[166:167], v[74:75], 0, s[30:31]
	s_nop 0
	s_nop 0
	s_nop 0
	v_lshl_add_u64 v[168:169], v[76:77], 0, s[30:31]
	s_nop 0
	s_mov_b64 s[30:31], 0x600
	s_nop 0
	s_nop 0
	s_nop 0
	s_nop 0
	s_nop 0
	ds_read_b128 a[16:19], v85 offset:32768
	ds_read_b128 a[20:23], v85 offset:36864
	ds_read_b128 a[24:27], v84
	ds_read_b128 a[28:31], v84 offset:4096
	s_waitcnt lgkmcnt(4)
	v_mfma_f32_32x32x16_bf16 v[48:63], a[0:3], a[8:11], v[48:63]
	s_nop 0
	v_mfma_f32_32x32x16_bf16 v[32:47], a[4:7], a[8:11], v[32:47]
	s_and_b32 m0, s32, 7
	s_lshl_b32 m0, m0, 12
	s_add_i32 m0, m0, 0x18400
	s_nop 0
	global_load_lds_dwordx4 v[160:161], off
	v_mfma_f32_32x32x16_bf16 v[16:31], a[0:3], a[12:15], v[16:31]
	v_mfma_f32_32x32x16_bf16 v[0:15], a[4:7], a[12:15], v[0:15]
	s_and_b32 m0, s32, 7
	s_lshl_b32 m0, m0, 12
	s_add_i32 m0, m0, 0x18800
	s_nop 0
	global_load_lds_dwordx4 v[162:163], off
	s_nop 0
	s_nop 0
	s_nop 0
	s_nop 0
	ds_read_b128 a[0:3], v87 offset:32768
	ds_read_b128 a[4:7], v87 offset:36864
	ds_read_b128 a[8:11], v86
	ds_read_b128 a[12:15], v86 offset:4096
	s_waitcnt lgkmcnt(5)
	v_mfma_f32_32x32x16_bf16 v[48:63], a[16:19], a[24:27], v[48:63]
	v_mfma_f32_32x32x16_bf16 v[32:47], a[20:23], a[24:27], v[32:47]
	s_and_b32 m0, s32, 7
	s_lshl_b32 m0, m0, 12
	s_add_i32 m0, m0, 0x18c00
	s_nop 0
	global_load_lds_dwordx4 v[164:165], off
	s_waitcnt lgkmcnt(4)
	v_mfma_f32_32x32x16_bf16 v[16:31], a[16:19], a[28:31], v[16:31]
	v_mfma_f32_32x32x16_bf16 v[0:15], a[20:23], a[28:31], v[0:15]
	s_and_b32 m0, s32, 7
	s_lshl_b32 m0, m0, 11
	s_add_i32 m0, m0, 0x20000
	s_nop 0
	global_load_lds_dwordx4 v[166:167], off
	s_nop 0
	s_nop 0
	s_nop 0
	s_nop 0
	ds_read_b128 a[16:19], v89 offset:32768
	ds_read_b128 a[20:23], v89 offset:36864
	ds_read_b128 a[24:27], v88
	ds_read_b128 a[28:31], v88 offset:4096
	s_waitcnt lgkmcnt(5)
	v_mfma_f32_32x32x16_bf16 v[48:63], a[0:3], a[8:11], v[48:63]
	v_mfma_f32_32x32x16_bf16 v[32:47], a[4:7], a[8:11], v[32:47]
	s_and_b32 m0, s32, 7
	s_lshl_b32 m0, m0, 11
	s_add_i32 m0, m0, 0x20400
	s_nop 0
	global_load_lds_dwordx4 v[168:169], off
	s_waitcnt lgkmcnt(4)
	v_mfma_f32_32x32x16_bf16 v[16:31], a[0:3], a[12:15], v[16:31]
	v_mfma_f32_32x32x16_bf16 v[0:15], a[4:7], a[12:15], v[0:15]
	s_nop 0
	s_nop 0
	s_nop 0
	s_nop 0
	s_waitcnt lgkmcnt(1)
	v_mfma_f32_32x32x16_bf16 v[48:63], a[16:19], a[24:27], v[48:63]
	v_mfma_f32_32x32x16_bf16 v[32:47], a[20:23], a[24:27], v[32:47]
	s_waitcnt vmcnt(6)
	s_waitcnt lgkmcnt(0)
	s_barrier
	ds_read_b128 a[12:15], v82 offset:53248
	ds_read_b128 a[8:11], v82 offset:49152
	ds_read_b128 a[4:7], v90
	ds_read_b128 a[0:3], v92
	v_mfma_f32_32x32x16_bf16 v[16:31], a[16:19], a[28:31], v[16:31]
	v_lshl_add_u64 v[170:171], v[66:67], 0, s[30:31]
	s_nop 0
	v_lshl_add_u64 v[172:173], v[68:69], 0, s[30:31]
	s_nop 0
	s_nop 0
	s_nop 0
	v_lshl_add_u64 v[174:175], v[70:71], 0, s[30:31]
	s_nop 0
	v_mfma_f32_32x32x16_bf16 v[0:15], a[20:23], a[28:31], v[0:15]
	s_and_b32 m0, s32, 7
	s_lshl_b32 m0, m0, 12
	s_add_i32 m0, m0, 0x0
	s_nop 0
	global_load_lds_dwordx4 v[170:171], off
	s_nop 0
	v_lshl_add_u64 v[176:177], v[72:73], 0, s[30:31]
	s_nop 0
	s_nop 0
	s_nop 0
	v_lshl_add_u64 v[178:179], v[74:75], 0, s[30:31]
	s_nop 0
	s_nop 0
	s_nop 0
	v_lshl_add_u64 v[180:181], v[76:77], 0, s[30:31]
	s_nop 0
	s_mov_b64 s[30:31], 0x680
	s_nop 0
	s_nop 0
	s_nop 0
	s_nop 0
	s_nop 0
	ds_read_b128 a[16:19], v93
	ds_read_b128 a[20:23], v91
	ds_read_b128 a[24:27], v84 offset:49152
	ds_read_b128 a[28:31], v84 offset:53248
	s_waitcnt lgkmcnt(4)
	v_mfma_f32_32x32x16_bf16 v[48:63], a[0:3], a[8:11], v[48:63]
	s_nop 0
	v_mfma_f32_32x32x16_bf16 v[32:47], a[4:7], a[8:11], v[32:47]
	s_and_b32 m0, s32, 7
	s_lshl_b32 m0, m0, 12
	s_add_i32 m0, m0, 0x400
	s_nop 0
	global_load_lds_dwordx4 v[172:173], off
	v_mfma_f32_32x32x16_bf16 v[16:31], a[0:3], a[12:15], v[16:31]
	v_mfma_f32_32x32x16_bf16 v[0:15], a[4:7], a[12:15], v[0:15]
	s_and_b32 m0, s32, 7
	s_lshl_b32 m0, m0, 12
	s_add_i32 m0, m0, 0x800
	s_nop 0
	global_load_lds_dwordx4 v[174:175], off
	s_nop 0
	s_nop 0
	s_nop 0
	s_nop 0
	ds_read_b128 a[0:3], v95
	ds_read_b128 a[4:7], v94
	ds_read_b128 a[8:11], v86 offset:49152
	ds_read_b128 a[12:15], v86 offset:53248
	s_waitcnt lgkmcnt(5)
	v_mfma_f32_32x32x16_bf16 v[48:63], a[16:19], a[24:27], v[48:63]
	v_mfma_f32_32x32x16_bf16 v[32:47], a[20:23], a[24:27], v[32:47]
	s_and_b32 m0, s32, 7
	s_lshl_b32 m0, m0, 12
	s_add_i32 m0, m0, 0xc00
	s_nop 0
	global_load_lds_dwordx4 v[176:177], off
	s_waitcnt lgkmcnt(4)
	v_mfma_f32_32x32x16_bf16 v[16:31], a[16:19], a[28:31], v[16:31]
	v_mfma_f32_32x32x16_bf16 v[0:15], a[20:23], a[28:31], v[0:15]
	s_and_b32 m0, s32, 7
	s_lshl_b32 m0, m0, 11
	s_add_i32 m0, m0, 0x8000
	s_nop 0
	global_load_lds_dwordx4 v[178:179], off
	s_nop 0
	s_nop 0
	s_nop 0
	s_nop 0
	ds_read_b128 a[16:19], v97
	ds_read_b128 a[20:23], v96
	ds_read_b128 a[24:27], v88 offset:49152
	ds_read_b128 a[28:31], v88 offset:53248
	s_waitcnt lgkmcnt(5)
	v_mfma_f32_32x32x16_bf16 v[48:63], a[0:3], a[8:11], v[48:63]
	v_mfma_f32_32x32x16_bf16 v[32:47], a[4:7], a[8:11], v[32:47]
	s_and_b32 m0, s32, 7
	s_lshl_b32 m0, m0, 11
	s_add_i32 m0, m0, 0x8400
	s_nop 0
	global_load_lds_dwordx4 v[180:181], off
	s_waitcnt lgkmcnt(4)
	v_mfma_f32_32x32x16_bf16 v[16:31], a[0:3], a[12:15], v[16:31]
	v_mfma_f32_32x32x16_bf16 v[0:15], a[4:7], a[12:15], v[0:15]
	s_nop 0
	s_nop 0
	s_nop 0
	s_nop 0
	s_waitcnt lgkmcnt(1)
	v_mfma_f32_32x32x16_bf16 v[48:63], a[16:19], a[24:27], v[48:63]
	v_mfma_f32_32x32x16_bf16 v[32:47], a[20:23], a[24:27], v[32:47]
	s_waitcnt vmcnt(6)
	s_waitcnt lgkmcnt(0)
	s_barrier
	ds_read_b128 a[12:15], v101
	ds_read_b128 a[8:11], v100
	ds_read_b128 a[4:7], v99
	ds_read_b128 a[0:3], v98
	v_mfma_f32_32x32x16_bf16 v[16:31], a[16:19], a[28:31], v[16:31]
	v_lshl_add_u64 v[158:159], v[66:67], 0, s[30:31]
	s_nop 0
	v_lshl_add_u64 v[160:161], v[68:69], 0, s[30:31]
	s_nop 0
	s_nop 0
	s_nop 0
	v_lshl_add_u64 v[162:163], v[70:71], 0, s[30:31]
	s_nop 0
	v_mfma_f32_32x32x16_bf16 v[0:15], a[20:23], a[28:31], v[0:15]
	s_and_b32 m0, s32, 7
	s_lshl_b32 m0, m0, 12
	s_add_i32 m0, m0, 0xc000
	s_nop 0
	global_load_lds_dwordx4 v[158:159], off
	s_nop 0
	v_lshl_add_u64 v[164:165], v[72:73], 0, s[30:31]
	s_nop 0
	s_nop 0
	s_nop 0
	v_lshl_add_u64 v[166:167], v[74:75], 0, s[30:31]
	s_nop 0
	s_nop 0
	s_nop 0
	v_lshl_add_u64 v[168:169], v[76:77], 0, s[30:31]
	s_nop 0
	s_mov_b64 s[30:31], 0x700
	s_nop 0
	s_nop 0
	s_nop 0
	s_nop 0
	s_nop 0
	ds_read_b128 a[16:19], v102
	ds_read_b128 a[20:23], v103
	ds_read_b128 a[24:27], v104
	ds_read_b128 a[28:31], v105
	s_waitcnt lgkmcnt(4)
	v_mfma_f32_32x32x16_bf16 v[48:63], a[0:3], a[8:11], v[48:63]
	s_nop 0
	v_mfma_f32_32x32x16_bf16 v[32:47], a[4:7], a[8:11], v[32:47]
	s_and_b32 m0, s32, 7
	s_lshl_b32 m0, m0, 12
	s_add_i32 m0, m0, 0xc400
	s_nop 0
	global_load_lds_dwordx4 v[160:161], off
	v_mfma_f32_32x32x16_bf16 v[16:31], a[0:3], a[12:15], v[16:31]
	v_mfma_f32_32x32x16_bf16 v[0:15], a[4:7], a[12:15], v[0:15]
	s_and_b32 m0, s32, 7
	s_lshl_b32 m0, m0, 12
	s_add_i32 m0, m0, 0xc800
	s_nop 0
	global_load_lds_dwordx4 v[162:163], off
	s_nop 0
	s_nop 0
	s_nop 0
	s_nop 0
	ds_read_b128 a[0:3], v106
	ds_read_b128 a[4:7], v107
	ds_read_b128 a[8:11], v108
	ds_read_b128 a[12:15], v109
	s_waitcnt lgkmcnt(5)
	v_mfma_f32_32x32x16_bf16 v[48:63], a[16:19], a[24:27], v[48:63]
	v_mfma_f32_32x32x16_bf16 v[32:47], a[20:23], a[24:27], v[32:47]
	s_and_b32 m0, s32, 7
	s_lshl_b32 m0, m0, 12
	s_add_i32 m0, m0, 0xcc00
	s_nop 0
	global_load_lds_dwordx4 v[164:165], off
	s_waitcnt lgkmcnt(4)
	v_mfma_f32_32x32x16_bf16 v[16:31], a[16:19], a[28:31], v[16:31]
	v_mfma_f32_32x32x16_bf16 v[0:15], a[20:23], a[28:31], v[0:15]
	s_and_b32 m0, s32, 7
	s_lshl_b32 m0, m0, 11
	s_add_i32 m0, m0, 0x14000
	s_nop 0
	global_load_lds_dwordx4 v[166:167], off
	s_nop 0
	s_nop 0
	s_nop 0
	s_nop 0
	ds_read_b128 a[16:19], v110
	ds_read_b128 a[20:23], v111
	ds_read_b128 a[24:27], v112
	ds_read_b128 a[28:31], v113
	s_waitcnt lgkmcnt(5)
	v_mfma_f32_32x32x16_bf16 v[48:63], a[0:3], a[8:11], v[48:63]
	v_mfma_f32_32x32x16_bf16 v[32:47], a[4:7], a[8:11], v[32:47]
	s_and_b32 m0, s32, 7
	s_lshl_b32 m0, m0, 11
	s_add_i32 m0, m0, 0x14400
	s_nop 0
	global_load_lds_dwordx4 v[168:169], off
	s_waitcnt lgkmcnt(4)
	v_mfma_f32_32x32x16_bf16 v[16:31], a[0:3], a[12:15], v[16:31]
	v_mfma_f32_32x32x16_bf16 v[0:15], a[4:7], a[12:15], v[0:15]
	s_nop 0
	s_nop 0
	s_nop 0
	s_nop 0
	s_waitcnt lgkmcnt(1)
	v_mfma_f32_32x32x16_bf16 v[48:63], a[16:19], a[24:27], v[48:63]
	v_mfma_f32_32x32x16_bf16 v[32:47], a[20:23], a[24:27], v[32:47]
	s_waitcnt vmcnt(6)
	s_waitcnt lgkmcnt(0)
	s_barrier
	ds_read_b128 a[12:15], v82 offset:4096
	ds_read_b128 a[8:11], v82
	ds_read_b128 a[4:7], v83 offset:36864
	ds_read_b128 a[0:3], v83 offset:32768
	v_mfma_f32_32x32x16_bf16 v[16:31], a[16:19], a[28:31], v[16:31]
	v_lshl_add_u64 v[170:171], v[66:67], 0, s[30:31]
	s_nop 0
	v_lshl_add_u64 v[172:173], v[68:69], 0, s[30:31]
	s_nop 0
	s_nop 0
	s_nop 0
	v_lshl_add_u64 v[174:175], v[70:71], 0, s[30:31]
	s_nop 0
	v_mfma_f32_32x32x16_bf16 v[0:15], a[20:23], a[28:31], v[0:15]
	s_and_b32 m0, s32, 7
	s_lshl_b32 m0, m0, 12
	s_add_i32 m0, m0, 0x18000
	s_nop 0
	global_load_lds_dwordx4 v[170:171], off
	s_nop 0
	v_lshl_add_u64 v[176:177], v[72:73], 0, s[30:31]
	s_nop 0
	s_nop 0
	s_nop 0
	v_lshl_add_u64 v[178:179], v[74:75], 0, s[30:31]
	s_nop 0
	s_nop 0
	s_nop 0
	v_lshl_add_u64 v[180:181], v[76:77], 0, s[30:31]
	s_nop 0
	s_mov_b64 s[30:31], 0x780
	s_nop 0
	s_nop 0
	s_nop 0
	s_nop 0
	s_nop 0
	ds_read_b128 a[16:19], v85 offset:32768
	ds_read_b128 a[20:23], v85 offset:36864
	ds_read_b128 a[24:27], v84
	ds_read_b128 a[28:31], v84 offset:4096
	s_waitcnt lgkmcnt(4)
	v_mfma_f32_32x32x16_bf16 v[48:63], a[0:3], a[8:11], v[48:63]
	v_lshl_add_u64 v[158:159], v[66:67], 0, s[30:31]
	s_nop 0
	v_mfma_f32_32x32x16_bf16 v[32:47], a[4:7], a[8:11], v[32:47]
	s_and_b32 m0, s32, 7
	s_lshl_b32 m0, m0, 12
	s_add_i32 m0, m0, 0x18400
	s_nop 0
	global_load_lds_dwordx4 v[172:173], off
	v_mfma_f32_32x32x16_bf16 v[16:31], a[0:3], a[12:15], v[16:31]
	v_mfma_f32_32x32x16_bf16 v[0:15], a[4:7], a[12:15], v[0:15]
	s_and_b32 m0, s32, 7
	s_lshl_b32 m0, m0, 12
	s_add_i32 m0, m0, 0x18800
	s_nop 0
	global_load_lds_dwordx4 v[174:175], off
	s_nop 0
	s_nop 0
	s_nop 0
	s_nop 0
	ds_read_b128 a[0:3], v87 offset:32768
	ds_read_b128 a[4:7], v87 offset:36864
	ds_read_b128 a[8:11], v86
	ds_read_b128 a[12:15], v86 offset:4096
	s_waitcnt lgkmcnt(5)
	v_mfma_f32_32x32x16_bf16 v[48:63], a[16:19], a[24:27], v[48:63]
	v_mfma_f32_32x32x16_bf16 v[32:47], a[20:23], a[24:27], v[32:47]
	s_and_b32 m0, s32, 7
	s_lshl_b32 m0, m0, 12
	s_add_i32 m0, m0, 0x18c00
	s_nop 0
	global_load_lds_dwordx4 v[176:177], off
	s_waitcnt lgkmcnt(4)
	v_mfma_f32_32x32x16_bf16 v[16:31], a[16:19], a[28:31], v[16:31]
	v_mfma_f32_32x32x16_bf16 v[0:15], a[20:23], a[28:31], v[0:15]
	s_and_b32 m0, s32, 7
	s_lshl_b32 m0, m0, 11
	s_add_i32 m0, m0, 0x20000
	s_nop 0
	global_load_lds_dwordx4 v[178:179], off
	s_nop 0
	s_nop 0
	s_nop 0
	s_nop 0
	ds_read_b128 a[16:19], v89 offset:32768
	ds_read_b128 a[20:23], v89 offset:36864
	ds_read_b128 a[24:27], v88
	ds_read_b128 a[28:31], v88 offset:4096
	s_waitcnt lgkmcnt(5)
	v_mfma_f32_32x32x16_bf16 v[48:63], a[0:3], a[8:11], v[48:63]
	v_mfma_f32_32x32x16_bf16 v[32:47], a[4:7], a[8:11], v[32:47]
	s_and_b32 m0, s32, 7
	s_lshl_b32 m0, m0, 11
	s_add_i32 m0, m0, 0x20400
	s_nop 0
	global_load_lds_dwordx4 v[180:181], off
	s_waitcnt lgkmcnt(4)
	v_mfma_f32_32x32x16_bf16 v[16:31], a[0:3], a[12:15], v[16:31]
	v_mfma_f32_32x32x16_bf16 v[0:15], a[4:7], a[12:15], v[0:15]
	s_nop 0
	s_nop 0
	s_nop 0
	s_nop 0
	s_waitcnt lgkmcnt(1)
	v_mfma_f32_32x32x16_bf16 v[48:63], a[16:19], a[24:27], v[48:63]
	v_mfma_f32_32x32x16_bf16 v[32:47], a[20:23], a[24:27], v[32:47]
	s_waitcnt vmcnt(6)
	s_waitcnt lgkmcnt(0)
	s_barrier
	ds_read_b128 a[12:15], v82 offset:53248
	ds_read_b128 a[8:11], v82 offset:49152
	ds_read_b128 a[4:7], v90
	ds_read_b128 a[0:3], v92
	s_nop 0
	v_lshl_add_u64 v[160:161], v[68:69], 0, s[30:31]
	s_nop 0
	v_mfma_f32_32x32x16_bf16 v[16:31], a[16:19], a[28:31], v[16:31]
	s_nop 0
	v_lshl_add_u64 v[162:163], v[70:71], 0, s[30:31]
	s_nop 0
	v_readlane_b32 s20, v215, 52
	s_nop 0
	v_lshl_add_u64 v[164:165], v[72:73], 0, s[30:31]
	s_nop 0
	v_mfma_f32_32x32x16_bf16 v[0:15], a[20:23], a[28:31], v[0:15]
	s_and_b32 m0, s32, 7
	s_lshl_b32 m0, m0, 12
	s_add_i32 m0, m0, 0x0
	s_nop 0
	global_load_lds_dwordx4 v[158:159], off
	s_nop 0
	v_lshl_add_u64 v[166:167], v[74:75], 0, s[30:31]
	s_nop 0
	v_readlane_b32 s21, v215, 53
	s_nop 0
	v_lshl_add_u64 v[168:169], v[76:77], 0, s[30:31]
	s_nop 0
	s_mov_b32 s23, 0
	s_nop 0
	s_nop 0
	s_nop 0
	s_nop 0
	s_nop 0
	ds_read_b128 a[16:19], v93
	ds_read_b128 a[20:23], v91
	ds_read_b128 a[24:27], v84 offset:49152
	ds_read_b128 a[28:31], v84 offset:53248
	s_waitcnt lgkmcnt(4)
	v_mfma_f32_32x32x16_bf16 v[48:63], a[0:3], a[8:11], v[48:63]
	v_mfma_f32_32x32x16_bf16 v[32:47], a[4:7], a[8:11], v[32:47]
	s_and_b32 m0, s32, 7
	s_lshl_b32 m0, m0, 12
	s_add_i32 m0, m0, 0x400
	s_nop 0
	global_load_lds_dwordx4 v[160:161], off
	v_mfma_f32_32x32x16_bf16 v[16:31], a[0:3], a[12:15], v[16:31]
	v_mfma_f32_32x32x16_bf16 v[0:15], a[4:7], a[12:15], v[0:15]
	s_and_b32 m0, s32, 7
	s_lshl_b32 m0, m0, 12
	s_add_i32 m0, m0, 0x800
	s_nop 0
	global_load_lds_dwordx4 v[162:163], off
	s_nop 0
	s_nop 0
	s_nop 0
	s_nop 0
	ds_read_b128 a[0:3], v95
	ds_read_b128 a[4:7], v94
	ds_read_b128 a[8:11], v86 offset:49152
	ds_read_b128 a[12:15], v86 offset:53248
	s_waitcnt lgkmcnt(5)
	v_mfma_f32_32x32x16_bf16 v[48:63], a[16:19], a[24:27], v[48:63]
	v_mfma_f32_32x32x16_bf16 v[32:47], a[20:23], a[24:27], v[32:47]
	s_and_b32 m0, s32, 7
	s_lshl_b32 m0, m0, 12
	s_add_i32 m0, m0, 0xc00
	s_nop 0
	global_load_lds_dwordx4 v[164:165], off
	s_waitcnt lgkmcnt(4)
	v_mfma_f32_32x32x16_bf16 v[16:31], a[16:19], a[28:31], v[16:31]
	v_mfma_f32_32x32x16_bf16 v[0:15], a[20:23], a[28:31], v[0:15]
	s_and_b32 m0, s32, 7
	s_lshl_b32 m0, m0, 11
	s_add_i32 m0, m0, 0x8000
	s_nop 0
	global_load_lds_dwordx4 v[166:167], off
	s_nop 0
	s_nop 0
	s_nop 0
	s_nop 0
	ds_read_b128 a[16:19], v97
	ds_read_b128 a[20:23], v96
	ds_read_b128 a[24:27], v88 offset:49152
	ds_read_b128 a[28:31], v88 offset:53248
	s_waitcnt lgkmcnt(5)
	v_mfma_f32_32x32x16_bf16 v[48:63], a[0:3], a[8:11], v[48:63]
	v_mfma_f32_32x32x16_bf16 v[32:47], a[4:7], a[8:11], v[32:47]
	s_and_b32 m0, s32, 7
	s_lshl_b32 m0, m0, 11
	s_add_i32 m0, m0, 0x8400
	s_nop 0
	global_load_lds_dwordx4 v[168:169], off
	s_waitcnt lgkmcnt(4)
	v_mfma_f32_32x32x16_bf16 v[16:31], a[0:3], a[12:15], v[16:31]
	v_mfma_f32_32x32x16_bf16 v[0:15], a[4:7], a[12:15], v[0:15]
	s_nop 0
	s_nop 0
	s_nop 0
	s_nop 0
	s_waitcnt lgkmcnt(1)
	v_mfma_f32_32x32x16_bf16 v[48:63], a[16:19], a[24:27], v[48:63]
	v_mfma_f32_32x32x16_bf16 v[32:47], a[20:23], a[24:27], v[32:47]
	s_waitcnt vmcnt(6)
	s_waitcnt lgkmcnt(0)
	s_barrier
	ds_read_b128 a[12:15], v101
	ds_read_b128 a[8:11], v100
	ds_read_b128 a[4:7], v99
	ds_read_b128 a[0:3], v98
	v_mfma_f32_32x32x16_bf16 v[16:31], a[16:19], a[28:31], v[16:31]
	v_mfma_f32_32x32x16_bf16 v[0:15], a[20:23], a[28:31], v[0:15]
	s_nop 0
	s_nop 0
	s_nop 0
	s_nop 0
	ds_read_b128 a[16:19], v102
	ds_read_b128 a[20:23], v103
	ds_read_b128 a[24:27], v104
	ds_read_b128 a[28:31], v105
	s_waitcnt lgkmcnt(4)
	v_mfma_f32_32x32x16_bf16 v[48:63], a[0:3], a[8:11], v[48:63]
	v_mfma_f32_32x32x16_bf16 v[32:47], a[4:7], a[8:11], v[32:47]
	v_mfma_f32_32x32x16_bf16 v[16:31], a[0:3], a[12:15], v[16:31]
	v_mfma_f32_32x32x16_bf16 v[0:15], a[4:7], a[12:15], v[0:15]
	s_nop 0
	s_nop 0
	s_nop 0
	s_nop 0
	ds_read_b128 a[0:3], v106
	ds_read_b128 a[4:7], v107
	ds_read_b128 a[8:11], v108
	ds_read_b128 a[12:15], v109
	s_waitcnt lgkmcnt(5)
	v_mfma_f32_32x32x16_bf16 v[48:63], a[16:19], a[24:27], v[48:63]
	v_mfma_f32_32x32x16_bf16 v[32:47], a[20:23], a[24:27], v[32:47]
	s_waitcnt lgkmcnt(4)
	v_mfma_f32_32x32x16_bf16 v[16:31], a[16:19], a[28:31], v[16:31]
	v_mfma_f32_32x32x16_bf16 v[0:15], a[20:23], a[28:31], v[0:15]
	s_nop 0
	s_nop 0
	s_nop 0
	s_nop 0
	ds_read_b128 a[16:19], v110
	ds_read_b128 a[20:23], v111
	ds_read_b128 a[24:27], v112
	ds_read_b128 a[28:31], v113
	s_waitcnt lgkmcnt(5)
	v_mfma_f32_32x32x16_bf16 v[48:63], a[0:3], a[8:11], v[48:63]
	v_mfma_f32_32x32x16_bf16 v[32:47], a[4:7], a[8:11], v[32:47]
	s_waitcnt lgkmcnt(4)
	v_mfma_f32_32x32x16_bf16 v[16:31], a[0:3], a[12:15], v[16:31]
	v_mfma_f32_32x32x16_bf16 v[0:15], a[4:7], a[12:15], v[0:15]
	s_nop 0
	s_nop 0
	s_nop 0
	s_nop 0
	s_waitcnt lgkmcnt(1)
	v_mfma_f32_32x32x16_bf16 v[48:63], a[16:19], a[24:27], v[48:63]
	v_mfma_f32_32x32x16_bf16 v[32:47], a[20:23], a[24:27], v[32:47]
	s_waitcnt vmcnt(0)
	s_waitcnt lgkmcnt(0)
	s_barrier
	ds_read_b128 a[12:15], v82 offset:4096
	ds_read_b128 a[8:11], v82
	ds_read_b128 a[4:7], v83 offset:36864
	ds_read_b128 a[0:3], v83 offset:32768
	v_mfma_f32_32x32x16_bf16 v[16:31], a[16:19], a[28:31], v[16:31]
	v_mfma_f32_32x32x16_bf16 v[0:15], a[20:23], a[28:31], v[0:15]
	s_nop 0
	s_nop 0
	s_nop 0
	s_nop 0
	ds_read_b128 a[16:19], v85 offset:32768
	ds_read_b128 a[20:23], v85 offset:36864
	ds_read_b128 a[24:27], v84
	ds_read_b128 a[28:31], v84 offset:4096
	s_waitcnt lgkmcnt(4)
	v_mfma_f32_32x32x16_bf16 v[48:63], a[0:3], a[8:11], v[48:63]
	v_mfma_f32_32x32x16_bf16 v[32:47], a[4:7], a[8:11], v[32:47]
	v_mfma_f32_32x32x16_bf16 v[16:31], a[0:3], a[12:15], v[16:31]
	v_mfma_f32_32x32x16_bf16 v[0:15], a[4:7], a[12:15], v[0:15]
	s_nop 0
	s_nop 0
	s_nop 0
	s_nop 0
	ds_read_b128 a[0:3], v87 offset:32768
	ds_read_b128 a[4:7], v87 offset:36864
	ds_read_b128 a[8:11], v86
	ds_read_b128 a[12:15], v86 offset:4096
	s_waitcnt lgkmcnt(5)
	v_mfma_f32_32x32x16_bf16 v[48:63], a[16:19], a[24:27], v[48:63]
	v_mfma_f32_32x32x16_bf16 v[32:47], a[20:23], a[24:27], v[32:47]
	s_waitcnt lgkmcnt(4)
	v_mfma_f32_32x32x16_bf16 v[16:31], a[16:19], a[28:31], v[16:31]
	v_mfma_f32_32x32x16_bf16 v[0:15], a[20:23], a[28:31], v[0:15]
	s_nop 0
	s_nop 0
	s_nop 0
	s_waitcnt lgkmcnt(1)
	v_mfma_f32_32x32x16_bf16 v[48:63], a[0:3], a[8:11], v[48:63]
	v_mfma_f32_32x32x16_bf16 v[32:47], a[4:7], a[8:11], v[32:47]
	s_nop 0
	s_waitcnt lgkmcnt(0)
	v_mfma_f32_32x32x16_bf16 v[0:15], a[4:7], a[12:15], v[0:15]
	v_mfma_f32_32x32x16_bf16 v[16:31], a[0:3], a[12:15], v[16:31]
	ds_read_b128 v[66:69], v89 offset:32768
	ds_read_b128 v[70:73], v88
	ds_read_b128 v[74:77], v89 offset:36864
	ds_read_b128 v[82:85], v88 offset:4096
	s_waitcnt lgkmcnt(0)
	s_barrier
	s_waitcnt lgkmcnt(0)
	v_mfma_f32_32x32x16_bf16 v[48:63], v[66:69], v[70:73], v[48:63]
	v_mfma_f32_32x32x16_bf16 v[32:47], v[74:77], v[70:73], v[32:47]
	s_nop 10
	ds_write_b128 v64, v[48:51]
	ds_write_b128 v64, v[52:55] offset:32
	ds_write_b128 v64, v[56:59] offset:64
	ds_write_b128 v64, v[60:63] offset:96
	ds_write_b128 v64, v[32:35] offset:128
	v_mfma_f32_32x32x16_bf16 v[0:15], v[74:77], v[82:85], v[0:15]
	v_mfma_f32_32x32x16_bf16 v[16:31], v[66:69], v[82:85], v[16:31]
	ds_write_b128 v64, v[36:39] offset:160
	ds_write_b128 v64, v[40:43] offset:192
	ds_write_b128 v64, v[44:47] offset:224
	s_nop 8
	ds_write_b128 v64, v[16:19] offset:16896
	ds_write_b128 v64, v[20:23] offset:16928
	ds_write_b128 v64, v[24:27] offset:16960
	ds_write_b128 v64, v[28:31] offset:16992
	ds_write_b128 v64, v[0:3] offset:17024
	ds_write_b128 v64, v[4:7] offset:17056
	ds_write_b128 v64, v[8:11] offset:17088
	ds_write_b128 v64, v[12:15] offset:17120
	s_waitcnt lgkmcnt(0)
	s_barrier
	v_lshl_or_b32 v0, v79, 2, s0
	v_ashrrev_i32_e32 v1, 31, v0
	v_lshl_add_u32 v4, v79, 4, 0
	v_cmp_eq_u32_e64 s[0:1], 0, v79
	v_lshl_add_u64 v[6:7], v[0:1], 2, s[92:93]
	v_lshl_add_u64 v[8:9], v[0:1], 1, s[20:21]
	s_branch .LBB0_96

.LBB0_159:
	v_mov_b32_e32 v78, v133
	s_lshl_b32 s22, s2, 8
	v_ashrrev_i32_e32 v6, 6, v78
	v_bfe_u32 v7, v78, 3, 3
	v_lshl_or_b32 v8, v6, 5, v7
	v_add_u32_e32 v0, s22, v8
	s_waitcnt lgkmcnt(0)
	v_ashrrev_i32_e32 v1, 31, v0
	v_lshlrev_b64 v[2:3], 11, v[0:1]
	v_bfe_u32 v1, v78, 4, 2
	v_readlane_b32 s0, v214, 4
	v_xor_b32_e32 v1, v1, v78
	v_readlane_b32 s1, v214, 5
	v_lshlrev_b32_e32 v1, 4, v1
	v_and_b32_e32 v64, 0x70, v1
	v_lshl_add_u64 v[2:3], s[0:1], 0, v[2:3]
	v_or_b32_e32 v1, 8, v8
	v_lshl_add_u64 v[66:67], v[2:3], 0, v[64:65]
	v_add_u32_e32 v2, s22, v1
	v_lshrrev_b32_e32 v1, 1, v1
	v_xor_b32_e32 v1, v1, v78
	v_ashrrev_i32_e32 v3, 31, v2
	v_lshlrev_b32_e32 v1, 4, v1
	v_or_b32_e32 v0, 16, v0
	v_lshlrev_b64 v[2:3], 11, v[2:3]
	v_and_b32_e32 v4, 0x70, v1
	v_ashrrev_i32_e32 v1, 31, v0
	v_lshl_add_u64 v[2:3], s[0:1], 0, v[2:3]
	v_mov_b32_e32 v5, v65
	v_lshlrev_b64 v[0:1], 11, v[0:1]
	v_lshl_add_u64 v[68:69], v[2:3], 0, v[4:5]
	v_lshl_add_u64 v[0:1], s[0:1], 0, v[0:1]
	v_or_b32_e32 v2, 24, v8
	v_lshl_add_u64 v[70:71], v[0:1], 0, v[64:65]
	v_add_u32_e32 v0, s22, v2
	v_lshrrev_b32_e32 v2, 1, v2
	v_ashrrev_i32_e32 v1, 31, v0
	v_xor_b32_e32 v2, v2, v78
	v_lshlrev_b64 v[0:1], 11, v[0:1]
	v_lshlrev_b32_e32 v2, 4, v2
	v_lshl_add_u64 v[0:1], s[0:1], 0, v[0:1]
	v_and_b32_e32 v2, 0x70, v2
	v_mov_b32_e32 v3, v65
	v_lshl_add_u64 v[72:73], v[0:1], 0, v[2:3]
	v_lshl_or_b32 v2, v6, 4, v7
	v_readlane_b32 s31, v214, 58
	v_lshlrev_b32_e32 v3, 12, v6
	v_add_u32_e32 v126, 0, v3
	v_add_u32_e32 v0, s31, v2
	v_ashrrev_i32_e32 v1, 31, v0
	v_lshlrev_b64 v[0:1], 11, v[0:1]
	s_waitcnt vmcnt(0)
	v_readfirstlane_b32 s37, v126
	v_add_u32_e32 v127, 0x400, v126
	v_lshl_add_u64 v[0:1], s[40:41], 0, v[0:1]
	v_or_b32_e32 v2, 8, v2
	s_waitcnt lgkmcnt(0)
	s_barrier
	s_mov_b32 m0, s37
	v_readfirstlane_b32 s38, v127
	v_add_u32_e32 v128, 0x800, v126
	v_lshlrev_b32_e32 v5, 11, v6
	v_and_b32_e32 v80, 1, v6
	v_lshl_add_u64 v[74:75], v[0:1], 0, v[64:65]
	v_add_u32_e32 v0, s31, v2
	v_lshrrev_b32_e32 v2, 1, v2
	global_load_lds_dwordx4 v[66:67], off
	s_mov_b32 m0, s38
	v_readfirstlane_b32 s39, v128
	v_add_u32_e32 v129, 0xc00, v126
	v_add_u32_e32 v6, 0, v5
	v_ashrrev_i32_e32 v1, 31, v0
	v_xor_b32_e32 v2, v2, v78
	global_load_lds_dwordx4 v[68:69], off
	s_mov_b32 m0, s39
	v_readfirstlane_b32 s48, v129
	v_add_u32_e32 v131, 0x8000, v6
	v_lshlrev_b64 v[0:1], 11, v[0:1]
	v_lshlrev_b32_e32 v2, 4, v2
	global_load_lds_dwordx4 v[70:71], off
	s_mov_b32 m0, s48
	v_readfirstlane_b32 s49, v131
	v_add_u32_e32 v130, 0x8400, v6
	v_lshl_add_u64 v[0:1], s[40:41], 0, v[0:1]
	v_and_b32_e32 v64, 0x70, v2
	global_load_lds_dwordx4 v[72:73], off
	s_mov_b32 m0, s49
	v_readfirstlane_b32 s53, v130
	v_add_u32_e32 v120, 0xc000, v126
	v_lshl_add_u64 v[76:77], v[0:1], 0, v[64:65]
	global_load_lds_dwordx4 v[74:75], off
	s_mov_b32 m0, s53
	s_mov_b64 s[0:1], 0x80
	v_readfirstlane_b32 s28, v120
	v_add_u32_e32 v121, 0xc400, v126
	global_load_lds_dwordx4 v[76:77], off
	v_lshl_add_u64 v[0:1], v[66:67], 0, s[0:1]
	s_mov_b32 m0, s28
	v_readfirstlane_b32 s29, v121
	v_add_u32_e32 v122, 0xc800, v126
	global_load_lds_dwordx4 v[0:1], off
	v_lshl_add_u64 v[0:1], v[68:69], 0, s[0:1]
	s_mov_b32 m0, s29
	v_readfirstlane_b32 s33, v122
	v_add_u32_e32 v123, 0xcc00, v126
	global_load_lds_dwordx4 v[0:1], off
	v_lshl_add_u64 v[0:1], v[70:71], 0, s[0:1]
	s_mov_b32 m0, s33
	v_readfirstlane_b32 s34, v123
	v_add_u32_e32 v124, s85, v5
	global_load_lds_dwordx4 v[0:1], off
	v_lshl_add_u64 v[0:1], v[72:73], 0, s[0:1]
	s_mov_b32 m0, s34
	v_readfirstlane_b32 s35, v124
	v_add_u32_e32 v125, 0x14400, v6
	global_load_lds_dwordx4 v[0:1], off
	v_lshl_add_u64 v[0:1], v[74:75], 0, s[0:1]
	s_mov_b32 m0, s35
	v_readfirstlane_b32 s36, v125
	global_load_lds_dwordx4 v[0:1], off
	v_lshl_add_u64 v[0:1], v[76:77], 0, s[0:1]
	s_mov_b32 m0, s36
	v_lshrrev_b32_e32 v2, 1, v78
	v_bfe_u32 v64, v78, 5, 1
	global_load_lds_dwordx4 v[0:1], off
	v_add_u32_e32 v114, s3, v3
	v_bitop3_b32 v0, v2, v64, 7 bitop3:0x6c
	s_waitcnt vmcnt(6)
	s_mov_b64 s[46:47], 0x100
	v_readfirstlane_b32 s0, v114
	v_add_u32_e32 v115, 0x400, v114
	v_lshlrev_b32_e32 v132, 4, v0
	s_waitcnt lgkmcnt(0)
	s_barrier
	v_lshl_add_u64 v[0:1], v[66:67], 0, s[46:47]
	s_mov_b32 m0, s0
	v_readfirstlane_b32 s1, v115
	v_add_u32_e32 v116, 0x800, v114
	global_load_lds_dwordx4 v[0:1], off
	v_lshl_add_u64 v[0:1], v[68:69], 0, s[46:47]
	s_mov_b32 m0, s1
	v_readfirstlane_b32 s20, v116
	v_add_u32_e32 v117, 0xc00, v114
	v_readlane_b32 s23, v212, 31
	v_and_b32_e32 v79, 31, v78
	global_load_lds_dwordx4 v[0:1], off
	v_lshl_add_u64 v[0:1], v[70:71], 0, s[46:47]
	s_mov_b32 m0, s20
	v_readfirstlane_b32 s21, v117
	v_add_u32_e32 v118, s23, v5
	v_add_u32_e32 v2, s3, v5
	v_lshlrev_b32_e32 v4, 7, v79
	global_load_lds_dwordx4 v[0:1], off
	v_lshl_add_u64 v[0:1], v[72:73], 0, s[46:47]
	s_mov_b32 m0, s21
	v_readfirstlane_b32 s23, v118
	v_add_u32_e32 v119, 0x8400, v2
	v_lshl_or_b32 v102, v80, 13, v4
	global_load_lds_dwordx4 v[0:1], off
	v_lshl_add_u64 v[0:1], v[74:75], 0, s[46:47]
	s_mov_b32 m0, s23
	v_readfirstlane_b32 s24, v119
	global_load_lds_dwordx4 v[0:1], off
	v_lshl_add_u64 v[0:1], v[76:77], 0, s[46:47]
	s_mov_b32 m0, s24
	v_add_u32_e32 v100, 0, v102
	global_load_lds_dwordx4 v[0:1], off
	v_add_u32_e32 v83, v100, v132
	v_ashrrev_i32_e32 v81, 7, v78
	ds_read_b128 a[0:3], v83 offset:32768
	ds_read_b128 a[4:7], v83 offset:36864
	v_lshl_or_b32 v134, v81, 13, v4
	v_add_u32_e32 v101, 0, v134
	v_add_u32_e32 v82, v101, v132
	ds_read_b128 a[8:11], v82
	ds_read_b128 a[12:15], v82 offset:4096
	v_lshrrev_b32_e32 v182, 6, v133
	s_nop 0
	v_readfirstlane_b32 s32, v182
	s_waitcnt lgkmcnt(1)
	v_mfma_f32_32x32x16_bf16 v[48:63], a[0:3], a[8:11], 0
	v_bfe_u32 v103, v78, 1, 3
	s_mov_b64 s[46:47], 0x180
	s_nop 0
	s_add_i32 s30, 0, 0xc000
	v_or_b32_e32 v143, 0x8000, v102
	v_or_b32_e32 v144, 0x9000, v102
	v_add_u32_e32 v145, s3, v134
	s_waitcnt vmcnt(12)
	v_mfma_f32_32x32x16_bf16 v[32:47], a[4:7], a[8:11], 0
	v_lshl_or_b32 v81, v81, 6, v79
	v_mul_lo_u32 v81, v81, s26
	s_mov_b64 s[80:81], 0x200
	s_waitcnt lgkmcnt(0)
	v_mfma_f32_32x32x16_bf16 v[16:31], a[0:3], a[12:15], 0
	v_bitop3_b32 v0, v64, v103, 2 bitop3:0x36
	v_lshlrev_b32_e32 v138, 4, v0
	v_add_u32_e32 v84, v101, v138
	ds_read_b128 a[28:31], v84 offset:4096
	s_nop 0
	s_nop 0
	ds_read_b128 a[24:27], v84
	s_nop 0
	v_add_u32_e32 v85, v100, v138
	ds_read_b128 a[20:23], v85 offset:36864
	s_nop 0
	s_nop 0
	ds_read_b128 a[16:19], v85 offset:32768
	s_nop 0
	s_nop 0
	s_nop 0
	s_nop 0
	s_nop 0
	s_nop 0
	v_mfma_f32_32x32x16_bf16 v[0:15], a[4:7], a[12:15], 0
	s_nop 0
	s_waitcnt lgkmcnt(0)
	v_mfma_f32_32x32x16_bf16 v[48:63], a[16:19], a[24:27], v[48:63]
	v_mfma_f32_32x32x16_bf16 v[32:47], a[20:23], a[24:27], v[32:47]
	v_mfma_f32_32x32x16_bf16 v[16:31], a[16:19], a[28:31], v[16:31]
	v_bitop3_b32 v86, v64, v103, 4 bitop3:0x36
	v_lshlrev_b32_e32 v139, 4, v86
	v_add_u32_e32 v86, v101, v139
	ds_read_b128 a[12:15], v86 offset:4096
	s_nop 0
	s_nop 0
	ds_read_b128 a[8:11], v86
	s_nop 0
	v_add_u32_e32 v87, v100, v139
	ds_read_b128 a[4:7], v87 offset:36864
	s_nop 0
	s_nop 0
	ds_read_b128 a[0:3], v87 offset:32768
	s_nop 0
	s_nop 0
	s_nop 0
	v_mfma_f32_32x32x16_bf16 v[0:15], a[20:23], a[28:31], v[0:15]
	s_nop 0
	s_nop 0
	s_nop 0
	s_nop 0
	s_waitcnt lgkmcnt(0)
	v_mfma_f32_32x32x16_bf16 v[48:63], a[0:3], a[8:11], v[48:63]
	v_mfma_f32_32x32x16_bf16 v[32:47], a[4:7], a[8:11], v[32:47]
	v_mfma_f32_32x32x16_bf16 v[16:31], a[0:3], a[12:15], v[16:31]
	v_bitop3_b32 v88, v64, v103, 6 bitop3:0x36
	v_lshlrev_b32_e32 v142, 4, v88
	v_add_u32_e32 v88, v101, v142
	ds_read_b128 a[28:31], v88 offset:4096
	s_nop 0
	s_nop 0
	ds_read_b128 a[24:27], v88
	s_nop 0
	v_add_u32_e32 v89, v100, v142
	ds_read_b128 a[20:23], v89 offset:36864
	s_nop 0
	s_nop 0
	ds_read_b128 a[16:19], v89 offset:32768
	s_nop 0
	s_nop 0
	s_nop 0
	v_lshlrev_b32_e32 v64, 4, v64
	v_lshl_or_b32 v64, v80, 8, v64
	v_add3_u32 v64, 0, v81, v64
	v_mfma_f32_32x32x16_bf16 v[0:15], a[4:7], a[12:15], v[0:15]
	s_nop 0
	s_nop 0
	s_nop 0
	s_nop 0
	s_waitcnt lgkmcnt(0)
	v_mfma_f32_32x32x16_bf16 v[48:63], a[16:19], a[24:27], v[48:63]
	v_mfma_f32_32x32x16_bf16 v[32:47], a[20:23], a[24:27], v[32:47]
	s_waitcnt vmcnt(6)
	s_waitcnt lgkmcnt(0)
	s_barrier
	ds_read_b128 a[12:15], v82 offset:53248
	ds_read_b128 a[8:11], v82 offset:49152
	v_add_u32_e32 v90, s30, v132
	v_add_u32_e32 v92, v90, v143
	v_add_u32_e32 v90, v90, v144
	ds_read_b128 a[4:7], v90
	ds_read_b128 a[0:3], v92
	v_mfma_f32_32x32x16_bf16 v[16:31], a[16:19], a[28:31], v[16:31]
	v_lshl_add_u64 v[158:159], v[66:67], 0, s[46:47]
	s_nop 0
	v_lshl_add_u64 v[160:161], v[68:69], 0, s[46:47]
	s_nop 0
	s_nop 0
	s_nop 0
	v_lshl_add_u64 v[162:163], v[70:71], 0, s[46:47]
	s_nop 0
	v_mfma_f32_32x32x16_bf16 v[0:15], a[20:23], a[28:31], v[0:15]
	s_and_b32 m0, s32, 7
	s_lshl_b32 m0, m0, 12
	s_add_i32 m0, m0, 0x0
	s_nop 0
	global_load_lds_dwordx4 v[158:159], off
	s_nop 0
	v_lshl_add_u64 v[164:165], v[72:73], 0, s[46:47]
	s_nop 0
	s_nop 0
	s_nop 0
	v_lshl_add_u64 v[166:167], v[74:75], 0, s[46:47]
	s_nop 0
	s_nop 0
	s_nop 0
	v_lshl_add_u64 v[168:169], v[76:77], 0, s[46:47]
	s_nop 0
	s_mov_b64 s[46:47], 0x200
	s_nop 0
	s_nop 0
	s_nop 0
	s_nop 0
	s_nop 0
	s_nop 0
	s_nop 0
	s_nop 0
	v_add_u32_e32 v91, s30, v138
	v_add_u32_e32 v93, v91, v143
	ds_read_b128 a[16:19], v93
	v_add_u32_e32 v91, v91, v144
	ds_read_b128 a[20:23], v91
	ds_read_b128 a[24:27], v84 offset:49152
	ds_read_b128 a[28:31], v84 offset:53248
	s_waitcnt lgkmcnt(4)
	v_mfma_f32_32x32x16_bf16 v[48:63], a[0:3], a[8:11], v[48:63]
	s_nop 0
	s_nop 0
	s_nop 0
	s_nop 0
	v_mfma_f32_32x32x16_bf16 v[32:47], a[4:7], a[8:11], v[32:47]
	s_and_b32 m0, s32, 7
	s_lshl_b32 m0, m0, 12
	s_add_i32 m0, m0, 0x400
	s_nop 0
	global_load_lds_dwordx4 v[160:161], off
	v_mfma_f32_32x32x16_bf16 v[16:31], a[0:3], a[12:15], v[16:31]
	v_mfma_f32_32x32x16_bf16 v[0:15], a[4:7], a[12:15], v[0:15]
	s_and_b32 m0, s32, 7
	s_lshl_b32 m0, m0, 12
	s_add_i32 m0, m0, 0x800
	s_nop 0
	global_load_lds_dwordx4 v[162:163], off
	s_nop 0
	s_nop 0
	s_nop 0
	s_nop 0
	v_add_u32_e32 v94, s30, v139
	v_add_u32_e32 v95, v94, v143
	ds_read_b128 a[0:3], v95
	v_add_u32_e32 v94, v94, v144
	ds_read_b128 a[4:7], v94
	ds_read_b128 a[8:11], v86 offset:49152
	ds_read_b128 a[12:15], v86 offset:53248
	s_waitcnt lgkmcnt(5)
	v_mfma_f32_32x32x16_bf16 v[48:63], a[16:19], a[24:27], v[48:63]
	v_mfma_f32_32x32x16_bf16 v[32:47], a[20:23], a[24:27], v[32:47]
	s_and_b32 m0, s32, 7
	s_lshl_b32 m0, m0, 12
	s_add_i32 m0, m0, 0xc00
	s_nop 0
	global_load_lds_dwordx4 v[164:165], off
	s_waitcnt lgkmcnt(4)
	v_mfma_f32_32x32x16_bf16 v[16:31], a[16:19], a[28:31], v[16:31]
	s_nop 0
	s_nop 0
	s_nop 0
	v_mfma_f32_32x32x16_bf16 v[0:15], a[20:23], a[28:31], v[0:15]
	s_and_b32 m0, s32, 7
	s_lshl_b32 m0, m0, 11
	s_add_i32 m0, m0, 0x8000
	s_nop 0
	global_load_lds_dwordx4 v[166:167], off
	s_nop 0
	s_nop 0
	s_nop 0
	s_nop 0
	v_add_u32_e32 v96, s30, v142
	v_add_u32_e32 v97, v96, v143
	ds_read_b128 a[16:19], v97
	v_add_u32_e32 v96, v96, v144
	ds_read_b128 a[20:23], v96
	ds_read_b128 a[24:27], v88 offset:49152
	ds_read_b128 a[28:31], v88 offset:53248
	s_waitcnt lgkmcnt(5)
	v_mfma_f32_32x32x16_bf16 v[48:63], a[0:3], a[8:11], v[48:63]
	v_mfma_f32_32x32x16_bf16 v[32:47], a[4:7], a[8:11], v[32:47]
	s_and_b32 m0, s32, 7
	s_lshl_b32 m0, m0, 11
	s_add_i32 m0, m0, 0x8400
	s_nop 0
	global_load_lds_dwordx4 v[168:169], off
	s_waitcnt lgkmcnt(4)
	v_mfma_f32_32x32x16_bf16 v[16:31], a[0:3], a[12:15], v[16:31]
	s_nop 0
	s_nop 0
	s_nop 0
	v_mfma_f32_32x32x16_bf16 v[0:15], a[4:7], a[12:15], v[0:15]
	s_nop 0
	s_nop 0
	s_nop 0
	s_nop 0
	s_waitcnt lgkmcnt(1)
	v_mfma_f32_32x32x16_bf16 v[48:63], a[16:19], a[24:27], v[48:63]
	v_mfma_f32_32x32x16_bf16 v[32:47], a[20:23], a[24:27], v[32:47]
	s_waitcnt vmcnt(6)
	s_waitcnt lgkmcnt(0)
	s_barrier
	v_add_u32_e32 v100, v145, v132
	ds_read_b128 a[8:11], v100
	v_add_u32_e32 v101, s3, v132
	v_add_u32_e32 v99, v101, v144
	ds_read_b128 a[4:7], v99
	s_nop 0
	v_add_u32_e32 v98, v101, v143
	v_or_b32_e32 v132, 0x1000, v134
	v_add_u32_e32 v101, v101, v132
	ds_read_b128 a[12:15], v101
	ds_read_b128 a[0:3], v98
	v_mfma_f32_32x32x16_bf16 v[16:31], a[16:19], a[28:31], v[16:31]
	v_lshl_add_u64 v[170:171], v[66:67], 0, s[46:47]
	s_nop 0
	v_lshl_add_u64 v[172:173], v[68:69], 0, s[46:47]
	s_nop 0
	s_nop 0
	s_nop 0
	v_lshl_add_u64 v[174:175], v[70:71], 0, s[46:47]
	s_nop 0
	v_mfma_f32_32x32x16_bf16 v[0:15], a[20:23], a[28:31], v[0:15]
	s_and_b32 m0, s32, 7
	s_lshl_b32 m0, m0, 12
	s_add_i32 m0, m0, 0xc000
	s_nop 0
	global_load_lds_dwordx4 v[170:171], off
	s_nop 0
	v_lshl_add_u64 v[176:177], v[72:73], 0, s[46:47]
	s_nop 0
	s_nop 0
	s_nop 0
	v_lshl_add_u64 v[178:179], v[74:75], 0, s[46:47]
	s_nop 0
	s_nop 0
	s_nop 0
	v_lshl_add_u64 v[180:181], v[76:77], 0, s[46:47]
	s_nop 0
	s_mov_b64 s[46:47], 0x280
	s_nop 0
	s_nop 0
	s_nop 0
	s_nop 0
	s_nop 0
	s_nop 0
	s_nop 0
	s_nop 0
	v_add_u32_e32 v105, s3, v138
	v_add_u32_e32 v102, v105, v143
	ds_read_b128 a[16:19], v102
	v_add_u32_e32 v103, v105, v144
	ds_read_b128 a[20:23], v103
	v_add_u32_e32 v104, v145, v138
	ds_read_b128 a[24:27], v104
	v_add_u32_e32 v105, v105, v132
	ds_read_b128 a[28:31], v105
	s_waitcnt lgkmcnt(4)
	v_mfma_f32_32x32x16_bf16 v[48:63], a[0:3], a[8:11], v[48:63]
	s_nop 0
	v_mfma_f32_32x32x16_bf16 v[32:47], a[4:7], a[8:11], v[32:47]
	s_and_b32 m0, s32, 7
	s_lshl_b32 m0, m0, 12
	s_add_i32 m0, m0, 0xc400
	s_nop 0
	global_load_lds_dwordx4 v[172:173], off
	s_nop 0
	s_nop 0
	s_nop 0
	s_nop 0
	s_nop 0
	v_mfma_f32_32x32x16_bf16 v[16:31], a[0:3], a[12:15], v[16:31]
	s_nop 0
	v_mfma_f32_32x32x16_bf16 v[0:15], a[4:7], a[12:15], v[0:15]
	s_and_b32 m0, s32, 7
	s_lshl_b32 m0, m0, 12
	s_add_i32 m0, m0, 0xc800
	s_nop 0
	global_load_lds_dwordx4 v[174:175], off
	s_nop 0
	s_nop 0
	s_nop 0
	v_add_u32_e32 v109, s3, v139
	v_add_u32_e32 v106, v109, v143
	ds_read_b128 a[0:3], v106
	v_add_u32_e32 v107, v109, v144
	ds_read_b128 a[4:7], v107
	v_add_u32_e32 v108, v145, v139
	ds_read_b128 a[8:11], v108
	v_add_u32_e32 v109, v109, v132
	ds_read_b128 a[12:15], v109
	s_waitcnt lgkmcnt(5)
	v_mfma_f32_32x32x16_bf16 v[48:63], a[16:19], a[24:27], v[48:63]
	v_mfma_f32_32x32x16_bf16 v[32:47], a[20:23], a[24:27], v[32:47]
	s_and_b32 m0, s32, 7
	s_lshl_b32 m0, m0, 12
	s_add_i32 m0, m0, 0xcc00
	s_nop 0
	global_load_lds_dwordx4 v[176:177], off
	s_waitcnt lgkmcnt(4)
	v_mfma_f32_32x32x16_bf16 v[16:31], a[16:19], a[28:31], v[16:31]
	s_nop 0
	s_nop 0
	s_nop 0
	s_nop 0
	s_nop 0
	s_nop 0
	v_mfma_f32_32x32x16_bf16 v[0:15], a[20:23], a[28:31], v[0:15]
	s_and_b32 m0, s32, 7
	s_lshl_b32 m0, m0, 11
	s_add_i32 m0, m0, 0x14000
	s_nop 0
	global_load_lds_dwordx4 v[178:179], off
	s_nop 0
	s_nop 0
	s_nop 0
	v_add_u32_e32 v113, s3, v142
	v_add_u32_e32 v110, v113, v143
	ds_read_b128 a[16:19], v110
	v_add_u32_e32 v111, v113, v144
	ds_read_b128 a[20:23], v111
	v_add_u32_e32 v112, v145, v142
	ds_read_b128 a[24:27], v112
	v_add_u32_e32 v113, v113, v132
	ds_read_b128 a[28:31], v113
	s_waitcnt lgkmcnt(5)
	v_mfma_f32_32x32x16_bf16 v[48:63], a[0:3], a[8:11], v[48:63]
	v_mfma_f32_32x32x16_bf16 v[32:47], a[4:7], a[8:11], v[32:47]
	s_and_b32 m0, s32, 7
	s_lshl_b32 m0, m0, 11
	s_add_i32 m0, m0, 0x14400
	s_nop 0
	global_load_lds_dwordx4 v[180:181], off
	s_waitcnt lgkmcnt(4)
	v_mfma_f32_32x32x16_bf16 v[16:31], a[0:3], a[12:15], v[16:31]
	s_nop 0
	s_nop 0
	s_nop 0
	s_nop 0
	s_nop 0
	s_nop 0
	v_mfma_f32_32x32x16_bf16 v[0:15], a[4:7], a[12:15], v[0:15]
	s_nop 0
	s_nop 0
	s_nop 0
	s_waitcnt lgkmcnt(1)
	v_mfma_f32_32x32x16_bf16 v[48:63], a[16:19], a[24:27], v[48:63]
	v_mfma_f32_32x32x16_bf16 v[32:47], a[20:23], a[24:27], v[32:47]
	s_waitcnt vmcnt(6)
	s_waitcnt lgkmcnt(0)
	s_barrier
	ds_read_b128 a[12:15], v82 offset:4096
	ds_read_b128 a[8:11], v82
	ds_read_b128 a[4:7], v83 offset:36864
	ds_read_b128 a[0:3], v83 offset:32768
	v_mfma_f32_32x32x16_bf16 v[16:31], a[16:19], a[28:31], v[16:31]
	v_lshl_add_u64 v[158:159], v[66:67], 0, s[46:47]
	s_nop 0
	v_lshl_add_u64 v[160:161], v[68:69], 0, s[46:47]
	s_nop 0
	s_nop 0
	s_nop 0
	v_lshl_add_u64 v[162:163], v[70:71], 0, s[46:47]
	s_nop 0
	v_mfma_f32_32x32x16_bf16 v[0:15], a[20:23], a[28:31], v[0:15]
	s_and_b32 m0, s32, 7
	s_lshl_b32 m0, m0, 12
	s_add_i32 m0, m0, 0x18000
	s_nop 0
	global_load_lds_dwordx4 v[158:159], off
	s_nop 0
	v_lshl_add_u64 v[164:165], v[72:73], 0, s[46:47]
	s_nop 0
	s_nop 0
	s_nop 0
	v_lshl_add_u64 v[166:167], v[74:75], 0, s[46:47]
	s_nop 0
	s_nop 0
	s_nop 0
	v_lshl_add_u64 v[168:169], v[76:77], 0, s[46:47]
	s_nop 0
	s_mov_b64 s[46:47], 0x300
	s_nop 0
	s_nop 0
	s_nop 0
	s_nop 0
	s_nop 0
	ds_read_b128 a[16:19], v85 offset:32768
	ds_read_b128 a[20:23], v85 offset:36864
	ds_read_b128 a[24:27], v84
	ds_read_b128 a[28:31], v84 offset:4096
	s_waitcnt lgkmcnt(4)
	v_mfma_f32_32x32x16_bf16 v[48:63], a[0:3], a[8:11], v[48:63]
	s_nop 0
	v_mfma_f32_32x32x16_bf16 v[32:47], a[4:7], a[8:11], v[32:47]
	s_and_b32 m0, s32, 7
	s_lshl_b32 m0, m0, 12
	s_add_i32 m0, m0, 0x18400
	s_nop 0
	global_load_lds_dwordx4 v[160:161], off
	v_mfma_f32_32x32x16_bf16 v[16:31], a[0:3], a[12:15], v[16:31]
	v_mfma_f32_32x32x16_bf16 v[0:15], a[4:7], a[12:15], v[0:15]
	s_and_b32 m0, s32, 7
	s_lshl_b32 m0, m0, 12
	s_add_i32 m0, m0, 0x18800
	s_nop 0
	global_load_lds_dwordx4 v[162:163], off
	s_nop 0
	s_nop 0
	s_nop 0
	s_nop 0
	ds_read_b128 a[0:3], v87 offset:32768
	ds_read_b128 a[4:7], v87 offset:36864
	ds_read_b128 a[8:11], v86
	ds_read_b128 a[12:15], v86 offset:4096
	s_waitcnt lgkmcnt(5)
	v_mfma_f32_32x32x16_bf16 v[48:63], a[16:19], a[24:27], v[48:63]
	v_mfma_f32_32x32x16_bf16 v[32:47], a[20:23], a[24:27], v[32:47]
	s_and_b32 m0, s32, 7
	s_lshl_b32 m0, m0, 12
	s_add_i32 m0, m0, 0x18c00
	s_nop 0
	global_load_lds_dwordx4 v[164:165], off
	s_waitcnt lgkmcnt(4)
	v_mfma_f32_32x32x16_bf16 v[16:31], a[16:19], a[28:31], v[16:31]
	v_mfma_f32_32x32x16_bf16 v[0:15], a[20:23], a[28:31], v[0:15]
	s_and_b32 m0, s32, 7
	s_lshl_b32 m0, m0, 11
	s_add_i32 m0, m0, 0x20000
	s_nop 0
	global_load_lds_dwordx4 v[166:167], off
	s_nop 0
	s_nop 0
	s_nop 0
	s_nop 0
	ds_read_b128 a[16:19], v89 offset:32768
	ds_read_b128 a[20:23], v89 offset:36864
	ds_read_b128 a[24:27], v88
	ds_read_b128 a[28:31], v88 offset:4096
	s_waitcnt lgkmcnt(5)
	v_mfma_f32_32x32x16_bf16 v[48:63], a[0:3], a[8:11], v[48:63]
	v_mfma_f32_32x32x16_bf16 v[32:47], a[4:7], a[8:11], v[32:47]
	s_and_b32 m0, s32, 7
	s_lshl_b32 m0, m0, 11
	s_add_i32 m0, m0, 0x20400
	s_nop 0
	global_load_lds_dwordx4 v[168:169], off
	s_waitcnt lgkmcnt(4)
	v_mfma_f32_32x32x16_bf16 v[16:31], a[0:3], a[12:15], v[16:31]
	v_mfma_f32_32x32x16_bf16 v[0:15], a[4:7], a[12:15], v[0:15]
	s_nop 0
	s_nop 0
	s_nop 0
	s_nop 0
	s_waitcnt lgkmcnt(1)
	v_mfma_f32_32x32x16_bf16 v[48:63], a[16:19], a[24:27], v[48:63]
	v_mfma_f32_32x32x16_bf16 v[32:47], a[20:23], a[24:27], v[32:47]
	s_waitcnt vmcnt(6)
	s_waitcnt lgkmcnt(0)
	s_barrier
	ds_read_b128 a[12:15], v82 offset:53248
	ds_read_b128 a[8:11], v82 offset:49152
	ds_read_b128 a[4:7], v90
	ds_read_b128 a[0:3], v92
	v_mfma_f32_32x32x16_bf16 v[16:31], a[16:19], a[28:31], v[16:31]
	v_lshl_add_u64 v[170:171], v[66:67], 0, s[46:47]
	s_nop 0
	v_lshl_add_u64 v[172:173], v[68:69], 0, s[46:47]
	s_nop 0
	s_nop 0
	s_nop 0
	v_lshl_add_u64 v[174:175], v[70:71], 0, s[46:47]
	s_nop 0
	v_mfma_f32_32x32x16_bf16 v[0:15], a[20:23], a[28:31], v[0:15]
	s_and_b32 m0, s32, 7
	s_lshl_b32 m0, m0, 12
	s_add_i32 m0, m0, 0x0
	s_nop 0
	global_load_lds_dwordx4 v[170:171], off
	s_nop 0
	v_lshl_add_u64 v[176:177], v[72:73], 0, s[46:47]
	s_nop 0
	s_mov_b64 s[38:39], 0x380
	s_nop 0
	v_lshl_add_u64 v[178:179], v[74:75], 0, s[46:47]
	s_nop 0
	v_readfirstlane_b32 s48, v117
	s_nop 0
	v_lshl_add_u64 v[180:181], v[76:77], 0, s[46:47]
	s_nop 0
	s_mov_b64 s[46:47], 0x580
	s_nop 0
	s_nop 0
	s_nop 0
	s_nop 0
	s_nop 0
	ds_read_b128 a[16:19], v93
	ds_read_b128 a[20:23], v91
	ds_read_b128 a[24:27], v84 offset:49152
	ds_read_b128 a[28:31], v84 offset:53248
	s_waitcnt lgkmcnt(4)
	v_mfma_f32_32x32x16_bf16 v[48:63], a[0:3], a[8:11], v[48:63]
	s_nop 0
	v_readfirstlane_b32 s49, v118
	v_readfirstlane_b32 s53, v119
	v_mfma_f32_32x32x16_bf16 v[32:47], a[4:7], a[8:11], v[32:47]
	s_and_b32 m0, s32, 7
	s_lshl_b32 m0, m0, 12
	s_add_i32 m0, m0, 0x400
	s_nop 0
	global_load_lds_dwordx4 v[172:173], off
	v_mfma_f32_32x32x16_bf16 v[16:31], a[0:3], a[12:15], v[16:31]
	v_mfma_f32_32x32x16_bf16 v[0:15], a[4:7], a[12:15], v[0:15]
	s_and_b32 m0, s32, 7
	s_lshl_b32 m0, m0, 12
	s_add_i32 m0, m0, 0x800
	s_nop 0
	global_load_lds_dwordx4 v[174:175], off
	s_nop 0
	s_nop 0
	s_nop 0
	s_nop 0
	ds_read_b128 a[0:3], v95
	ds_read_b128 a[4:7], v94
	ds_read_b128 a[8:11], v86 offset:49152
	ds_read_b128 a[12:15], v86 offset:53248
	s_waitcnt lgkmcnt(5)
	v_mfma_f32_32x32x16_bf16 v[48:63], a[16:19], a[24:27], v[48:63]
	v_mfma_f32_32x32x16_bf16 v[32:47], a[20:23], a[24:27], v[32:47]
	s_and_b32 m0, s32, 7
	s_lshl_b32 m0, m0, 12
	s_add_i32 m0, m0, 0xc00
	s_nop 0
	global_load_lds_dwordx4 v[176:177], off
	s_waitcnt lgkmcnt(4)
	v_mfma_f32_32x32x16_bf16 v[16:31], a[16:19], a[28:31], v[16:31]
	v_mfma_f32_32x32x16_bf16 v[0:15], a[20:23], a[28:31], v[0:15]
	s_and_b32 m0, s32, 7
	s_lshl_b32 m0, m0, 11
	s_add_i32 m0, m0, 0x8000
	s_nop 0
	global_load_lds_dwordx4 v[178:179], off
	s_nop 0
	s_nop 0
	s_nop 0
	s_nop 0
	ds_read_b128 a[16:19], v97
	ds_read_b128 a[20:23], v96
	ds_read_b128 a[24:27], v88 offset:49152
	ds_read_b128 a[28:31], v88 offset:53248
	s_waitcnt lgkmcnt(5)
	v_mfma_f32_32x32x16_bf16 v[48:63], a[0:3], a[8:11], v[48:63]
	v_mfma_f32_32x32x16_bf16 v[32:47], a[4:7], a[8:11], v[32:47]
	s_and_b32 m0, s32, 7
	s_lshl_b32 m0, m0, 11
	s_add_i32 m0, m0, 0x8400
	s_nop 0
	global_load_lds_dwordx4 v[180:181], off
	s_waitcnt lgkmcnt(4)
	v_mfma_f32_32x32x16_bf16 v[16:31], a[0:3], a[12:15], v[16:31]
	v_mfma_f32_32x32x16_bf16 v[0:15], a[4:7], a[12:15], v[0:15]
	s_nop 0
	s_nop 0
	s_nop 0
	s_nop 0
	s_waitcnt lgkmcnt(1)
	v_mfma_f32_32x32x16_bf16 v[48:63], a[16:19], a[24:27], v[48:63]
	v_mfma_f32_32x32x16_bf16 v[32:47], a[20:23], a[24:27], v[32:47]
	s_waitcnt vmcnt(6)
	s_waitcnt lgkmcnt(0)
	s_barrier
	ds_read_b128 a[12:15], v101
	ds_read_b128 a[8:11], v100
	ds_read_b128 a[4:7], v99
	ds_read_b128 a[0:3], v98
	v_mfma_f32_32x32x16_bf16 v[16:31], a[16:19], a[28:31], v[16:31]
	v_lshl_add_u64 v[158:159], v[66:67], 0, s[38:39]
	s_nop 0
	v_lshl_add_u64 v[160:161], v[68:69], 0, s[38:39]
	s_nop 0
	s_mov_b64 s[28:29], 0x400
	s_nop 0
	v_lshl_add_u64 v[162:163], v[70:71], 0, s[38:39]
	s_nop 0
	v_mfma_f32_32x32x16_bf16 v[0:15], a[20:23], a[28:31], v[0:15]
	s_and_b32 m0, s32, 7
	s_lshl_b32 m0, m0, 12
	s_add_i32 m0, m0, 0xc000
	s_nop 0
	global_load_lds_dwordx4 v[158:159], off
	s_nop 0
	v_lshl_add_u64 v[164:165], v[72:73], 0, s[38:39]
	s_nop 0
	v_readfirstlane_b32 s33, v122
	s_nop 0
	v_lshl_add_u64 v[166:167], v[74:75], 0, s[38:39]
	s_nop 0
	v_readfirstlane_b32 s34, v123
	s_nop 0
	v_lshl_add_u64 v[168:169], v[76:77], 0, s[38:39]
	s_nop 0
	s_mov_b64 s[36:37], 0x500
	s_nop 0
	s_nop 0
	s_nop 0
	s_nop 0
	s_nop 0
	ds_read_b128 a[16:19], v102
	ds_read_b128 a[20:23], v103
	ds_read_b128 a[24:27], v104
	ds_read_b128 a[28:31], v105
	s_waitcnt lgkmcnt(4)
	v_mfma_f32_32x32x16_bf16 v[48:63], a[0:3], a[8:11], v[48:63]
	s_nop 0
	v_readfirstlane_b32 s0, v126
	v_readfirstlane_b32 s35, v124
	v_readfirstlane_b32 s38, v115
	v_readfirstlane_b32 s39, v116
	v_mfma_f32_32x32x16_bf16 v[32:47], a[4:7], a[8:11], v[32:47]
	s_and_b32 m0, s32, 7
	s_lshl_b32 m0, m0, 12
	s_add_i32 m0, m0, 0xc400
	s_nop 0
	global_load_lds_dwordx4 v[160:161], off
	v_mfma_f32_32x32x16_bf16 v[16:31], a[0:3], a[12:15], v[16:31]
	v_mfma_f32_32x32x16_bf16 v[0:15], a[4:7], a[12:15], v[0:15]
	s_and_b32 m0, s32, 7
	s_lshl_b32 m0, m0, 12
	s_add_i32 m0, m0, 0xc800
	s_nop 0
	global_load_lds_dwordx4 v[162:163], off
	s_nop 0
	s_nop 0
	s_nop 0
	s_nop 0
	ds_read_b128 a[0:3], v106
	ds_read_b128 a[4:7], v107
	ds_read_b128 a[8:11], v108
	ds_read_b128 a[12:15], v109
	s_waitcnt lgkmcnt(5)
	v_mfma_f32_32x32x16_bf16 v[48:63], a[16:19], a[24:27], v[48:63]
	v_mfma_f32_32x32x16_bf16 v[32:47], a[20:23], a[24:27], v[32:47]
	s_and_b32 m0, s32, 7
	s_lshl_b32 m0, m0, 12
	s_add_i32 m0, m0, 0xcc00
	s_nop 0
	global_load_lds_dwordx4 v[164:165], off
	s_waitcnt lgkmcnt(4)
	v_mfma_f32_32x32x16_bf16 v[16:31], a[16:19], a[28:31], v[16:31]
	v_mfma_f32_32x32x16_bf16 v[0:15], a[20:23], a[28:31], v[0:15]
	s_and_b32 m0, s32, 7
	s_lshl_b32 m0, m0, 11
	s_add_i32 m0, m0, 0x14000
	s_nop 0
	global_load_lds_dwordx4 v[166:167], off
	s_nop 0
	s_nop 0
	s_nop 0
	s_nop 0
	ds_read_b128 a[16:19], v110
	ds_read_b128 a[20:23], v111
	ds_read_b128 a[24:27], v112
	ds_read_b128 a[28:31], v113
	s_waitcnt lgkmcnt(5)
	v_mfma_f32_32x32x16_bf16 v[48:63], a[0:3], a[8:11], v[48:63]
	v_mfma_f32_32x32x16_bf16 v[32:47], a[4:7], a[8:11], v[32:47]
	s_and_b32 m0, s32, 7
	s_lshl_b32 m0, m0, 11
	s_add_i32 m0, m0, 0x14400
	s_nop 0
	global_load_lds_dwordx4 v[168:169], off
	s_waitcnt lgkmcnt(4)
	v_mfma_f32_32x32x16_bf16 v[16:31], a[0:3], a[12:15], v[16:31]
	v_mfma_f32_32x32x16_bf16 v[0:15], a[4:7], a[12:15], v[0:15]
	s_nop 0
	s_nop 0
	s_nop 0
	s_nop 0
	s_waitcnt lgkmcnt(1)
	v_mfma_f32_32x32x16_bf16 v[48:63], a[16:19], a[24:27], v[48:63]
	v_mfma_f32_32x32x16_bf16 v[32:47], a[20:23], a[24:27], v[32:47]
	s_waitcnt vmcnt(6)
	s_waitcnt lgkmcnt(0)
	s_barrier
	ds_read_b128 a[12:15], v82 offset:4096
	ds_read_b128 a[8:11], v82
	ds_read_b128 a[4:7], v83 offset:36864
	ds_read_b128 a[0:3], v83 offset:32768
	v_mfma_f32_32x32x16_bf16 v[16:31], a[16:19], a[28:31], v[16:31]
	v_lshl_add_u64 v[170:171], v[66:67], 0, s[28:29]
	s_nop 0
	v_lshl_add_u64 v[172:173], v[68:69], 0, s[28:29]
	s_nop 0
	v_readfirstlane_b32 s1, v127
	s_nop 0
	v_lshl_add_u64 v[174:175], v[70:71], 0, s[28:29]
	s_nop 0
	v_mfma_f32_32x32x16_bf16 v[0:15], a[20:23], a[28:31], v[0:15]
	s_and_b32 m0, s32, 7
	s_lshl_b32 m0, m0, 12
	s_add_i32 m0, m0, 0x18000
	s_nop 0
	global_load_lds_dwordx4 v[170:171], off
	s_nop 0
	v_lshl_add_u64 v[176:177], v[72:73], 0, s[28:29]
	s_nop 0
	v_readfirstlane_b32 s20, v128
	s_nop 0
	v_lshl_add_u64 v[178:179], v[74:75], 0, s[28:29]
	s_nop 0
	v_readfirstlane_b32 s21, v129
	s_nop 0
	v_lshl_add_u64 v[180:181], v[76:77], 0, s[28:29]
	s_nop 0
	s_mov_b64 s[28:29], 0x480
	s_nop 0
	s_nop 0
	s_nop 0
	s_nop 0
	s_nop 0
	ds_read_b128 a[16:19], v85 offset:32768
	ds_read_b128 a[20:23], v85 offset:36864
	ds_read_b128 a[24:27], v84
	ds_read_b128 a[28:31], v84 offset:4096
	s_waitcnt lgkmcnt(4)
	v_mfma_f32_32x32x16_bf16 v[48:63], a[0:3], a[8:11], v[48:63]
	s_nop 0
	v_lshl_add_u64 v[162:163], v[70:71], 0, s[28:29]
	v_readfirstlane_b32 s23, v131
	v_readfirstlane_b32 s24, v130
	v_mfma_f32_32x32x16_bf16 v[32:47], a[4:7], a[8:11], v[32:47]
	s_and_b32 m0, s32, 7
	s_lshl_b32 m0, m0, 12
	s_add_i32 m0, m0, 0x18400
	s_nop 0
	global_load_lds_dwordx4 v[172:173], off
	v_mfma_f32_32x32x16_bf16 v[16:31], a[0:3], a[12:15], v[16:31]
	v_mfma_f32_32x32x16_bf16 v[0:15], a[4:7], a[12:15], v[0:15]
	s_and_b32 m0, s32, 7
	s_lshl_b32 m0, m0, 12
	s_add_i32 m0, m0, 0x18800
	s_nop 0
	global_load_lds_dwordx4 v[174:175], off
	s_nop 0
	s_nop 0
	s_nop 0
	s_nop 0
	ds_read_b128 a[0:3], v87 offset:32768
	ds_read_b128 a[4:7], v87 offset:36864
	ds_read_b128 a[8:11], v86
	ds_read_b128 a[12:15], v86 offset:4096
	s_waitcnt lgkmcnt(5)
	v_mfma_f32_32x32x16_bf16 v[48:63], a[16:19], a[24:27], v[48:63]
	v_mfma_f32_32x32x16_bf16 v[32:47], a[20:23], a[24:27], v[32:47]
	s_and_b32 m0, s32, 7
	s_lshl_b32 m0, m0, 12
	s_add_i32 m0, m0, 0x18c00
	s_nop 0
	global_load_lds_dwordx4 v[176:177], off
	s_waitcnt lgkmcnt(4)
	v_mfma_f32_32x32x16_bf16 v[16:31], a[16:19], a[28:31], v[16:31]
	v_mfma_f32_32x32x16_bf16 v[0:15], a[20:23], a[28:31], v[0:15]
	s_and_b32 m0, s32, 7
	s_lshl_b32 m0, m0, 11
	s_add_i32 m0, m0, 0x20000
	s_nop 0
	global_load_lds_dwordx4 v[178:179], off
	s_nop 0
	s_nop 0
	s_nop 0
	s_nop 0
	ds_read_b128 a[16:19], v89 offset:32768
	ds_read_b128 a[20:23], v89 offset:36864
	ds_read_b128 a[24:27], v88
	ds_read_b128 a[28:31], v88 offset:4096
	s_waitcnt lgkmcnt(5)
	v_mfma_f32_32x32x16_bf16 v[48:63], a[0:3], a[8:11], v[48:63]
	v_mfma_f32_32x32x16_bf16 v[32:47], a[4:7], a[8:11], v[32:47]
	s_and_b32 m0, s32, 7
	s_lshl_b32 m0, m0, 11
	s_add_i32 m0, m0, 0x20400
	s_nop 0
	global_load_lds_dwordx4 v[180:181], off
	s_waitcnt lgkmcnt(4)
	v_mfma_f32_32x32x16_bf16 v[16:31], a[0:3], a[12:15], v[16:31]
	v_mfma_f32_32x32x16_bf16 v[0:15], a[4:7], a[12:15], v[0:15]
	s_nop 0
	s_nop 0
	s_nop 0
	s_nop 0
	s_waitcnt lgkmcnt(1)
	v_mfma_f32_32x32x16_bf16 v[48:63], a[16:19], a[24:27], v[48:63]
	v_mfma_f32_32x32x16_bf16 v[32:47], a[20:23], a[24:27], v[32:47]
	s_waitcnt vmcnt(6)
	s_waitcnt lgkmcnt(0)
	s_barrier
	ds_read_b128 a[12:15], v82 offset:53248
	ds_read_b128 a[8:11], v82 offset:49152
	ds_read_b128 a[4:7], v90
	ds_read_b128 a[0:3], v92
	v_mfma_f32_32x32x16_bf16 v[16:31], a[16:19], a[28:31], v[16:31]
	v_lshl_add_u64 v[158:159], v[66:67], 0, s[28:29]
	s_nop 0
	v_lshl_add_u64 v[160:161], v[68:69], 0, s[28:29]
	s_nop 0
	s_nop 0
	s_nop 0
	s_nop 0
	v_mfma_f32_32x32x16_bf16 v[0:15], a[20:23], a[28:31], v[0:15]
	s_and_b32 m0, s32, 7
	s_lshl_b32 m0, m0, 12
	s_add_i32 m0, m0, 0x0
	s_nop 0
	global_load_lds_dwordx4 v[158:159], off
	s_nop 0
	v_lshl_add_u64 v[164:165], v[72:73], 0, s[28:29]
	s_nop 0
	s_nop 0
	s_nop 0
	v_lshl_add_u64 v[166:167], v[74:75], 0, s[28:29]
	s_nop 0
	s_nop 0
	s_nop 0
	v_lshl_add_u64 v[168:169], v[76:77], 0, s[28:29]
	s_nop 0
	v_readfirstlane_b32 s28, v120
	s_nop 0
	s_nop 0
	s_nop 0
	s_nop 0
	s_nop 0
	ds_read_b128 a[16:19], v93
	ds_read_b128 a[20:23], v91
	ds_read_b128 a[24:27], v84 offset:49152
	ds_read_b128 a[28:31], v84 offset:53248
	s_waitcnt lgkmcnt(4)
	v_mfma_f32_32x32x16_bf16 v[48:63], a[0:3], a[8:11], v[48:63]
	s_nop 0
	v_readfirstlane_b32 s29, v121
	v_lshl_add_u64 v[174:175], v[70:71], 0, s[36:37]
	v_mfma_f32_32x32x16_bf16 v[32:47], a[4:7], a[8:11], v[32:47]
	s_and_b32 m0, s32, 7
	s_lshl_b32 m0, m0, 12
	s_add_i32 m0, m0, 0x400
	s_nop 0
	global_load_lds_dwordx4 v[160:161], off
	v_mfma_f32_32x32x16_bf16 v[16:31], a[0:3], a[12:15], v[16:31]
	v_mfma_f32_32x32x16_bf16 v[0:15], a[4:7], a[12:15], v[0:15]
	s_and_b32 m0, s32, 7
	s_lshl_b32 m0, m0, 12
	s_add_i32 m0, m0, 0x800
	s_nop 0
	global_load_lds_dwordx4 v[162:163], off
	s_nop 0
	s_nop 0
	s_nop 0
	s_nop 0
	ds_read_b128 a[0:3], v95
	ds_read_b128 a[4:7], v94
	ds_read_b128 a[8:11], v86 offset:49152
	ds_read_b128 a[12:15], v86 offset:53248
	s_waitcnt lgkmcnt(5)
	v_mfma_f32_32x32x16_bf16 v[48:63], a[16:19], a[24:27], v[48:63]
	v_mfma_f32_32x32x16_bf16 v[32:47], a[20:23], a[24:27], v[32:47]
	s_and_b32 m0, s32, 7
	s_lshl_b32 m0, m0, 12
	s_add_i32 m0, m0, 0xc00
	s_nop 0
	global_load_lds_dwordx4 v[164:165], off
	s_waitcnt lgkmcnt(4)
	v_mfma_f32_32x32x16_bf16 v[16:31], a[16:19], a[28:31], v[16:31]
	v_mfma_f32_32x32x16_bf16 v[0:15], a[20:23], a[28:31], v[0:15]
	s_and_b32 m0, s32, 7
	s_lshl_b32 m0, m0, 11
	s_add_i32 m0, m0, 0x8000
	s_nop 0
	global_load_lds_dwordx4 v[166:167], off
	s_nop 0
	s_nop 0
	s_nop 0
	s_nop 0
	ds_read_b128 a[16:19], v97
	ds_read_b128 a[20:23], v96
	ds_read_b128 a[24:27], v88 offset:49152
	ds_read_b128 a[28:31], v88 offset:53248
	s_waitcnt lgkmcnt(5)
	v_mfma_f32_32x32x16_bf16 v[48:63], a[0:3], a[8:11], v[48:63]
	v_mfma_f32_32x32x16_bf16 v[32:47], a[4:7], a[8:11], v[32:47]
	s_and_b32 m0, s32, 7
	s_lshl_b32 m0, m0, 11
	s_add_i32 m0, m0, 0x8400
	s_nop 0
	global_load_lds_dwordx4 v[168:169], off
	s_waitcnt lgkmcnt(4)
	v_mfma_f32_32x32x16_bf16 v[16:31], a[0:3], a[12:15], v[16:31]
	v_mfma_f32_32x32x16_bf16 v[0:15], a[4:7], a[12:15], v[0:15]
	s_nop 0
	s_nop 0
	s_nop 0
	s_nop 0
	s_waitcnt lgkmcnt(1)
	v_mfma_f32_32x32x16_bf16 v[48:63], a[16:19], a[24:27], v[48:63]
	v_mfma_f32_32x32x16_bf16 v[32:47], a[20:23], a[24:27], v[32:47]
	s_waitcnt vmcnt(6)
	s_waitcnt lgkmcnt(0)
	s_barrier
	ds_read_b128 a[12:15], v101
	ds_read_b128 a[8:11], v100
	ds_read_b128 a[4:7], v99
	ds_read_b128 a[0:3], v98
	v_mfma_f32_32x32x16_bf16 v[16:31], a[16:19], a[28:31], v[16:31]
	v_lshl_add_u64 v[170:171], v[66:67], 0, s[36:37]
	s_nop 0
	v_lshl_add_u64 v[172:173], v[68:69], 0, s[36:37]
	s_nop 0
	s_nop 0
	s_nop 0
	s_nop 0
	v_mfma_f32_32x32x16_bf16 v[0:15], a[20:23], a[28:31], v[0:15]
	s_and_b32 m0, s32, 7
	s_lshl_b32 m0, m0, 12
	s_add_i32 m0, m0, 0xc000
	s_nop 0
	global_load_lds_dwordx4 v[170:171], off
	s_nop 0
	v_lshl_add_u64 v[176:177], v[72:73], 0, s[36:37]
	s_nop 0
	s_nop 0
	s_nop 0
	v_lshl_add_u64 v[178:179], v[74:75], 0, s[36:37]
	s_nop 0
	s_nop 0
	s_nop 0
	v_lshl_add_u64 v[180:181], v[76:77], 0, s[36:37]
	v_readfirstlane_b32 s36, v125
	s_nop 0
	v_readfirstlane_b32 s37, v114
	s_nop 0
	s_nop 0
	s_nop 0
	s_nop 0
	s_nop 0
	ds_read_b128 a[16:19], v102
	ds_read_b128 a[20:23], v103
	ds_read_b128 a[24:27], v104
	ds_read_b128 a[28:31], v105
	s_waitcnt lgkmcnt(4)
	v_mfma_f32_32x32x16_bf16 v[48:63], a[0:3], a[8:11], v[48:63]
	s_nop 0
	v_lshl_add_u64 v[162:163], v[70:71], 0, s[46:47]
	v_mfma_f32_32x32x16_bf16 v[32:47], a[4:7], a[8:11], v[32:47]
	s_and_b32 m0, s32, 7
	s_lshl_b32 m0, m0, 12
	s_add_i32 m0, m0, 0xc400
	s_nop 0
	global_load_lds_dwordx4 v[172:173], off
	v_mfma_f32_32x32x16_bf16 v[16:31], a[0:3], a[12:15], v[16:31]
	v_mfma_f32_32x32x16_bf16 v[0:15], a[4:7], a[12:15], v[0:15]
	s_and_b32 m0, s32, 7
	s_lshl_b32 m0, m0, 12
	s_add_i32 m0, m0, 0xc800
	s_nop 0
	global_load_lds_dwordx4 v[174:175], off
	s_nop 0
	s_nop 0
	s_nop 0
	s_nop 0
	ds_read_b128 a[0:3], v106
	ds_read_b128 a[4:7], v107
	ds_read_b128 a[8:11], v108
	ds_read_b128 a[12:15], v109
	s_waitcnt lgkmcnt(5)
	v_mfma_f32_32x32x16_bf16 v[48:63], a[16:19], a[24:27], v[48:63]
	v_mfma_f32_32x32x16_bf16 v[32:47], a[20:23], a[24:27], v[32:47]
	s_and_b32 m0, s32, 7
	s_lshl_b32 m0, m0, 12
	s_add_i32 m0, m0, 0xcc00
	s_nop 0
	global_load_lds_dwordx4 v[176:177], off
	s_waitcnt lgkmcnt(4)
	v_mfma_f32_32x32x16_bf16 v[16:31], a[16:19], a[28:31], v[16:31]
	v_mfma_f32_32x32x16_bf16 v[0:15], a[20:23], a[28:31], v[0:15]
	s_and_b32 m0, s32, 7
	s_lshl_b32 m0, m0, 11
	s_add_i32 m0, m0, 0x14000
	s_nop 0
	global_load_lds_dwordx4 v[178:179], off
	s_nop 0
	s_nop 0
	s_nop 0
	s_nop 0
	ds_read_b128 a[16:19], v110
	ds_read_b128 a[20:23], v111
	ds_read_b128 a[24:27], v112
	ds_read_b128 a[28:31], v113
	s_waitcnt lgkmcnt(5)
	v_mfma_f32_32x32x16_bf16 v[48:63], a[0:3], a[8:11], v[48:63]
	v_mfma_f32_32x32x16_bf16 v[32:47], a[4:7], a[8:11], v[32:47]
	s_and_b32 m0, s32, 7
	s_lshl_b32 m0, m0, 11
	s_add_i32 m0, m0, 0x14400
	s_nop 0
	global_load_lds_dwordx4 v[180:181], off
	s_waitcnt lgkmcnt(4)
	v_mfma_f32_32x32x16_bf16 v[16:31], a[0:3], a[12:15], v[16:31]
	v_mfma_f32_32x32x16_bf16 v[0:15], a[4:7], a[12:15], v[0:15]
	s_nop 0
	s_nop 0
	s_nop 0
	s_nop 0
	s_waitcnt lgkmcnt(1)
	v_mfma_f32_32x32x16_bf16 v[48:63], a[16:19], a[24:27], v[48:63]
	v_mfma_f32_32x32x16_bf16 v[32:47], a[20:23], a[24:27], v[32:47]
	s_waitcnt vmcnt(6)
	s_waitcnt lgkmcnt(0)
	s_barrier
	ds_read_b128 a[12:15], v82 offset:4096
	ds_read_b128 a[8:11], v82
	ds_read_b128 a[4:7], v83 offset:36864
	ds_read_b128 a[0:3], v83 offset:32768
	v_mfma_f32_32x32x16_bf16 v[16:31], a[16:19], a[28:31], v[16:31]
	v_lshl_add_u64 v[158:159], v[66:67], 0, s[46:47]
	s_nop 0
	v_lshl_add_u64 v[160:161], v[68:69], 0, s[46:47]
	s_nop 0
	s_nop 0
	s_nop 0
	s_nop 0
	v_mfma_f32_32x32x16_bf16 v[0:15], a[20:23], a[28:31], v[0:15]
	s_and_b32 m0, s32, 7
	s_lshl_b32 m0, m0, 12
	s_add_i32 m0, m0, 0x18000
	s_nop 0
	global_load_lds_dwordx4 v[158:159], off
	s_nop 0
	v_lshl_add_u64 v[164:165], v[72:73], 0, s[46:47]
	s_nop 0
	s_nop 0
	s_nop 0
	v_lshl_add_u64 v[166:167], v[74:75], 0, s[46:47]
	s_nop 0
	s_nop 0
	s_nop 0
	v_lshl_add_u64 v[168:169], v[76:77], 0, s[46:47]
	s_nop 0
	s_mov_b64 s[46:47], 0x600
	s_nop 0
	s_nop 0
	s_nop 0
	s_nop 0
	s_nop 0
	ds_read_b128 a[16:19], v85 offset:32768
	ds_read_b128 a[20:23], v85 offset:36864
	ds_read_b128 a[24:27], v84
	ds_read_b128 a[28:31], v84 offset:4096
	s_waitcnt lgkmcnt(4)
	v_mfma_f32_32x32x16_bf16 v[48:63], a[0:3], a[8:11], v[48:63]
	s_nop 0
	v_mfma_f32_32x32x16_bf16 v[32:47], a[4:7], a[8:11], v[32:47]
	s_and_b32 m0, s32, 7
	s_lshl_b32 m0, m0, 12
	s_add_i32 m0, m0, 0x18400
	s_nop 0
	global_load_lds_dwordx4 v[160:161], off
	v_mfma_f32_32x32x16_bf16 v[16:31], a[0:3], a[12:15], v[16:31]
	v_mfma_f32_32x32x16_bf16 v[0:15], a[4:7], a[12:15], v[0:15]
	s_and_b32 m0, s32, 7
	s_lshl_b32 m0, m0, 12
	s_add_i32 m0, m0, 0x18800
	s_nop 0
	global_load_lds_dwordx4 v[162:163], off
	s_nop 0
	s_nop 0
	s_nop 0
	s_nop 0
	ds_read_b128 a[0:3], v87 offset:32768
	ds_read_b128 a[4:7], v87 offset:36864
	ds_read_b128 a[8:11], v86
	ds_read_b128 a[12:15], v86 offset:4096
	s_waitcnt lgkmcnt(5)
	v_mfma_f32_32x32x16_bf16 v[48:63], a[16:19], a[24:27], v[48:63]
	v_mfma_f32_32x32x16_bf16 v[32:47], a[20:23], a[24:27], v[32:47]
	s_and_b32 m0, s32, 7
	s_lshl_b32 m0, m0, 12
	s_add_i32 m0, m0, 0x18c00
	s_nop 0
	global_load_lds_dwordx4 v[164:165], off
	s_waitcnt lgkmcnt(4)
	v_mfma_f32_32x32x16_bf16 v[16:31], a[16:19], a[28:31], v[16:31]
	v_mfma_f32_32x32x16_bf16 v[0:15], a[20:23], a[28:31], v[0:15]
	s_and_b32 m0, s32, 7
	s_lshl_b32 m0, m0, 11
	s_add_i32 m0, m0, 0x20000
	s_nop 0
	global_load_lds_dwordx4 v[166:167], off
	s_nop 0
	s_nop 0
	s_nop 0
	s_nop 0
	ds_read_b128 a[16:19], v89 offset:32768
	ds_read_b128 a[20:23], v89 offset:36864
	ds_read_b128 a[24:27], v88
	ds_read_b128 a[28:31], v88 offset:4096
	s_waitcnt lgkmcnt(5)
	v_mfma_f32_32x32x16_bf16 v[48:63], a[0:3], a[8:11], v[48:63]
	v_mfma_f32_32x32x16_bf16 v[32:47], a[4:7], a[8:11], v[32:47]
	s_and_b32 m0, s32, 7
	s_lshl_b32 m0, m0, 11
	s_add_i32 m0, m0, 0x20400
	s_nop 0
	global_load_lds_dwordx4 v[168:169], off
	s_waitcnt lgkmcnt(4)
	v_mfma_f32_32x32x16_bf16 v[16:31], a[0:3], a[12:15], v[16:31]
	v_mfma_f32_32x32x16_bf16 v[0:15], a[4:7], a[12:15], v[0:15]
	s_nop 0
	s_nop 0
	s_nop 0
	s_nop 0
	s_waitcnt lgkmcnt(1)
	v_mfma_f32_32x32x16_bf16 v[48:63], a[16:19], a[24:27], v[48:63]
	v_mfma_f32_32x32x16_bf16 v[32:47], a[20:23], a[24:27], v[32:47]
	s_waitcnt vmcnt(6)
	s_waitcnt lgkmcnt(0)
	s_barrier
	ds_read_b128 a[12:15], v82 offset:53248
	ds_read_b128 a[8:11], v82 offset:49152
	ds_read_b128 a[4:7], v90
	ds_read_b128 a[0:3], v92
	v_mfma_f32_32x32x16_bf16 v[16:31], a[16:19], a[28:31], v[16:31]
	v_lshl_add_u64 v[170:171], v[66:67], 0, s[46:47]
	s_nop 0
	v_lshl_add_u64 v[172:173], v[68:69], 0, s[46:47]
	s_nop 0
	s_nop 0
	s_nop 0
	v_lshl_add_u64 v[174:175], v[70:71], 0, s[46:47]
	s_nop 0
	v_mfma_f32_32x32x16_bf16 v[0:15], a[20:23], a[28:31], v[0:15]
	s_and_b32 m0, s32, 7
	s_lshl_b32 m0, m0, 12
	s_add_i32 m0, m0, 0x0
	s_nop 0
	global_load_lds_dwordx4 v[170:171], off
	s_nop 0
	v_lshl_add_u64 v[176:177], v[72:73], 0, s[46:47]
	s_nop 0
	s_nop 0
	s_nop 0
	v_lshl_add_u64 v[178:179], v[74:75], 0, s[46:47]
	s_nop 0
	s_nop 0
	s_nop 0
	v_lshl_add_u64 v[180:181], v[76:77], 0, s[46:47]
	s_nop 0
	s_mov_b64 s[46:47], 0x680
	s_nop 0
	s_nop 0
	s_nop 0
	s_nop 0
	s_nop 0
	ds_read_b128 a[16:19], v93
	ds_read_b128 a[20:23], v91
	ds_read_b128 a[24:27], v84 offset:49152
	ds_read_b128 a[28:31], v84 offset:53248
	s_waitcnt lgkmcnt(4)
	v_mfma_f32_32x32x16_bf16 v[48:63], a[0:3], a[8:11], v[48:63]
	s_nop 0
	v_mfma_f32_32x32x16_bf16 v[32:47], a[4:7], a[8:11], v[32:47]
	s_and_b32 m0, s32, 7
	s_lshl_b32 m0, m0, 12
	s_add_i32 m0, m0, 0x400
	s_nop 0
	global_load_lds_dwordx4 v[172:173], off
	v_mfma_f32_32x32x16_bf16 v[16:31], a[0:3], a[12:15], v[16:31]
	v_mfma_f32_32x32x16_bf16 v[0:15], a[4:7], a[12:15], v[0:15]
	s_and_b32 m0, s32, 7
	s_lshl_b32 m0, m0, 12
	s_add_i32 m0, m0, 0x800
	s_nop 0
	global_load_lds_dwordx4 v[174:175], off
	s_nop 0
	s_nop 0
	s_nop 0
	s_nop 0
	ds_read_b128 a[0:3], v95
	ds_read_b128 a[4:7], v94
	ds_read_b128 a[8:11], v86 offset:49152
	ds_read_b128 a[12:15], v86 offset:53248
	s_waitcnt lgkmcnt(5)
	v_mfma_f32_32x32x16_bf16 v[48:63], a[16:19], a[24:27], v[48:63]
	v_mfma_f32_32x32x16_bf16 v[32:47], a[20:23], a[24:27], v[32:47]
	s_and_b32 m0, s32, 7
	s_lshl_b32 m0, m0, 12
	s_add_i32 m0, m0, 0xc00
	s_nop 0
	global_load_lds_dwordx4 v[176:177], off
	s_waitcnt lgkmcnt(4)
	v_mfma_f32_32x32x16_bf16 v[16:31], a[16:19], a[28:31], v[16:31]
	v_mfma_f32_32x32x16_bf16 v[0:15], a[20:23], a[28:31], v[0:15]
	s_and_b32 m0, s32, 7
	s_lshl_b32 m0, m0, 11
	s_add_i32 m0, m0, 0x8000
	s_nop 0
	global_load_lds_dwordx4 v[178:179], off
	s_nop 0
	s_nop 0
	s_nop 0
	s_nop 0
	ds_read_b128 a[16:19], v97
	ds_read_b128 a[20:23], v96
	ds_read_b128 a[24:27], v88 offset:49152
	ds_read_b128 a[28:31], v88 offset:53248
	s_waitcnt lgkmcnt(5)
	v_mfma_f32_32x32x16_bf16 v[48:63], a[0:3], a[8:11], v[48:63]
	v_mfma_f32_32x32x16_bf16 v[32:47], a[4:7], a[8:11], v[32:47]
	s_and_b32 m0, s32, 7
	s_lshl_b32 m0, m0, 11
	s_add_i32 m0, m0, 0x8400
	s_nop 0
	global_load_lds_dwordx4 v[180:181], off
	s_waitcnt lgkmcnt(4)
	v_mfma_f32_32x32x16_bf16 v[16:31], a[0:3], a[12:15], v[16:31]
	v_mfma_f32_32x32x16_bf16 v[0:15], a[4:7], a[12:15], v[0:15]
	s_nop 0
	s_nop 0
	s_nop 0
	s_nop 0
	s_waitcnt lgkmcnt(1)
	v_mfma_f32_32x32x16_bf16 v[48:63], a[16:19], a[24:27], v[48:63]
	v_mfma_f32_32x32x16_bf16 v[32:47], a[20:23], a[24:27], v[32:47]
	s_waitcnt vmcnt(6)
	s_waitcnt lgkmcnt(0)
	s_barrier
	ds_read_b128 a[12:15], v101
	ds_read_b128 a[8:11], v100
	ds_read_b128 a[4:7], v99
	ds_read_b128 a[0:3], v98
	v_mfma_f32_32x32x16_bf16 v[16:31], a[16:19], a[28:31], v[16:31]
	v_lshl_add_u64 v[158:159], v[66:67], 0, s[46:47]
	s_nop 0
	v_lshl_add_u64 v[160:161], v[68:69], 0, s[46:47]
	s_nop 0
	s_mov_b64 s[28:29], 0x700
	s_nop 0
	v_lshl_add_u64 v[162:163], v[70:71], 0, s[46:47]
	s_nop 0
	v_mfma_f32_32x32x16_bf16 v[0:15], a[20:23], a[28:31], v[0:15]
	s_and_b32 m0, s32, 7
	s_lshl_b32 m0, m0, 12
	s_add_i32 m0, m0, 0xc000
	s_nop 0
	global_load_lds_dwordx4 v[158:159], off
	s_nop 0
	v_lshl_add_u64 v[164:165], v[72:73], 0, s[46:47]
	s_nop 0
	s_nop 0
	s_nop 0
	v_lshl_add_u64 v[166:167], v[74:75], 0, s[46:47]
	s_nop 0
	s_nop 0
	s_nop 0
	v_lshl_add_u64 v[168:169], v[76:77], 0, s[46:47]
	s_nop 0
	s_nop 0
	s_nop 0
	s_nop 0
	s_nop 0
	s_nop 0
	s_nop 0
	ds_read_b128 a[16:19], v102
	ds_read_b128 a[20:23], v103
	ds_read_b128 a[24:27], v104
	ds_read_b128 a[28:31], v105
	s_waitcnt lgkmcnt(4)
	v_mfma_f32_32x32x16_bf16 v[48:63], a[0:3], a[8:11], v[48:63]
	s_nop 0
	v_mfma_f32_32x32x16_bf16 v[32:47], a[4:7], a[8:11], v[32:47]
	s_and_b32 m0, s32, 7
	s_lshl_b32 m0, m0, 12
	s_add_i32 m0, m0, 0xc400
	s_nop 0
	global_load_lds_dwordx4 v[160:161], off
	v_mfma_f32_32x32x16_bf16 v[16:31], a[0:3], a[12:15], v[16:31]
	v_mfma_f32_32x32x16_bf16 v[0:15], a[4:7], a[12:15], v[0:15]
	s_and_b32 m0, s32, 7
	s_lshl_b32 m0, m0, 12
	s_add_i32 m0, m0, 0xc800
	s_nop 0
	global_load_lds_dwordx4 v[162:163], off
	s_nop 0
	s_nop 0
	s_nop 0
	s_nop 0
	ds_read_b128 a[0:3], v106
	ds_read_b128 a[4:7], v107
	ds_read_b128 a[8:11], v108
	ds_read_b128 a[12:15], v109
	s_waitcnt lgkmcnt(5)
	v_mfma_f32_32x32x16_bf16 v[48:63], a[16:19], a[24:27], v[48:63]
	v_mfma_f32_32x32x16_bf16 v[32:47], a[20:23], a[24:27], v[32:47]
	s_and_b32 m0, s32, 7
	s_lshl_b32 m0, m0, 12
	s_add_i32 m0, m0, 0xcc00
	s_nop 0
	global_load_lds_dwordx4 v[164:165], off
	s_waitcnt lgkmcnt(4)
	v_mfma_f32_32x32x16_bf16 v[16:31], a[16:19], a[28:31], v[16:31]
	v_mfma_f32_32x32x16_bf16 v[0:15], a[20:23], a[28:31], v[0:15]
	s_and_b32 m0, s32, 7
	s_lshl_b32 m0, m0, 11
	s_add_i32 m0, m0, 0x14000
	s_nop 0
	global_load_lds_dwordx4 v[166:167], off
	s_nop 0
	s_nop 0
	s_nop 0
	s_nop 0
	ds_read_b128 a[16:19], v110
	ds_read_b128 a[20:23], v111
	ds_read_b128 a[24:27], v112
	ds_read_b128 a[28:31], v113
	s_waitcnt lgkmcnt(5)
	v_mfma_f32_32x32x16_bf16 v[48:63], a[0:3], a[8:11], v[48:63]
	v_mfma_f32_32x32x16_bf16 v[32:47], a[4:7], a[8:11], v[32:47]
	s_and_b32 m0, s32, 7
	s_lshl_b32 m0, m0, 11
	s_add_i32 m0, m0, 0x14400
	s_nop 0
	global_load_lds_dwordx4 v[168:169], off
	s_waitcnt lgkmcnt(4)
	v_mfma_f32_32x32x16_bf16 v[16:31], a[0:3], a[12:15], v[16:31]
	v_mfma_f32_32x32x16_bf16 v[0:15], a[4:7], a[12:15], v[0:15]
	s_nop 0
	s_nop 0
	s_nop 0
	s_nop 0
	s_waitcnt lgkmcnt(1)
	v_mfma_f32_32x32x16_bf16 v[48:63], a[16:19], a[24:27], v[48:63]
	v_mfma_f32_32x32x16_bf16 v[32:47], a[20:23], a[24:27], v[32:47]
	s_waitcnt vmcnt(6)
	s_waitcnt lgkmcnt(0)
	s_barrier
	ds_read_b128 a[12:15], v82 offset:4096
	ds_read_b128 a[8:11], v82
	ds_read_b128 a[4:7], v83 offset:36864
	ds_read_b128 a[0:3], v83 offset:32768
	v_mfma_f32_32x32x16_bf16 v[16:31], a[16:19], a[28:31], v[16:31]
	v_lshl_add_u64 v[170:171], v[66:67], 0, s[28:29]
	s_nop 0
	v_lshl_add_u64 v[172:173], v[68:69], 0, s[28:29]
	s_nop 0
	s_nop 0
	s_nop 0
	v_lshl_add_u64 v[174:175], v[70:71], 0, s[28:29]
	s_nop 0
	v_mfma_f32_32x32x16_bf16 v[0:15], a[20:23], a[28:31], v[0:15]
	s_and_b32 m0, s32, 7
	s_lshl_b32 m0, m0, 12
	s_add_i32 m0, m0, 0x18000
	s_nop 0
	global_load_lds_dwordx4 v[170:171], off
	s_nop 0
	v_lshl_add_u64 v[176:177], v[72:73], 0, s[28:29]
	s_nop 0
	s_nop 0
	s_nop 0
	v_lshl_add_u64 v[178:179], v[74:75], 0, s[28:29]
	s_nop 0
	s_nop 0
	s_nop 0
	v_lshl_add_u64 v[180:181], v[76:77], 0, s[28:29]
	s_nop 0
	s_mov_b64 s[28:29], 0x780
	s_nop 0
	s_nop 0
	s_nop 0
	s_nop 0
	s_nop 0
	ds_read_b128 a[16:19], v85 offset:32768
	ds_read_b128 a[20:23], v85 offset:36864
	ds_read_b128 a[24:27], v84
	ds_read_b128 a[28:31], v84 offset:4096
	s_waitcnt lgkmcnt(4)
	v_mfma_f32_32x32x16_bf16 v[48:63], a[0:3], a[8:11], v[48:63]
	v_lshl_add_u64 v[158:159], v[66:67], 0, s[28:29]
	s_nop 0
	v_mfma_f32_32x32x16_bf16 v[32:47], a[4:7], a[8:11], v[32:47]
	s_and_b32 m0, s32, 7
	s_lshl_b32 m0, m0, 12
	s_add_i32 m0, m0, 0x18400
	s_nop 0
	global_load_lds_dwordx4 v[172:173], off
	v_mfma_f32_32x32x16_bf16 v[16:31], a[0:3], a[12:15], v[16:31]
	v_mfma_f32_32x32x16_bf16 v[0:15], a[4:7], a[12:15], v[0:15]
	s_and_b32 m0, s32, 7
	s_lshl_b32 m0, m0, 12
	s_add_i32 m0, m0, 0x18800
	s_nop 0
	global_load_lds_dwordx4 v[174:175], off
	s_nop 0
	s_nop 0
	s_nop 0
	s_nop 0
	ds_read_b128 a[0:3], v87 offset:32768
	ds_read_b128 a[4:7], v87 offset:36864
	ds_read_b128 a[8:11], v86
	ds_read_b128 a[12:15], v86 offset:4096
	s_waitcnt lgkmcnt(5)
	v_mfma_f32_32x32x16_bf16 v[48:63], a[16:19], a[24:27], v[48:63]
	v_mfma_f32_32x32x16_bf16 v[32:47], a[20:23], a[24:27], v[32:47]
	s_and_b32 m0, s32, 7
	s_lshl_b32 m0, m0, 12
	s_add_i32 m0, m0, 0x18c00
	s_nop 0
	global_load_lds_dwordx4 v[176:177], off
	s_waitcnt lgkmcnt(4)
	v_mfma_f32_32x32x16_bf16 v[16:31], a[16:19], a[28:31], v[16:31]
	v_mfma_f32_32x32x16_bf16 v[0:15], a[20:23], a[28:31], v[0:15]
	s_and_b32 m0, s32, 7
	s_lshl_b32 m0, m0, 11
	s_add_i32 m0, m0, 0x20000
	s_nop 0
	global_load_lds_dwordx4 v[178:179], off
	s_nop 0
	s_nop 0
	s_nop 0
	s_nop 0
	ds_read_b128 a[16:19], v89 offset:32768
	ds_read_b128 a[20:23], v89 offset:36864
	ds_read_b128 a[24:27], v88
	ds_read_b128 a[28:31], v88 offset:4096
	s_waitcnt lgkmcnt(5)
	v_mfma_f32_32x32x16_bf16 v[48:63], a[0:3], a[8:11], v[48:63]
	v_mfma_f32_32x32x16_bf16 v[32:47], a[4:7], a[8:11], v[32:47]
	s_and_b32 m0, s32, 7
	s_lshl_b32 m0, m0, 11
	s_add_i32 m0, m0, 0x20400
	s_nop 0
	global_load_lds_dwordx4 v[180:181], off
	s_waitcnt lgkmcnt(4)
	v_mfma_f32_32x32x16_bf16 v[16:31], a[0:3], a[12:15], v[16:31]
	v_mfma_f32_32x32x16_bf16 v[0:15], a[4:7], a[12:15], v[0:15]
	s_nop 0
	s_nop 0
	s_nop 0
	s_nop 0
	s_waitcnt lgkmcnt(1)
	v_mfma_f32_32x32x16_bf16 v[48:63], a[16:19], a[24:27], v[48:63]
	v_mfma_f32_32x32x16_bf16 v[32:47], a[20:23], a[24:27], v[32:47]
	s_waitcnt vmcnt(6)
	s_waitcnt lgkmcnt(0)
	s_barrier
	ds_read_b128 a[12:15], v82 offset:53248
	ds_read_b128 a[8:11], v82 offset:49152
	ds_read_b128 a[4:7], v90
	ds_read_b128 a[0:3], v92
	s_nop 0
	v_lshl_add_u64 v[160:161], v[68:69], 0, s[28:29]
	s_nop 0
	v_mfma_f32_32x32x16_bf16 v[16:31], a[16:19], a[28:31], v[16:31]
	s_nop 0
	v_lshl_add_u64 v[162:163], v[70:71], 0, s[28:29]
	s_nop 0
	v_cmp_eq_u32_e64 s[0:1], 0, v79
	s_nop 0
	v_lshl_add_u64 v[164:165], v[72:73], 0, s[28:29]
	s_nop 0
	v_mfma_f32_32x32x16_bf16 v[0:15], a[20:23], a[28:31], v[0:15]
	s_and_b32 m0, s32, 7
	s_lshl_b32 m0, m0, 12
	s_add_i32 m0, m0, 0x0
	s_nop 0
	global_load_lds_dwordx4 v[158:159], off
	s_nop 0
	v_lshl_add_u64 v[166:167], v[74:75], 0, s[28:29]
	s_nop 0
	v_readlane_b32 s20, v215, 52
	s_nop 0
	v_lshl_add_u64 v[168:169], v[76:77], 0, s[28:29]
	s_nop 0
	v_readlane_b32 s21, v215, 53
	s_nop 0
	s_nop 0
	s_nop 0
	s_nop 0
	s_nop 0
	ds_read_b128 a[16:19], v93
	ds_read_b128 a[20:23], v91
	ds_read_b128 a[24:27], v84 offset:49152
	ds_read_b128 a[28:31], v84 offset:53248
	s_waitcnt lgkmcnt(4)
	v_mfma_f32_32x32x16_bf16 v[48:63], a[0:3], a[8:11], v[48:63]
	s_mov_b32 s23, 0
	v_mfma_f32_32x32x16_bf16 v[32:47], a[4:7], a[8:11], v[32:47]
	s_and_b32 m0, s32, 7
	s_lshl_b32 m0, m0, 12
	s_add_i32 m0, m0, 0x400
	s_nop 0
	global_load_lds_dwordx4 v[160:161], off
	v_mfma_f32_32x32x16_bf16 v[16:31], a[0:3], a[12:15], v[16:31]
	v_mfma_f32_32x32x16_bf16 v[0:15], a[4:7], a[12:15], v[0:15]
	s_and_b32 m0, s32, 7
	s_lshl_b32 m0, m0, 12
	s_add_i32 m0, m0, 0x800
	s_nop 0
	global_load_lds_dwordx4 v[162:163], off
	s_nop 0
	s_nop 0
	s_nop 0
	s_nop 0
	ds_read_b128 a[0:3], v95
	ds_read_b128 a[4:7], v94
	ds_read_b128 a[8:11], v86 offset:49152
	ds_read_b128 a[12:15], v86 offset:53248
	s_waitcnt lgkmcnt(5)
	v_mfma_f32_32x32x16_bf16 v[48:63], a[16:19], a[24:27], v[48:63]
	v_mfma_f32_32x32x16_bf16 v[32:47], a[20:23], a[24:27], v[32:47]
	s_and_b32 m0, s32, 7
	s_lshl_b32 m0, m0, 12
	s_add_i32 m0, m0, 0xc00
	s_nop 0
	global_load_lds_dwordx4 v[164:165], off
	s_waitcnt lgkmcnt(4)
	v_mfma_f32_32x32x16_bf16 v[16:31], a[16:19], a[28:31], v[16:31]
	v_mfma_f32_32x32x16_bf16 v[0:15], a[20:23], a[28:31], v[0:15]
	s_and_b32 m0, s32, 7
	s_lshl_b32 m0, m0, 11
	s_add_i32 m0, m0, 0x8000
	s_nop 0
	global_load_lds_dwordx4 v[166:167], off
	s_nop 0
	s_nop 0
	s_nop 0
	s_nop 0
	ds_read_b128 a[16:19], v97
	ds_read_b128 a[20:23], v96
	ds_read_b128 a[24:27], v88 offset:49152
	ds_read_b128 a[28:31], v88 offset:53248
	s_waitcnt lgkmcnt(5)
	v_mfma_f32_32x32x16_bf16 v[48:63], a[0:3], a[8:11], v[48:63]
	v_mfma_f32_32x32x16_bf16 v[32:47], a[4:7], a[8:11], v[32:47]
	s_and_b32 m0, s32, 7
	s_lshl_b32 m0, m0, 11
	s_add_i32 m0, m0, 0x8400
	s_nop 0
	global_load_lds_dwordx4 v[168:169], off
	s_waitcnt lgkmcnt(4)
	v_mfma_f32_32x32x16_bf16 v[16:31], a[0:3], a[12:15], v[16:31]
	v_mfma_f32_32x32x16_bf16 v[0:15], a[4:7], a[12:15], v[0:15]
	s_nop 0
	s_nop 0
	s_nop 0
	s_nop 0
	s_waitcnt lgkmcnt(1)
	v_mfma_f32_32x32x16_bf16 v[48:63], a[16:19], a[24:27], v[48:63]
	v_mfma_f32_32x32x16_bf16 v[32:47], a[20:23], a[24:27], v[32:47]
	s_waitcnt vmcnt(6)
	s_waitcnt lgkmcnt(0)
	s_barrier
	ds_read_b128 a[12:15], v101
	ds_read_b128 a[8:11], v100
	ds_read_b128 a[4:7], v99
	ds_read_b128 a[0:3], v98
	v_mfma_f32_32x32x16_bf16 v[16:31], a[16:19], a[28:31], v[16:31]
	v_mfma_f32_32x32x16_bf16 v[0:15], a[20:23], a[28:31], v[0:15]
	s_nop 0
	s_nop 0
	s_nop 0
	s_nop 0
	ds_read_b128 a[16:19], v102
	ds_read_b128 a[20:23], v103
	ds_read_b128 a[24:27], v104
	ds_read_b128 a[28:31], v105
	s_waitcnt lgkmcnt(4)
	v_mfma_f32_32x32x16_bf16 v[48:63], a[0:3], a[8:11], v[48:63]
	v_mfma_f32_32x32x16_bf16 v[32:47], a[4:7], a[8:11], v[32:47]
	v_mfma_f32_32x32x16_bf16 v[16:31], a[0:3], a[12:15], v[16:31]
	v_mfma_f32_32x32x16_bf16 v[0:15], a[4:7], a[12:15], v[0:15]
	s_nop 0
	s_nop 0
	s_nop 0
	s_nop 0
	ds_read_b128 a[0:3], v106
	ds_read_b128 a[4:7], v107
	ds_read_b128 a[8:11], v108
	ds_read_b128 a[12:15], v109
	s_waitcnt lgkmcnt(5)
	v_mfma_f32_32x32x16_bf16 v[48:63], a[16:19], a[24:27], v[48:63]
	v_mfma_f32_32x32x16_bf16 v[32:47], a[20:23], a[24:27], v[32:47]
	s_waitcnt lgkmcnt(4)
	v_mfma_f32_32x32x16_bf16 v[16:31], a[16:19], a[28:31], v[16:31]
	v_mfma_f32_32x32x16_bf16 v[0:15], a[20:23], a[28:31], v[0:15]
	s_nop 0
	s_nop 0
	s_nop 0
	s_nop 0
	ds_read_b128 a[16:19], v110
	ds_read_b128 a[20:23], v111
	ds_read_b128 a[24:27], v112
	ds_read_b128 a[28:31], v113
	s_waitcnt lgkmcnt(5)
	v_mfma_f32_32x32x16_bf16 v[48:63], a[0:3], a[8:11], v[48:63]
	v_mfma_f32_32x32x16_bf16 v[32:47], a[4:7], a[8:11], v[32:47]
	s_waitcnt lgkmcnt(4)
	v_mfma_f32_32x32x16_bf16 v[16:31], a[0:3], a[12:15], v[16:31]
	v_mfma_f32_32x32x16_bf16 v[0:15], a[4:7], a[12:15], v[0:15]
	s_nop 0
	s_nop 0
	s_nop 0
	s_nop 0
	s_waitcnt lgkmcnt(1)
	v_mfma_f32_32x32x16_bf16 v[48:63], a[16:19], a[24:27], v[48:63]
	v_mfma_f32_32x32x16_bf16 v[32:47], a[20:23], a[24:27], v[32:47]
	s_waitcnt vmcnt(0)
	s_waitcnt lgkmcnt(0)
	s_barrier
	ds_read_b128 a[12:15], v82 offset:4096
	ds_read_b128 a[8:11], v82
	ds_read_b128 a[4:7], v83 offset:36864
	ds_read_b128 a[0:3], v83 offset:32768
	v_mfma_f32_32x32x16_bf16 v[16:31], a[16:19], a[28:31], v[16:31]
	v_mfma_f32_32x32x16_bf16 v[0:15], a[20:23], a[28:31], v[0:15]
	s_nop 0
	s_nop 0
	s_nop 0
	s_nop 0
	ds_read_b128 a[16:19], v85 offset:32768
	ds_read_b128 a[20:23], v85 offset:36864
	ds_read_b128 a[24:27], v84
	ds_read_b128 a[28:31], v84 offset:4096
	s_waitcnt lgkmcnt(4)
	v_mfma_f32_32x32x16_bf16 v[48:63], a[0:3], a[8:11], v[48:63]
	v_mfma_f32_32x32x16_bf16 v[32:47], a[4:7], a[8:11], v[32:47]
	v_mfma_f32_32x32x16_bf16 v[16:31], a[0:3], a[12:15], v[16:31]
	v_mfma_f32_32x32x16_bf16 v[0:15], a[4:7], a[12:15], v[0:15]
	s_nop 0
	s_nop 0
	s_nop 0
	s_nop 0
	ds_read_b128 a[0:3], v87 offset:32768
	ds_read_b128 a[4:7], v87 offset:36864
	ds_read_b128 a[8:11], v86
	ds_read_b128 a[12:15], v86 offset:4096
	s_waitcnt lgkmcnt(5)
	v_mfma_f32_32x32x16_bf16 v[48:63], a[16:19], a[24:27], v[48:63]
	v_mfma_f32_32x32x16_bf16 v[32:47], a[20:23], a[24:27], v[32:47]
	s_waitcnt lgkmcnt(4)
	v_mfma_f32_32x32x16_bf16 v[16:31], a[16:19], a[28:31], v[16:31]
	v_mfma_f32_32x32x16_bf16 v[0:15], a[20:23], a[28:31], v[0:15]
	s_nop 0
	s_nop 0
	s_nop 0
	s_waitcnt lgkmcnt(1)
	v_mfma_f32_32x32x16_bf16 v[48:63], a[0:3], a[8:11], v[48:63]
	v_mfma_f32_32x32x16_bf16 v[32:47], a[4:7], a[8:11], v[32:47]
	s_nop 0
	s_waitcnt lgkmcnt(0)
	v_mfma_f32_32x32x16_bf16 v[0:15], a[4:7], a[12:15], v[0:15]
	v_mfma_f32_32x32x16_bf16 v[16:31], a[0:3], a[12:15], v[16:31]
	ds_read_b128 v[66:69], v89 offset:32768
	ds_read_b128 v[70:73], v88
	ds_read_b128 v[74:77], v89 offset:36864
	ds_read_b128 v[82:85], v88 offset:4096
	s_waitcnt lgkmcnt(0)
	s_barrier
	s_waitcnt lgkmcnt(0)
	v_mfma_f32_32x32x16_bf16 v[48:63], v[66:69], v[70:73], v[48:63]
	v_mfma_f32_32x32x16_bf16 v[32:47], v[74:77], v[70:73], v[32:47]
	s_nop 10
	ds_write_b128 v64, v[48:51]
	ds_write_b128 v64, v[52:55] offset:32
	ds_write_b128 v64, v[56:59] offset:64
	ds_write_b128 v64, v[60:63] offset:96
	ds_write_b128 v64, v[32:35] offset:128
	v_mfma_f32_32x32x16_bf16 v[0:15], v[74:77], v[82:85], v[0:15]
	v_mfma_f32_32x32x16_bf16 v[16:31], v[66:69], v[82:85], v[16:31]
	ds_write_b128 v64, v[36:39] offset:160
	ds_write_b128 v64, v[40:43] offset:192
	ds_write_b128 v64, v[44:47] offset:224
	s_nop 8
	ds_write_b128 v64, v[16:19] offset:16896
	ds_write_b128 v64, v[20:23] offset:16928
	ds_write_b128 v64, v[24:27] offset:16960
	ds_write_b128 v64, v[28:31] offset:16992
	ds_write_b128 v64, v[0:3] offset:17024
	ds_write_b128 v64, v[4:7] offset:17056
	ds_write_b128 v64, v[8:11] offset:17088
	ds_write_b128 v64, v[12:15] offset:17120
	s_waitcnt lgkmcnt(0)
	s_barrier
	v_lshl_or_b32 v0, v79, 2, s31
	v_ashrrev_i32_e32 v1, 31, v0
	v_lshl_add_u32 v4, v79, 4, 0
	v_lshl_add_u64 v[6:7], v[0:1], 2, s[92:93]
	v_lshl_add_u64 v[8:9], v[0:1], 1, s[20:21]
	s_branch .LBB0_161

.LBB0_242:
	s_or_b64 exec, exec, s[0:1]
	v_mov_b32_e32 v74, v133
	s_barrier
	v_readlane_b32 s53, v214, 24
	v_ashrrev_i32_e32 v12, 6, v74
	v_bfe_u32 v4, v74, 3, 3
	v_lshl_or_b32 v2, v12, 4, v4
	v_add_u32_e32 v0, s53, v2
	v_bfe_u32 v5, v74, 4, 2
	v_ashrrev_i32_e32 v1, 31, v0
	v_xor_b32_e32 v5, v5, v74
	v_lshlrev_b64 v[0:1], 11, v[0:1]
	v_lshlrev_b32_e32 v5, 4, v5
	v_lshl_add_u64 v[0:1], s[40:41], 0, v[0:1]
	v_or_b32_e32 v13, 8, v2
	v_lshl_or_b32 v4, v12, 5, v4
	v_and_b32_e32 v64, 0x70, v5
	v_add_u32_e32 v2, s53, v13
	v_ashrrev_i32_e32 v5, 31, v4
	v_readlane_b32 s0, v214, 4
	v_lshl_add_u64 v[70:71], v[0:1], 0, v[64:65]
	v_lshrrev_b32_e32 v0, 1, v13
	v_ashrrev_i32_e32 v3, 31, v2
	v_lshlrev_b64 v[6:7], 11, v[4:5]
	v_readlane_b32 s1, v214, 5
	v_xor_b32_e32 v0, v0, v74
	v_lshlrev_b64 v[2:3], 11, v[2:3]
	v_lshl_add_u64 v[6:7], s[0:1], 0, v[6:7]
	v_lshlrev_b32_e32 v0, 4, v0
	v_lshl_add_u64 v[2:3], s[40:41], 0, v[2:3]
	v_lshl_add_u64 v[66:67], v[6:7], 0, v[64:65]
	v_lshrrev_b32_e32 v4, 1, v4
	v_and_b32_e32 v64, 0x70, v0
	v_bitop3_b32 v4, v4, v74, 4 bitop3:0x36
	v_lshl_add_u64 v[72:73], v[2:3], 0, v[64:65]
	v_lshlrev_b32_e32 v3, 12, v12
	v_lshlrev_b32_e32 v4, 4, v4
	v_add_u32_e32 v127, 0, v3
	s_mov_b64 s[0:1], 0x2000000
	v_and_b32_e32 v4, 0x70, v4
	v_mov_b32_e32 v5, v65
	s_waitcnt vmcnt(0)
	v_readfirstlane_b32 s38, v127
	v_add_u32_e32 v126, 0x400, v127
	v_lshl_add_u64 v[8:9], v[66:67], 0, s[0:1]
	v_lshl_add_u64 v[68:69], v[6:7], 0, v[4:5]
	s_mov_b64 s[0:1], 0x2004000
	s_waitcnt lgkmcnt(0)
	s_barrier
	s_mov_b32 m0, s38
	v_readfirstlane_b32 s37, v126
	v_lshl_add_u64 v[4:5], v[68:69], 0, s[0:1]
	global_load_lds_dwordx4 v[8:9], off
	s_mov_b32 m0, s37
	v_add_u32_e32 v124, 0x800, v127
	global_load_lds_dwordx4 v[4:5], off
	v_lshlrev_b32_e32 v4, 11, v12
	s_mov_b64 s[0:1], 0x2008000
	v_readfirstlane_b32 s36, v124
	v_add_u32_e32 v122, 0xc00, v127
	v_add_u32_e32 v5, 0, v4
	v_lshl_add_u64 v[6:7], v[66:67], 0, s[0:1]
	s_mov_b64 s[0:1], 0x200c000
	s_mov_b32 m0, s36
	v_readfirstlane_b32 s35, v122
	v_add_u32_e32 v125, 0x8000, v5
	v_lshl_add_u64 v[10:11], v[68:69], 0, s[0:1]
	global_load_lds_dwordx4 v[6:7], off
	s_mov_b32 m0, s35
	v_readfirstlane_b32 s39, v125
	v_add_u32_e32 v123, 0x8400, v5
	global_load_lds_dwordx4 v[10:11], off
	s_mov_b32 m0, s39
	v_readfirstlane_b32 s40, v123
	v_add_u32_e32 v116, 0xc000, v127
	global_load_lds_dwordx4 v[70:71], off
	s_mov_b32 m0, s40
	s_mov_b64 s[0:1], 0x2000080
	v_readfirstlane_b32 s23, v116
	v_add_u32_e32 v117, 0xc400, v127
	global_load_lds_dwordx4 v[72:73], off
	v_lshl_add_u64 v[0:1], v[66:67], 0, s[0:1]
	s_mov_b32 m0, s23
	s_mov_b64 s[0:1], 0x2004080
	v_readfirstlane_b32 s24, v117
	v_add_u32_e32 v118, 0xc800, v127
	global_load_lds_dwordx4 v[0:1], off
	v_lshl_add_u64 v[0:1], v[68:69], 0, s[0:1]
	s_mov_b32 m0, s24
	s_mov_b64 s[0:1], 0x2008080
	v_readfirstlane_b32 s28, v118
	v_add_u32_e32 v119, 0xcc00, v127
	global_load_lds_dwordx4 v[0:1], off
	v_lshl_add_u64 v[0:1], v[66:67], 0, s[0:1]
	s_mov_b32 m0, s28
	s_mov_b64 s[0:1], 0x200c080
	v_readfirstlane_b32 s29, v119
	v_add_u32_e32 v120, s85, v4
	global_load_lds_dwordx4 v[0:1], off
	v_lshl_add_u64 v[0:1], v[68:69], 0, s[0:1]
	s_mov_b32 m0, s29
	s_mov_b64 s[0:1], 0x80
	v_readfirstlane_b32 s33, v120
	v_add_u32_e32 v121, 0x14400, v5
	global_load_lds_dwordx4 v[0:1], off
	v_lshl_add_u64 v[0:1], v[70:71], 0, s[0:1]
	s_mov_b32 m0, s33
	v_readfirstlane_b32 s34, v121
	v_lshrrev_b32_e32 v2, 1, v74
	v_bfe_u32 v64, v74, 5, 1
	global_load_lds_dwordx4 v[0:1], off
	v_lshl_add_u64 v[0:1], v[72:73], 0, s[0:1]
	s_mov_b32 m0, s34
	s_mov_b64 s[0:1], 0x2000100
	global_load_lds_dwordx4 v[0:1], off
	v_bitop3_b32 v0, v2, v64, 7 bitop3:0x6c
	v_add_u32_e32 v110, s3, v3
	v_lshlrev_b32_e32 v128, 4, v0
	s_waitcnt vmcnt(6)
	v_lshl_add_u64 v[0:1], v[66:67], 0, s[0:1]
	v_readfirstlane_b32 s0, v110
	v_add_u32_e32 v111, 0x400, v110
	s_waitcnt lgkmcnt(0)
	s_barrier
	s_mov_b32 m0, s0
	s_mov_b64 s[20:21], 0x2004100
	v_readfirstlane_b32 s1, v111
	v_add_u32_e32 v112, 0x800, v110
	global_load_lds_dwordx4 v[0:1], off
	v_lshl_add_u64 v[0:1], v[68:69], 0, s[20:21]
	s_mov_b32 m0, s1
	s_mov_b64 s[20:21], 0x2008100
	v_readfirstlane_b32 s2, v112
	global_load_lds_dwordx4 v[0:1], off
	v_lshl_add_u64 v[0:1], v[66:67], 0, s[20:21]
	s_mov_b32 m0, s2
	s_mov_b64 s[20:21], 0x200c100
	global_load_lds_dwordx4 v[0:1], off
	v_lshl_add_u64 v[0:1], v[68:69], 0, s[20:21]
	v_add_u32_e32 v113, 0xc00, v110
	v_readlane_b32 s21, v212, 31
	v_and_b32_e32 v75, 31, v74
	v_readfirstlane_b32 s20, v113
	v_add_u32_e32 v114, s21, v4
	v_add_u32_e32 v2, s3, v4
	v_and_b32_e32 v76, 1, v12
	v_lshlrev_b32_e32 v13, 7, v75
	s_mov_b32 m0, s20
	s_mov_b64 s[30:31], 0x100
	v_readfirstlane_b32 s21, v114
	v_add_u32_e32 v115, 0x8400, v2
	v_lshl_or_b32 v98, v76, 13, v13
	global_load_lds_dwordx4 v[0:1], off
	v_lshl_add_u64 v[0:1], v[70:71], 0, s[30:31]
	s_mov_b32 m0, s21
	v_readfirstlane_b32 s22, v115
	global_load_lds_dwordx4 v[0:1], off
	v_lshl_add_u64 v[0:1], v[72:73], 0, s[30:31]
	s_mov_b32 m0, s22
	v_add_u32_e32 v96, 0, v98
	global_load_lds_dwordx4 v[0:1], off
	v_add_u32_e32 v79, v96, v128
	v_ashrrev_i32_e32 v77, 7, v74
	ds_read_b128 a[0:3], v79 offset:32768
	ds_read_b128 a[4:7], v79 offset:36864
	v_lshl_or_b32 v129, v77, 13, v13
	v_add_u32_e32 v97, 0, v129
	v_add_u32_e32 v78, v97, v128
	ds_read_b128 a[8:11], v78
	ds_read_b128 a[12:15], v78 offset:4096
	s_waitcnt lgkmcnt(1)
	v_mfma_f32_32x32x16_bf16 v[48:63], a[0:3], a[8:11], 0
	v_bfe_u32 v99, v74, 1, 3
	s_mov_b64 s[30:31], 0x2000180
	s_mov_b32 m0, s38
	v_or_b32_e32 v139, 0x8000, v98
	v_or_b32_e32 v140, 0x9000, v98
	v_add_u32_e32 v141, s3, v129
	v_or_b32_e32 v142, 0x1000, v129
	v_mfma_f32_32x32x16_bf16 v[32:47], a[4:7], a[8:11], 0
	v_lshl_or_b32 v77, v77, 6, v75
	v_mul_lo_u32 v77, v77, s26
	s_mov_b64 s[80:81], 0x200
	s_waitcnt lgkmcnt(0)
	v_mfma_f32_32x32x16_bf16 v[16:31], a[0:3], a[12:15], 0
	v_bitop3_b32 v0, v64, v99, 2 bitop3:0x36
	v_lshlrev_b32_e32 v132, 4, v0
	v_add_u32_e32 v80, v97, v132
	ds_read_b128 a[28:31], v80 offset:4096
	s_nop 0
	s_nop 0
	ds_read_b128 a[24:27], v80
	s_nop 0
	v_add_u32_e32 v81, v96, v132
	ds_read_b128 a[20:23], v81 offset:36864
	s_nop 0
	s_nop 0
	ds_read_b128 a[16:19], v81 offset:32768
	s_nop 0
	s_nop 0
	s_nop 0
	s_nop 0
	s_nop 0
	s_nop 0
	v_mfma_f32_32x32x16_bf16 v[0:15], a[4:7], a[12:15], 0
	s_nop 0
	s_waitcnt lgkmcnt(0)
	v_mfma_f32_32x32x16_bf16 v[48:63], a[16:19], a[24:27], v[48:63]
	v_mfma_f32_32x32x16_bf16 v[32:47], a[20:23], a[24:27], v[32:47]
	v_mfma_f32_32x32x16_bf16 v[16:31], a[16:19], a[28:31], v[16:31]
	v_bitop3_b32 v82, v64, v99, 4 bitop3:0x36
	v_lshlrev_b32_e32 v134, 4, v82
	v_add_u32_e32 v82, v97, v134
	ds_read_b128 a[12:15], v82 offset:4096
	s_nop 0
	s_nop 0
	ds_read_b128 a[8:11], v82
	s_nop 0
	v_add_u32_e32 v83, v96, v134
	ds_read_b128 a[4:7], v83 offset:36864
	s_nop 0
	s_nop 0
	ds_read_b128 a[0:3], v83 offset:32768
	s_nop 0
	s_nop 0
	s_nop 0
	v_mfma_f32_32x32x16_bf16 v[0:15], a[20:23], a[28:31], v[0:15]
	s_nop 0
	s_nop 0
	s_nop 0
	s_nop 0
	s_waitcnt lgkmcnt(0)
	v_mfma_f32_32x32x16_bf16 v[48:63], a[0:3], a[8:11], v[48:63]
	v_mfma_f32_32x32x16_bf16 v[32:47], a[4:7], a[8:11], v[32:47]
	v_mfma_f32_32x32x16_bf16 v[16:31], a[0:3], a[12:15], v[16:31]
	v_bitop3_b32 v84, v64, v99, 6 bitop3:0x36
	v_lshlrev_b32_e32 v138, 4, v84
	v_add_u32_e32 v84, v97, v138
	ds_read_b128 a[28:31], v84 offset:4096
	s_nop 0
	s_nop 0
	ds_read_b128 a[24:27], v84
	s_nop 0
	v_add_u32_e32 v85, v96, v138
	ds_read_b128 a[20:23], v85 offset:36864
	s_nop 0
	s_nop 0
	ds_read_b128 a[16:19], v85 offset:32768
	s_nop 0
	s_nop 0
	s_nop 0
	v_lshlrev_b32_e32 v64, 4, v64
	v_lshl_or_b32 v64, v76, 8, v64
	v_add3_u32 v64, 0, v77, v64
	v_mfma_f32_32x32x16_bf16 v[0:15], a[4:7], a[12:15], v[0:15]
	s_nop 0
	s_nop 0
	s_nop 0
	s_nop 0
	s_waitcnt lgkmcnt(0)
	v_mfma_f32_32x32x16_bf16 v[48:63], a[16:19], a[24:27], v[48:63]
	v_mfma_f32_32x32x16_bf16 v[32:47], a[20:23], a[24:27], v[32:47]
	s_waitcnt vmcnt(6)
	s_waitcnt lgkmcnt(0)
	s_barrier
	ds_read_b128 a[12:15], v78 offset:53248
	ds_read_b128 a[8:11], v78 offset:49152
	v_mfma_f32_32x32x16_bf16 v[16:31], a[16:19], a[28:31], v[16:31]
	v_lshl_add_u64 v[86:87], v[66:67], 0, s[30:31]
	s_mov_b64 s[30:31], 0x2004180
	global_load_lds_dwordx4 v[86:87], off
	v_lshl_add_u64 v[86:87], v[68:69], 0, s[30:31]
	s_mov_b32 m0, s37
	s_mov_b64 s[30:31], 0x2008180
	global_load_lds_dwordx4 v[86:87], off
	v_lshl_add_u64 v[86:87], v[66:67], 0, s[30:31]
	s_mov_b32 m0, s36
	s_mov_b64 s[30:31], 0x200c180
	global_load_lds_dwordx4 v[86:87], off
	v_lshl_add_u64 v[86:87], v[68:69], 0, s[30:31]
	s_mov_b32 m0, s35
	s_mov_b64 s[30:31], 0x180
	global_load_lds_dwordx4 v[86:87], off
	v_lshl_add_u64 v[86:87], v[70:71], 0, s[30:31]
	s_mov_b32 m0, s39
	v_mfma_f32_32x32x16_bf16 v[0:15], a[20:23], a[28:31], v[0:15]
	global_load_lds_dwordx4 v[86:87], off
	v_lshl_add_u64 v[86:87], v[72:73], 0, s[30:31]
	s_mov_b32 m0, s40
	s_add_i32 s30, 0, 0xc000
	global_load_lds_dwordx4 v[86:87], off
	v_add_u32_e32 v86, s30, v128
	v_add_u32_e32 v88, v86, v139
	v_add_u32_e32 v86, v86, v140
	ds_read_b128 a[4:7], v86
	ds_read_b128 a[0:3], v88
	s_nop 0
	s_nop 0
	s_nop 0
	s_nop 0
	s_nop 0
	s_nop 0
	s_nop 0
	v_add_u32_e32 v87, s30, v132
	v_add_u32_e32 v89, v87, v139
	ds_read_b128 a[16:19], v89
	v_add_u32_e32 v87, v87, v140
	ds_read_b128 a[20:23], v87
	ds_read_b128 a[24:27], v80 offset:49152
	ds_read_b128 a[28:31], v80 offset:53248
	s_waitcnt lgkmcnt(4)
	v_mfma_f32_32x32x16_bf16 v[48:63], a[0:3], a[8:11], v[48:63]
	s_nop 0
	s_nop 0
	s_nop 0
	s_mov_b32 m0, s23
	v_mfma_f32_32x32x16_bf16 v[32:47], a[4:7], a[8:11], v[32:47]
	v_mfma_f32_32x32x16_bf16 v[16:31], a[0:3], a[12:15], v[16:31]
	v_mfma_f32_32x32x16_bf16 v[0:15], a[4:7], a[12:15], v[0:15]
	s_nop 0
	s_nop 0
	s_nop 0
	s_nop 0
	v_add_u32_e32 v90, s30, v134
	v_add_u32_e32 v91, v90, v139
	ds_read_b128 a[0:3], v91
	v_add_u32_e32 v90, v90, v140
	ds_read_b128 a[4:7], v90
	ds_read_b128 a[8:11], v82 offset:49152
	ds_read_b128 a[12:15], v82 offset:53248
	s_waitcnt lgkmcnt(5)
	v_mfma_f32_32x32x16_bf16 v[48:63], a[16:19], a[24:27], v[48:63]
	v_mfma_f32_32x32x16_bf16 v[32:47], a[20:23], a[24:27], v[32:47]
	s_waitcnt lgkmcnt(4)
	v_mfma_f32_32x32x16_bf16 v[16:31], a[16:19], a[28:31], v[16:31]
	s_nop 0
	s_nop 0
	s_nop 0
	v_mfma_f32_32x32x16_bf16 v[0:15], a[20:23], a[28:31], v[0:15]
	s_nop 0
	s_nop 0
	s_nop 0
	s_nop 0
	v_add_u32_e32 v92, s30, v138
	v_add_u32_e32 v93, v92, v139
	ds_read_b128 a[16:19], v93
	v_add_u32_e32 v92, v92, v140
	ds_read_b128 a[20:23], v92
	ds_read_b128 a[24:27], v84 offset:49152
	ds_read_b128 a[28:31], v84 offset:53248
	s_waitcnt lgkmcnt(5)
	v_mfma_f32_32x32x16_bf16 v[48:63], a[0:3], a[8:11], v[48:63]
	v_mfma_f32_32x32x16_bf16 v[32:47], a[4:7], a[8:11], v[32:47]
	s_waitcnt lgkmcnt(4)
	v_mfma_f32_32x32x16_bf16 v[16:31], a[0:3], a[12:15], v[16:31]
	s_nop 0
	s_nop 0
	s_nop 0
	s_mov_b64 s[30:31], 0x2000200
	v_mfma_f32_32x32x16_bf16 v[0:15], a[4:7], a[12:15], v[0:15]
	s_nop 0
	s_nop 0
	s_nop 0
	s_nop 0
	s_waitcnt lgkmcnt(1)
	v_mfma_f32_32x32x16_bf16 v[48:63], a[16:19], a[24:27], v[48:63]
	v_mfma_f32_32x32x16_bf16 v[32:47], a[20:23], a[24:27], v[32:47]
	s_waitcnt vmcnt(6)
	s_waitcnt lgkmcnt(0)
	s_barrier
	v_add_u32_e32 v96, v141, v128
	ds_read_b128 a[8:11], v96
	v_mfma_f32_32x32x16_bf16 v[16:31], a[16:19], a[28:31], v[16:31]
	v_lshl_add_u64 v[94:95], v[66:67], 0, s[30:31]
	s_mov_b64 s[30:31], 0x2004200
	global_load_lds_dwordx4 v[94:95], off
	v_lshl_add_u64 v[94:95], v[68:69], 0, s[30:31]
	s_mov_b32 m0, s24
	s_mov_b64 s[30:31], 0x2008200
	global_load_lds_dwordx4 v[94:95], off
	v_lshl_add_u64 v[94:95], v[66:67], 0, s[30:31]
	s_mov_b32 m0, s28
	s_mov_b64 s[30:31], 0x200c200
	global_load_lds_dwordx4 v[94:95], off
	v_lshl_add_u64 v[94:95], v[68:69], 0, s[30:31]
	s_mov_b32 m0, s29
	s_mov_b64 s[30:31], 0x200
	global_load_lds_dwordx4 v[94:95], off
	v_lshl_add_u64 v[94:95], v[70:71], 0, s[30:31]
	s_mov_b32 m0, s33
	v_add_u32_e32 v97, s3, v128
	global_load_lds_dwordx4 v[94:95], off
	v_lshl_add_u64 v[94:95], v[72:73], 0, s[30:31]
	s_mov_b32 m0, s34
	v_mfma_f32_32x32x16_bf16 v[0:15], a[20:23], a[28:31], v[0:15]
	global_load_lds_dwordx4 v[94:95], off
	v_add_u32_e32 v95, v97, v140
	ds_read_b128 a[4:7], v95
	v_add_u32_e32 v94, v97, v139
	v_add_u32_e32 v97, v97, v142
	ds_read_b128 a[12:15], v97
	ds_read_b128 a[0:3], v94
	s_nop 0
	s_nop 0
	s_nop 0
	s_nop 0
	s_nop 0
	s_nop 0
	s_nop 0
	s_nop 0
	v_add_u32_e32 v101, s3, v132
	v_add_u32_e32 v98, v101, v139
	ds_read_b128 a[16:19], v98
	v_add_u32_e32 v99, v101, v140
	ds_read_b128 a[20:23], v99
	v_add_u32_e32 v100, v141, v132
	ds_read_b128 a[24:27], v100
	v_add_u32_e32 v101, v101, v142
	ds_read_b128 a[28:31], v101
	s_waitcnt lgkmcnt(4)
	v_mfma_f32_32x32x16_bf16 v[48:63], a[0:3], a[8:11], v[48:63]
	s_mov_b64 s[30:31], 0x2000280
	s_mov_b32 m0, s0
	v_mfma_f32_32x32x16_bf16 v[32:47], a[4:7], a[8:11], v[32:47]
	s_nop 0
	s_nop 0
	s_nop 0
	s_nop 0
	s_nop 0
	v_mfma_f32_32x32x16_bf16 v[16:31], a[0:3], a[12:15], v[16:31]
	s_nop 0
	v_mfma_f32_32x32x16_bf16 v[0:15], a[4:7], a[12:15], v[0:15]
	s_nop 0
	s_nop 0
	s_nop 0
	v_add_u32_e32 v105, s3, v134
	v_add_u32_e32 v102, v105, v139
	ds_read_b128 a[0:3], v102
	v_add_u32_e32 v103, v105, v140
	ds_read_b128 a[4:7], v103
	v_add_u32_e32 v104, v141, v134
	ds_read_b128 a[8:11], v104
	v_add_u32_e32 v105, v105, v142
	ds_read_b128 a[12:15], v105
	s_waitcnt lgkmcnt(5)
	v_mfma_f32_32x32x16_bf16 v[48:63], a[16:19], a[24:27], v[48:63]
	v_mfma_f32_32x32x16_bf16 v[32:47], a[20:23], a[24:27], v[32:47]
	s_waitcnt lgkmcnt(4)
	v_mfma_f32_32x32x16_bf16 v[16:31], a[16:19], a[28:31], v[16:31]
	s_nop 0
	s_nop 0
	s_nop 0
	s_nop 0
	s_nop 0
	s_nop 0
	v_mfma_f32_32x32x16_bf16 v[0:15], a[20:23], a[28:31], v[0:15]
	s_nop 0
	s_nop 0
	s_nop 0
	v_add_u32_e32 v109, s3, v138
	v_add_u32_e32 v106, v109, v139
	ds_read_b128 a[16:19], v106
	v_add_u32_e32 v107, v109, v140
	ds_read_b128 a[20:23], v107
	v_add_u32_e32 v108, v141, v138
	ds_read_b128 a[24:27], v108
	v_add_u32_e32 v109, v109, v142
	ds_read_b128 a[28:31], v109
	s_waitcnt lgkmcnt(5)
	v_mfma_f32_32x32x16_bf16 v[48:63], a[0:3], a[8:11], v[48:63]
	v_mfma_f32_32x32x16_bf16 v[32:47], a[4:7], a[8:11], v[32:47]
	s_waitcnt lgkmcnt(4)
	v_mfma_f32_32x32x16_bf16 v[16:31], a[0:3], a[12:15], v[16:31]
	s_nop 0
	s_nop 0
	s_nop 0
	s_nop 0
	s_nop 0
	s_nop 0
	v_mfma_f32_32x32x16_bf16 v[0:15], a[4:7], a[12:15], v[0:15]
	s_nop 0
	s_nop 0
	s_nop 0
	s_waitcnt lgkmcnt(1)
	v_mfma_f32_32x32x16_bf16 v[48:63], a[16:19], a[24:27], v[48:63]
	v_mfma_f32_32x32x16_bf16 v[32:47], a[20:23], a[24:27], v[32:47]
	s_waitcnt vmcnt(6)
	s_waitcnt lgkmcnt(0)
	s_barrier
	ds_read_b128 a[12:15], v78 offset:4096
	ds_read_b128 a[8:11], v78
	ds_read_b128 a[4:7], v79 offset:36864
	ds_read_b128 a[0:3], v79 offset:32768
	v_mfma_f32_32x32x16_bf16 v[16:31], a[16:19], a[28:31], v[16:31]
	v_lshl_add_u64 v[128:129], v[66:67], 0, s[30:31]
	s_mov_b64 s[30:31], 0x2004280
	global_load_lds_dwordx4 v[128:129], off
	v_lshl_add_u64 v[128:129], v[68:69], 0, s[30:31]
	s_mov_b32 m0, s1
	s_mov_b64 s[30:31], 0x2008280
	global_load_lds_dwordx4 v[128:129], off
	v_lshl_add_u64 v[128:129], v[66:67], 0, s[30:31]
	s_mov_b32 m0, s2
	s_mov_b64 s[30:31], 0x200c280
	global_load_lds_dwordx4 v[128:129], off
	v_lshl_add_u64 v[128:129], v[68:69], 0, s[30:31]
	s_mov_b32 m0, s20
	s_mov_b64 s[30:31], 0x280
	global_load_lds_dwordx4 v[128:129], off
	v_lshl_add_u64 v[128:129], v[70:71], 0, s[30:31]
	s_mov_b32 m0, s21
	v_mfma_f32_32x32x16_bf16 v[0:15], a[20:23], a[28:31], v[0:15]
	global_load_lds_dwordx4 v[128:129], off
	v_lshl_add_u64 v[128:129], v[72:73], 0, s[30:31]
	s_mov_b32 m0, s22
	s_mov_b64 s[30:31], 0x2000300
	global_load_lds_dwordx4 v[128:129], off
	s_nop 0
	s_nop 0
	s_nop 0
	s_nop 0
	ds_read_b128 a[16:19], v81 offset:32768
	ds_read_b128 a[20:23], v81 offset:36864
	ds_read_b128 a[24:27], v80
	ds_read_b128 a[28:31], v80 offset:4096
	s_waitcnt lgkmcnt(4)
	v_mfma_f32_32x32x16_bf16 v[48:63], a[0:3], a[8:11], v[48:63]
	s_mov_b32 m0, s38
	v_readfirstlane_b32 s38, v113
	v_mfma_f32_32x32x16_bf16 v[32:47], a[4:7], a[8:11], v[32:47]
	v_mfma_f32_32x32x16_bf16 v[16:31], a[0:3], a[12:15], v[16:31]
	v_mfma_f32_32x32x16_bf16 v[0:15], a[4:7], a[12:15], v[0:15]
	s_nop 0
	s_nop 0
	s_nop 0
	s_nop 0
	ds_read_b128 a[0:3], v83 offset:32768
	ds_read_b128 a[4:7], v83 offset:36864
	ds_read_b128 a[8:11], v82
	ds_read_b128 a[12:15], v82 offset:4096
	s_waitcnt lgkmcnt(5)
	v_mfma_f32_32x32x16_bf16 v[48:63], a[16:19], a[24:27], v[48:63]
	v_mfma_f32_32x32x16_bf16 v[32:47], a[20:23], a[24:27], v[32:47]
	s_waitcnt lgkmcnt(4)
	v_mfma_f32_32x32x16_bf16 v[16:31], a[16:19], a[28:31], v[16:31]
	v_mfma_f32_32x32x16_bf16 v[0:15], a[20:23], a[28:31], v[0:15]
	s_nop 0
	s_nop 0
	s_nop 0
	s_nop 0
	ds_read_b128 a[16:19], v85 offset:32768
	ds_read_b128 a[20:23], v85 offset:36864
	ds_read_b128 a[24:27], v84
	ds_read_b128 a[28:31], v84 offset:4096
	s_waitcnt lgkmcnt(5)
	v_mfma_f32_32x32x16_bf16 v[48:63], a[0:3], a[8:11], v[48:63]
	v_mfma_f32_32x32x16_bf16 v[32:47], a[4:7], a[8:11], v[32:47]
	s_waitcnt lgkmcnt(4)
	v_mfma_f32_32x32x16_bf16 v[16:31], a[0:3], a[12:15], v[16:31]
	v_mfma_f32_32x32x16_bf16 v[0:15], a[4:7], a[12:15], v[0:15]
	s_nop 0
	s_nop 0
	s_nop 0
	s_nop 0
	s_waitcnt lgkmcnt(1)
	v_mfma_f32_32x32x16_bf16 v[48:63], a[16:19], a[24:27], v[48:63]
	v_mfma_f32_32x32x16_bf16 v[32:47], a[20:23], a[24:27], v[32:47]
	s_waitcnt vmcnt(6)
	s_waitcnt lgkmcnt(0)
	s_barrier
	ds_read_b128 a[12:15], v78 offset:53248
	ds_read_b128 a[8:11], v78 offset:49152
	ds_read_b128 a[4:7], v86
	ds_read_b128 a[0:3], v88
	v_mfma_f32_32x32x16_bf16 v[16:31], a[16:19], a[28:31], v[16:31]
	v_lshl_add_u64 v[128:129], v[66:67], 0, s[30:31]
	s_mov_b64 s[30:31], 0x2004300
	global_load_lds_dwordx4 v[128:129], off
	v_lshl_add_u64 v[128:129], v[68:69], 0, s[30:31]
	s_mov_b32 m0, s37
	s_mov_b64 s[30:31], 0x2008300
	global_load_lds_dwordx4 v[128:129], off
	v_lshl_add_u64 v[128:129], v[66:67], 0, s[30:31]
	s_mov_b32 m0, s36
	s_mov_b64 s[30:31], 0x200c300
	global_load_lds_dwordx4 v[128:129], off
	v_lshl_add_u64 v[128:129], v[68:69], 0, s[30:31]
	s_mov_b32 m0, s35
	s_mov_b64 s[30:31], 0x300
	global_load_lds_dwordx4 v[128:129], off
	v_lshl_add_u64 v[128:129], v[70:71], 0, s[30:31]
	s_mov_b32 m0, s39
	v_mfma_f32_32x32x16_bf16 v[0:15], a[20:23], a[28:31], v[0:15]
	global_load_lds_dwordx4 v[128:129], off
	v_lshl_add_u64 v[128:129], v[72:73], 0, s[30:31]
	s_mov_b32 m0, s40
	s_mov_b64 s[30:31], 0x2000380
	global_load_lds_dwordx4 v[128:129], off
	s_nop 0
	s_nop 0
	s_nop 0
	s_nop 0
	ds_read_b128 a[16:19], v89
	ds_read_b128 a[20:23], v87
	ds_read_b128 a[24:27], v80 offset:49152
	ds_read_b128 a[28:31], v80 offset:53248
	s_waitcnt lgkmcnt(4)
	v_mfma_f32_32x32x16_bf16 v[48:63], a[0:3], a[8:11], v[48:63]
	s_mov_b32 m0, s23
	v_readfirstlane_b32 s35, v110
	v_readfirstlane_b32 s36, v111
	v_readfirstlane_b32 s37, v112
	v_readfirstlane_b32 s39, v114
	v_readfirstlane_b32 s40, v115
	v_mfma_f32_32x32x16_bf16 v[32:47], a[4:7], a[8:11], v[32:47]
	v_mfma_f32_32x32x16_bf16 v[16:31], a[0:3], a[12:15], v[16:31]
	v_mfma_f32_32x32x16_bf16 v[0:15], a[4:7], a[12:15], v[0:15]
	s_nop 0
	s_nop 0
	s_nop 0
	s_nop 0
	ds_read_b128 a[0:3], v91
	ds_read_b128 a[4:7], v90
	ds_read_b128 a[8:11], v82 offset:49152
	ds_read_b128 a[12:15], v82 offset:53248
	s_waitcnt lgkmcnt(5)
	v_mfma_f32_32x32x16_bf16 v[48:63], a[16:19], a[24:27], v[48:63]
	v_mfma_f32_32x32x16_bf16 v[32:47], a[20:23], a[24:27], v[32:47]
	s_waitcnt lgkmcnt(4)
	v_mfma_f32_32x32x16_bf16 v[16:31], a[16:19], a[28:31], v[16:31]
	v_mfma_f32_32x32x16_bf16 v[0:15], a[20:23], a[28:31], v[0:15]
	s_nop 0
	s_nop 0
	s_nop 0
	s_nop 0
	ds_read_b128 a[16:19], v93
	ds_read_b128 a[20:23], v92
	ds_read_b128 a[24:27], v84 offset:49152
	ds_read_b128 a[28:31], v84 offset:53248
	s_waitcnt lgkmcnt(5)
	v_mfma_f32_32x32x16_bf16 v[48:63], a[0:3], a[8:11], v[48:63]
	v_mfma_f32_32x32x16_bf16 v[32:47], a[4:7], a[8:11], v[32:47]
	s_waitcnt lgkmcnt(4)
	v_mfma_f32_32x32x16_bf16 v[16:31], a[0:3], a[12:15], v[16:31]
	v_mfma_f32_32x32x16_bf16 v[0:15], a[4:7], a[12:15], v[0:15]
	s_nop 0
	s_nop 0
	s_nop 0
	s_nop 0
	s_waitcnt lgkmcnt(1)
	v_mfma_f32_32x32x16_bf16 v[48:63], a[16:19], a[24:27], v[48:63]
	v_mfma_f32_32x32x16_bf16 v[32:47], a[20:23], a[24:27], v[32:47]
	s_waitcnt vmcnt(6)
	s_waitcnt lgkmcnt(0)
	s_barrier
	ds_read_b128 a[12:15], v97
	ds_read_b128 a[8:11], v96
	ds_read_b128 a[4:7], v95
	ds_read_b128 a[0:3], v94
	v_mfma_f32_32x32x16_bf16 v[16:31], a[16:19], a[28:31], v[16:31]
	v_lshl_add_u64 v[128:129], v[66:67], 0, s[30:31]
	s_mov_b64 s[30:31], 0x2004380
	global_load_lds_dwordx4 v[128:129], off
	v_lshl_add_u64 v[128:129], v[68:69], 0, s[30:31]
	s_mov_b32 m0, s24
	s_mov_b64 s[30:31], 0x2008380
	global_load_lds_dwordx4 v[128:129], off
	v_lshl_add_u64 v[128:129], v[66:67], 0, s[30:31]
	s_mov_b32 m0, s28
	s_mov_b64 s[30:31], 0x200c380
	global_load_lds_dwordx4 v[128:129], off
	v_lshl_add_u64 v[128:129], v[68:69], 0, s[30:31]
	s_mov_b32 m0, s29
	s_mov_b64 s[28:29], 0x380
	global_load_lds_dwordx4 v[128:129], off
	v_lshl_add_u64 v[128:129], v[70:71], 0, s[28:29]
	s_mov_b32 m0, s33
	v_mfma_f32_32x32x16_bf16 v[0:15], a[20:23], a[28:31], v[0:15]
	global_load_lds_dwordx4 v[128:129], off
	v_lshl_add_u64 v[128:129], v[72:73], 0, s[28:29]
	s_mov_b32 m0, s34
	s_mov_b64 s[28:29], 0x2000400
	global_load_lds_dwordx4 v[128:129], off
	s_nop 0
	s_nop 0
	s_nop 0
	s_nop 0
	ds_read_b128 a[16:19], v98
	ds_read_b128 a[20:23], v99
	ds_read_b128 a[24:27], v100
	ds_read_b128 a[28:31], v101
	s_waitcnt lgkmcnt(4)
	v_mfma_f32_32x32x16_bf16 v[48:63], a[0:3], a[8:11], v[48:63]
	s_mov_b32 m0, s0
	v_readfirstlane_b32 s24, v117
	s_mov_b64 s[30:31], 0x200c500
	v_readfirstlane_b32 s33, v120
	v_readfirstlane_b32 s34, v121
	v_mfma_f32_32x32x16_bf16 v[32:47], a[4:7], a[8:11], v[32:47]
	v_mfma_f32_32x32x16_bf16 v[16:31], a[0:3], a[12:15], v[16:31]
	v_mfma_f32_32x32x16_bf16 v[0:15], a[4:7], a[12:15], v[0:15]
	s_nop 0
	s_nop 0
	s_nop 0
	s_nop 0
	ds_read_b128 a[0:3], v102
	ds_read_b128 a[4:7], v103
	ds_read_b128 a[8:11], v104
	ds_read_b128 a[12:15], v105
	s_waitcnt lgkmcnt(5)
	v_mfma_f32_32x32x16_bf16 v[48:63], a[16:19], a[24:27], v[48:63]
	v_mfma_f32_32x32x16_bf16 v[32:47], a[20:23], a[24:27], v[32:47]
	s_waitcnt lgkmcnt(4)
	v_mfma_f32_32x32x16_bf16 v[16:31], a[16:19], a[28:31], v[16:31]
	v_mfma_f32_32x32x16_bf16 v[0:15], a[20:23], a[28:31], v[0:15]
	s_nop 0
	s_nop 0
	s_nop 0
	s_nop 0
	ds_read_b128 a[16:19], v106
	ds_read_b128 a[20:23], v107
	ds_read_b128 a[24:27], v108
	ds_read_b128 a[28:31], v109
	s_waitcnt lgkmcnt(5)
	v_mfma_f32_32x32x16_bf16 v[48:63], a[0:3], a[8:11], v[48:63]
	v_mfma_f32_32x32x16_bf16 v[32:47], a[4:7], a[8:11], v[32:47]
	s_waitcnt lgkmcnt(4)
	v_mfma_f32_32x32x16_bf16 v[16:31], a[0:3], a[12:15], v[16:31]
	v_mfma_f32_32x32x16_bf16 v[0:15], a[4:7], a[12:15], v[0:15]
	s_nop 0
	s_nop 0
	s_nop 0
	s_nop 0
	s_waitcnt lgkmcnt(1)
	v_mfma_f32_32x32x16_bf16 v[48:63], a[16:19], a[24:27], v[48:63]
	v_mfma_f32_32x32x16_bf16 v[32:47], a[20:23], a[24:27], v[32:47]
	s_waitcnt vmcnt(6)
	s_waitcnt lgkmcnt(0)
	s_barrier
	ds_read_b128 a[12:15], v78 offset:4096
	ds_read_b128 a[8:11], v78
	ds_read_b128 a[4:7], v79 offset:36864
	ds_read_b128 a[0:3], v79 offset:32768
	v_mfma_f32_32x32x16_bf16 v[16:31], a[16:19], a[28:31], v[16:31]
	v_lshl_add_u64 v[128:129], v[66:67], 0, s[28:29]
	s_mov_b64 s[28:29], 0x2004400
	global_load_lds_dwordx4 v[128:129], off
	v_lshl_add_u64 v[128:129], v[68:69], 0, s[28:29]
	s_mov_b32 m0, s1
	s_mov_b64 s[0:1], 0x2008400
	global_load_lds_dwordx4 v[128:129], off
	v_lshl_add_u64 v[128:129], v[66:67], 0, s[0:1]
	s_mov_b32 m0, s2
	s_mov_b64 s[0:1], 0x200c400
	global_load_lds_dwordx4 v[128:129], off
	v_lshl_add_u64 v[128:129], v[68:69], 0, s[0:1]
	s_mov_b32 m0, s20
	s_mov_b64 s[0:1], 0x400
	global_load_lds_dwordx4 v[128:129], off
	v_lshl_add_u64 v[128:129], v[70:71], 0, s[0:1]
	s_mov_b32 m0, s21
	v_mfma_f32_32x32x16_bf16 v[0:15], a[20:23], a[28:31], v[0:15]
	global_load_lds_dwordx4 v[128:129], off
	v_lshl_add_u64 v[128:129], v[72:73], 0, s[0:1]
	s_mov_b32 m0, s22
	s_mov_b64 s[0:1], 0x2000480
	global_load_lds_dwordx4 v[128:129], off
	s_nop 0
	s_nop 0
	s_nop 0
	s_nop 0
	ds_read_b128 a[16:19], v81 offset:32768
	ds_read_b128 a[20:23], v81 offset:36864
	ds_read_b128 a[24:27], v80
	ds_read_b128 a[28:31], v80 offset:4096
	s_waitcnt lgkmcnt(4)
	v_mfma_f32_32x32x16_bf16 v[48:63], a[0:3], a[8:11], v[48:63]
	s_mov_b64 s[20:21], 0x2004480
	v_readfirstlane_b32 s2, v124
	s_mov_b64 s[22:23], 0x480
	s_mov_b64 s[28:29], 0x2000500
	v_mfma_f32_32x32x16_bf16 v[32:47], a[4:7], a[8:11], v[32:47]
	v_mfma_f32_32x32x16_bf16 v[16:31], a[0:3], a[12:15], v[16:31]
	v_mfma_f32_32x32x16_bf16 v[0:15], a[4:7], a[12:15], v[0:15]
	s_nop 0
	s_nop 0
	s_nop 0
	s_nop 0
	ds_read_b128 a[0:3], v83 offset:32768
	ds_read_b128 a[4:7], v83 offset:36864
	ds_read_b128 a[8:11], v82
	ds_read_b128 a[12:15], v82 offset:4096
	s_waitcnt lgkmcnt(5)
	v_mfma_f32_32x32x16_bf16 v[48:63], a[16:19], a[24:27], v[48:63]
	v_mfma_f32_32x32x16_bf16 v[32:47], a[20:23], a[24:27], v[32:47]
	s_waitcnt lgkmcnt(4)
	v_mfma_f32_32x32x16_bf16 v[16:31], a[16:19], a[28:31], v[16:31]
	v_mfma_f32_32x32x16_bf16 v[0:15], a[20:23], a[28:31], v[0:15]
	s_nop 0
	s_nop 0
	s_nop 0
	s_nop 0
	ds_read_b128 a[16:19], v85 offset:32768
	ds_read_b128 a[20:23], v85 offset:36864
	ds_read_b128 a[24:27], v84
	ds_read_b128 a[28:31], v84 offset:4096
	s_waitcnt lgkmcnt(5)
	v_mfma_f32_32x32x16_bf16 v[48:63], a[0:3], a[8:11], v[48:63]
	v_mfma_f32_32x32x16_bf16 v[32:47], a[4:7], a[8:11], v[32:47]
	s_waitcnt lgkmcnt(4)
	v_mfma_f32_32x32x16_bf16 v[16:31], a[0:3], a[12:15], v[16:31]
	v_mfma_f32_32x32x16_bf16 v[0:15], a[4:7], a[12:15], v[0:15]
	s_nop 0
	s_nop 0
	s_nop 0
	s_nop 0
	s_waitcnt lgkmcnt(1)
	v_mfma_f32_32x32x16_bf16 v[48:63], a[16:19], a[24:27], v[48:63]
	v_mfma_f32_32x32x16_bf16 v[32:47], a[20:23], a[24:27], v[32:47]
	s_waitcnt vmcnt(6)
	s_waitcnt lgkmcnt(0)
	s_barrier
	ds_read_b128 a[12:15], v78 offset:53248
	ds_read_b128 a[8:11], v78 offset:49152
	ds_read_b128 a[4:7], v86
	ds_read_b128 a[0:3], v88
	v_mfma_f32_32x32x16_bf16 v[16:31], a[16:19], a[28:31], v[16:31]
	v_lshl_add_u64 v[128:129], v[66:67], 0, s[0:1]
	v_readfirstlane_b32 s0, v127
	s_mov_b32 m0, s0
	v_readfirstlane_b32 s1, v126
	global_load_lds_dwordx4 v[128:129], off
	v_lshl_add_u64 v[128:129], v[68:69], 0, s[20:21]
	s_mov_b32 m0, s1
	s_mov_b64 s[20:21], 0x2008480
	global_load_lds_dwordx4 v[128:129], off
	v_lshl_add_u64 v[126:127], v[66:67], 0, s[20:21]
	s_mov_b32 m0, s2
	s_mov_b64 s[20:21], 0x200c480
	global_load_lds_dwordx4 v[126:127], off
	v_lshl_add_u64 v[126:127], v[68:69], 0, s[20:21]
	v_readfirstlane_b32 s20, v122
	s_mov_b32 m0, s20
	v_readfirstlane_b32 s21, v125
	global_load_lds_dwordx4 v[126:127], off
	v_lshl_add_u64 v[126:127], v[70:71], 0, s[22:23]
	s_mov_b32 m0, s21
	v_lshl_add_u64 v[124:125], v[72:73], 0, s[22:23]
	v_readfirstlane_b32 s22, v123
	global_load_lds_dwordx4 v[126:127], off
	s_mov_b32 m0, s22
	v_mfma_f32_32x32x16_bf16 v[0:15], a[20:23], a[28:31], v[0:15]
	global_load_lds_dwordx4 v[124:125], off
	s_nop 0
	s_nop 0
	s_nop 0
	v_readfirstlane_b32 s23, v116
	s_mov_b32 m0, s23
	s_nop 0
	ds_read_b128 a[16:19], v89
	ds_read_b128 a[20:23], v87
	ds_read_b128 a[24:27], v80 offset:49152
	ds_read_b128 a[28:31], v80 offset:53248
	s_waitcnt lgkmcnt(4)
	v_mfma_f32_32x32x16_bf16 v[48:63], a[0:3], a[8:11], v[48:63]
	v_mfma_f32_32x32x16_bf16 v[32:47], a[4:7], a[8:11], v[32:47]
	v_mfma_f32_32x32x16_bf16 v[16:31], a[0:3], a[12:15], v[16:31]
	v_mfma_f32_32x32x16_bf16 v[0:15], a[4:7], a[12:15], v[0:15]
	s_nop 0
	s_nop 0
	s_nop 0
	s_nop 0
	ds_read_b128 a[0:3], v91
	ds_read_b128 a[4:7], v90
	ds_read_b128 a[8:11], v82 offset:49152
	ds_read_b128 a[12:15], v82 offset:53248
	s_waitcnt lgkmcnt(5)
	v_mfma_f32_32x32x16_bf16 v[48:63], a[16:19], a[24:27], v[48:63]
	v_mfma_f32_32x32x16_bf16 v[32:47], a[20:23], a[24:27], v[32:47]
	s_waitcnt lgkmcnt(4)
	v_mfma_f32_32x32x16_bf16 v[16:31], a[16:19], a[28:31], v[16:31]
	v_mfma_f32_32x32x16_bf16 v[0:15], a[20:23], a[28:31], v[0:15]
	s_nop 0
	s_nop 0
	s_nop 0
	s_nop 0
	ds_read_b128 a[16:19], v93
	ds_read_b128 a[20:23], v92
	ds_read_b128 a[24:27], v84 offset:49152
	ds_read_b128 a[28:31], v84 offset:53248
	s_waitcnt lgkmcnt(5)
	v_mfma_f32_32x32x16_bf16 v[48:63], a[0:3], a[8:11], v[48:63]
	v_mfma_f32_32x32x16_bf16 v[32:47], a[4:7], a[8:11], v[32:47]
	s_waitcnt lgkmcnt(4)
	v_mfma_f32_32x32x16_bf16 v[16:31], a[0:3], a[12:15], v[16:31]
	v_mfma_f32_32x32x16_bf16 v[0:15], a[4:7], a[12:15], v[0:15]
	s_nop 0
	s_nop 0
	s_nop 0
	s_nop 0
	s_waitcnt lgkmcnt(1)
	v_mfma_f32_32x32x16_bf16 v[48:63], a[16:19], a[24:27], v[48:63]
	v_mfma_f32_32x32x16_bf16 v[32:47], a[20:23], a[24:27], v[32:47]
	s_waitcnt vmcnt(6)
	s_waitcnt lgkmcnt(0)
	s_barrier
	ds_read_b128 a[12:15], v97
	ds_read_b128 a[8:11], v96
	ds_read_b128 a[4:7], v95
	ds_read_b128 a[0:3], v94
	v_mfma_f32_32x32x16_bf16 v[16:31], a[16:19], a[28:31], v[16:31]
	v_lshl_add_u64 v[122:123], v[66:67], 0, s[28:29]
	s_mov_b64 s[28:29], 0x2004500
	global_load_lds_dwordx4 v[122:123], off
	v_lshl_add_u64 v[122:123], v[68:69], 0, s[28:29]
	s_mov_b64 s[28:29], 0x2008500
	s_mov_b32 m0, s24
	v_lshl_add_u64 v[116:117], v[66:67], 0, s[28:29]
	v_readfirstlane_b32 s28, v118
	global_load_lds_dwordx4 v[122:123], off
	s_mov_b32 m0, s28
	v_readfirstlane_b32 s29, v119
	global_load_lds_dwordx4 v[116:117], off
	v_lshl_add_u64 v[116:117], v[68:69], 0, s[30:31]
	s_mov_b32 m0, s29
	s_mov_b64 s[30:31], 0x500
	global_load_lds_dwordx4 v[116:117], off
	v_lshl_add_u64 v[116:117], v[70:71], 0, s[30:31]
	s_mov_b32 m0, s33
	v_mfma_f32_32x32x16_bf16 v[0:15], a[20:23], a[28:31], v[0:15]
	global_load_lds_dwordx4 v[116:117], off
	v_lshl_add_u64 v[116:117], v[72:73], 0, s[30:31]
	s_mov_b32 m0, s34
	s_mov_b64 s[30:31], 0x2000580
	global_load_lds_dwordx4 v[116:117], off
	s_nop 0
	s_nop 0
	s_nop 0
	s_nop 0
	ds_read_b128 a[16:19], v98
	ds_read_b128 a[20:23], v99
	ds_read_b128 a[24:27], v100
	ds_read_b128 a[28:31], v101
	s_waitcnt lgkmcnt(4)
	v_mfma_f32_32x32x16_bf16 v[48:63], a[0:3], a[8:11], v[48:63]
	s_mov_b32 m0, s35
	v_mfma_f32_32x32x16_bf16 v[32:47], a[4:7], a[8:11], v[32:47]
	v_mfma_f32_32x32x16_bf16 v[16:31], a[0:3], a[12:15], v[16:31]
	v_mfma_f32_32x32x16_bf16 v[0:15], a[4:7], a[12:15], v[0:15]
	s_nop 0
	s_nop 0
	s_nop 0
	s_nop 0
	ds_read_b128 a[0:3], v102
	ds_read_b128 a[4:7], v103
	ds_read_b128 a[8:11], v104
	ds_read_b128 a[12:15], v105
	s_waitcnt lgkmcnt(5)
	v_mfma_f32_32x32x16_bf16 v[48:63], a[16:19], a[24:27], v[48:63]
	v_mfma_f32_32x32x16_bf16 v[32:47], a[20:23], a[24:27], v[32:47]
	s_waitcnt lgkmcnt(4)
	v_mfma_f32_32x32x16_bf16 v[16:31], a[16:19], a[28:31], v[16:31]
	v_mfma_f32_32x32x16_bf16 v[0:15], a[20:23], a[28:31], v[0:15]
	s_nop 0
	s_nop 0
	s_nop 0
	s_nop 0
	ds_read_b128 a[16:19], v106
	ds_read_b128 a[20:23], v107
	ds_read_b128 a[24:27], v108
	ds_read_b128 a[28:31], v109
	s_waitcnt lgkmcnt(5)
	v_mfma_f32_32x32x16_bf16 v[48:63], a[0:3], a[8:11], v[48:63]
	v_mfma_f32_32x32x16_bf16 v[32:47], a[4:7], a[8:11], v[32:47]
	s_waitcnt lgkmcnt(4)
	v_mfma_f32_32x32x16_bf16 v[16:31], a[0:3], a[12:15], v[16:31]
	v_mfma_f32_32x32x16_bf16 v[0:15], a[4:7], a[12:15], v[0:15]
	s_nop 0
	s_nop 0
	s_nop 0
	s_nop 0
	s_waitcnt lgkmcnt(1)
	v_mfma_f32_32x32x16_bf16 v[48:63], a[16:19], a[24:27], v[48:63]
	v_mfma_f32_32x32x16_bf16 v[32:47], a[20:23], a[24:27], v[32:47]
	s_waitcnt vmcnt(6)
	s_waitcnt lgkmcnt(0)
	s_barrier
	ds_read_b128 a[12:15], v78 offset:4096
	ds_read_b128 a[8:11], v78
	ds_read_b128 a[4:7], v79 offset:36864
	ds_read_b128 a[0:3], v79 offset:32768
	v_mfma_f32_32x32x16_bf16 v[16:31], a[16:19], a[28:31], v[16:31]
	v_lshl_add_u64 v[116:117], v[66:67], 0, s[30:31]
	s_mov_b64 s[30:31], 0x2004580
	global_load_lds_dwordx4 v[116:117], off
	v_lshl_add_u64 v[116:117], v[68:69], 0, s[30:31]
	s_mov_b32 m0, s36
	s_mov_b64 s[30:31], 0x2008580
	global_load_lds_dwordx4 v[116:117], off
	v_lshl_add_u64 v[110:111], v[66:67], 0, s[30:31]
	s_mov_b32 m0, s37
	s_mov_b64 s[30:31], 0x200c580
	global_load_lds_dwordx4 v[110:111], off
	v_lshl_add_u64 v[110:111], v[68:69], 0, s[30:31]
	s_mov_b32 m0, s38
	s_mov_b64 s[30:31], 0x580
	global_load_lds_dwordx4 v[110:111], off
	v_lshl_add_u64 v[110:111], v[70:71], 0, s[30:31]
	s_mov_b32 m0, s39
	v_mfma_f32_32x32x16_bf16 v[0:15], a[20:23], a[28:31], v[0:15]
	global_load_lds_dwordx4 v[110:111], off
	v_lshl_add_u64 v[110:111], v[72:73], 0, s[30:31]
	s_mov_b32 m0, s40
	s_mov_b64 s[30:31], 0x2000600
	global_load_lds_dwordx4 v[110:111], off
	s_nop 0
	s_nop 0
	s_nop 0
	s_nop 0
	ds_read_b128 a[16:19], v81 offset:32768
	ds_read_b128 a[20:23], v81 offset:36864
	ds_read_b128 a[24:27], v80
	ds_read_b128 a[28:31], v80 offset:4096
	s_waitcnt lgkmcnt(4)
	v_mfma_f32_32x32x16_bf16 v[48:63], a[0:3], a[8:11], v[48:63]
	s_mov_b32 m0, s0
	v_mfma_f32_32x32x16_bf16 v[32:47], a[4:7], a[8:11], v[32:47]
	v_mfma_f32_32x32x16_bf16 v[16:31], a[0:3], a[12:15], v[16:31]
	v_mfma_f32_32x32x16_bf16 v[0:15], a[4:7], a[12:15], v[0:15]
	s_nop 0
	s_nop 0
	s_nop 0
	s_nop 0
	ds_read_b128 a[0:3], v83 offset:32768
	ds_read_b128 a[4:7], v83 offset:36864
	ds_read_b128 a[8:11], v82
	ds_read_b128 a[12:15], v82 offset:4096
	s_waitcnt lgkmcnt(5)
	v_mfma_f32_32x32x16_bf16 v[48:63], a[16:19], a[24:27], v[48:63]
	v_mfma_f32_32x32x16_bf16 v[32:47], a[20:23], a[24:27], v[32:47]
	s_waitcnt lgkmcnt(4)
	v_mfma_f32_32x32x16_bf16 v[16:31], a[16:19], a[28:31], v[16:31]
	v_mfma_f32_32x32x16_bf16 v[0:15], a[20:23], a[28:31], v[0:15]
	s_nop 0
	s_nop 0
	s_nop 0
	s_nop 0
	ds_read_b128 a[16:19], v85 offset:32768
	ds_read_b128 a[20:23], v85 offset:36864
	ds_read_b128 a[24:27], v84
	ds_read_b128 a[28:31], v84 offset:4096
	s_waitcnt lgkmcnt(5)
	v_mfma_f32_32x32x16_bf16 v[48:63], a[0:3], a[8:11], v[48:63]
	v_mfma_f32_32x32x16_bf16 v[32:47], a[4:7], a[8:11], v[32:47]
	s_waitcnt lgkmcnt(4)
	v_mfma_f32_32x32x16_bf16 v[16:31], a[0:3], a[12:15], v[16:31]
	v_mfma_f32_32x32x16_bf16 v[0:15], a[4:7], a[12:15], v[0:15]
	s_nop 0
	s_nop 0
	s_nop 0
	s_nop 0
	s_waitcnt lgkmcnt(1)
	v_mfma_f32_32x32x16_bf16 v[48:63], a[16:19], a[24:27], v[48:63]
	v_mfma_f32_32x32x16_bf16 v[32:47], a[20:23], a[24:27], v[32:47]
	s_waitcnt vmcnt(6)
	s_waitcnt lgkmcnt(0)
	s_barrier
	ds_read_b128 a[12:15], v78 offset:53248
	ds_read_b128 a[8:11], v78 offset:49152
	ds_read_b128 a[4:7], v86
	ds_read_b128 a[0:3], v88
	v_mfma_f32_32x32x16_bf16 v[16:31], a[16:19], a[28:31], v[16:31]
	v_lshl_add_u64 v[110:111], v[66:67], 0, s[30:31]
	s_mov_b64 s[30:31], 0x2004600
	global_load_lds_dwordx4 v[110:111], off
	v_lshl_add_u64 v[110:111], v[68:69], 0, s[30:31]
	s_mov_b32 m0, s1
	s_mov_b64 s[30:31], 0x2008600
	global_load_lds_dwordx4 v[110:111], off
	v_lshl_add_u64 v[110:111], v[66:67], 0, s[30:31]
	s_mov_b32 m0, s2
	s_mov_b64 s[30:31], 0x200c600
	global_load_lds_dwordx4 v[110:111], off
	v_lshl_add_u64 v[110:111], v[68:69], 0, s[30:31]
	s_mov_b32 m0, s20
	s_mov_b64 s[30:31], 0x600
	global_load_lds_dwordx4 v[110:111], off
	v_lshl_add_u64 v[110:111], v[70:71], 0, s[30:31]
	s_mov_b32 m0, s21
	v_mfma_f32_32x32x16_bf16 v[0:15], a[20:23], a[28:31], v[0:15]
	global_load_lds_dwordx4 v[110:111], off
	v_lshl_add_u64 v[110:111], v[72:73], 0, s[30:31]
	s_mov_b32 m0, s22
	s_mov_b64 s[30:31], 0x2000680
	global_load_lds_dwordx4 v[110:111], off
	s_nop 0
	s_nop 0
	s_nop 0
	s_nop 0
	ds_read_b128 a[16:19], v89
	ds_read_b128 a[20:23], v87
	ds_read_b128 a[24:27], v80 offset:49152
	ds_read_b128 a[28:31], v80 offset:53248
	s_waitcnt lgkmcnt(4)
	v_mfma_f32_32x32x16_bf16 v[48:63], a[0:3], a[8:11], v[48:63]
	s_mov_b32 m0, s23
	v_mfma_f32_32x32x16_bf16 v[32:47], a[4:7], a[8:11], v[32:47]
	v_mfma_f32_32x32x16_bf16 v[16:31], a[0:3], a[12:15], v[16:31]
	v_mfma_f32_32x32x16_bf16 v[0:15], a[4:7], a[12:15], v[0:15]
	s_nop 0
	s_nop 0
	s_nop 0
	s_nop 0
	ds_read_b128 a[0:3], v91
	ds_read_b128 a[4:7], v90
	ds_read_b128 a[8:11], v82 offset:49152
	ds_read_b128 a[12:15], v82 offset:53248
	s_waitcnt lgkmcnt(5)
	v_mfma_f32_32x32x16_bf16 v[48:63], a[16:19], a[24:27], v[48:63]
	v_mfma_f32_32x32x16_bf16 v[32:47], a[20:23], a[24:27], v[32:47]
	s_waitcnt lgkmcnt(4)
	v_mfma_f32_32x32x16_bf16 v[16:31], a[16:19], a[28:31], v[16:31]
	v_mfma_f32_32x32x16_bf16 v[0:15], a[20:23], a[28:31], v[0:15]
	s_nop 0
	s_nop 0
	s_nop 0
	s_nop 0
	ds_read_b128 a[16:19], v93
	ds_read_b128 a[20:23], v92
	ds_read_b128 a[24:27], v84 offset:49152
	ds_read_b128 a[28:31], v84 offset:53248
	s_waitcnt lgkmcnt(5)
	v_mfma_f32_32x32x16_bf16 v[48:63], a[0:3], a[8:11], v[48:63]
	v_mfma_f32_32x32x16_bf16 v[32:47], a[4:7], a[8:11], v[32:47]
	s_waitcnt lgkmcnt(4)
	v_mfma_f32_32x32x16_bf16 v[16:31], a[0:3], a[12:15], v[16:31]
	v_mfma_f32_32x32x16_bf16 v[0:15], a[4:7], a[12:15], v[0:15]
	s_nop 0
	s_nop 0
	s_nop 0
	s_nop 0
	s_waitcnt lgkmcnt(1)
	v_mfma_f32_32x32x16_bf16 v[48:63], a[16:19], a[24:27], v[48:63]
	v_mfma_f32_32x32x16_bf16 v[32:47], a[20:23], a[24:27], v[32:47]
	s_waitcnt vmcnt(6)
	s_waitcnt lgkmcnt(0)
	s_barrier
	ds_read_b128 a[12:15], v97
	ds_read_b128 a[8:11], v96
	ds_read_b128 a[4:7], v95
	ds_read_b128 a[0:3], v94
	v_mfma_f32_32x32x16_bf16 v[16:31], a[16:19], a[28:31], v[16:31]
	v_lshl_add_u64 v[110:111], v[66:67], 0, s[30:31]
	s_mov_b64 s[30:31], 0x2004680
	global_load_lds_dwordx4 v[110:111], off
	v_lshl_add_u64 v[110:111], v[68:69], 0, s[30:31]
	s_mov_b32 m0, s24
	s_mov_b64 s[30:31], 0x2008680
	global_load_lds_dwordx4 v[110:111], off
	v_lshl_add_u64 v[110:111], v[66:67], 0, s[30:31]
	s_mov_b32 m0, s28
	s_mov_b64 s[30:31], 0x200c680
	global_load_lds_dwordx4 v[110:111], off
	v_lshl_add_u64 v[110:111], v[68:69], 0, s[30:31]
	s_mov_b32 m0, s29
	s_mov_b64 s[28:29], 0x680
	global_load_lds_dwordx4 v[110:111], off
	v_lshl_add_u64 v[110:111], v[70:71], 0, s[28:29]
	s_mov_b32 m0, s33
	v_mfma_f32_32x32x16_bf16 v[0:15], a[20:23], a[28:31], v[0:15]
	global_load_lds_dwordx4 v[110:111], off
	v_lshl_add_u64 v[110:111], v[72:73], 0, s[28:29]
	s_mov_b32 m0, s34
	s_mov_b64 s[28:29], 0x2000700
	global_load_lds_dwordx4 v[110:111], off
	s_nop 0
	s_nop 0
	s_nop 0
	s_nop 0
	ds_read_b128 a[16:19], v98
	ds_read_b128 a[20:23], v99
	ds_read_b128 a[24:27], v100
	ds_read_b128 a[28:31], v101
	s_waitcnt lgkmcnt(4)
	v_mfma_f32_32x32x16_bf16 v[48:63], a[0:3], a[8:11], v[48:63]
	s_mov_b32 m0, s35
	v_mfma_f32_32x32x16_bf16 v[32:47], a[4:7], a[8:11], v[32:47]
	v_mfma_f32_32x32x16_bf16 v[16:31], a[0:3], a[12:15], v[16:31]
	v_mfma_f32_32x32x16_bf16 v[0:15], a[4:7], a[12:15], v[0:15]
	s_nop 0
	s_nop 0
	s_nop 0
	s_nop 0
	ds_read_b128 a[0:3], v102
	ds_read_b128 a[4:7], v103
	ds_read_b128 a[8:11], v104
	ds_read_b128 a[12:15], v105
	s_waitcnt lgkmcnt(5)
	v_mfma_f32_32x32x16_bf16 v[48:63], a[16:19], a[24:27], v[48:63]
	v_mfma_f32_32x32x16_bf16 v[32:47], a[20:23], a[24:27], v[32:47]
	s_waitcnt lgkmcnt(4)
	v_mfma_f32_32x32x16_bf16 v[16:31], a[16:19], a[28:31], v[16:31]
	v_mfma_f32_32x32x16_bf16 v[0:15], a[20:23], a[28:31], v[0:15]
	s_nop 0
	s_nop 0
	s_nop 0
	s_nop 0
	ds_read_b128 a[16:19], v106
	ds_read_b128 a[20:23], v107
	ds_read_b128 a[24:27], v108
	ds_read_b128 a[28:31], v109
	s_waitcnt lgkmcnt(5)
	v_mfma_f32_32x32x16_bf16 v[48:63], a[0:3], a[8:11], v[48:63]
	v_mfma_f32_32x32x16_bf16 v[32:47], a[4:7], a[8:11], v[32:47]
	s_waitcnt lgkmcnt(4)
	v_mfma_f32_32x32x16_bf16 v[16:31], a[0:3], a[12:15], v[16:31]
	v_mfma_f32_32x32x16_bf16 v[0:15], a[4:7], a[12:15], v[0:15]
	s_nop 0
	s_nop 0
	s_nop 0
	s_nop 0
	s_waitcnt lgkmcnt(1)
	v_mfma_f32_32x32x16_bf16 v[48:63], a[16:19], a[24:27], v[48:63]
	v_mfma_f32_32x32x16_bf16 v[32:47], a[20:23], a[24:27], v[32:47]
	s_waitcnt vmcnt(6)
	s_waitcnt lgkmcnt(0)
	s_barrier
	ds_read_b128 a[12:15], v78 offset:4096
	ds_read_b128 a[8:11], v78
	ds_read_b128 a[4:7], v79 offset:36864
	ds_read_b128 a[0:3], v79 offset:32768
	v_mfma_f32_32x32x16_bf16 v[16:31], a[16:19], a[28:31], v[16:31]
	v_lshl_add_u64 v[110:111], v[66:67], 0, s[28:29]
	s_mov_b64 s[28:29], 0x2004700
	global_load_lds_dwordx4 v[110:111], off
	v_lshl_add_u64 v[110:111], v[68:69], 0, s[28:29]
	s_mov_b32 m0, s36
	s_mov_b64 s[28:29], 0x2008700
	global_load_lds_dwordx4 v[110:111], off
	v_lshl_add_u64 v[110:111], v[66:67], 0, s[28:29]
	s_mov_b32 m0, s37
	s_mov_b64 s[28:29], 0x200c700
	global_load_lds_dwordx4 v[110:111], off
	v_lshl_add_u64 v[110:111], v[68:69], 0, s[28:29]
	s_mov_b32 m0, s38
	s_mov_b64 s[28:29], 0x700
	global_load_lds_dwordx4 v[110:111], off
	v_lshl_add_u64 v[110:111], v[70:71], 0, s[28:29]
	s_mov_b32 m0, s39
	v_mfma_f32_32x32x16_bf16 v[0:15], a[20:23], a[28:31], v[0:15]
	global_load_lds_dwordx4 v[110:111], off
	v_lshl_add_u64 v[110:111], v[72:73], 0, s[28:29]
	s_mov_b32 m0, s40
	s_mov_b64 s[28:29], 0x2000780
	global_load_lds_dwordx4 v[110:111], off
	s_nop 0
	s_nop 0
	s_nop 0
	s_nop 0
	ds_read_b128 a[16:19], v81 offset:32768
	ds_read_b128 a[20:23], v81 offset:36864
	ds_read_b128 a[24:27], v80
	ds_read_b128 a[28:31], v80 offset:4096
	s_waitcnt lgkmcnt(4)
	v_mfma_f32_32x32x16_bf16 v[48:63], a[0:3], a[8:11], v[48:63]
	s_mov_b32 m0, s0
	v_mfma_f32_32x32x16_bf16 v[32:47], a[4:7], a[8:11], v[32:47]
	v_mfma_f32_32x32x16_bf16 v[16:31], a[0:3], a[12:15], v[16:31]
	v_mfma_f32_32x32x16_bf16 v[0:15], a[4:7], a[12:15], v[0:15]
	s_nop 0
	s_nop 0
	s_nop 0
	s_nop 0
	ds_read_b128 a[0:3], v83 offset:32768
	ds_read_b128 a[4:7], v83 offset:36864
	ds_read_b128 a[8:11], v82
	ds_read_b128 a[12:15], v82 offset:4096
	s_waitcnt lgkmcnt(5)
	v_mfma_f32_32x32x16_bf16 v[48:63], a[16:19], a[24:27], v[48:63]
	v_mfma_f32_32x32x16_bf16 v[32:47], a[20:23], a[24:27], v[32:47]
	s_waitcnt lgkmcnt(4)
	v_mfma_f32_32x32x16_bf16 v[16:31], a[16:19], a[28:31], v[16:31]
	v_mfma_f32_32x32x16_bf16 v[0:15], a[20:23], a[28:31], v[0:15]
	s_nop 0
	s_nop 0
	s_nop 0
	s_nop 0
	ds_read_b128 a[16:19], v85 offset:32768
	ds_read_b128 a[20:23], v85 offset:36864
	ds_read_b128 a[24:27], v84
	ds_read_b128 a[28:31], v84 offset:4096
	s_waitcnt lgkmcnt(5)
	v_mfma_f32_32x32x16_bf16 v[48:63], a[0:3], a[8:11], v[48:63]
	v_mfma_f32_32x32x16_bf16 v[32:47], a[4:7], a[8:11], v[32:47]
	s_waitcnt lgkmcnt(4)
	v_mfma_f32_32x32x16_bf16 v[16:31], a[0:3], a[12:15], v[16:31]
	v_mfma_f32_32x32x16_bf16 v[0:15], a[4:7], a[12:15], v[0:15]
	s_nop 0
	s_nop 0
	s_nop 0
	s_nop 0
	s_waitcnt lgkmcnt(1)
	v_mfma_f32_32x32x16_bf16 v[48:63], a[16:19], a[24:27], v[48:63]
	v_mfma_f32_32x32x16_bf16 v[32:47], a[20:23], a[24:27], v[32:47]
	s_waitcnt vmcnt(6)
	s_waitcnt lgkmcnt(0)
	s_barrier
	ds_read_b128 a[12:15], v78 offset:53248
	ds_read_b128 a[8:11], v78 offset:49152
	ds_read_b128 a[4:7], v86
	ds_read_b128 a[0:3], v88
	v_mfma_f32_32x32x16_bf16 v[16:31], a[16:19], a[28:31], v[16:31]
	v_lshl_add_u64 v[110:111], v[66:67], 0, s[28:29]
	s_mov_b64 s[28:29], 0x2004780
	global_load_lds_dwordx4 v[110:111], off
	v_lshl_add_u64 v[110:111], v[68:69], 0, s[28:29]
	s_mov_b32 m0, s1
	s_mov_b64 s[0:1], 0x2008780
	global_load_lds_dwordx4 v[110:111], off
	v_lshl_add_u64 v[66:67], v[66:67], 0, s[0:1]
	s_mov_b32 m0, s2
	s_mov_b64 s[0:1], 0x200c780
	global_load_lds_dwordx4 v[66:67], off
	v_lshl_add_u64 v[66:67], v[68:69], 0, s[0:1]
	s_mov_b32 m0, s20
	s_mov_b64 s[0:1], 0x780
	global_load_lds_dwordx4 v[66:67], off
	v_lshl_add_u64 v[66:67], v[70:71], 0, s[0:1]
	s_mov_b32 m0, s21
	v_mfma_f32_32x32x16_bf16 v[0:15], a[20:23], a[28:31], v[0:15]
	global_load_lds_dwordx4 v[66:67], off
	v_lshl_add_u64 v[66:67], v[72:73], 0, s[0:1]
	s_mov_b32 m0, s22
	v_readlane_b32 s0, v215, 52
	global_load_lds_dwordx4 v[66:67], off
	s_nop 0
	s_nop 0
	s_nop 0
	s_nop 0
	ds_read_b128 a[16:19], v89
	ds_read_b128 a[20:23], v87
	ds_read_b128 a[24:27], v80 offset:49152
	ds_read_b128 a[28:31], v80 offset:53248
	s_waitcnt lgkmcnt(4)
	v_mfma_f32_32x32x16_bf16 v[48:63], a[0:3], a[8:11], v[48:63]
	v_readlane_b32 s1, v215, 53
	s_mov_b32 s2, 0
	v_mfma_f32_32x32x16_bf16 v[32:47], a[4:7], a[8:11], v[32:47]
	v_mfma_f32_32x32x16_bf16 v[16:31], a[0:3], a[12:15], v[16:31]
	v_mfma_f32_32x32x16_bf16 v[0:15], a[4:7], a[12:15], v[0:15]
	s_nop 0
	s_nop 0
	s_nop 0
	s_nop 0
	ds_read_b128 a[0:3], v91
	ds_read_b128 a[4:7], v90
	ds_read_b128 a[8:11], v82 offset:49152
	ds_read_b128 a[12:15], v82 offset:53248
	s_waitcnt lgkmcnt(5)
	v_mfma_f32_32x32x16_bf16 v[48:63], a[16:19], a[24:27], v[48:63]
	v_mfma_f32_32x32x16_bf16 v[32:47], a[20:23], a[24:27], v[32:47]
	s_waitcnt lgkmcnt(4)
	v_mfma_f32_32x32x16_bf16 v[16:31], a[16:19], a[28:31], v[16:31]
	v_mfma_f32_32x32x16_bf16 v[0:15], a[20:23], a[28:31], v[0:15]
	s_nop 0
	s_nop 0
	s_nop 0
	s_nop 0
	ds_read_b128 a[16:19], v93
	ds_read_b128 a[20:23], v92
	ds_read_b128 a[24:27], v84 offset:49152
	ds_read_b128 a[28:31], v84 offset:53248
	s_waitcnt lgkmcnt(5)
	v_mfma_f32_32x32x16_bf16 v[48:63], a[0:3], a[8:11], v[48:63]
	v_mfma_f32_32x32x16_bf16 v[32:47], a[4:7], a[8:11], v[32:47]
	s_waitcnt lgkmcnt(4)
	v_mfma_f32_32x32x16_bf16 v[16:31], a[0:3], a[12:15], v[16:31]
	v_mfma_f32_32x32x16_bf16 v[0:15], a[4:7], a[12:15], v[0:15]
	s_nop 0
	s_nop 0
	s_nop 0
	s_nop 0
	s_waitcnt lgkmcnt(1)
	v_mfma_f32_32x32x16_bf16 v[48:63], a[16:19], a[24:27], v[48:63]
	v_mfma_f32_32x32x16_bf16 v[32:47], a[20:23], a[24:27], v[32:47]
	s_waitcnt vmcnt(6)
	s_waitcnt lgkmcnt(0)
	s_barrier
	ds_read_b128 a[12:15], v97
	ds_read_b128 a[8:11], v96
	ds_read_b128 a[4:7], v95
	ds_read_b128 a[0:3], v94
	v_mfma_f32_32x32x16_bf16 v[16:31], a[16:19], a[28:31], v[16:31]
	v_mfma_f32_32x32x16_bf16 v[0:15], a[20:23], a[28:31], v[0:15]
	s_nop 0
	s_nop 0
	s_nop 0
	s_nop 0
	ds_read_b128 a[16:19], v98
	ds_read_b128 a[20:23], v99
	ds_read_b128 a[24:27], v100
	ds_read_b128 a[28:31], v101
	s_waitcnt lgkmcnt(4)
	v_mfma_f32_32x32x16_bf16 v[48:63], a[0:3], a[8:11], v[48:63]
	v_mfma_f32_32x32x16_bf16 v[32:47], a[4:7], a[8:11], v[32:47]
	v_mfma_f32_32x32x16_bf16 v[16:31], a[0:3], a[12:15], v[16:31]
	v_mfma_f32_32x32x16_bf16 v[0:15], a[4:7], a[12:15], v[0:15]
	s_nop 0
	s_nop 0
	s_nop 0
	s_nop 0
	ds_read_b128 a[0:3], v102
	ds_read_b128 a[4:7], v103
	ds_read_b128 a[8:11], v104
	ds_read_b128 a[12:15], v105
	s_waitcnt lgkmcnt(5)
	v_mfma_f32_32x32x16_bf16 v[48:63], a[16:19], a[24:27], v[48:63]
	v_mfma_f32_32x32x16_bf16 v[32:47], a[20:23], a[24:27], v[32:47]
	s_waitcnt lgkmcnt(4)
	v_mfma_f32_32x32x16_bf16 v[16:31], a[16:19], a[28:31], v[16:31]
	v_mfma_f32_32x32x16_bf16 v[0:15], a[20:23], a[28:31], v[0:15]
	s_nop 0
	s_nop 0
	s_nop 0
	s_nop 0
	ds_read_b128 a[16:19], v106
	ds_read_b128 a[20:23], v107
	ds_read_b128 a[24:27], v108
	ds_read_b128 a[28:31], v109
	s_waitcnt lgkmcnt(5)
	v_mfma_f32_32x32x16_bf16 v[48:63], a[0:3], a[8:11], v[48:63]
	v_mfma_f32_32x32x16_bf16 v[32:47], a[4:7], a[8:11], v[32:47]
	s_waitcnt lgkmcnt(4)
	v_mfma_f32_32x32x16_bf16 v[16:31], a[0:3], a[12:15], v[16:31]
	v_mfma_f32_32x32x16_bf16 v[0:15], a[4:7], a[12:15], v[0:15]
	s_nop 0
	s_nop 0
	s_nop 0
	s_nop 0
	s_waitcnt lgkmcnt(1)
	v_mfma_f32_32x32x16_bf16 v[48:63], a[16:19], a[24:27], v[48:63]
	v_mfma_f32_32x32x16_bf16 v[32:47], a[20:23], a[24:27], v[32:47]
	s_waitcnt vmcnt(0)
	s_waitcnt lgkmcnt(0)
	s_barrier
	ds_read_b128 a[12:15], v78 offset:4096
	ds_read_b128 a[8:11], v78
	ds_read_b128 a[4:7], v79 offset:36864
	ds_read_b128 a[0:3], v79 offset:32768
	v_mfma_f32_32x32x16_bf16 v[16:31], a[16:19], a[28:31], v[16:31]
	v_mfma_f32_32x32x16_bf16 v[0:15], a[20:23], a[28:31], v[0:15]
	s_nop 0
	s_nop 0
	s_nop 0
	s_nop 0
	ds_read_b128 a[16:19], v81 offset:32768
	ds_read_b128 a[20:23], v81 offset:36864
	ds_read_b128 a[24:27], v80
	ds_read_b128 a[28:31], v80 offset:4096
	s_waitcnt lgkmcnt(4)
	v_mfma_f32_32x32x16_bf16 v[48:63], a[0:3], a[8:11], v[48:63]
	v_mfma_f32_32x32x16_bf16 v[32:47], a[4:7], a[8:11], v[32:47]
	v_mfma_f32_32x32x16_bf16 v[16:31], a[0:3], a[12:15], v[16:31]
	v_mfma_f32_32x32x16_bf16 v[0:15], a[4:7], a[12:15], v[0:15]
	s_nop 0
	s_nop 0
	s_nop 0
	s_nop 0
	ds_read_b128 a[0:3], v83 offset:32768
	ds_read_b128 a[4:7], v83 offset:36864
	ds_read_b128 a[8:11], v82
	ds_read_b128 a[12:15], v82 offset:4096
	s_waitcnt lgkmcnt(5)
	v_mfma_f32_32x32x16_bf16 v[48:63], a[16:19], a[24:27], v[48:63]
	v_mfma_f32_32x32x16_bf16 v[32:47], a[20:23], a[24:27], v[32:47]
	s_waitcnt lgkmcnt(4)
	v_mfma_f32_32x32x16_bf16 v[16:31], a[16:19], a[28:31], v[16:31]
	v_mfma_f32_32x32x16_bf16 v[0:15], a[20:23], a[28:31], v[0:15]
	s_nop 0
	s_nop 0
	s_nop 0
	s_waitcnt lgkmcnt(1)
	v_mfma_f32_32x32x16_bf16 v[48:63], a[0:3], a[8:11], v[48:63]
	v_mfma_f32_32x32x16_bf16 v[32:47], a[4:7], a[8:11], v[32:47]
	s_nop 0
	s_waitcnt lgkmcnt(0)
	v_mfma_f32_32x32x16_bf16 v[0:15], a[4:7], a[12:15], v[0:15]
	v_mfma_f32_32x32x16_bf16 v[16:31], a[0:3], a[12:15], v[16:31]
	ds_read_b128 v[66:69], v85 offset:32768
	ds_read_b128 v[70:73], v84
	ds_read_b128 v[78:81], v85 offset:36864
	ds_read_b128 v[82:85], v84 offset:4096
	s_waitcnt lgkmcnt(0)
	s_barrier
	s_waitcnt lgkmcnt(0)
	v_mfma_f32_32x32x16_bf16 v[48:63], v[66:69], v[70:73], v[48:63]
	v_mfma_f32_32x32x16_bf16 v[32:47], v[78:81], v[70:73], v[32:47]
	s_nop 10
	ds_write_b128 v64, v[48:51]
	ds_write_b128 v64, v[52:55] offset:32
	ds_write_b128 v64, v[56:59] offset:64
	ds_write_b128 v64, v[60:63] offset:96
	ds_write_b128 v64, v[32:35] offset:128
	v_mfma_f32_32x32x16_bf16 v[0:15], v[78:81], v[82:85], v[0:15]
	v_mfma_f32_32x32x16_bf16 v[16:31], v[66:69], v[82:85], v[16:31]
	ds_write_b128 v64, v[36:39] offset:160
	ds_write_b128 v64, v[40:43] offset:192
	ds_write_b128 v64, v[44:47] offset:224
	s_nop 8
	ds_write_b128 v64, v[16:19] offset:16896
	ds_write_b128 v64, v[20:23] offset:16928
	ds_write_b128 v64, v[24:27] offset:16960
	ds_write_b128 v64, v[28:31] offset:16992
	ds_write_b128 v64, v[0:3] offset:17024
	ds_write_b128 v64, v[4:7] offset:17056
	ds_write_b128 v64, v[8:11] offset:17088
	ds_write_b128 v64, v[12:15] offset:17120
	s_waitcnt lgkmcnt(0)
	s_barrier
	v_lshl_or_b32 v0, v75, 2, s53
	v_ashrrev_i32_e32 v1, 31, v0
	v_lshl_add_u32 v4, v75, 4, 0
	v_lshl_add_u64 v[6:7], v[0:1], 2, s[92:93]
	v_lshl_add_u64 v[8:9], v[0:1], 1, s[0:1]
	v_cmp_eq_u32_e64 s[0:1], 0, v75
	s_branch .LBB0_244

.LBB0_585:
	s_and_b64 vcc, exec, s[0:1]
	s_cbranch_vccz .LBB0_518
	s_mul_hi_i32 s0, s33, 0x51eb851f
	s_lshr_b32 s1, s0, 31
	s_ashr_i32 s0, s0, 3
	v_mov_b32_e32 v78, v133
	s_add_i32 s21, s0, s1
	s_lshl_b32 s20, s21, 8
	v_ashrrev_i32_e32 v6, 6, v78
	v_bfe_u32 v7, v78, 3, 3
	v_lshl_or_b32 v8, v6, 5, v7
	v_add_u32_e32 v0, s20, v8
	s_waitcnt lgkmcnt(0)
	v_ashrrev_i32_e32 v1, 31, v0
	v_lshlrev_b64 v[2:3], 11, v[0:1]
	v_bfe_u32 v1, v78, 4, 2
	v_readlane_b32 s0, v215, 52
	v_xor_b32_e32 v1, v1, v78
	v_readlane_b32 s1, v215, 53
	v_lshlrev_b32_e32 v1, 4, v1
	v_and_b32_e32 v64, 0x70, v1
	v_lshl_add_u64 v[2:3], s[0:1], 0, v[2:3]
	v_or_b32_e32 v1, 8, v8
	v_lshl_add_u64 v[66:67], v[2:3], 0, v[64:65]
	v_add_u32_e32 v2, s20, v1
	v_lshrrev_b32_e32 v1, 1, v1
	v_xor_b32_e32 v1, v1, v78
	v_ashrrev_i32_e32 v3, 31, v2
	v_lshlrev_b32_e32 v1, 4, v1
	v_or_b32_e32 v0, 16, v0
	v_lshlrev_b64 v[2:3], 11, v[2:3]
	v_and_b32_e32 v4, 0x70, v1
	v_ashrrev_i32_e32 v1, 31, v0
	v_lshl_add_u64 v[2:3], s[0:1], 0, v[2:3]
	v_mov_b32_e32 v5, v65
	v_lshlrev_b64 v[0:1], 11, v[0:1]
	v_lshl_add_u64 v[68:69], v[2:3], 0, v[4:5]
	v_lshl_add_u64 v[0:1], s[0:1], 0, v[0:1]
	v_or_b32_e32 v2, 24, v8
	v_lshl_add_u64 v[70:71], v[0:1], 0, v[64:65]
	v_add_u32_e32 v0, s20, v2
	v_lshrrev_b32_e32 v2, 1, v2
	v_ashrrev_i32_e32 v1, 31, v0
	v_xor_b32_e32 v2, v2, v78
	v_lshlrev_b64 v[0:1], 11, v[0:1]
	v_lshlrev_b32_e32 v2, 4, v2
	v_lshl_add_u64 v[0:1], s[0:1], 0, v[0:1]
	v_and_b32_e32 v2, 0x70, v2
	v_mov_b32_e32 v3, v65
	v_lshl_or_b32 v4, v6, 4, v7
	s_mulk_i32 s21, 0xc80
	v_lshl_add_u64 v[72:73], v[0:1], 0, v[2:3]
	v_subrev_u32_e32 v0, s21, v4
	v_add_u32_e32 v0, s23, v0
	v_ashrrev_i32_e32 v1, 31, v0
	v_lshlrev_b64 v[2:3], 11, v[0:1]
	v_lshl_add_u64 v[2:3], s[96:97], 0, v[2:3]
	v_lshl_add_u64 v[74:75], v[2:3], 0, v[64:65]
	v_lshlrev_b32_e32 v3, 12, v6
	v_add_u32_e32 v126, 0, v3
	s_waitcnt vmcnt(0)
	v_add_u32_e32 v127, 0x400, v126
	v_readfirstlane_b32 s41, v126
	v_or_b32_e32 v2, 8, v4
	s_waitcnt lgkmcnt(0)
	s_barrier
	s_mov_b32 m0, s41
	v_readfirstlane_b32 s42, v127
	v_add_u32_e32 v128, 0x800, v126
	v_lshlrev_b32_e32 v5, 11, v6
	v_and_b32_e32 v79, 1, v6
	v_add_u32_e32 v0, 8, v0
	v_lshrrev_b32_e32 v2, 1, v2
	global_load_lds_dwordx4 v[66:67], off
	s_mov_b32 m0, s42
	v_readfirstlane_b32 s43, v128
	v_add_u32_e32 v129, 0xc00, v126
	v_add_u32_e32 v6, 0, v5
	v_ashrrev_i32_e32 v1, 31, v0
	v_xor_b32_e32 v2, v2, v78
	global_load_lds_dwordx4 v[68:69], off
	s_mov_b32 m0, s43
	v_readfirstlane_b32 s44, v129
	v_add_u32_e32 v131, 0x8000, v6
	v_lshlrev_b64 v[0:1], 11, v[0:1]
	v_lshlrev_b32_e32 v2, 4, v2
	global_load_lds_dwordx4 v[70:71], off
	s_mov_b32 m0, s44
	v_readfirstlane_b32 s45, v131
	v_add_u32_e32 v130, 0x8400, v6
	v_lshl_add_u64 v[0:1], s[96:97], 0, v[0:1]
	v_and_b32_e32 v64, 0x70, v2
	global_load_lds_dwordx4 v[72:73], off
	s_mov_b32 m0, s45
	v_readfirstlane_b32 s46, v130
	v_add_u32_e32 v120, 0xc000, v126
	v_lshl_add_u64 v[76:77], v[0:1], 0, v[64:65]
	global_load_lds_dwordx4 v[74:75], off
	s_mov_b32 m0, s46
	s_mov_b64 s[0:1], 0x80
	v_readfirstlane_b32 s35, v120
	v_add_u32_e32 v121, 0xc400, v126
	global_load_lds_dwordx4 v[76:77], off
	v_lshl_add_u64 v[0:1], v[66:67], 0, s[0:1]
	s_mov_b32 m0, s35
	v_readfirstlane_b32 s36, v121
	v_add_u32_e32 v122, 0xc800, v126
	global_load_lds_dwordx4 v[0:1], off
	v_lshl_add_u64 v[0:1], v[68:69], 0, s[0:1]
	s_mov_b32 m0, s36
	v_readfirstlane_b32 s37, v122
	v_add_u32_e32 v123, 0xcc00, v126
	global_load_lds_dwordx4 v[0:1], off
	v_lshl_add_u64 v[0:1], v[70:71], 0, s[0:1]
	s_mov_b32 m0, s37
	v_readfirstlane_b32 s38, v123
	v_add_u32_e32 v124, s85, v5
	global_load_lds_dwordx4 v[0:1], off
	v_lshl_add_u64 v[0:1], v[72:73], 0, s[0:1]
	s_mov_b32 m0, s38
	v_readfirstlane_b32 s39, v124
	v_add_u32_e32 v125, 0x14400, v6
	global_load_lds_dwordx4 v[0:1], off
	v_lshl_add_u64 v[0:1], v[74:75], 0, s[0:1]
	s_mov_b32 m0, s39
	v_readfirstlane_b32 s40, v125
	global_load_lds_dwordx4 v[0:1], off
	v_lshl_add_u64 v[0:1], v[76:77], 0, s[0:1]
	s_mov_b32 m0, s40
	v_lshrrev_b32_e32 v2, 1, v78
	v_bfe_u32 v64, v78, 5, 1
	global_load_lds_dwordx4 v[0:1], off
	v_add_u32_e32 v114, s3, v3
	v_bitop3_b32 v0, v2, v64, 7 bitop3:0x6c
	s_waitcnt vmcnt(6)
	s_mov_b64 s[30:31], 0x100
	v_readfirstlane_b32 s0, v114
	v_add_u32_e32 v115, 0x400, v114
	v_lshlrev_b32_e32 v132, 4, v0
	s_waitcnt lgkmcnt(0)
	s_barrier
	v_lshl_add_u64 v[0:1], v[66:67], 0, s[30:31]
	s_mov_b32 m0, s0
	v_readfirstlane_b32 s1, v115
	v_add_u32_e32 v116, 0x800, v114
	global_load_lds_dwordx4 v[0:1], off
	v_lshl_add_u64 v[0:1], v[68:69], 0, s[30:31]
	s_mov_b32 m0, s1
	v_readfirstlane_b32 s24, v116
	v_add_u32_e32 v117, 0xc00, v114
	v_readlane_b32 s29, v212, 31
	v_and_b32_e32 v81, 31, v78
	global_load_lds_dwordx4 v[0:1], off
	v_lshl_add_u64 v[0:1], v[70:71], 0, s[30:31]
	s_mov_b32 m0, s24
	v_readfirstlane_b32 s28, v117
	v_add_u32_e32 v118, s29, v5
	v_add_u32_e32 v2, s3, v5
	v_lshlrev_b32_e32 v4, 7, v81
	global_load_lds_dwordx4 v[0:1], off
	v_lshl_add_u64 v[0:1], v[72:73], 0, s[30:31]
	s_mov_b32 m0, s28
	v_readfirstlane_b32 s29, v118
	v_add_u32_e32 v119, 0x8400, v2
	v_lshl_or_b32 v102, v79, 13, v4
	global_load_lds_dwordx4 v[0:1], off
	v_lshl_add_u64 v[0:1], v[74:75], 0, s[30:31]
	s_mov_b32 m0, s29
	v_readfirstlane_b32 s34, v119
	global_load_lds_dwordx4 v[0:1], off
	v_lshl_add_u64 v[0:1], v[76:77], 0, s[30:31]
	s_mov_b32 m0, s34
	v_add_u32_e32 v100, 0, v102
	global_load_lds_dwordx4 v[0:1], off
	v_add_u32_e32 v83, v100, v132
	v_ashrrev_i32_e32 v80, 7, v78
	ds_read_b128 a[0:3], v83 offset:32768
	ds_read_b128 a[4:7], v83 offset:36864
	v_lshl_or_b32 v134, v80, 13, v4
	v_add_u32_e32 v101, 0, v134
	v_add_u32_e32 v82, v101, v132
	ds_read_b128 a[8:11], v82
	ds_read_b128 a[12:15], v82 offset:4096
	v_lshrrev_b32_e32 v182, 6, v133
	s_nop 0
	v_readfirstlane_b32 s32, v182
	s_waitcnt lgkmcnt(1)
	v_mfma_f32_32x32x16_bf16 v[48:63], a[0:3], a[8:11], 0
	v_bfe_u32 v103, v78, 1, 3
	s_mov_b64 s[30:31], 0x180
	s_nop 0
	v_or_b32_e32 v143, 0x8000, v102
	v_or_b32_e32 v144, 0x9000, v102
	v_add_u32_e32 v145, s3, v134
	s_mov_b64 s[80:81], 0x200
	s_waitcnt vmcnt(12)
	v_mfma_f32_32x32x16_bf16 v[32:47], a[4:7], a[8:11], 0
	s_waitcnt lgkmcnt(0)
	v_mfma_f32_32x32x16_bf16 v[16:31], a[0:3], a[12:15], 0
	v_bitop3_b32 v0, v64, v103, 2 bitop3:0x36
	v_lshlrev_b32_e32 v138, 4, v0
	v_add_u32_e32 v84, v101, v138
	ds_read_b128 a[28:31], v84 offset:4096
	s_nop 0
	s_nop 0
	ds_read_b128 a[24:27], v84
	s_nop 0
	v_add_u32_e32 v85, v100, v138
	ds_read_b128 a[20:23], v85 offset:36864
	s_nop 0
	s_nop 0
	ds_read_b128 a[16:19], v85 offset:32768
	s_nop 0
	s_nop 0
	s_nop 0
	s_nop 0
	s_nop 0
	s_nop 0
	v_mfma_f32_32x32x16_bf16 v[0:15], a[4:7], a[12:15], 0
	s_nop 0
	s_waitcnt lgkmcnt(0)
	v_mfma_f32_32x32x16_bf16 v[48:63], a[16:19], a[24:27], v[48:63]
	v_mfma_f32_32x32x16_bf16 v[32:47], a[20:23], a[24:27], v[32:47]
	v_mfma_f32_32x32x16_bf16 v[16:31], a[16:19], a[28:31], v[16:31]
	v_bitop3_b32 v86, v64, v103, 4 bitop3:0x36
	v_lshlrev_b32_e32 v139, 4, v86
	v_add_u32_e32 v86, v101, v139
	ds_read_b128 a[12:15], v86 offset:4096
	s_nop 0
	s_nop 0
	ds_read_b128 a[8:11], v86
	s_nop 0
	v_add_u32_e32 v87, v100, v139
	ds_read_b128 a[4:7], v87 offset:36864
	s_nop 0
	s_nop 0
	ds_read_b128 a[0:3], v87 offset:32768
	s_nop 0
	s_nop 0
	s_nop 0
	v_mfma_f32_32x32x16_bf16 v[0:15], a[20:23], a[28:31], v[0:15]
	s_nop 0
	s_nop 0
	s_nop 0
	s_waitcnt lgkmcnt(0)
	v_mfma_f32_32x32x16_bf16 v[48:63], a[0:3], a[8:11], v[48:63]
	v_mfma_f32_32x32x16_bf16 v[32:47], a[4:7], a[8:11], v[32:47]
	s_nop 0
	v_mfma_f32_32x32x16_bf16 v[16:31], a[0:3], a[12:15], v[16:31]
	v_bitop3_b32 v88, v64, v103, 6 bitop3:0x36
	v_lshlrev_b32_e32 v142, 4, v88
	v_add_u32_e32 v88, v101, v142
	ds_read_b128 a[28:31], v88 offset:4096
	s_nop 0
	s_nop 0
	ds_read_b128 a[24:27], v88
	s_nop 0
	v_add_u32_e32 v89, v100, v142
	ds_read_b128 a[20:23], v89 offset:36864
	s_nop 0
	s_nop 0
	ds_read_b128 a[16:19], v89 offset:32768
	s_nop 0
	s_nop 0
	s_nop 0
	v_mfma_f32_32x32x16_bf16 v[0:15], a[4:7], a[12:15], v[0:15]
	s_nop 0
	s_nop 0
	s_nop 0
	s_waitcnt lgkmcnt(0)
	v_mfma_f32_32x32x16_bf16 v[48:63], a[16:19], a[24:27], v[48:63]
	v_mfma_f32_32x32x16_bf16 v[32:47], a[20:23], a[24:27], v[32:47]
	s_nop 0
	s_waitcnt vmcnt(6)
	s_waitcnt lgkmcnt(0)
	s_barrier
	ds_read_b128 a[12:15], v82 offset:53248
	ds_read_b128 a[8:11], v82 offset:49152
	v_mfma_f32_32x32x16_bf16 v[16:31], a[16:19], a[28:31], v[16:31]
	v_lshl_add_u64 v[158:159], v[66:67], 0, s[30:31]
	s_nop 0
	v_lshl_add_u64 v[160:161], v[68:69], 0, s[30:31]
	s_nop 0
	s_nop 0
	s_nop 0
	v_lshl_add_u64 v[162:163], v[70:71], 0, s[30:31]
	s_nop 0
	v_mfma_f32_32x32x16_bf16 v[0:15], a[20:23], a[28:31], v[0:15]
	s_and_b32 m0, s32, 7
	s_lshl_b32 m0, m0, 12
	s_add_i32 m0, m0, 0x0
	s_nop 0
	global_load_lds_dwordx4 v[158:159], off
	s_nop 0
	v_lshl_add_u64 v[164:165], v[72:73], 0, s[30:31]
	s_nop 0
	s_nop 0
	s_nop 0
	v_lshl_add_u64 v[166:167], v[74:75], 0, s[30:31]
	s_nop 0
	s_nop 0
	s_nop 0
	v_lshl_add_u64 v[168:169], v[76:77], 0, s[30:31]
	s_nop 0
	s_add_i32 s30, 0, 0xc000
	v_add_u32_e32 v90, s30, v132
	v_add_u32_e32 v92, v90, v143
	v_add_u32_e32 v90, v90, v144
	ds_read_b128 a[4:7], v90
	ds_read_b128 a[0:3], v92
	s_nop 0
	s_nop 0
	s_nop 0
	s_nop 0
	s_nop 0
	s_nop 0
	s_nop 0
	s_nop 0
	v_add_u32_e32 v91, s30, v138
	v_add_u32_e32 v93, v91, v143
	ds_read_b128 a[16:19], v93
	v_add_u32_e32 v91, v91, v144
	ds_read_b128 a[20:23], v91
	ds_read_b128 a[24:27], v84 offset:49152
	ds_read_b128 a[28:31], v84 offset:53248
	s_waitcnt lgkmcnt(4)
	v_mfma_f32_32x32x16_bf16 v[48:63], a[0:3], a[8:11], v[48:63]
	s_nop 0
	s_nop 0
	s_nop 0
	s_nop 0
	v_mfma_f32_32x32x16_bf16 v[32:47], a[4:7], a[8:11], v[32:47]
	s_and_b32 m0, s32, 7
	s_lshl_b32 m0, m0, 12
	s_add_i32 m0, m0, 0x400
	s_nop 0
	global_load_lds_dwordx4 v[160:161], off
	v_mfma_f32_32x32x16_bf16 v[16:31], a[0:3], a[12:15], v[16:31]
	v_mfma_f32_32x32x16_bf16 v[0:15], a[4:7], a[12:15], v[0:15]
	s_and_b32 m0, s32, 7
	s_lshl_b32 m0, m0, 12
	s_add_i32 m0, m0, 0x800
	s_nop 0
	global_load_lds_dwordx4 v[162:163], off
	s_nop 0
	s_nop 0
	s_nop 0
	s_nop 0
	v_add_u32_e32 v94, s30, v139
	v_add_u32_e32 v95, v94, v143
	ds_read_b128 a[0:3], v95
	v_add_u32_e32 v94, v94, v144
	ds_read_b128 a[4:7], v94
	ds_read_b128 a[8:11], v86 offset:49152
	ds_read_b128 a[12:15], v86 offset:53248
	s_waitcnt lgkmcnt(5)
	v_mfma_f32_32x32x16_bf16 v[48:63], a[16:19], a[24:27], v[48:63]
	v_mfma_f32_32x32x16_bf16 v[32:47], a[20:23], a[24:27], v[32:47]
	s_and_b32 m0, s32, 7
	s_lshl_b32 m0, m0, 12
	s_add_i32 m0, m0, 0xc00
	s_nop 0
	global_load_lds_dwordx4 v[164:165], off
	s_waitcnt lgkmcnt(4)
	v_mfma_f32_32x32x16_bf16 v[16:31], a[16:19], a[28:31], v[16:31]
	s_nop 0
	s_nop 0
	s_nop 0
	v_mfma_f32_32x32x16_bf16 v[0:15], a[20:23], a[28:31], v[0:15]
	s_and_b32 m0, s32, 7
	s_lshl_b32 m0, m0, 11
	s_add_i32 m0, m0, 0x8000
	s_nop 0
	global_load_lds_dwordx4 v[166:167], off
	s_nop 0
	s_nop 0
	s_nop 0
	s_nop 0
	v_add_u32_e32 v96, s30, v142
	v_add_u32_e32 v97, v96, v143
	ds_read_b128 a[16:19], v97
	v_add_u32_e32 v96, v96, v144
	ds_read_b128 a[20:23], v96
	ds_read_b128 a[24:27], v88 offset:49152
	ds_read_b128 a[28:31], v88 offset:53248
	s_waitcnt lgkmcnt(5)
	v_mfma_f32_32x32x16_bf16 v[48:63], a[0:3], a[8:11], v[48:63]
	v_mfma_f32_32x32x16_bf16 v[32:47], a[4:7], a[8:11], v[32:47]
	s_and_b32 m0, s32, 7
	s_lshl_b32 m0, m0, 11
	s_add_i32 m0, m0, 0x8400
	s_nop 0
	global_load_lds_dwordx4 v[168:169], off
	s_waitcnt lgkmcnt(4)
	v_mfma_f32_32x32x16_bf16 v[16:31], a[0:3], a[12:15], v[16:31]
	s_nop 0
	s_nop 0
	s_nop 0
	s_mov_b64 s[30:31], 0x200
	v_mfma_f32_32x32x16_bf16 v[0:15], a[4:7], a[12:15], v[0:15]
	s_nop 0
	s_nop 0
	s_nop 0
	s_nop 0
	s_waitcnt lgkmcnt(1)
	v_mfma_f32_32x32x16_bf16 v[48:63], a[16:19], a[24:27], v[48:63]
	v_mfma_f32_32x32x16_bf16 v[32:47], a[20:23], a[24:27], v[32:47]
	s_waitcnt vmcnt(6)
	s_waitcnt lgkmcnt(0)
	s_barrier
	v_add_u32_e32 v100, v145, v132
	ds_read_b128 a[8:11], v100
	v_add_u32_e32 v101, s3, v132
	v_add_u32_e32 v99, v101, v144
	ds_read_b128 a[4:7], v99
	s_nop 0
	v_add_u32_e32 v98, v101, v143
	v_or_b32_e32 v132, 0x1000, v134
	v_add_u32_e32 v101, v101, v132
	ds_read_b128 a[12:15], v101
	ds_read_b128 a[0:3], v98
	v_mfma_f32_32x32x16_bf16 v[16:31], a[16:19], a[28:31], v[16:31]
	v_lshl_add_u64 v[170:171], v[66:67], 0, s[30:31]
	s_nop 0
	v_lshl_add_u64 v[172:173], v[68:69], 0, s[30:31]
	s_nop 0
	s_nop 0
	s_nop 0
	v_lshl_add_u64 v[174:175], v[70:71], 0, s[30:31]
	s_nop 0
	v_mfma_f32_32x32x16_bf16 v[0:15], a[20:23], a[28:31], v[0:15]
	s_and_b32 m0, s32, 7
	s_lshl_b32 m0, m0, 12
	s_add_i32 m0, m0, 0xc000
	s_nop 0
	global_load_lds_dwordx4 v[170:171], off
	s_nop 0
	v_lshl_add_u64 v[176:177], v[72:73], 0, s[30:31]
	s_nop 0
	s_nop 0
	s_nop 0
	v_lshl_add_u64 v[178:179], v[74:75], 0, s[30:31]
	s_nop 0
	s_nop 0
	s_nop 0
	v_lshl_add_u64 v[180:181], v[76:77], 0, s[30:31]
	s_nop 0
	s_mov_b64 s[30:31], 0x280
	s_nop 0
	s_nop 0
	s_nop 0
	s_nop 0
	s_nop 0
	s_nop 0
	s_nop 0
	s_nop 0
	v_add_u32_e32 v105, s3, v138
	v_add_u32_e32 v102, v105, v143
	ds_read_b128 a[16:19], v102
	v_add_u32_e32 v103, v105, v144
	ds_read_b128 a[20:23], v103
	v_add_u32_e32 v104, v145, v138
	ds_read_b128 a[24:27], v104
	v_add_u32_e32 v105, v105, v132
	ds_read_b128 a[28:31], v105
	s_waitcnt lgkmcnt(4)
	v_mfma_f32_32x32x16_bf16 v[48:63], a[0:3], a[8:11], v[48:63]
	s_nop 0
	v_mfma_f32_32x32x16_bf16 v[32:47], a[4:7], a[8:11], v[32:47]
	s_and_b32 m0, s32, 7
	s_lshl_b32 m0, m0, 12
	s_add_i32 m0, m0, 0xc400
	s_nop 0
	global_load_lds_dwordx4 v[172:173], off
	s_nop 0
	s_nop 0
	s_nop 0
	s_nop 0
	s_nop 0
	v_mfma_f32_32x32x16_bf16 v[16:31], a[0:3], a[12:15], v[16:31]
	s_nop 0
	v_mfma_f32_32x32x16_bf16 v[0:15], a[4:7], a[12:15], v[0:15]
	s_and_b32 m0, s32, 7
	s_lshl_b32 m0, m0, 12
	s_add_i32 m0, m0, 0xc800
	s_nop 0
	global_load_lds_dwordx4 v[174:175], off
	s_nop 0
	s_nop 0
	s_nop 0
	v_add_u32_e32 v109, s3, v139
	v_add_u32_e32 v106, v109, v143
	ds_read_b128 a[0:3], v106
	v_add_u32_e32 v107, v109, v144
	ds_read_b128 a[4:7], v107
	v_add_u32_e32 v108, v145, v139
	ds_read_b128 a[8:11], v108
	v_add_u32_e32 v109, v109, v132
	ds_read_b128 a[12:15], v109
	s_waitcnt lgkmcnt(5)
	v_mfma_f32_32x32x16_bf16 v[48:63], a[16:19], a[24:27], v[48:63]
	v_mfma_f32_32x32x16_bf16 v[32:47], a[20:23], a[24:27], v[32:47]
	s_and_b32 m0, s32, 7
	s_lshl_b32 m0, m0, 12
	s_add_i32 m0, m0, 0xcc00
	s_nop 0
	global_load_lds_dwordx4 v[176:177], off
	s_waitcnt lgkmcnt(4)
	v_mfma_f32_32x32x16_bf16 v[16:31], a[16:19], a[28:31], v[16:31]
	s_nop 0
	s_nop 0
	s_nop 0
	s_nop 0
	s_nop 0
	s_nop 0
	v_mfma_f32_32x32x16_bf16 v[0:15], a[20:23], a[28:31], v[0:15]
	s_and_b32 m0, s32, 7
	s_lshl_b32 m0, m0, 11
	s_add_i32 m0, m0, 0x14000
	s_nop 0
	global_load_lds_dwordx4 v[178:179], off
	s_nop 0
	s_nop 0
	s_nop 0
	v_add_u32_e32 v113, s3, v142
	v_add_u32_e32 v110, v113, v143
	ds_read_b128 a[16:19], v110
	v_add_u32_e32 v111, v113, v144
	ds_read_b128 a[20:23], v111
	v_add_u32_e32 v112, v145, v142
	ds_read_b128 a[24:27], v112
	v_add_u32_e32 v113, v113, v132
	ds_read_b128 a[28:31], v113
	s_waitcnt lgkmcnt(5)
	v_mfma_f32_32x32x16_bf16 v[48:63], a[0:3], a[8:11], v[48:63]
	v_mfma_f32_32x32x16_bf16 v[32:47], a[4:7], a[8:11], v[32:47]
	s_and_b32 m0, s32, 7
	s_lshl_b32 m0, m0, 11
	s_add_i32 m0, m0, 0x14400
	s_nop 0
	global_load_lds_dwordx4 v[180:181], off
	s_waitcnt lgkmcnt(4)
	v_mfma_f32_32x32x16_bf16 v[16:31], a[0:3], a[12:15], v[16:31]
	s_nop 0
	s_nop 0
	s_nop 0
	s_nop 0
	s_nop 0
	s_nop 0
	v_mfma_f32_32x32x16_bf16 v[0:15], a[4:7], a[12:15], v[0:15]
	s_nop 0
	s_nop 0
	s_nop 0
	s_waitcnt lgkmcnt(1)
	v_mfma_f32_32x32x16_bf16 v[48:63], a[16:19], a[24:27], v[48:63]
	v_mfma_f32_32x32x16_bf16 v[32:47], a[20:23], a[24:27], v[32:47]
	s_waitcnt vmcnt(6)
	s_waitcnt lgkmcnt(0)
	s_barrier
	ds_read_b128 a[12:15], v82 offset:4096
	ds_read_b128 a[8:11], v82
	ds_read_b128 a[4:7], v83 offset:36864
	ds_read_b128 a[0:3], v83 offset:32768
	v_mfma_f32_32x32x16_bf16 v[16:31], a[16:19], a[28:31], v[16:31]
	v_lshl_add_u64 v[158:159], v[66:67], 0, s[30:31]
	s_nop 0
	v_lshl_add_u64 v[160:161], v[68:69], 0, s[30:31]
	s_nop 0
	s_nop 0
	s_nop 0
	v_lshl_add_u64 v[162:163], v[70:71], 0, s[30:31]
	s_nop 0
	v_mfma_f32_32x32x16_bf16 v[0:15], a[20:23], a[28:31], v[0:15]
	s_and_b32 m0, s32, 7
	s_lshl_b32 m0, m0, 12
	s_add_i32 m0, m0, 0x18000
	s_nop 0
	global_load_lds_dwordx4 v[158:159], off
	s_nop 0
	v_lshl_add_u64 v[164:165], v[72:73], 0, s[30:31]
	s_nop 0
	s_nop 0
	s_nop 0
	v_lshl_add_u64 v[166:167], v[74:75], 0, s[30:31]
	s_nop 0
	s_nop 0
	s_nop 0
	v_lshl_add_u64 v[168:169], v[76:77], 0, s[30:31]
	s_nop 0
	s_mov_b64 s[30:31], 0x300
	s_nop 0
	s_nop 0
	s_nop 0
	s_nop 0
	s_nop 0
	ds_read_b128 a[16:19], v85 offset:32768
	ds_read_b128 a[20:23], v85 offset:36864
	ds_read_b128 a[24:27], v84
	ds_read_b128 a[28:31], v84 offset:4096
	s_waitcnt lgkmcnt(4)
	v_mfma_f32_32x32x16_bf16 v[48:63], a[0:3], a[8:11], v[48:63]
	s_nop 0
	v_readfirstlane_b32 s41, v114
	v_mfma_f32_32x32x16_bf16 v[32:47], a[4:7], a[8:11], v[32:47]
	s_and_b32 m0, s32, 7
	s_lshl_b32 m0, m0, 12
	s_add_i32 m0, m0, 0x18400
	s_nop 0
	global_load_lds_dwordx4 v[160:161], off
	v_mfma_f32_32x32x16_bf16 v[16:31], a[0:3], a[12:15], v[16:31]
	v_mfma_f32_32x32x16_bf16 v[0:15], a[4:7], a[12:15], v[0:15]
	s_and_b32 m0, s32, 7
	s_lshl_b32 m0, m0, 12
	s_add_i32 m0, m0, 0x18800
	s_nop 0
	global_load_lds_dwordx4 v[162:163], off
	s_nop 0
	s_nop 0
	s_nop 0
	s_nop 0
	ds_read_b128 a[0:3], v87 offset:32768
	ds_read_b128 a[4:7], v87 offset:36864
	ds_read_b128 a[8:11], v86
	ds_read_b128 a[12:15], v86 offset:4096
	s_waitcnt lgkmcnt(5)
	v_mfma_f32_32x32x16_bf16 v[48:63], a[16:19], a[24:27], v[48:63]
	v_mfma_f32_32x32x16_bf16 v[32:47], a[20:23], a[24:27], v[32:47]
	s_and_b32 m0, s32, 7
	s_lshl_b32 m0, m0, 12
	s_add_i32 m0, m0, 0x18c00
	s_nop 0
	global_load_lds_dwordx4 v[164:165], off
	s_waitcnt lgkmcnt(4)
	v_mfma_f32_32x32x16_bf16 v[16:31], a[16:19], a[28:31], v[16:31]
	v_mfma_f32_32x32x16_bf16 v[0:15], a[20:23], a[28:31], v[0:15]
	s_and_b32 m0, s32, 7
	s_lshl_b32 m0, m0, 11
	s_add_i32 m0, m0, 0x20000
	s_nop 0
	global_load_lds_dwordx4 v[166:167], off
	s_nop 0
	s_nop 0
	s_nop 0
	s_nop 0
	ds_read_b128 a[16:19], v89 offset:32768
	ds_read_b128 a[20:23], v89 offset:36864
	ds_read_b128 a[24:27], v88
	ds_read_b128 a[28:31], v88 offset:4096
	s_waitcnt lgkmcnt(5)
	v_mfma_f32_32x32x16_bf16 v[48:63], a[0:3], a[8:11], v[48:63]
	v_mfma_f32_32x32x16_bf16 v[32:47], a[4:7], a[8:11], v[32:47]
	s_and_b32 m0, s32, 7
	s_lshl_b32 m0, m0, 11
	s_add_i32 m0, m0, 0x20400
	s_nop 0
	global_load_lds_dwordx4 v[168:169], off
	s_waitcnt lgkmcnt(4)
	v_mfma_f32_32x32x16_bf16 v[16:31], a[0:3], a[12:15], v[16:31]
	v_mfma_f32_32x32x16_bf16 v[0:15], a[4:7], a[12:15], v[0:15]
	s_nop 0
	s_nop 0
	s_nop 0
	s_nop 0
	s_waitcnt lgkmcnt(1)
	v_mfma_f32_32x32x16_bf16 v[48:63], a[16:19], a[24:27], v[48:63]
	v_mfma_f32_32x32x16_bf16 v[32:47], a[20:23], a[24:27], v[32:47]
	s_waitcnt vmcnt(6)
	s_waitcnt lgkmcnt(0)
	s_barrier
	ds_read_b128 a[12:15], v82 offset:53248
	ds_read_b128 a[8:11], v82 offset:49152
	ds_read_b128 a[4:7], v90
	ds_read_b128 a[0:3], v92
	v_mfma_f32_32x32x16_bf16 v[16:31], a[16:19], a[28:31], v[16:31]
	v_lshl_add_u64 v[170:171], v[66:67], 0, s[30:31]
	s_nop 0
	v_lshl_add_u64 v[172:173], v[68:69], 0, s[30:31]
	s_nop 0
	v_readfirstlane_b32 s42, v115
	s_nop 0
	v_lshl_add_u64 v[174:175], v[70:71], 0, s[30:31]
	s_nop 0
	v_mfma_f32_32x32x16_bf16 v[0:15], a[20:23], a[28:31], v[0:15]
	s_and_b32 m0, s32, 7
	s_lshl_b32 m0, m0, 12
	s_add_i32 m0, m0, 0x0
	s_nop 0
	global_load_lds_dwordx4 v[170:171], off
	s_nop 0
	v_lshl_add_u64 v[176:177], v[72:73], 0, s[30:31]
	s_nop 0
	v_readfirstlane_b32 s43, v116
	s_nop 0
	v_lshl_add_u64 v[178:179], v[74:75], 0, s[30:31]
	s_nop 0
	v_readfirstlane_b32 s44, v117
	s_nop 0
	v_lshl_add_u64 v[180:181], v[76:77], 0, s[30:31]
	s_nop 0
	s_mov_b64 s[30:31], 0x380
	s_nop 0
	s_nop 0
	s_nop 0
	s_nop 0
	s_nop 0
	ds_read_b128 a[16:19], v93
	ds_read_b128 a[20:23], v91
	ds_read_b128 a[24:27], v84 offset:49152
	ds_read_b128 a[28:31], v84 offset:53248
	s_waitcnt lgkmcnt(4)
	v_mfma_f32_32x32x16_bf16 v[48:63], a[0:3], a[8:11], v[48:63]
	s_nop 0
	v_readfirstlane_b32 s35, v120
	v_readfirstlane_b32 s45, v118
	v_readfirstlane_b32 s46, v119
	v_mfma_f32_32x32x16_bf16 v[32:47], a[4:7], a[8:11], v[32:47]
	s_and_b32 m0, s32, 7
	s_lshl_b32 m0, m0, 12
	s_add_i32 m0, m0, 0x400
	s_nop 0
	global_load_lds_dwordx4 v[172:173], off
	v_mfma_f32_32x32x16_bf16 v[16:31], a[0:3], a[12:15], v[16:31]
	v_mfma_f32_32x32x16_bf16 v[0:15], a[4:7], a[12:15], v[0:15]
	s_and_b32 m0, s32, 7
	s_lshl_b32 m0, m0, 12
	s_add_i32 m0, m0, 0x800
	s_nop 0
	global_load_lds_dwordx4 v[174:175], off
	s_nop 0
	s_nop 0
	s_nop 0
	s_nop 0
	ds_read_b128 a[0:3], v95
	ds_read_b128 a[4:7], v94
	ds_read_b128 a[8:11], v86 offset:49152
	ds_read_b128 a[12:15], v86 offset:53248
	s_waitcnt lgkmcnt(5)
	v_mfma_f32_32x32x16_bf16 v[48:63], a[16:19], a[24:27], v[48:63]
	v_mfma_f32_32x32x16_bf16 v[32:47], a[20:23], a[24:27], v[32:47]
	s_and_b32 m0, s32, 7
	s_lshl_b32 m0, m0, 12
	s_add_i32 m0, m0, 0xc00
	s_nop 0
	global_load_lds_dwordx4 v[176:177], off
	s_waitcnt lgkmcnt(4)
	v_mfma_f32_32x32x16_bf16 v[16:31], a[16:19], a[28:31], v[16:31]
	v_mfma_f32_32x32x16_bf16 v[0:15], a[20:23], a[28:31], v[0:15]
	s_and_b32 m0, s32, 7
	s_lshl_b32 m0, m0, 11
	s_add_i32 m0, m0, 0x8000
	s_nop 0
	global_load_lds_dwordx4 v[178:179], off
	s_nop 0
	s_nop 0
	s_nop 0
	s_nop 0
	ds_read_b128 a[16:19], v97
	ds_read_b128 a[20:23], v96
	ds_read_b128 a[24:27], v88 offset:49152
	ds_read_b128 a[28:31], v88 offset:53248
	s_waitcnt lgkmcnt(5)
	v_mfma_f32_32x32x16_bf16 v[48:63], a[0:3], a[8:11], v[48:63]
	v_mfma_f32_32x32x16_bf16 v[32:47], a[4:7], a[8:11], v[32:47]
	s_and_b32 m0, s32, 7
	s_lshl_b32 m0, m0, 11
	s_add_i32 m0, m0, 0x8400
	s_nop 0
	global_load_lds_dwordx4 v[180:181], off
	s_waitcnt lgkmcnt(4)
	v_mfma_f32_32x32x16_bf16 v[16:31], a[0:3], a[12:15], v[16:31]
	v_mfma_f32_32x32x16_bf16 v[0:15], a[4:7], a[12:15], v[0:15]
	s_nop 0
	s_nop 0
	s_nop 0
	s_nop 0
	s_waitcnt lgkmcnt(1)
	v_mfma_f32_32x32x16_bf16 v[48:63], a[16:19], a[24:27], v[48:63]
	v_mfma_f32_32x32x16_bf16 v[32:47], a[20:23], a[24:27], v[32:47]
	s_waitcnt vmcnt(6)
	s_waitcnt lgkmcnt(0)
	s_barrier
	ds_read_b128 a[12:15], v101
	ds_read_b128 a[8:11], v100
	ds_read_b128 a[4:7], v99
	ds_read_b128 a[0:3], v98
	v_mfma_f32_32x32x16_bf16 v[16:31], a[16:19], a[28:31], v[16:31]
	v_lshl_add_u64 v[158:159], v[66:67], 0, s[30:31]
	s_nop 0
	v_lshl_add_u64 v[160:161], v[68:69], 0, s[30:31]
	s_nop 0
	v_readfirstlane_b32 s36, v121
	s_nop 0
	v_lshl_add_u64 v[162:163], v[70:71], 0, s[30:31]
	s_nop 0
	v_mfma_f32_32x32x16_bf16 v[0:15], a[20:23], a[28:31], v[0:15]
	s_and_b32 m0, s32, 7
	s_lshl_b32 m0, m0, 12
	s_add_i32 m0, m0, 0xc000
	s_nop 0
	global_load_lds_dwordx4 v[158:159], off
	s_nop 0
	v_lshl_add_u64 v[164:165], v[72:73], 0, s[30:31]
	s_nop 0
	v_readfirstlane_b32 s37, v122
	s_nop 0
	v_lshl_add_u64 v[166:167], v[74:75], 0, s[30:31]
	s_nop 0
	v_readfirstlane_b32 s38, v123
	s_nop 0
	v_lshl_add_u64 v[168:169], v[76:77], 0, s[30:31]
	s_nop 0
	s_mov_b64 s[30:31], 0x400
	s_nop 0
	s_nop 0
	s_nop 0
	s_nop 0
	s_nop 0
	ds_read_b128 a[16:19], v102
	ds_read_b128 a[20:23], v103
	ds_read_b128 a[24:27], v104
	ds_read_b128 a[28:31], v105
	s_waitcnt lgkmcnt(4)
	v_mfma_f32_32x32x16_bf16 v[48:63], a[0:3], a[8:11], v[48:63]
	s_nop 0
	v_readfirstlane_b32 s0, v126
	v_readfirstlane_b32 s39, v124
	v_readfirstlane_b32 s40, v125
	v_mfma_f32_32x32x16_bf16 v[32:47], a[4:7], a[8:11], v[32:47]
	s_and_b32 m0, s32, 7
	s_lshl_b32 m0, m0, 12
	s_add_i32 m0, m0, 0xc400
	s_nop 0
	global_load_lds_dwordx4 v[160:161], off
	v_mfma_f32_32x32x16_bf16 v[16:31], a[0:3], a[12:15], v[16:31]
	v_mfma_f32_32x32x16_bf16 v[0:15], a[4:7], a[12:15], v[0:15]
	s_and_b32 m0, s32, 7
	s_lshl_b32 m0, m0, 12
	s_add_i32 m0, m0, 0xc800
	s_nop 0
	global_load_lds_dwordx4 v[162:163], off
	s_nop 0
	s_nop 0
	s_nop 0
	s_nop 0
	ds_read_b128 a[0:3], v106
	ds_read_b128 a[4:7], v107
	ds_read_b128 a[8:11], v108
	ds_read_b128 a[12:15], v109
	s_waitcnt lgkmcnt(5)
	v_mfma_f32_32x32x16_bf16 v[48:63], a[16:19], a[24:27], v[48:63]
	v_mfma_f32_32x32x16_bf16 v[32:47], a[20:23], a[24:27], v[32:47]
	s_and_b32 m0, s32, 7
	s_lshl_b32 m0, m0, 12
	s_add_i32 m0, m0, 0xcc00
	s_nop 0
	global_load_lds_dwordx4 v[164:165], off
	s_waitcnt lgkmcnt(4)
	v_mfma_f32_32x32x16_bf16 v[16:31], a[16:19], a[28:31], v[16:31]
	v_mfma_f32_32x32x16_bf16 v[0:15], a[20:23], a[28:31], v[0:15]
	s_and_b32 m0, s32, 7
	s_lshl_b32 m0, m0, 11
	s_add_i32 m0, m0, 0x14000
	s_nop 0
	global_load_lds_dwordx4 v[166:167], off
	s_nop 0
	s_nop 0
	s_nop 0
	s_nop 0
	ds_read_b128 a[16:19], v110
	ds_read_b128 a[20:23], v111
	ds_read_b128 a[24:27], v112
	ds_read_b128 a[28:31], v113
	s_waitcnt lgkmcnt(5)
	v_mfma_f32_32x32x16_bf16 v[48:63], a[0:3], a[8:11], v[48:63]
	v_mfma_f32_32x32x16_bf16 v[32:47], a[4:7], a[8:11], v[32:47]
	s_and_b32 m0, s32, 7
	s_lshl_b32 m0, m0, 11
	s_add_i32 m0, m0, 0x14400
	s_nop 0
	global_load_lds_dwordx4 v[168:169], off
	s_waitcnt lgkmcnt(4)
	v_mfma_f32_32x32x16_bf16 v[16:31], a[0:3], a[12:15], v[16:31]
	v_mfma_f32_32x32x16_bf16 v[0:15], a[4:7], a[12:15], v[0:15]
	s_nop 0
	s_nop 0
	s_nop 0
	s_nop 0
	s_waitcnt lgkmcnt(1)
	v_mfma_f32_32x32x16_bf16 v[48:63], a[16:19], a[24:27], v[48:63]
	v_mfma_f32_32x32x16_bf16 v[32:47], a[20:23], a[24:27], v[32:47]
	s_waitcnt vmcnt(6)
	s_waitcnt lgkmcnt(0)
	s_barrier
	ds_read_b128 a[12:15], v82 offset:4096
	ds_read_b128 a[8:11], v82
	ds_read_b128 a[4:7], v83 offset:36864
	ds_read_b128 a[0:3], v83 offset:32768
	v_mfma_f32_32x32x16_bf16 v[16:31], a[16:19], a[28:31], v[16:31]
	v_lshl_add_u64 v[170:171], v[66:67], 0, s[30:31]
	s_nop 0
	v_lshl_add_u64 v[172:173], v[68:69], 0, s[30:31]
	s_nop 0
	v_readfirstlane_b32 s1, v127
	s_nop 0
	v_lshl_add_u64 v[174:175], v[70:71], 0, s[30:31]
	s_nop 0
	v_mfma_f32_32x32x16_bf16 v[0:15], a[20:23], a[28:31], v[0:15]
	s_and_b32 m0, s32, 7
	s_lshl_b32 m0, m0, 12
	s_add_i32 m0, m0, 0x18000
	s_nop 0
	global_load_lds_dwordx4 v[170:171], off
	s_nop 0
	v_lshl_add_u64 v[176:177], v[72:73], 0, s[30:31]
	s_nop 0
	v_readfirstlane_b32 s24, v128
	s_nop 0
	v_lshl_add_u64 v[178:179], v[74:75], 0, s[30:31]
	s_nop 0
	v_readfirstlane_b32 s28, v129
	s_nop 0
	v_lshl_add_u64 v[180:181], v[76:77], 0, s[30:31]
	s_nop 0
	s_mov_b64 s[30:31], 0x480
	s_nop 0
	s_nop 0
	s_nop 0
	s_nop 0
	s_nop 0
	ds_read_b128 a[16:19], v85 offset:32768
	ds_read_b128 a[20:23], v85 offset:36864
	ds_read_b128 a[24:27], v84
	ds_read_b128 a[28:31], v84 offset:4096
	s_waitcnt lgkmcnt(4)
	v_mfma_f32_32x32x16_bf16 v[48:63], a[0:3], a[8:11], v[48:63]
	s_nop 0
	v_lshl_add_u64 v[162:163], v[70:71], 0, s[30:31]
	v_readfirstlane_b32 s29, v131
	v_readfirstlane_b32 s34, v130
	v_mfma_f32_32x32x16_bf16 v[32:47], a[4:7], a[8:11], v[32:47]
	s_and_b32 m0, s32, 7
	s_lshl_b32 m0, m0, 12
	s_add_i32 m0, m0, 0x18400
	s_nop 0
	global_load_lds_dwordx4 v[172:173], off
	v_mfma_f32_32x32x16_bf16 v[16:31], a[0:3], a[12:15], v[16:31]
	v_mfma_f32_32x32x16_bf16 v[0:15], a[4:7], a[12:15], v[0:15]
	s_and_b32 m0, s32, 7
	s_lshl_b32 m0, m0, 12
	s_add_i32 m0, m0, 0x18800
	s_nop 0
	global_load_lds_dwordx4 v[174:175], off
	s_nop 0
	s_nop 0
	s_nop 0
	s_nop 0
	ds_read_b128 a[0:3], v87 offset:32768
	ds_read_b128 a[4:7], v87 offset:36864
	ds_read_b128 a[8:11], v86
	ds_read_b128 a[12:15], v86 offset:4096
	s_waitcnt lgkmcnt(5)
	v_mfma_f32_32x32x16_bf16 v[48:63], a[16:19], a[24:27], v[48:63]
	v_mfma_f32_32x32x16_bf16 v[32:47], a[20:23], a[24:27], v[32:47]
	s_and_b32 m0, s32, 7
	s_lshl_b32 m0, m0, 12
	s_add_i32 m0, m0, 0x18c00
	s_nop 0
	global_load_lds_dwordx4 v[176:177], off
	s_waitcnt lgkmcnt(4)
	v_mfma_f32_32x32x16_bf16 v[16:31], a[16:19], a[28:31], v[16:31]
	v_mfma_f32_32x32x16_bf16 v[0:15], a[20:23], a[28:31], v[0:15]
	s_and_b32 m0, s32, 7
	s_lshl_b32 m0, m0, 11
	s_add_i32 m0, m0, 0x20000
	s_nop 0
	global_load_lds_dwordx4 v[178:179], off
	s_nop 0
	s_nop 0
	s_nop 0
	s_nop 0
	ds_read_b128 a[16:19], v89 offset:32768
	ds_read_b128 a[20:23], v89 offset:36864
	ds_read_b128 a[24:27], v88
	ds_read_b128 a[28:31], v88 offset:4096
	s_waitcnt lgkmcnt(5)
	v_mfma_f32_32x32x16_bf16 v[48:63], a[0:3], a[8:11], v[48:63]
	v_mfma_f32_32x32x16_bf16 v[32:47], a[4:7], a[8:11], v[32:47]
	s_and_b32 m0, s32, 7
	s_lshl_b32 m0, m0, 11
	s_add_i32 m0, m0, 0x20400
	s_nop 0
	global_load_lds_dwordx4 v[180:181], off
	s_waitcnt lgkmcnt(4)
	v_mfma_f32_32x32x16_bf16 v[16:31], a[0:3], a[12:15], v[16:31]
	v_mfma_f32_32x32x16_bf16 v[0:15], a[4:7], a[12:15], v[0:15]
	s_nop 0
	s_nop 0
	s_nop 0
	s_nop 0
	s_waitcnt lgkmcnt(1)
	v_mfma_f32_32x32x16_bf16 v[48:63], a[16:19], a[24:27], v[48:63]
	v_mfma_f32_32x32x16_bf16 v[32:47], a[20:23], a[24:27], v[32:47]
	s_waitcnt vmcnt(6)
	s_waitcnt lgkmcnt(0)
	s_barrier
	ds_read_b128 a[12:15], v82 offset:53248
	ds_read_b128 a[8:11], v82 offset:49152
	ds_read_b128 a[4:7], v90
	ds_read_b128 a[0:3], v92
	v_mfma_f32_32x32x16_bf16 v[16:31], a[16:19], a[28:31], v[16:31]
	v_lshl_add_u64 v[158:159], v[66:67], 0, s[30:31]
	s_nop 0
	v_lshl_add_u64 v[160:161], v[68:69], 0, s[30:31]
	s_nop 0
	s_nop 0
	s_nop 0
	s_nop 0
	v_mfma_f32_32x32x16_bf16 v[0:15], a[20:23], a[28:31], v[0:15]
	s_and_b32 m0, s32, 7
	s_lshl_b32 m0, m0, 12
	s_add_i32 m0, m0, 0x0
	s_nop 0
	global_load_lds_dwordx4 v[158:159], off
	s_nop 0
	v_lshl_add_u64 v[164:165], v[72:73], 0, s[30:31]
	s_nop 0
	s_nop 0
	s_nop 0
	v_lshl_add_u64 v[166:167], v[74:75], 0, s[30:31]
	s_nop 0
	s_nop 0
	s_nop 0
	v_lshl_add_u64 v[168:169], v[76:77], 0, s[30:31]
	s_nop 0
	s_mov_b64 s[30:31], 0x500
	s_nop 0
	s_nop 0
	s_nop 0
	s_nop 0
	s_nop 0
	ds_read_b128 a[16:19], v93
	ds_read_b128 a[20:23], v91
	ds_read_b128 a[24:27], v84 offset:49152
	ds_read_b128 a[28:31], v84 offset:53248
	s_waitcnt lgkmcnt(4)
	v_mfma_f32_32x32x16_bf16 v[48:63], a[0:3], a[8:11], v[48:63]
	s_nop 0
	v_lshl_add_u64 v[174:175], v[70:71], 0, s[30:31]
	v_mfma_f32_32x32x16_bf16 v[32:47], a[4:7], a[8:11], v[32:47]
	s_and_b32 m0, s32, 7
	s_lshl_b32 m0, m0, 12
	s_add_i32 m0, m0, 0x400
	s_nop 0
	global_load_lds_dwordx4 v[160:161], off
	v_mfma_f32_32x32x16_bf16 v[16:31], a[0:3], a[12:15], v[16:31]
	v_mfma_f32_32x32x16_bf16 v[0:15], a[4:7], a[12:15], v[0:15]
	s_and_b32 m0, s32, 7
	s_lshl_b32 m0, m0, 12
	s_add_i32 m0, m0, 0x800
	s_nop 0
	global_load_lds_dwordx4 v[162:163], off
	s_nop 0
	s_nop 0
	s_nop 0
	s_nop 0
	ds_read_b128 a[0:3], v95
	ds_read_b128 a[4:7], v94
	ds_read_b128 a[8:11], v86 offset:49152
	ds_read_b128 a[12:15], v86 offset:53248
	s_waitcnt lgkmcnt(5)
	v_mfma_f32_32x32x16_bf16 v[48:63], a[16:19], a[24:27], v[48:63]
	v_mfma_f32_32x32x16_bf16 v[32:47], a[20:23], a[24:27], v[32:47]
	s_and_b32 m0, s32, 7
	s_lshl_b32 m0, m0, 12
	s_add_i32 m0, m0, 0xc00
	s_nop 0
	global_load_lds_dwordx4 v[164:165], off
	s_waitcnt lgkmcnt(4)
	v_mfma_f32_32x32x16_bf16 v[16:31], a[16:19], a[28:31], v[16:31]
	v_mfma_f32_32x32x16_bf16 v[0:15], a[20:23], a[28:31], v[0:15]
	s_and_b32 m0, s32, 7
	s_lshl_b32 m0, m0, 11
	s_add_i32 m0, m0, 0x8000
	s_nop 0
	global_load_lds_dwordx4 v[166:167], off
	s_nop 0
	s_nop 0
	s_nop 0
	s_nop 0
	ds_read_b128 a[16:19], v97
	ds_read_b128 a[20:23], v96
	ds_read_b128 a[24:27], v88 offset:49152
	ds_read_b128 a[28:31], v88 offset:53248
	s_waitcnt lgkmcnt(5)
	v_mfma_f32_32x32x16_bf16 v[48:63], a[0:3], a[8:11], v[48:63]
	v_mfma_f32_32x32x16_bf16 v[32:47], a[4:7], a[8:11], v[32:47]
	s_and_b32 m0, s32, 7
	s_lshl_b32 m0, m0, 11
	s_add_i32 m0, m0, 0x8400
	s_nop 0
	global_load_lds_dwordx4 v[168:169], off
	s_waitcnt lgkmcnt(4)
	v_mfma_f32_32x32x16_bf16 v[16:31], a[0:3], a[12:15], v[16:31]
	v_mfma_f32_32x32x16_bf16 v[0:15], a[4:7], a[12:15], v[0:15]
	s_nop 0
	s_nop 0
	s_nop 0
	s_nop 0
	s_waitcnt lgkmcnt(1)
	v_mfma_f32_32x32x16_bf16 v[48:63], a[16:19], a[24:27], v[48:63]
	v_mfma_f32_32x32x16_bf16 v[32:47], a[20:23], a[24:27], v[32:47]
	s_waitcnt vmcnt(6)
	s_waitcnt lgkmcnt(0)
	s_barrier
	ds_read_b128 a[12:15], v101
	ds_read_b128 a[8:11], v100
	ds_read_b128 a[4:7], v99
	ds_read_b128 a[0:3], v98
	v_mfma_f32_32x32x16_bf16 v[16:31], a[16:19], a[28:31], v[16:31]
	v_lshl_add_u64 v[170:171], v[66:67], 0, s[30:31]
	s_nop 0
	v_lshl_add_u64 v[172:173], v[68:69], 0, s[30:31]
	s_nop 0
	s_nop 0
	s_nop 0
	s_nop 0
	v_mfma_f32_32x32x16_bf16 v[0:15], a[20:23], a[28:31], v[0:15]
	s_and_b32 m0, s32, 7
	s_lshl_b32 m0, m0, 12
	s_add_i32 m0, m0, 0xc000
	s_nop 0
	global_load_lds_dwordx4 v[170:171], off
	s_nop 0
	v_lshl_add_u64 v[176:177], v[72:73], 0, s[30:31]
	s_nop 0
	s_nop 0
	s_nop 0
	v_lshl_add_u64 v[178:179], v[74:75], 0, s[30:31]
	s_nop 0
	s_nop 0
	s_nop 0
	v_lshl_add_u64 v[180:181], v[76:77], 0, s[30:31]
	s_nop 0
	s_mov_b64 s[30:31], 0x580
	s_nop 0
	s_nop 0
	s_nop 0
	s_nop 0
	s_nop 0
	ds_read_b128 a[16:19], v102
	ds_read_b128 a[20:23], v103
	ds_read_b128 a[24:27], v104
	ds_read_b128 a[28:31], v105
	s_waitcnt lgkmcnt(4)
	v_mfma_f32_32x32x16_bf16 v[48:63], a[0:3], a[8:11], v[48:63]
	s_nop 0
	v_lshl_add_u64 v[162:163], v[70:71], 0, s[30:31]
	v_mfma_f32_32x32x16_bf16 v[32:47], a[4:7], a[8:11], v[32:47]
	s_and_b32 m0, s32, 7
	s_lshl_b32 m0, m0, 12
	s_add_i32 m0, m0, 0xc400
	s_nop 0
	global_load_lds_dwordx4 v[172:173], off
	v_mfma_f32_32x32x16_bf16 v[16:31], a[0:3], a[12:15], v[16:31]
	v_mfma_f32_32x32x16_bf16 v[0:15], a[4:7], a[12:15], v[0:15]
	s_and_b32 m0, s32, 7
	s_lshl_b32 m0, m0, 12
	s_add_i32 m0, m0, 0xc800
	s_nop 0
	global_load_lds_dwordx4 v[174:175], off
	s_nop 0
	s_nop 0
	s_nop 0
	s_nop 0
	ds_read_b128 a[0:3], v106
	ds_read_b128 a[4:7], v107
	ds_read_b128 a[8:11], v108
	ds_read_b128 a[12:15], v109
	s_waitcnt lgkmcnt(5)
	v_mfma_f32_32x32x16_bf16 v[48:63], a[16:19], a[24:27], v[48:63]
	v_mfma_f32_32x32x16_bf16 v[32:47], a[20:23], a[24:27], v[32:47]
	s_and_b32 m0, s32, 7
	s_lshl_b32 m0, m0, 12
	s_add_i32 m0, m0, 0xcc00
	s_nop 0
	global_load_lds_dwordx4 v[176:177], off
	s_waitcnt lgkmcnt(4)
	v_mfma_f32_32x32x16_bf16 v[16:31], a[16:19], a[28:31], v[16:31]
	v_mfma_f32_32x32x16_bf16 v[0:15], a[20:23], a[28:31], v[0:15]
	s_and_b32 m0, s32, 7
	s_lshl_b32 m0, m0, 11
	s_add_i32 m0, m0, 0x14000
	s_nop 0
	global_load_lds_dwordx4 v[178:179], off
	s_nop 0
	s_nop 0
	s_nop 0
	s_nop 0
	ds_read_b128 a[16:19], v110
	ds_read_b128 a[20:23], v111
	ds_read_b128 a[24:27], v112
	ds_read_b128 a[28:31], v113
	s_waitcnt lgkmcnt(5)
	v_mfma_f32_32x32x16_bf16 v[48:63], a[0:3], a[8:11], v[48:63]
	v_mfma_f32_32x32x16_bf16 v[32:47], a[4:7], a[8:11], v[32:47]
	s_and_b32 m0, s32, 7
	s_lshl_b32 m0, m0, 11
	s_add_i32 m0, m0, 0x14400
	s_nop 0
	global_load_lds_dwordx4 v[180:181], off
	s_waitcnt lgkmcnt(4)
	v_mfma_f32_32x32x16_bf16 v[16:31], a[0:3], a[12:15], v[16:31]
	v_mfma_f32_32x32x16_bf16 v[0:15], a[4:7], a[12:15], v[0:15]
	s_nop 0
	s_nop 0
	s_nop 0
	s_nop 0
	s_waitcnt lgkmcnt(1)
	v_mfma_f32_32x32x16_bf16 v[48:63], a[16:19], a[24:27], v[48:63]
	v_mfma_f32_32x32x16_bf16 v[32:47], a[20:23], a[24:27], v[32:47]
	s_waitcnt vmcnt(6)
	s_waitcnt lgkmcnt(0)
	s_barrier
	ds_read_b128 a[12:15], v82 offset:4096
	ds_read_b128 a[8:11], v82
	ds_read_b128 a[4:7], v83 offset:36864
	ds_read_b128 a[0:3], v83 offset:32768
	v_mfma_f32_32x32x16_bf16 v[16:31], a[16:19], a[28:31], v[16:31]
	v_lshl_add_u64 v[158:159], v[66:67], 0, s[30:31]
	s_nop 0
	v_lshl_add_u64 v[160:161], v[68:69], 0, s[30:31]
	s_nop 0
	s_nop 0
	s_nop 0
	s_nop 0
	v_mfma_f32_32x32x16_bf16 v[0:15], a[20:23], a[28:31], v[0:15]
	s_and_b32 m0, s32, 7
	s_lshl_b32 m0, m0, 12
	s_add_i32 m0, m0, 0x18000
	s_nop 0
	global_load_lds_dwordx4 v[158:159], off
	s_nop 0
	v_lshl_add_u64 v[164:165], v[72:73], 0, s[30:31]
	s_nop 0
	s_nop 0
	s_nop 0
	v_lshl_add_u64 v[166:167], v[74:75], 0, s[30:31]
	s_nop 0
	s_nop 0
	s_nop 0
	v_lshl_add_u64 v[168:169], v[76:77], 0, s[30:31]
	s_nop 0
	s_mov_b64 s[30:31], 0x600
	s_nop 0
	s_nop 0
	s_nop 0
	s_nop 0
	s_nop 0
	ds_read_b128 a[16:19], v85 offset:32768
	ds_read_b128 a[20:23], v85 offset:36864
	ds_read_b128 a[24:27], v84
	ds_read_b128 a[28:31], v84 offset:4096
	s_waitcnt lgkmcnt(4)
	v_mfma_f32_32x32x16_bf16 v[48:63], a[0:3], a[8:11], v[48:63]
	s_nop 0
	v_mfma_f32_32x32x16_bf16 v[32:47], a[4:7], a[8:11], v[32:47]
	s_and_b32 m0, s32, 7
	s_lshl_b32 m0, m0, 12
	s_add_i32 m0, m0, 0x18400
	s_nop 0
	global_load_lds_dwordx4 v[160:161], off
	v_mfma_f32_32x32x16_bf16 v[16:31], a[0:3], a[12:15], v[16:31]
	v_mfma_f32_32x32x16_bf16 v[0:15], a[4:7], a[12:15], v[0:15]
	s_and_b32 m0, s32, 7
	s_lshl_b32 m0, m0, 12
	s_add_i32 m0, m0, 0x18800
	s_nop 0
	global_load_lds_dwordx4 v[162:163], off
	s_nop 0
	s_nop 0
	s_nop 0
	s_nop 0
	ds_read_b128 a[0:3], v87 offset:32768
	ds_read_b128 a[4:7], v87 offset:36864
	ds_read_b128 a[8:11], v86
	ds_read_b128 a[12:15], v86 offset:4096
	s_waitcnt lgkmcnt(5)
	v_mfma_f32_32x32x16_bf16 v[48:63], a[16:19], a[24:27], v[48:63]
	v_mfma_f32_32x32x16_bf16 v[32:47], a[20:23], a[24:27], v[32:47]
	s_and_b32 m0, s32, 7
	s_lshl_b32 m0, m0, 12
	s_add_i32 m0, m0, 0x18c00
	s_nop 0
	global_load_lds_dwordx4 v[164:165], off
	s_waitcnt lgkmcnt(4)
	v_mfma_f32_32x32x16_bf16 v[16:31], a[16:19], a[28:31], v[16:31]
	v_mfma_f32_32x32x16_bf16 v[0:15], a[20:23], a[28:31], v[0:15]
	s_and_b32 m0, s32, 7
	s_lshl_b32 m0, m0, 11
	s_add_i32 m0, m0, 0x20000
	s_nop 0
	global_load_lds_dwordx4 v[166:167], off
	s_nop 0
	s_nop 0
	s_nop 0
	s_nop 0
	ds_read_b128 a[16:19], v89 offset:32768
	ds_read_b128 a[20:23], v89 offset:36864
	ds_read_b128 a[24:27], v88
	ds_read_b128 a[28:31], v88 offset:4096
	s_waitcnt lgkmcnt(5)
	v_mfma_f32_32x32x16_bf16 v[48:63], a[0:3], a[8:11], v[48:63]
	v_mfma_f32_32x32x16_bf16 v[32:47], a[4:7], a[8:11], v[32:47]
	s_and_b32 m0, s32, 7
	s_lshl_b32 m0, m0, 11
	s_add_i32 m0, m0, 0x20400
	s_nop 0
	global_load_lds_dwordx4 v[168:169], off
	s_waitcnt lgkmcnt(4)
	v_mfma_f32_32x32x16_bf16 v[16:31], a[0:3], a[12:15], v[16:31]
	v_mfma_f32_32x32x16_bf16 v[0:15], a[4:7], a[12:15], v[0:15]
	s_nop 0
	s_nop 0
	s_nop 0
	s_nop 0
	s_waitcnt lgkmcnt(1)
	v_mfma_f32_32x32x16_bf16 v[48:63], a[16:19], a[24:27], v[48:63]
	v_mfma_f32_32x32x16_bf16 v[32:47], a[20:23], a[24:27], v[32:47]
	s_waitcnt vmcnt(6)
	s_waitcnt lgkmcnt(0)
	s_barrier
	ds_read_b128 a[12:15], v82 offset:53248
	ds_read_b128 a[8:11], v82 offset:49152
	ds_read_b128 a[4:7], v90
	ds_read_b128 a[0:3], v92
	v_mfma_f32_32x32x16_bf16 v[16:31], a[16:19], a[28:31], v[16:31]
	v_lshl_add_u64 v[170:171], v[66:67], 0, s[30:31]
	s_nop 0
	v_lshl_add_u64 v[172:173], v[68:69], 0, s[30:31]
	s_nop 0
	s_nop 0
	s_nop 0
	v_lshl_add_u64 v[174:175], v[70:71], 0, s[30:31]
	s_nop 0
	v_mfma_f32_32x32x16_bf16 v[0:15], a[20:23], a[28:31], v[0:15]
	s_and_b32 m0, s32, 7
	s_lshl_b32 m0, m0, 12
	s_add_i32 m0, m0, 0x0
	s_nop 0
	global_load_lds_dwordx4 v[170:171], off
	s_nop 0
	v_lshl_add_u64 v[176:177], v[72:73], 0, s[30:31]
	s_nop 0
	s_nop 0
	s_nop 0
	v_lshl_add_u64 v[178:179], v[74:75], 0, s[30:31]
	s_nop 0
	s_nop 0
	s_nop 0
	v_lshl_add_u64 v[180:181], v[76:77], 0, s[30:31]
	s_nop 0
	s_mov_b64 s[30:31], 0x680
	s_nop 0
	s_nop 0
	s_nop 0
	s_nop 0
	s_nop 0
	ds_read_b128 a[16:19], v93
	ds_read_b128 a[20:23], v91
	ds_read_b128 a[24:27], v84 offset:49152
	ds_read_b128 a[28:31], v84 offset:53248
	s_waitcnt lgkmcnt(4)
	v_mfma_f32_32x32x16_bf16 v[48:63], a[0:3], a[8:11], v[48:63]
	s_nop 0
	v_mfma_f32_32x32x16_bf16 v[32:47], a[4:7], a[8:11], v[32:47]
	s_and_b32 m0, s32, 7
	s_lshl_b32 m0, m0, 12
	s_add_i32 m0, m0, 0x400
	s_nop 0
	global_load_lds_dwordx4 v[172:173], off
	v_mfma_f32_32x32x16_bf16 v[16:31], a[0:3], a[12:15], v[16:31]
	v_mfma_f32_32x32x16_bf16 v[0:15], a[4:7], a[12:15], v[0:15]
	s_and_b32 m0, s32, 7
	s_lshl_b32 m0, m0, 12
	s_add_i32 m0, m0, 0x800
	s_nop 0
	global_load_lds_dwordx4 v[174:175], off
	s_nop 0
	s_nop 0
	s_nop 0
	s_nop 0
	ds_read_b128 a[0:3], v95
	ds_read_b128 a[4:7], v94
	ds_read_b128 a[8:11], v86 offset:49152
	ds_read_b128 a[12:15], v86 offset:53248
	s_waitcnt lgkmcnt(5)
	v_mfma_f32_32x32x16_bf16 v[48:63], a[16:19], a[24:27], v[48:63]
	v_mfma_f32_32x32x16_bf16 v[32:47], a[20:23], a[24:27], v[32:47]
	s_and_b32 m0, s32, 7
	s_lshl_b32 m0, m0, 12
	s_add_i32 m0, m0, 0xc00
	s_nop 0
	global_load_lds_dwordx4 v[176:177], off
	s_waitcnt lgkmcnt(4)
	v_mfma_f32_32x32x16_bf16 v[16:31], a[16:19], a[28:31], v[16:31]
	v_mfma_f32_32x32x16_bf16 v[0:15], a[20:23], a[28:31], v[0:15]
	s_and_b32 m0, s32, 7
	s_lshl_b32 m0, m0, 11
	s_add_i32 m0, m0, 0x8000
	s_nop 0
	global_load_lds_dwordx4 v[178:179], off
	s_nop 0
	s_nop 0
	s_nop 0
	s_nop 0
	ds_read_b128 a[16:19], v97
	ds_read_b128 a[20:23], v96
	ds_read_b128 a[24:27], v88 offset:49152
	ds_read_b128 a[28:31], v88 offset:53248
	s_waitcnt lgkmcnt(5)
	v_mfma_f32_32x32x16_bf16 v[48:63], a[0:3], a[8:11], v[48:63]
	v_mfma_f32_32x32x16_bf16 v[32:47], a[4:7], a[8:11], v[32:47]
	s_and_b32 m0, s32, 7
	s_lshl_b32 m0, m0, 11
	s_add_i32 m0, m0, 0x8400
	s_nop 0
	global_load_lds_dwordx4 v[180:181], off
	s_waitcnt lgkmcnt(4)
	v_mfma_f32_32x32x16_bf16 v[16:31], a[0:3], a[12:15], v[16:31]
	v_mfma_f32_32x32x16_bf16 v[0:15], a[4:7], a[12:15], v[0:15]
	s_nop 0
	s_nop 0
	s_nop 0
	s_nop 0
	s_waitcnt lgkmcnt(1)
	v_mfma_f32_32x32x16_bf16 v[48:63], a[16:19], a[24:27], v[48:63]
	v_mfma_f32_32x32x16_bf16 v[32:47], a[20:23], a[24:27], v[32:47]
	s_waitcnt vmcnt(6)
	s_waitcnt lgkmcnt(0)
	s_barrier
	ds_read_b128 a[12:15], v101
	ds_read_b128 a[8:11], v100
	ds_read_b128 a[4:7], v99
	ds_read_b128 a[0:3], v98
	v_mfma_f32_32x32x16_bf16 v[16:31], a[16:19], a[28:31], v[16:31]
	v_lshl_add_u64 v[158:159], v[66:67], 0, s[30:31]
	s_nop 0
	v_lshl_add_u64 v[160:161], v[68:69], 0, s[30:31]
	s_nop 0
	s_nop 0
	s_nop 0
	v_lshl_add_u64 v[162:163], v[70:71], 0, s[30:31]
	s_nop 0
	v_mfma_f32_32x32x16_bf16 v[0:15], a[20:23], a[28:31], v[0:15]
	s_and_b32 m0, s32, 7
	s_lshl_b32 m0, m0, 12
	s_add_i32 m0, m0, 0xc000
	s_nop 0
	global_load_lds_dwordx4 v[158:159], off
	s_nop 0
	v_lshl_add_u64 v[164:165], v[72:73], 0, s[30:31]
	s_nop 0
	s_nop 0
	s_nop 0
	v_lshl_add_u64 v[166:167], v[74:75], 0, s[30:31]
	s_nop 0
	s_nop 0
	s_nop 0
	v_lshl_add_u64 v[168:169], v[76:77], 0, s[30:31]
	s_nop 0
	s_mov_b64 s[30:31], 0x700
	s_nop 0
	s_nop 0
	s_nop 0
	s_nop 0
	s_nop 0
	ds_read_b128 a[16:19], v102
	ds_read_b128 a[20:23], v103
	ds_read_b128 a[24:27], v104
	ds_read_b128 a[28:31], v105
	s_waitcnt lgkmcnt(4)
	v_mfma_f32_32x32x16_bf16 v[48:63], a[0:3], a[8:11], v[48:63]
	s_nop 0
	v_mfma_f32_32x32x16_bf16 v[32:47], a[4:7], a[8:11], v[32:47]
	s_and_b32 m0, s32, 7
	s_lshl_b32 m0, m0, 12
	s_add_i32 m0, m0, 0xc400
	s_nop 0
	global_load_lds_dwordx4 v[160:161], off
	v_mfma_f32_32x32x16_bf16 v[16:31], a[0:3], a[12:15], v[16:31]
	v_mfma_f32_32x32x16_bf16 v[0:15], a[4:7], a[12:15], v[0:15]
	s_and_b32 m0, s32, 7
	s_lshl_b32 m0, m0, 12
	s_add_i32 m0, m0, 0xc800
	s_nop 0
	global_load_lds_dwordx4 v[162:163], off
	s_nop 0
	s_nop 0
	s_nop 0
	s_nop 0
	ds_read_b128 a[0:3], v106
	ds_read_b128 a[4:7], v107
	ds_read_b128 a[8:11], v108
	ds_read_b128 a[12:15], v109
	s_waitcnt lgkmcnt(5)
	v_mfma_f32_32x32x16_bf16 v[48:63], a[16:19], a[24:27], v[48:63]
	v_mfma_f32_32x32x16_bf16 v[32:47], a[20:23], a[24:27], v[32:47]
	s_and_b32 m0, s32, 7
	s_lshl_b32 m0, m0, 12
	s_add_i32 m0, m0, 0xcc00
	s_nop 0
	global_load_lds_dwordx4 v[164:165], off
	s_waitcnt lgkmcnt(4)
	v_mfma_f32_32x32x16_bf16 v[16:31], a[16:19], a[28:31], v[16:31]
	v_mfma_f32_32x32x16_bf16 v[0:15], a[20:23], a[28:31], v[0:15]
	s_and_b32 m0, s32, 7
	s_lshl_b32 m0, m0, 11
	s_add_i32 m0, m0, 0x14000
	s_nop 0
	global_load_lds_dwordx4 v[166:167], off
	s_nop 0
	s_nop 0
	s_nop 0
	s_nop 0
	ds_read_b128 a[16:19], v110
	ds_read_b128 a[20:23], v111
	ds_read_b128 a[24:27], v112
	ds_read_b128 a[28:31], v113
	s_waitcnt lgkmcnt(5)
	v_mfma_f32_32x32x16_bf16 v[48:63], a[0:3], a[8:11], v[48:63]
	v_mfma_f32_32x32x16_bf16 v[32:47], a[4:7], a[8:11], v[32:47]
	s_and_b32 m0, s32, 7
	s_lshl_b32 m0, m0, 11
	s_add_i32 m0, m0, 0x14400
	s_nop 0
	global_load_lds_dwordx4 v[168:169], off
	s_waitcnt lgkmcnt(4)
	v_mfma_f32_32x32x16_bf16 v[16:31], a[0:3], a[12:15], v[16:31]
	v_mfma_f32_32x32x16_bf16 v[0:15], a[4:7], a[12:15], v[0:15]
	s_nop 0
	s_nop 0
	s_nop 0
	s_nop 0
	s_waitcnt lgkmcnt(1)
	v_mfma_f32_32x32x16_bf16 v[48:63], a[16:19], a[24:27], v[48:63]
	v_mfma_f32_32x32x16_bf16 v[32:47], a[20:23], a[24:27], v[32:47]
	s_waitcnt vmcnt(6)
	s_waitcnt lgkmcnt(0)
	s_barrier
	ds_read_b128 a[12:15], v82 offset:4096
	ds_read_b128 a[8:11], v82
	ds_read_b128 a[4:7], v83 offset:36864
	ds_read_b128 a[0:3], v83 offset:32768
	v_mfma_f32_32x32x16_bf16 v[16:31], a[16:19], a[28:31], v[16:31]
	v_lshl_add_u64 v[170:171], v[66:67], 0, s[30:31]
	s_nop 0
	v_lshl_add_u64 v[172:173], v[68:69], 0, s[30:31]
	s_nop 0
	s_nop 0
	s_nop 0
	v_lshl_add_u64 v[174:175], v[70:71], 0, s[30:31]
	s_nop 0
	v_mfma_f32_32x32x16_bf16 v[0:15], a[20:23], a[28:31], v[0:15]
	s_and_b32 m0, s32, 7
	s_lshl_b32 m0, m0, 12
	s_add_i32 m0, m0, 0x18000
	s_nop 0
	global_load_lds_dwordx4 v[170:171], off
	s_nop 0
	v_lshl_add_u64 v[176:177], v[72:73], 0, s[30:31]
	s_nop 0
	s_nop 0
	s_nop 0
	v_lshl_add_u64 v[178:179], v[74:75], 0, s[30:31]
	s_nop 0
	s_nop 0
	s_nop 0
	v_lshl_add_u64 v[180:181], v[76:77], 0, s[30:31]
	s_nop 0
	s_mov_b64 s[30:31], 0x780
	s_nop 0
	s_nop 0
	s_nop 0
	s_nop 0
	s_nop 0
	ds_read_b128 a[16:19], v85 offset:32768
	ds_read_b128 a[20:23], v85 offset:36864
	ds_read_b128 a[24:27], v84
	ds_read_b128 a[28:31], v84 offset:4096
	s_waitcnt lgkmcnt(4)
	v_mfma_f32_32x32x16_bf16 v[48:63], a[0:3], a[8:11], v[48:63]
	v_lshl_add_u64 v[158:159], v[66:67], 0, s[30:31]
	s_nop 0
	v_mfma_f32_32x32x16_bf16 v[32:47], a[4:7], a[8:11], v[32:47]
	s_and_b32 m0, s32, 7
	s_lshl_b32 m0, m0, 12
	s_add_i32 m0, m0, 0x18400
	s_nop 0
	global_load_lds_dwordx4 v[172:173], off
	v_mfma_f32_32x32x16_bf16 v[16:31], a[0:3], a[12:15], v[16:31]
	v_mfma_f32_32x32x16_bf16 v[0:15], a[4:7], a[12:15], v[0:15]
	s_and_b32 m0, s32, 7
	s_lshl_b32 m0, m0, 12
	s_add_i32 m0, m0, 0x18800
	s_nop 0
	global_load_lds_dwordx4 v[174:175], off
	s_nop 0
	s_nop 0
	s_nop 0
	s_nop 0
	ds_read_b128 a[0:3], v87 offset:32768
	ds_read_b128 a[4:7], v87 offset:36864
	ds_read_b128 a[8:11], v86
	ds_read_b128 a[12:15], v86 offset:4096
	s_waitcnt lgkmcnt(5)
	v_mfma_f32_32x32x16_bf16 v[48:63], a[16:19], a[24:27], v[48:63]
	v_mfma_f32_32x32x16_bf16 v[32:47], a[20:23], a[24:27], v[32:47]
	s_and_b32 m0, s32, 7
	s_lshl_b32 m0, m0, 12
	s_add_i32 m0, m0, 0x18c00
	s_nop 0
	global_load_lds_dwordx4 v[176:177], off
	s_waitcnt lgkmcnt(4)
	v_mfma_f32_32x32x16_bf16 v[16:31], a[16:19], a[28:31], v[16:31]
	v_mfma_f32_32x32x16_bf16 v[0:15], a[20:23], a[28:31], v[0:15]
	s_and_b32 m0, s32, 7
	s_lshl_b32 m0, m0, 11
	s_add_i32 m0, m0, 0x20000
	s_nop 0
	global_load_lds_dwordx4 v[178:179], off
	s_nop 0
	s_nop 0
	s_nop 0
	s_nop 0
	ds_read_b128 a[16:19], v89 offset:32768
	ds_read_b128 a[20:23], v89 offset:36864
	ds_read_b128 a[24:27], v88
	ds_read_b128 a[28:31], v88 offset:4096
	s_waitcnt lgkmcnt(5)
	v_mfma_f32_32x32x16_bf16 v[48:63], a[0:3], a[8:11], v[48:63]
	v_mfma_f32_32x32x16_bf16 v[32:47], a[4:7], a[8:11], v[32:47]
	s_and_b32 m0, s32, 7
	s_lshl_b32 m0, m0, 11
	s_add_i32 m0, m0, 0x20400
	s_nop 0
	global_load_lds_dwordx4 v[180:181], off
	s_waitcnt lgkmcnt(4)
	v_mfma_f32_32x32x16_bf16 v[16:31], a[0:3], a[12:15], v[16:31]
	v_mfma_f32_32x32x16_bf16 v[0:15], a[4:7], a[12:15], v[0:15]
	s_nop 0
	s_nop 0
	s_nop 0
	s_nop 0
	s_waitcnt lgkmcnt(1)
	v_mfma_f32_32x32x16_bf16 v[48:63], a[16:19], a[24:27], v[48:63]
	v_mfma_f32_32x32x16_bf16 v[32:47], a[20:23], a[24:27], v[32:47]
	s_waitcnt vmcnt(6)
	s_waitcnt lgkmcnt(0)
	s_barrier
	ds_read_b128 a[12:15], v82 offset:53248
	ds_read_b128 a[8:11], v82 offset:49152
	ds_read_b128 a[4:7], v90
	ds_read_b128 a[0:3], v92
	s_nop 0
	v_lshl_add_u64 v[160:161], v[68:69], 0, s[30:31]
	s_nop 0
	v_mfma_f32_32x32x16_bf16 v[16:31], a[16:19], a[28:31], v[16:31]
	s_nop 0
	v_lshl_add_u64 v[162:163], v[70:71], 0, s[30:31]
	s_nop 0
	s_nop 0
	s_nop 0
	v_lshl_add_u64 v[164:165], v[72:73], 0, s[30:31]
	s_nop 0
	v_mfma_f32_32x32x16_bf16 v[0:15], a[20:23], a[28:31], v[0:15]
	s_and_b32 m0, s32, 7
	s_lshl_b32 m0, m0, 12
	s_add_i32 m0, m0, 0x0
	s_nop 0
	global_load_lds_dwordx4 v[158:159], off
	s_nop 0
	v_lshl_add_u64 v[166:167], v[74:75], 0, s[30:31]
	s_nop 0
	s_nop 0
	s_nop 0
	v_lshl_add_u64 v[168:169], v[76:77], 0, s[30:31]
	s_nop 0
	s_nop 0
	s_nop 0
	s_nop 0
	s_nop 0
	s_nop 0
	s_nop 0
	ds_read_b128 a[16:19], v93
	ds_read_b128 a[20:23], v91
	ds_read_b128 a[24:27], v84 offset:49152
	ds_read_b128 a[28:31], v84 offset:53248
	s_waitcnt lgkmcnt(4)
	v_mfma_f32_32x32x16_bf16 v[48:63], a[0:3], a[8:11], v[48:63]
	v_mfma_f32_32x32x16_bf16 v[32:47], a[4:7], a[8:11], v[32:47]
	s_and_b32 m0, s32, 7
	s_lshl_b32 m0, m0, 12
	s_add_i32 m0, m0, 0x400
	s_nop 0
	global_load_lds_dwordx4 v[160:161], off
	v_mfma_f32_32x32x16_bf16 v[16:31], a[0:3], a[12:15], v[16:31]
	v_mfma_f32_32x32x16_bf16 v[0:15], a[4:7], a[12:15], v[0:15]
	s_and_b32 m0, s32, 7
	s_lshl_b32 m0, m0, 12
	s_add_i32 m0, m0, 0x800
	s_nop 0
	global_load_lds_dwordx4 v[162:163], off
	s_nop 0
	s_nop 0
	s_nop 0
	s_nop 0
	ds_read_b128 a[0:3], v95
	ds_read_b128 a[4:7], v94
	ds_read_b128 a[8:11], v86 offset:49152
	ds_read_b128 a[12:15], v86 offset:53248
	s_waitcnt lgkmcnt(5)
	v_mfma_f32_32x32x16_bf16 v[48:63], a[16:19], a[24:27], v[48:63]
	v_mfma_f32_32x32x16_bf16 v[32:47], a[20:23], a[24:27], v[32:47]
	s_and_b32 m0, s32, 7
	s_lshl_b32 m0, m0, 12
	s_add_i32 m0, m0, 0xc00
	s_nop 0
	global_load_lds_dwordx4 v[164:165], off
	s_waitcnt lgkmcnt(4)
	v_mfma_f32_32x32x16_bf16 v[16:31], a[16:19], a[28:31], v[16:31]
	v_mfma_f32_32x32x16_bf16 v[0:15], a[20:23], a[28:31], v[0:15]
	s_and_b32 m0, s32, 7
	s_lshl_b32 m0, m0, 11
	s_add_i32 m0, m0, 0x8000
	s_nop 0
	global_load_lds_dwordx4 v[166:167], off
	s_nop 0
	s_nop 0
	s_nop 0
	s_nop 0
	ds_read_b128 a[16:19], v97
	ds_read_b128 a[20:23], v96
	ds_read_b128 a[24:27], v88 offset:49152
	ds_read_b128 a[28:31], v88 offset:53248
	s_waitcnt lgkmcnt(5)
	v_mfma_f32_32x32x16_bf16 v[48:63], a[0:3], a[8:11], v[48:63]
	v_mfma_f32_32x32x16_bf16 v[32:47], a[4:7], a[8:11], v[32:47]
	s_and_b32 m0, s32, 7
	s_lshl_b32 m0, m0, 11
	s_add_i32 m0, m0, 0x8400
	s_nop 0
	global_load_lds_dwordx4 v[168:169], off
	s_waitcnt lgkmcnt(4)
	v_mfma_f32_32x32x16_bf16 v[16:31], a[0:3], a[12:15], v[16:31]
	v_mfma_f32_32x32x16_bf16 v[0:15], a[4:7], a[12:15], v[0:15]
	s_nop 0
	s_nop 0
	s_nop 0
	s_nop 0
	s_waitcnt lgkmcnt(1)
	v_mfma_f32_32x32x16_bf16 v[48:63], a[16:19], a[24:27], v[48:63]
	v_mfma_f32_32x32x16_bf16 v[32:47], a[20:23], a[24:27], v[32:47]
	s_waitcnt vmcnt(6)
	s_waitcnt lgkmcnt(0)
	s_barrier
	ds_read_b128 a[12:15], v101
	ds_read_b128 a[8:11], v100
	ds_read_b128 a[4:7], v99
	ds_read_b128 a[0:3], v98
	v_mfma_f32_32x32x16_bf16 v[16:31], a[16:19], a[28:31], v[16:31]
	v_mfma_f32_32x32x16_bf16 v[0:15], a[20:23], a[28:31], v[0:15]
	s_nop 0
	s_nop 0
	s_nop 0
	s_nop 0
	ds_read_b128 a[16:19], v102
	ds_read_b128 a[20:23], v103
	ds_read_b128 a[24:27], v104
	ds_read_b128 a[28:31], v105
	s_waitcnt lgkmcnt(4)
	v_mfma_f32_32x32x16_bf16 v[48:63], a[0:3], a[8:11], v[48:63]
	v_mfma_f32_32x32x16_bf16 v[32:47], a[4:7], a[8:11], v[32:47]
	v_mfma_f32_32x32x16_bf16 v[16:31], a[0:3], a[12:15], v[16:31]
	v_mfma_f32_32x32x16_bf16 v[0:15], a[4:7], a[12:15], v[0:15]
	s_nop 0
	s_nop 0
	s_nop 0
	s_nop 0
	ds_read_b128 a[0:3], v106
	ds_read_b128 a[4:7], v107
	ds_read_b128 a[8:11], v108
	ds_read_b128 a[12:15], v109
	s_waitcnt lgkmcnt(5)
	v_mfma_f32_32x32x16_bf16 v[48:63], a[16:19], a[24:27], v[48:63]
	v_mfma_f32_32x32x16_bf16 v[32:47], a[20:23], a[24:27], v[32:47]
	s_waitcnt lgkmcnt(4)
	v_mfma_f32_32x32x16_bf16 v[16:31], a[16:19], a[28:31], v[16:31]
	v_mfma_f32_32x32x16_bf16 v[0:15], a[20:23], a[28:31], v[0:15]
	s_nop 0
	s_nop 0
	s_nop 0
	s_nop 0
	ds_read_b128 a[16:19], v110
	ds_read_b128 a[20:23], v111
	ds_read_b128 a[24:27], v112
	ds_read_b128 a[28:31], v113
	s_waitcnt lgkmcnt(5)
	v_mfma_f32_32x32x16_bf16 v[48:63], a[0:3], a[8:11], v[48:63]
	v_mfma_f32_32x32x16_bf16 v[32:47], a[4:7], a[8:11], v[32:47]
	s_waitcnt lgkmcnt(4)
	v_mfma_f32_32x32x16_bf16 v[16:31], a[0:3], a[12:15], v[16:31]
	v_mfma_f32_32x32x16_bf16 v[0:15], a[4:7], a[12:15], v[0:15]
	s_nop 0
	s_nop 0
	s_nop 0
	s_nop 0
	s_waitcnt lgkmcnt(1)
	v_mfma_f32_32x32x16_bf16 v[48:63], a[16:19], a[24:27], v[48:63]
	v_mfma_f32_32x32x16_bf16 v[32:47], a[20:23], a[24:27], v[32:47]
	s_waitcnt vmcnt(0)
	s_waitcnt lgkmcnt(0)
	s_barrier
	ds_read_b128 a[12:15], v82 offset:4096
	ds_read_b128 a[8:11], v82
	ds_read_b128 a[4:7], v83 offset:36864
	ds_read_b128 a[0:3], v83 offset:32768
	v_mfma_f32_32x32x16_bf16 v[16:31], a[16:19], a[28:31], v[16:31]
	v_mfma_f32_32x32x16_bf16 v[0:15], a[20:23], a[28:31], v[0:15]
	s_nop 0
	s_nop 0
	s_nop 0
	s_nop 0
	ds_read_b128 a[16:19], v85 offset:32768
	ds_read_b128 a[20:23], v85 offset:36864
	ds_read_b128 a[24:27], v84
	ds_read_b128 a[28:31], v84 offset:4096
	s_waitcnt lgkmcnt(4)
	v_mfma_f32_32x32x16_bf16 v[48:63], a[0:3], a[8:11], v[48:63]
	v_mfma_f32_32x32x16_bf16 v[32:47], a[4:7], a[8:11], v[32:47]
	v_mfma_f32_32x32x16_bf16 v[16:31], a[0:3], a[12:15], v[16:31]
	v_mfma_f32_32x32x16_bf16 v[0:15], a[4:7], a[12:15], v[0:15]
	s_nop 0
	s_nop 0
	s_nop 0
	s_nop 0
	ds_read_b128 a[0:3], v87 offset:32768
	ds_read_b128 a[4:7], v87 offset:36864
	ds_read_b128 a[8:11], v86
	ds_read_b128 a[12:15], v86 offset:4096
	s_waitcnt lgkmcnt(5)
	v_mfma_f32_32x32x16_bf16 v[48:63], a[16:19], a[24:27], v[48:63]
	v_mfma_f32_32x32x16_bf16 v[32:47], a[20:23], a[24:27], v[32:47]
	s_waitcnt lgkmcnt(4)
	v_mfma_f32_32x32x16_bf16 v[16:31], a[16:19], a[28:31], v[16:31]
	v_mfma_f32_32x32x16_bf16 v[0:15], a[20:23], a[28:31], v[0:15]
	s_nop 0
	s_nop 0
	s_nop 0
	s_nop 0
	s_waitcnt lgkmcnt(1)
	v_mfma_f32_32x32x16_bf16 v[48:63], a[0:3], a[8:11], v[48:63]
	v_mfma_f32_32x32x16_bf16 v[32:47], a[4:7], a[8:11], v[32:47]
	s_waitcnt lgkmcnt(0)
	v_mfma_f32_32x32x16_bf16 v[16:31], a[0:3], a[12:15], v[16:31]
	v_mfma_f32_32x32x16_bf16 v[0:15], a[4:7], a[12:15], v[0:15]
	ds_read_b128 v[66:69], v89 offset:32768
	ds_read_b128 v[70:73], v88
	ds_read_b128 v[74:77], v89 offset:36864
	ds_read_b128 v[82:85], v88 offset:4096
	s_waitcnt lgkmcnt(0)
	s_barrier
	s_waitcnt lgkmcnt(0)
	v_mfma_f32_32x32x16_bf16 v[48:63], v[66:69], v[70:73], v[48:63]
	v_mfma_f32_32x32x16_bf16 v[32:47], v[74:77], v[70:73], v[32:47]
	v_mov_b32_e32 v70, 0
	v_mfma_f32_32x32x16_bf16 v[16:31], v[66:69], v[82:85], v[16:31]
	v_lshl_or_b32 v69, v80, 6, v81
	v_add_u32_e32 v66, s20, v69
	v_cmp_gt_i32_e32 vcc, s69, v66
	v_mov_b32_e32 v68, 0
	v_ashrrev_i32_e32 v67, 31, v66
	v_mfma_f32_32x32x16_bf16 v[0:15], v[74:77], v[82:85], v[0:15]
	s_and_saveexec_b64 s[0:1], vcc
	s_cbranch_execz .LBB0_588
	v_lshl_add_u64 v[70:71], v[66:67], 2, s[76:77]
	global_load_dword v70, v[70:71], off
	s_waitcnt vmcnt(0)
	v_fmamk_f32 v70, v70, 0x3a800000, v188
	v_mul_f32_e32 v71, 0x4b800000, v70
	v_cmp_gt_f32_e32 vcc, s82, v70
	s_nop 1
	v_cndmask_b32_e32 v70, v70, v71, vcc
	v_rsq_f32_e32 v70, v70
	s_nop 0
	v_mul_f32_e32 v71, 0x45800000, v70
	v_cndmask_b32_e32 v70, v70, v71, vcc

.LBB0_612:
	v_readlane_b32 s0, v212, 1
	s_cmp_ge_i32 s56, s0
	s_mov_b64 s[0:1], -1
	s_cbranch_scc0 .LBB0_742
	s_ashr_i32 s1, s52, 31
	s_lshr_b32 s0, s1, 27
	s_add_i32 s2, s52, s0
	s_ashr_i32 s0, s2, 5
	s_and_b32 s2, s2, 0xffe0
	s_sub_i32 s2, s52, s2
	s_lshr_b32 s1, s1, 30
	s_bfe_i32 s20, s2, 0x80000
	s_add_i32 s1, s52, s1
	s_bfe_u32 s20, s20, 0x2000d
	s_and_b32 s1, s1, 0x1fffffc
	s_add_i32 s2, s2, s20
	s_sub_i32 s23, s52, s1
	s_ashr_i32 s1, s0, 31
	s_bfe_i32 s2, s2, 0x80000
	s_lshl_b64 s[20:21], s[0:1], 20
	v_readlane_b32 s22, v215, 46
	s_sext_i32_i16 s2, s2
	s_add_u32 s20, s22, s20
	v_readlane_b32 s22, v215, 47
	v_mov_b32_e32 v12, v133
	s_addc_u32 s21, s22, s21
	s_lshl_b32 s2, s2, 6
	s_and_b32 s22, s2, 0xffffff00
	v_ashrrev_i32_e32 v6, 6, v12
	v_bfe_u32 v7, v12, 3, 3
	v_lshl_or_b32 v8, v6, 5, v7
	v_add_u32_e32 v0, s22, v8
	s_waitcnt lgkmcnt(0)
	v_ashrrev_i32_e32 v1, 31, v0
	v_lshlrev_b64 v[2:3], 11, v[0:1]
	v_bfe_u32 v1, v12, 4, 2
	v_readlane_b32 s28, v215, 50
	v_xor_b32_e32 v1, v1, v12
	v_readlane_b32 s29, v215, 51
	v_lshlrev_b32_e32 v1, 4, v1
	v_and_b32_e32 v64, 0x70, v1
	v_lshl_add_u64 v[2:3], s[28:29], 0, v[2:3]
	v_or_b32_e32 v1, 8, v8
	v_lshl_add_u64 v[66:67], v[2:3], 0, v[64:65]
	v_add_u32_e32 v2, s22, v1
	v_lshrrev_b32_e32 v1, 1, v1
	v_xor_b32_e32 v1, v1, v12
	v_ashrrev_i32_e32 v3, 31, v2
	v_lshlrev_b32_e32 v1, 4, v1
	v_or_b32_e32 v0, 16, v0
	v_lshlrev_b64 v[2:3], 11, v[2:3]
	v_and_b32_e32 v4, 0x70, v1
	v_ashrrev_i32_e32 v1, 31, v0
	v_lshl_add_u64 v[2:3], s[28:29], 0, v[2:3]
	v_mov_b32_e32 v5, v65
	v_lshlrev_b64 v[0:1], 11, v[0:1]
	v_lshl_add_u64 v[68:69], v[2:3], 0, v[4:5]
	v_lshl_add_u64 v[0:1], s[28:29], 0, v[0:1]
	v_or_b32_e32 v2, 24, v8
	v_lshl_add_u64 v[70:71], v[0:1], 0, v[64:65]
	v_add_u32_e32 v0, s22, v2
	v_lshrrev_b32_e32 v2, 1, v2
	v_ashrrev_i32_e32 v1, 31, v0
	v_xor_b32_e32 v2, v2, v12
	v_lshlrev_b64 v[0:1], 11, v[0:1]
	v_lshlrev_b32_e32 v2, 4, v2
	v_lshl_add_u64 v[0:1], s[28:29], 0, v[0:1]
	v_and_b32_e32 v2, 0x70, v2
	v_mov_b32_e32 v3, v65
	s_lshl_b32 s2, s23, 7
	v_lshl_add_u64 v[72:73], v[0:1], 0, v[2:3]
	v_lshl_or_b32 v2, v6, 4, v7
	v_add_u32_e32 v0, s2, v2
	v_lshlrev_b32_e32 v3, 12, v6
	v_ashrrev_i32_e32 v1, 31, v0
	v_add_u32_e32 v125, 0, v3
	v_lshlrev_b64 v[0:1], 11, v[0:1]
	s_waitcnt vmcnt(0)
	v_readfirstlane_b32 s42, v125
	v_add_u32_e32 v126, 0x400, v125
	v_lshl_add_u64 v[0:1], s[20:21], 0, v[0:1]
	v_or_b32_e32 v2, 8, v2
	s_waitcnt lgkmcnt(0)
	s_barrier
	s_mov_b32 m0, s42
	v_readfirstlane_b32 s43, v126
	v_add_u32_e32 v127, 0x800, v125
	v_lshlrev_b32_e32 v5, 11, v6
	v_and_b32_e32 v79, 1, v6
	v_lshl_add_u64 v[74:75], v[0:1], 0, v[64:65]
	v_add_u32_e32 v0, s2, v2
	v_lshrrev_b32_e32 v2, 1, v2
	global_load_lds_dwordx4 v[66:67], off
	s_mov_b32 m0, s43
	v_readfirstlane_b32 s44, v127
	v_add_u32_e32 v128, 0xc00, v125
	v_add_u32_e32 v6, 0, v5
	v_ashrrev_i32_e32 v1, 31, v0
	v_xor_b32_e32 v2, v2, v12
	global_load_lds_dwordx4 v[68:69], off
	s_mov_b32 m0, s44
	v_readfirstlane_b32 s45, v128
	v_add_u32_e32 v130, 0x8000, v6
	v_lshlrev_b64 v[0:1], 11, v[0:1]
	v_lshlrev_b32_e32 v2, 4, v2
	global_load_lds_dwordx4 v[70:71], off
	s_mov_b32 m0, s45
	v_readfirstlane_b32 s46, v130
	v_add_u32_e32 v129, 0x8400, v6
	v_lshl_add_u64 v[0:1], s[20:21], 0, v[0:1]
	v_and_b32_e32 v64, 0x70, v2
	global_load_lds_dwordx4 v[72:73], off
	s_mov_b32 m0, s46
	v_readfirstlane_b32 s47, v129
	v_add_u32_e32 v119, 0xc000, v125
	v_lshl_add_u64 v[76:77], v[0:1], 0, v[64:65]
	global_load_lds_dwordx4 v[74:75], off
	s_mov_b32 m0, s47
	s_mov_b64 s[20:21], 0x80
	v_readfirstlane_b32 s36, v119
	v_add_u32_e32 v120, 0xc400, v125
	global_load_lds_dwordx4 v[76:77], off
	v_lshl_add_u64 v[0:1], v[66:67], 0, s[20:21]
	s_mov_b32 m0, s36
	v_readfirstlane_b32 s37, v120
	v_add_u32_e32 v121, 0xc800, v125
	global_load_lds_dwordx4 v[0:1], off
	v_lshl_add_u64 v[0:1], v[68:69], 0, s[20:21]
	s_mov_b32 m0, s37
	v_readfirstlane_b32 s38, v121
	v_add_u32_e32 v122, 0xcc00, v125
	global_load_lds_dwordx4 v[0:1], off
	v_lshl_add_u64 v[0:1], v[70:71], 0, s[20:21]
	s_mov_b32 m0, s38
	v_readfirstlane_b32 s39, v122
	v_add_u32_e32 v123, s85, v5
	global_load_lds_dwordx4 v[0:1], off
	v_lshl_add_u64 v[0:1], v[72:73], 0, s[20:21]
	s_mov_b32 m0, s39
	v_readfirstlane_b32 s40, v123
	v_add_u32_e32 v124, 0x14400, v6
	global_load_lds_dwordx4 v[0:1], off
	v_lshl_add_u64 v[0:1], v[74:75], 0, s[20:21]
	s_mov_b32 m0, s40
	v_readfirstlane_b32 s41, v124
	global_load_lds_dwordx4 v[0:1], off
	v_lshl_add_u64 v[0:1], v[76:77], 0, s[20:21]
	s_mov_b32 m0, s41
	v_lshrrev_b32_e32 v2, 1, v12
	v_bfe_u32 v64, v12, 5, 1
	global_load_lds_dwordx4 v[0:1], off
	v_add_u32_e32 v113, s3, v3
	v_bitop3_b32 v0, v2, v64, 7 bitop3:0x6c
	s_waitcnt vmcnt(6)
	s_mov_b64 s[30:31], 0x100
	v_readfirstlane_b32 s20, v113
	v_add_u32_e32 v114, 0x400, v113
	v_lshlrev_b32_e32 v110, 4, v0
	s_waitcnt lgkmcnt(0)
	s_barrier
	v_lshl_add_u64 v[0:1], v[66:67], 0, s[30:31]
	s_mov_b32 m0, s20
	v_readfirstlane_b32 s21, v114
	v_add_u32_e32 v115, 0x800, v113
	global_load_lds_dwordx4 v[0:1], off
	v_lshl_add_u64 v[0:1], v[68:69], 0, s[30:31]
	s_mov_b32 m0, s21
	v_readfirstlane_b32 s23, v115
	v_add_u32_e32 v116, 0xc00, v113
	v_readlane_b32 s29, v212, 31
	v_and_b32_e32 v80, 31, v12
	global_load_lds_dwordx4 v[0:1], off
	v_lshl_add_u64 v[0:1], v[70:71], 0, s[30:31]
	s_mov_b32 m0, s23
	v_readfirstlane_b32 s28, v116
	v_add_u32_e32 v117, s29, v5
	v_add_u32_e32 v2, s3, v5
	v_lshlrev_b32_e32 v4, 7, v80
	global_load_lds_dwordx4 v[0:1], off
	v_lshl_add_u64 v[0:1], v[72:73], 0, s[30:31]
	s_mov_b32 m0, s28
	v_readfirstlane_b32 s29, v117
	v_add_u32_e32 v118, 0x8400, v2
	v_lshl_or_b32 v102, v79, 13, v4
	global_load_lds_dwordx4 v[0:1], off
	v_lshl_add_u64 v[0:1], v[74:75], 0, s[30:31]
	s_mov_b32 m0, s29
	v_readfirstlane_b32 s33, v118
	global_load_lds_dwordx4 v[0:1], off
	v_lshl_add_u64 v[0:1], v[76:77], 0, s[30:31]
	s_mov_b32 m0, s33
	v_add_u32_e32 v100, 0, v102
	global_load_lds_dwordx4 v[0:1], off
	v_add_u32_e32 v82, v100, v110
	v_ashrrev_i32_e32 v78, 7, v12
	ds_read_b128 a[0:3], v82 offset:32768
	ds_read_b128 a[4:7], v82 offset:36864
	v_lshl_or_b32 v111, v78, 13, v4
	v_add_u32_e32 v101, 0, v111
	v_add_u32_e32 v81, v101, v110
	ds_read_b128 a[8:11], v81
	ds_read_b128 a[12:15], v81 offset:4096
	v_lshrrev_b32_e32 v182, 6, v133
	s_nop 0
	v_readfirstlane_b32 s32, v182
	s_waitcnt lgkmcnt(1)
	v_mfma_f32_32x32x16_bf16 v[48:63], a[0:3], a[8:11], 0
	v_bfe_u32 v103, v12, 1, 3
	v_bitop3_b32 v85, v64, v103, 4 bitop3:0x36
	v_lshlrev_b32_e32 v131, 4, v85
	v_add_u32_e32 v85, v101, v131
	s_mov_b64 s[30:31], 0x180
	s_nop 0
	v_or_b32_e32 v146, 0x8000, v102
	s_waitcnt vmcnt(12)
	v_mfma_f32_32x32x16_bf16 v[32:47], a[4:7], a[8:11], 0
	v_or_b32_e32 v147, 0x9000, v102
	v_add_u32_e32 v138, s3, v110
	v_add_u32_e32 v148, s3, v111
	v_or_b32_e32 v149, 0x1000, v111
	s_mov_b64 s[60:61], 0x80
	s_mov_b64 s[80:81], 0x200
	s_waitcnt lgkmcnt(0)
	v_mfma_f32_32x32x16_bf16 v[16:31], a[0:3], a[12:15], 0
	v_bitop3_b32 v0, v64, v103, 2 bitop3:0x36
	v_lshlrev_b32_e32 v112, 4, v0
	v_add_u32_e32 v83, v101, v112
	ds_read_b128 a[28:31], v83 offset:4096
	s_nop 0
	s_nop 0
	ds_read_b128 a[24:27], v83
	s_nop 0
	v_add_u32_e32 v84, v100, v112
	ds_read_b128 a[20:23], v84 offset:36864
	s_nop 0
	s_nop 0
	ds_read_b128 a[16:19], v84 offset:32768
	s_nop 0
	s_nop 0
	s_nop 0
	s_nop 0
	s_nop 0
	s_nop 0
	v_mfma_f32_32x32x16_bf16 v[0:15], a[4:7], a[12:15], 0
	v_add_u32_e32 v142, s3, v112
	s_nop 0
	v_add_u32_e32 v86, v100, v131
	ds_read_b128 a[0:3], v86 offset:32768
	ds_read_b128 a[4:7], v86 offset:36864
	ds_read_b128 a[8:11], v85
	ds_read_b128 a[12:15], v85 offset:4096
	s_waitcnt lgkmcnt(4)
	v_mfma_f32_32x32x16_bf16 v[48:63], a[16:19], a[24:27], v[48:63]
	v_mfma_f32_32x32x16_bf16 v[32:47], a[20:23], a[24:27], v[32:47]
	v_mfma_f32_32x32x16_bf16 v[16:31], a[16:19], a[28:31], v[16:31]
	s_nop 0
	v_bitop3_b32 v87, v64, v103, 6 bitop3:0x36
	v_lshlrev_b32_e32 v132, 4, v87
	v_add_u32_e32 v87, v101, v132
	v_lshlrev_b32_e32 v64, 2, v64
	v_mfma_f32_32x32x16_bf16 v[0:15], a[20:23], a[28:31], v[0:15]
	s_nop 0
	s_nop 0
	s_nop 0
	v_add_u32_e32 v88, v100, v132
	ds_read_b128 a[16:19], v88 offset:32768
	ds_read_b128 a[20:23], v88 offset:36864
	ds_read_b128 a[24:27], v87
	ds_read_b128 a[28:31], v87 offset:4096
	s_waitcnt lgkmcnt(5)
	v_mfma_f32_32x32x16_bf16 v[48:63], a[0:3], a[8:11], v[48:63]
	v_mfma_f32_32x32x16_bf16 v[32:47], a[4:7], a[8:11], v[32:47]
	s_nop 0
	s_waitcnt lgkmcnt(4)
	v_mfma_f32_32x32x16_bf16 v[16:31], a[0:3], a[12:15], v[16:31]
	s_nop 0
	v_mfma_f32_32x32x16_bf16 v[0:15], a[4:7], a[12:15], v[0:15]
	s_nop 0
	s_nop 0
	s_nop 0
	s_waitcnt lgkmcnt(1)
	v_mfma_f32_32x32x16_bf16 v[48:63], a[16:19], a[24:27], v[48:63]
	v_mfma_f32_32x32x16_bf16 v[32:47], a[20:23], a[24:27], v[32:47]
	s_nop 0
	s_waitcnt vmcnt(6)
	s_waitcnt lgkmcnt(0)
	s_barrier
	ds_read_b128 a[12:15], v81 offset:53248
	ds_read_b128 a[8:11], v81 offset:49152
	v_mfma_f32_32x32x16_bf16 v[16:31], a[16:19], a[28:31], v[16:31]
	v_lshl_add_u64 v[158:159], v[66:67], 0, s[30:31]
	s_nop 0
	v_lshl_add_u64 v[160:161], v[68:69], 0, s[30:31]
	s_nop 0
	s_nop 0
	s_nop 0
	v_lshl_add_u64 v[162:163], v[70:71], 0, s[30:31]
	s_nop 0
	v_mfma_f32_32x32x16_bf16 v[0:15], a[20:23], a[28:31], v[0:15]
	s_and_b32 m0, s32, 7
	s_lshl_b32 m0, m0, 12
	s_add_i32 m0, m0, 0x0
	s_nop 0
	global_load_lds_dwordx4 v[158:159], off
	s_nop 0
	v_lshl_add_u64 v[164:165], v[72:73], 0, s[30:31]
	s_nop 0
	s_nop 0
	s_nop 0
	v_lshl_add_u64 v[166:167], v[74:75], 0, s[30:31]
	s_nop 0
	s_nop 0
	s_nop 0
	v_lshl_add_u64 v[168:169], v[76:77], 0, s[30:31]
	s_add_i32 s30, 0, 0xc000
	v_add_u32_e32 v89, s30, v110
	v_add_u32_e32 v91, v89, v146
	v_add_u32_e32 v89, v89, v147
	ds_read_b128 a[4:7], v89
	ds_read_b128 a[0:3], v91
	s_nop 0
	s_nop 0
	s_nop 0
	s_nop 0
	s_nop 0
	s_nop 0
	s_nop 0
	s_nop 0
	s_nop 0
	v_add_u32_e32 v90, s30, v112
	v_add_u32_e32 v92, v90, v146
	ds_read_b128 a[16:19], v92
	v_add_u32_e32 v90, v90, v147
	ds_read_b128 a[20:23], v90
	ds_read_b128 a[24:27], v83 offset:49152
	ds_read_b128 a[28:31], v83 offset:53248
	s_waitcnt lgkmcnt(4)
	v_mfma_f32_32x32x16_bf16 v[48:63], a[0:3], a[8:11], v[48:63]
	s_nop 0
	s_nop 0
	v_mfma_f32_32x32x16_bf16 v[32:47], a[4:7], a[8:11], v[32:47]
	s_and_b32 m0, s32, 7
	s_lshl_b32 m0, m0, 12
	s_add_i32 m0, m0, 0x400
	s_nop 0
	global_load_lds_dwordx4 v[160:161], off
	v_mfma_f32_32x32x16_bf16 v[16:31], a[0:3], a[12:15], v[16:31]
	s_nop 0
	s_nop 0
	v_add_u32_e32 v93, s30, v131
	v_mfma_f32_32x32x16_bf16 v[0:15], a[4:7], a[12:15], v[0:15]
	s_and_b32 m0, s32, 7
	s_lshl_b32 m0, m0, 12
	s_add_i32 m0, m0, 0x800
	s_nop 0
	global_load_lds_dwordx4 v[162:163], off
	s_nop 0
	s_nop 0
	s_nop 0
	s_nop 0
	v_add_u32_e32 v94, v93, v146
	ds_read_b128 a[0:3], v94
	v_add_u32_e32 v93, v93, v147
	ds_read_b128 a[4:7], v93
	ds_read_b128 a[8:11], v85 offset:49152
	ds_read_b128 a[12:15], v85 offset:53248
	s_waitcnt lgkmcnt(5)
	v_mfma_f32_32x32x16_bf16 v[48:63], a[16:19], a[24:27], v[48:63]
	v_mfma_f32_32x32x16_bf16 v[32:47], a[20:23], a[24:27], v[32:47]
	s_and_b32 m0, s32, 7
	s_lshl_b32 m0, m0, 12
	s_add_i32 m0, m0, 0xc00
	s_nop 0
	global_load_lds_dwordx4 v[164:165], off
	s_waitcnt lgkmcnt(4)
	v_mfma_f32_32x32x16_bf16 v[16:31], a[16:19], a[28:31], v[16:31]
	s_nop 0
	s_nop 0
	v_add_u32_e32 v95, s30, v132
	s_mov_b64 s[30:31], 0x200
	v_mfma_f32_32x32x16_bf16 v[0:15], a[20:23], a[28:31], v[0:15]
	s_and_b32 m0, s32, 7
	s_lshl_b32 m0, m0, 11
	s_add_i32 m0, m0, 0x8000
	s_nop 0
	global_load_lds_dwordx4 v[166:167], off
	s_nop 0
	s_nop 0
	s_nop 0
	s_nop 0
	v_add_u32_e32 v96, v95, v146
	ds_read_b128 a[16:19], v96
	v_add_u32_e32 v95, v95, v147
	ds_read_b128 a[20:23], v95
	ds_read_b128 a[24:27], v87 offset:49152
	ds_read_b128 a[28:31], v87 offset:53248
	s_waitcnt lgkmcnt(5)
	v_mfma_f32_32x32x16_bf16 v[48:63], a[0:3], a[8:11], v[48:63]
	v_mfma_f32_32x32x16_bf16 v[32:47], a[4:7], a[8:11], v[32:47]
	s_and_b32 m0, s32, 7
	s_lshl_b32 m0, m0, 11
	s_add_i32 m0, m0, 0x8400
	s_nop 0
	global_load_lds_dwordx4 v[168:169], off
	s_waitcnt lgkmcnt(4)
	v_mfma_f32_32x32x16_bf16 v[16:31], a[0:3], a[12:15], v[16:31]
	s_nop 0
	s_nop 0
	v_add_u32_e32 v97, v138, v146
	v_mfma_f32_32x32x16_bf16 v[0:15], a[4:7], a[12:15], v[0:15]
	s_nop 0
	s_nop 0
	s_nop 0
	s_nop 0
	s_waitcnt lgkmcnt(1)
	v_mfma_f32_32x32x16_bf16 v[48:63], a[16:19], a[24:27], v[48:63]
	v_mfma_f32_32x32x16_bf16 v[32:47], a[20:23], a[24:27], v[32:47]
	s_waitcnt vmcnt(6)
	s_waitcnt lgkmcnt(0)
	s_barrier
	v_add_u32_e32 v100, v138, v149
	ds_read_b128 a[12:15], v100
	v_add_u32_e32 v99, v148, v110
	ds_read_b128 a[8:11], v99
	v_add_u32_e32 v98, v138, v147
	ds_read_b128 a[4:7], v98
	ds_read_b128 a[0:3], v97
	v_mfma_f32_32x32x16_bf16 v[16:31], a[16:19], a[28:31], v[16:31]
	v_lshl_add_u64 v[170:171], v[66:67], 0, s[30:31]
	s_nop 0
	v_lshl_add_u64 v[172:173], v[68:69], 0, s[30:31]
	s_nop 0
	s_nop 0
	s_nop 0
	v_lshl_add_u64 v[174:175], v[70:71], 0, s[30:31]
	s_nop 0
	v_mfma_f32_32x32x16_bf16 v[0:15], a[20:23], a[28:31], v[0:15]
	s_and_b32 m0, s32, 7
	s_lshl_b32 m0, m0, 12
	s_add_i32 m0, m0, 0xc000
	s_nop 0
	global_load_lds_dwordx4 v[170:171], off
	s_nop 0
	v_lshl_add_u64 v[176:177], v[72:73], 0, s[30:31]
	s_nop 0
	s_nop 0
	s_nop 0
	v_lshl_add_u64 v[178:179], v[74:75], 0, s[30:31]
	s_nop 0
	s_nop 0
	s_nop 0
	v_lshl_add_u64 v[180:181], v[76:77], 0, s[30:31]
	s_nop 0
	s_mov_b64 s[30:31], 0x280
	s_nop 0
	s_nop 0
	s_nop 0
	s_nop 0
	s_nop 0
	s_nop 0
	v_add_u32_e32 v101, v142, v146
	ds_read_b128 a[16:19], v101
	v_add_u32_e32 v102, v142, v147
	ds_read_b128 a[20:23], v102
	v_add_u32_e32 v103, v148, v112
	ds_read_b128 a[24:27], v103
	v_add_u32_e32 v104, v142, v149
	ds_read_b128 a[28:31], v104
	s_waitcnt lgkmcnt(4)
	v_mfma_f32_32x32x16_bf16 v[48:63], a[0:3], a[8:11], v[48:63]
	s_nop 0
	v_mfma_f32_32x32x16_bf16 v[32:47], a[4:7], a[8:11], v[32:47]
	s_and_b32 m0, s32, 7
	s_lshl_b32 m0, m0, 12
	s_add_i32 m0, m0, 0xc400
	s_nop 0
	global_load_lds_dwordx4 v[172:173], off
	s_nop 0
	s_nop 0
	s_nop 0
	s_nop 0
	s_nop 0
	s_nop 0
	v_add_u32_e32 v112, s3, v131
	v_mfma_f32_32x32x16_bf16 v[16:31], a[0:3], a[12:15], v[16:31]
	s_nop 0
	v_mfma_f32_32x32x16_bf16 v[0:15], a[4:7], a[12:15], v[0:15]
	s_and_b32 m0, s32, 7
	s_lshl_b32 m0, m0, 12
	s_add_i32 m0, m0, 0xc800
	s_nop 0
	global_load_lds_dwordx4 v[174:175], off
	s_nop 0
	s_nop 0
	v_add_u32_e32 v105, v112, v146
	s_nop 0
	ds_read_b128 a[0:3], v105
	v_add_u32_e32 v106, v112, v147
	ds_read_b128 a[4:7], v106
	v_add_u32_e32 v107, v148, v131
	ds_read_b128 a[8:11], v107
	v_add_u32_e32 v108, v112, v149
	ds_read_b128 a[12:15], v108
	s_waitcnt lgkmcnt(5)
	v_mfma_f32_32x32x16_bf16 v[48:63], a[16:19], a[24:27], v[48:63]
	v_mfma_f32_32x32x16_bf16 v[32:47], a[20:23], a[24:27], v[32:47]
	s_and_b32 m0, s32, 7
	s_lshl_b32 m0, m0, 12
	s_add_i32 m0, m0, 0xcc00
	s_nop 0
	global_load_lds_dwordx4 v[176:177], off
	s_waitcnt lgkmcnt(4)
	v_mfma_f32_32x32x16_bf16 v[16:31], a[16:19], a[28:31], v[16:31]
	s_nop 0
	s_nop 0
	s_nop 0
	v_mfma_f32_32x32x16_bf16 v[0:15], a[20:23], a[28:31], v[0:15]
	s_and_b32 m0, s32, 7
	s_lshl_b32 m0, m0, 11
	s_add_i32 m0, m0, 0x14000
	s_nop 0
	global_load_lds_dwordx4 v[178:179], off
	s_nop 0
	s_nop 0
	v_add_u32_e32 v112, s3, v132
	v_add_u32_e32 v109, v112, v146
	ds_read_b128 a[16:19], v109
	v_add_u32_e32 v110, v112, v147
	ds_read_b128 a[20:23], v110
	v_add_u32_e32 v111, v148, v132
	ds_read_b128 a[24:27], v111
	v_add_u32_e32 v112, v112, v149
	ds_read_b128 a[28:31], v112
	s_waitcnt lgkmcnt(5)
	v_mfma_f32_32x32x16_bf16 v[48:63], a[0:3], a[8:11], v[48:63]
	v_mfma_f32_32x32x16_bf16 v[32:47], a[4:7], a[8:11], v[32:47]
	s_and_b32 m0, s32, 7
	s_lshl_b32 m0, m0, 11
	s_add_i32 m0, m0, 0x14400
	s_nop 0
	global_load_lds_dwordx4 v[180:181], off
	s_nop 0
	s_nop 0
	s_nop 0
	s_nop 0
	s_nop 0
	s_nop 0
	s_nop 0
	s_waitcnt lgkmcnt(4)
	v_mfma_f32_32x32x16_bf16 v[16:31], a[0:3], a[12:15], v[16:31]
	s_nop 0
	v_mfma_f32_32x32x16_bf16 v[0:15], a[4:7], a[12:15], v[0:15]
	s_nop 0
	s_nop 0
	s_nop 0
	s_waitcnt lgkmcnt(1)
	v_mfma_f32_32x32x16_bf16 v[48:63], a[16:19], a[24:27], v[48:63]
	v_mfma_f32_32x32x16_bf16 v[32:47], a[20:23], a[24:27], v[32:47]
	s_waitcnt vmcnt(6)
	s_waitcnt lgkmcnt(0)
	s_barrier
	ds_read_b128 a[12:15], v81 offset:4096
	ds_read_b128 a[8:11], v81
	ds_read_b128 a[4:7], v82 offset:36864
	ds_read_b128 a[0:3], v82 offset:32768
	v_mfma_f32_32x32x16_bf16 v[16:31], a[16:19], a[28:31], v[16:31]
	v_lshl_add_u64 v[158:159], v[66:67], 0, s[30:31]
	s_nop 0
	v_lshl_add_u64 v[160:161], v[68:69], 0, s[30:31]
	s_nop 0
	s_nop 0
	s_nop 0
	v_lshl_add_u64 v[162:163], v[70:71], 0, s[30:31]
	s_nop 0
	v_mfma_f32_32x32x16_bf16 v[0:15], a[20:23], a[28:31], v[0:15]
	s_and_b32 m0, s32, 7
	s_lshl_b32 m0, m0, 12
	s_add_i32 m0, m0, 0x18000
	s_nop 0
	global_load_lds_dwordx4 v[158:159], off
	s_nop 0
	v_lshl_add_u64 v[164:165], v[72:73], 0, s[30:31]
	s_nop 0
	s_nop 0
	s_nop 0
	v_lshl_add_u64 v[166:167], v[74:75], 0, s[30:31]
	s_nop 0
	s_nop 0
	s_nop 0
	v_lshl_add_u64 v[168:169], v[76:77], 0, s[30:31]
	s_nop 0
	s_mov_b64 s[30:31], 0x300
	s_nop 0
	s_nop 0
	s_nop 0
	s_nop 0
	s_nop 0
	ds_read_b128 a[16:19], v84 offset:32768
	ds_read_b128 a[20:23], v84 offset:36864
	ds_read_b128 a[24:27], v83
	ds_read_b128 a[28:31], v83 offset:4096
	s_waitcnt lgkmcnt(4)
	v_mfma_f32_32x32x16_bf16 v[48:63], a[0:3], a[8:11], v[48:63]
	s_nop 0
	v_readfirstlane_b32 s42, v113
	v_mfma_f32_32x32x16_bf16 v[32:47], a[4:7], a[8:11], v[32:47]
	s_and_b32 m0, s32, 7
	s_lshl_b32 m0, m0, 12
	s_add_i32 m0, m0, 0x18400
	s_nop 0
	global_load_lds_dwordx4 v[160:161], off
	v_mfma_f32_32x32x16_bf16 v[16:31], a[0:3], a[12:15], v[16:31]
	v_mfma_f32_32x32x16_bf16 v[0:15], a[4:7], a[12:15], v[0:15]
	s_and_b32 m0, s32, 7
	s_lshl_b32 m0, m0, 12
	s_add_i32 m0, m0, 0x18800
	s_nop 0
	global_load_lds_dwordx4 v[162:163], off
	s_nop 0
	s_nop 0
	s_nop 0
	s_nop 0
	ds_read_b128 a[0:3], v86 offset:32768
	ds_read_b128 a[4:7], v86 offset:36864
	ds_read_b128 a[8:11], v85
	ds_read_b128 a[12:15], v85 offset:4096
	s_waitcnt lgkmcnt(5)
	v_mfma_f32_32x32x16_bf16 v[48:63], a[16:19], a[24:27], v[48:63]
	v_mfma_f32_32x32x16_bf16 v[32:47], a[20:23], a[24:27], v[32:47]
	s_and_b32 m0, s32, 7
	s_lshl_b32 m0, m0, 12
	s_add_i32 m0, m0, 0x18c00
	s_nop 0
	global_load_lds_dwordx4 v[164:165], off
	s_waitcnt lgkmcnt(4)
	v_mfma_f32_32x32x16_bf16 v[16:31], a[16:19], a[28:31], v[16:31]
	v_mfma_f32_32x32x16_bf16 v[0:15], a[20:23], a[28:31], v[0:15]
	s_and_b32 m0, s32, 7
	s_lshl_b32 m0, m0, 11
	s_add_i32 m0, m0, 0x20000
	s_nop 0
	global_load_lds_dwordx4 v[166:167], off
	s_nop 0
	s_nop 0
	s_nop 0
	s_nop 0
	ds_read_b128 a[16:19], v88 offset:32768
	ds_read_b128 a[20:23], v88 offset:36864
	ds_read_b128 a[24:27], v87
	ds_read_b128 a[28:31], v87 offset:4096
	s_waitcnt lgkmcnt(5)
	v_mfma_f32_32x32x16_bf16 v[48:63], a[0:3], a[8:11], v[48:63]
	v_mfma_f32_32x32x16_bf16 v[32:47], a[4:7], a[8:11], v[32:47]
	s_and_b32 m0, s32, 7
	s_lshl_b32 m0, m0, 11
	s_add_i32 m0, m0, 0x20400
	s_nop 0
	global_load_lds_dwordx4 v[168:169], off
	s_waitcnt lgkmcnt(4)
	v_mfma_f32_32x32x16_bf16 v[16:31], a[0:3], a[12:15], v[16:31]
	v_mfma_f32_32x32x16_bf16 v[0:15], a[4:7], a[12:15], v[0:15]
	s_nop 0
	s_nop 0
	s_nop 0
	s_nop 0
	s_waitcnt lgkmcnt(1)
	v_mfma_f32_32x32x16_bf16 v[48:63], a[16:19], a[24:27], v[48:63]
	v_mfma_f32_32x32x16_bf16 v[32:47], a[20:23], a[24:27], v[32:47]
	s_waitcnt vmcnt(6)
	s_waitcnt lgkmcnt(0)
	s_barrier
	ds_read_b128 a[12:15], v81 offset:53248
	ds_read_b128 a[8:11], v81 offset:49152
	ds_read_b128 a[4:7], v89
	ds_read_b128 a[0:3], v91
	v_mfma_f32_32x32x16_bf16 v[16:31], a[16:19], a[28:31], v[16:31]
	v_lshl_add_u64 v[170:171], v[66:67], 0, s[30:31]
	s_nop 0
	v_lshl_add_u64 v[172:173], v[68:69], 0, s[30:31]
	s_nop 0
	v_readfirstlane_b32 s43, v114
	s_nop 0
	v_lshl_add_u64 v[174:175], v[70:71], 0, s[30:31]
	s_nop 0
	v_mfma_f32_32x32x16_bf16 v[0:15], a[20:23], a[28:31], v[0:15]
	s_and_b32 m0, s32, 7
	s_lshl_b32 m0, m0, 12
	s_add_i32 m0, m0, 0x0
	s_nop 0
	global_load_lds_dwordx4 v[170:171], off
	s_nop 0
	v_lshl_add_u64 v[176:177], v[72:73], 0, s[30:31]
	s_nop 0
	v_readfirstlane_b32 s44, v115
	s_nop 0
	v_lshl_add_u64 v[178:179], v[74:75], 0, s[30:31]
	s_nop 0
	v_readfirstlane_b32 s45, v116
	s_nop 0
	v_lshl_add_u64 v[180:181], v[76:77], 0, s[30:31]
	s_nop 0
	s_mov_b64 s[30:31], 0x380
	s_nop 0
	s_nop 0
	s_nop 0
	s_nop 0
	s_nop 0
	ds_read_b128 a[16:19], v92
	ds_read_b128 a[20:23], v90
	ds_read_b128 a[24:27], v83 offset:49152
	ds_read_b128 a[28:31], v83 offset:53248
	s_waitcnt lgkmcnt(4)
	v_mfma_f32_32x32x16_bf16 v[48:63], a[0:3], a[8:11], v[48:63]
	s_nop 0
	v_readfirstlane_b32 s36, v119
	v_readfirstlane_b32 s46, v117
	v_readfirstlane_b32 s47, v118
	v_mfma_f32_32x32x16_bf16 v[32:47], a[4:7], a[8:11], v[32:47]
	s_and_b32 m0, s32, 7
	s_lshl_b32 m0, m0, 12
	s_add_i32 m0, m0, 0x400
	s_nop 0
	global_load_lds_dwordx4 v[172:173], off
	v_mfma_f32_32x32x16_bf16 v[16:31], a[0:3], a[12:15], v[16:31]
	v_mfma_f32_32x32x16_bf16 v[0:15], a[4:7], a[12:15], v[0:15]
	s_and_b32 m0, s32, 7
	s_lshl_b32 m0, m0, 12
	s_add_i32 m0, m0, 0x800
	s_nop 0
	global_load_lds_dwordx4 v[174:175], off
	s_nop 0
	s_nop 0
	s_nop 0
	s_nop 0
	ds_read_b128 a[0:3], v94
	ds_read_b128 a[4:7], v93
	ds_read_b128 a[8:11], v85 offset:49152
	ds_read_b128 a[12:15], v85 offset:53248
	s_waitcnt lgkmcnt(5)
	v_mfma_f32_32x32x16_bf16 v[48:63], a[16:19], a[24:27], v[48:63]
	v_mfma_f32_32x32x16_bf16 v[32:47], a[20:23], a[24:27], v[32:47]
	s_and_b32 m0, s32, 7
	s_lshl_b32 m0, m0, 12
	s_add_i32 m0, m0, 0xc00
	s_nop 0
	global_load_lds_dwordx4 v[176:177], off
	s_waitcnt lgkmcnt(4)
	v_mfma_f32_32x32x16_bf16 v[16:31], a[16:19], a[28:31], v[16:31]
	v_mfma_f32_32x32x16_bf16 v[0:15], a[20:23], a[28:31], v[0:15]
	s_and_b32 m0, s32, 7
	s_lshl_b32 m0, m0, 11
	s_add_i32 m0, m0, 0x8000
	s_nop 0
	global_load_lds_dwordx4 v[178:179], off
	s_nop 0
	s_nop 0
	s_nop 0
	s_nop 0
	ds_read_b128 a[16:19], v96
	ds_read_b128 a[20:23], v95
	ds_read_b128 a[24:27], v87 offset:49152
	ds_read_b128 a[28:31], v87 offset:53248
	s_waitcnt lgkmcnt(5)
	v_mfma_f32_32x32x16_bf16 v[48:63], a[0:3], a[8:11], v[48:63]
	v_mfma_f32_32x32x16_bf16 v[32:47], a[4:7], a[8:11], v[32:47]
	s_and_b32 m0, s32, 7
	s_lshl_b32 m0, m0, 11
	s_add_i32 m0, m0, 0x8400
	s_nop 0
	global_load_lds_dwordx4 v[180:181], off
	s_waitcnt lgkmcnt(4)
	v_mfma_f32_32x32x16_bf16 v[16:31], a[0:3], a[12:15], v[16:31]
	v_mfma_f32_32x32x16_bf16 v[0:15], a[4:7], a[12:15], v[0:15]
	s_nop 0
	s_nop 0
	s_nop 0
	s_nop 0
	s_waitcnt lgkmcnt(1)
	v_mfma_f32_32x32x16_bf16 v[48:63], a[16:19], a[24:27], v[48:63]
	v_mfma_f32_32x32x16_bf16 v[32:47], a[20:23], a[24:27], v[32:47]
	s_waitcnt vmcnt(6)
	s_waitcnt lgkmcnt(0)
	s_barrier
	ds_read_b128 a[12:15], v100
	ds_read_b128 a[8:11], v99
	ds_read_b128 a[4:7], v98
	ds_read_b128 a[0:3], v97
	v_mfma_f32_32x32x16_bf16 v[16:31], a[16:19], a[28:31], v[16:31]
	v_lshl_add_u64 v[158:159], v[66:67], 0, s[30:31]
	s_nop 0
	v_lshl_add_u64 v[160:161], v[68:69], 0, s[30:31]
	s_nop 0
	v_readfirstlane_b32 s37, v120
	s_nop 0
	v_lshl_add_u64 v[162:163], v[70:71], 0, s[30:31]
	s_nop 0
	v_mfma_f32_32x32x16_bf16 v[0:15], a[20:23], a[28:31], v[0:15]
	s_and_b32 m0, s32, 7
	s_lshl_b32 m0, m0, 12
	s_add_i32 m0, m0, 0xc000
	s_nop 0
	global_load_lds_dwordx4 v[158:159], off
	s_nop 0
	v_lshl_add_u64 v[164:165], v[72:73], 0, s[30:31]
	s_nop 0
	v_readfirstlane_b32 s38, v121
	s_nop 0
	v_lshl_add_u64 v[166:167], v[74:75], 0, s[30:31]
	s_nop 0
	v_readfirstlane_b32 s39, v122
	s_nop 0
	v_lshl_add_u64 v[168:169], v[76:77], 0, s[30:31]
	s_nop 0
	s_mov_b64 s[30:31], 0x400
	s_nop 0
	s_nop 0
	s_nop 0
	s_nop 0
	s_nop 0
	ds_read_b128 a[16:19], v101
	ds_read_b128 a[20:23], v102
	ds_read_b128 a[24:27], v103
	ds_read_b128 a[28:31], v104
	s_waitcnt lgkmcnt(4)
	v_mfma_f32_32x32x16_bf16 v[48:63], a[0:3], a[8:11], v[48:63]
	s_nop 0
	v_readfirstlane_b32 s20, v125
	v_readfirstlane_b32 s40, v123
	v_readfirstlane_b32 s41, v124
	v_mfma_f32_32x32x16_bf16 v[32:47], a[4:7], a[8:11], v[32:47]
	s_and_b32 m0, s32, 7
	s_lshl_b32 m0, m0, 12
	s_add_i32 m0, m0, 0xc400
	s_nop 0
	global_load_lds_dwordx4 v[160:161], off
	v_mfma_f32_32x32x16_bf16 v[16:31], a[0:3], a[12:15], v[16:31]
	v_mfma_f32_32x32x16_bf16 v[0:15], a[4:7], a[12:15], v[0:15]
	s_and_b32 m0, s32, 7
	s_lshl_b32 m0, m0, 12
	s_add_i32 m0, m0, 0xc800
	s_nop 0
	global_load_lds_dwordx4 v[162:163], off
	s_nop 0
	s_nop 0
	s_nop 0
	s_nop 0
	ds_read_b128 a[0:3], v105
	ds_read_b128 a[4:7], v106
	ds_read_b128 a[8:11], v107
	ds_read_b128 a[12:15], v108
	s_waitcnt lgkmcnt(5)
	v_mfma_f32_32x32x16_bf16 v[48:63], a[16:19], a[24:27], v[48:63]
	v_mfma_f32_32x32x16_bf16 v[32:47], a[20:23], a[24:27], v[32:47]
	s_and_b32 m0, s32, 7
	s_lshl_b32 m0, m0, 12
	s_add_i32 m0, m0, 0xcc00
	s_nop 0
	global_load_lds_dwordx4 v[164:165], off
	s_waitcnt lgkmcnt(4)
	v_mfma_f32_32x32x16_bf16 v[16:31], a[16:19], a[28:31], v[16:31]
	v_mfma_f32_32x32x16_bf16 v[0:15], a[20:23], a[28:31], v[0:15]
	s_and_b32 m0, s32, 7
	s_lshl_b32 m0, m0, 11
	s_add_i32 m0, m0, 0x14000
	s_nop 0
	global_load_lds_dwordx4 v[166:167], off
	s_nop 0
	s_nop 0
	s_nop 0
	s_nop 0
	ds_read_b128 a[16:19], v109
	ds_read_b128 a[20:23], v110
	ds_read_b128 a[24:27], v111
	ds_read_b128 a[28:31], v112
	s_waitcnt lgkmcnt(5)
	v_mfma_f32_32x32x16_bf16 v[48:63], a[0:3], a[8:11], v[48:63]
	v_mfma_f32_32x32x16_bf16 v[32:47], a[4:7], a[8:11], v[32:47]
	s_and_b32 m0, s32, 7
	s_lshl_b32 m0, m0, 11
	s_add_i32 m0, m0, 0x14400
	s_nop 0
	global_load_lds_dwordx4 v[168:169], off
	s_waitcnt lgkmcnt(4)
	v_mfma_f32_32x32x16_bf16 v[16:31], a[0:3], a[12:15], v[16:31]
	v_mfma_f32_32x32x16_bf16 v[0:15], a[4:7], a[12:15], v[0:15]
	s_nop 0
	s_nop 0
	s_nop 0
	s_nop 0
	s_waitcnt lgkmcnt(1)
	v_mfma_f32_32x32x16_bf16 v[48:63], a[16:19], a[24:27], v[48:63]
	v_mfma_f32_32x32x16_bf16 v[32:47], a[20:23], a[24:27], v[32:47]
	s_waitcnt vmcnt(6)
	s_waitcnt lgkmcnt(0)
	s_barrier
	ds_read_b128 a[12:15], v81 offset:4096
	ds_read_b128 a[8:11], v81
	ds_read_b128 a[4:7], v82 offset:36864
	ds_read_b128 a[0:3], v82 offset:32768
	v_mfma_f32_32x32x16_bf16 v[16:31], a[16:19], a[28:31], v[16:31]
	v_lshl_add_u64 v[170:171], v[66:67], 0, s[30:31]
	s_nop 0
	v_lshl_add_u64 v[172:173], v[68:69], 0, s[30:31]
	s_nop 0
	v_readfirstlane_b32 s21, v126
	s_nop 0
	v_lshl_add_u64 v[174:175], v[70:71], 0, s[30:31]
	s_nop 0
	v_mfma_f32_32x32x16_bf16 v[0:15], a[20:23], a[28:31], v[0:15]
	s_and_b32 m0, s32, 7
	s_lshl_b32 m0, m0, 12
	s_add_i32 m0, m0, 0x18000
	s_nop 0
	global_load_lds_dwordx4 v[170:171], off
	s_nop 0
	v_lshl_add_u64 v[176:177], v[72:73], 0, s[30:31]
	s_nop 0
	v_readfirstlane_b32 s23, v127
	s_nop 0
	v_lshl_add_u64 v[178:179], v[74:75], 0, s[30:31]
	s_nop 0
	v_readfirstlane_b32 s28, v128
	s_nop 0
	v_lshl_add_u64 v[180:181], v[76:77], 0, s[30:31]
	s_nop 0
	s_mov_b64 s[30:31], 0x480
	s_nop 0
	s_nop 0
	s_nop 0
	s_nop 0
	s_nop 0
	ds_read_b128 a[16:19], v84 offset:32768
	ds_read_b128 a[20:23], v84 offset:36864
	ds_read_b128 a[24:27], v83
	ds_read_b128 a[28:31], v83 offset:4096
	s_waitcnt lgkmcnt(4)
	v_mfma_f32_32x32x16_bf16 v[48:63], a[0:3], a[8:11], v[48:63]
	s_nop 0
	v_lshl_add_u64 v[164:165], v[72:73], 0, s[30:31]
	v_readfirstlane_b32 s29, v130
	v_readfirstlane_b32 s33, v129
	v_mfma_f32_32x32x16_bf16 v[32:47], a[4:7], a[8:11], v[32:47]
	s_and_b32 m0, s32, 7
	s_lshl_b32 m0, m0, 12
	s_add_i32 m0, m0, 0x18400
	s_nop 0
	global_load_lds_dwordx4 v[172:173], off
	v_mfma_f32_32x32x16_bf16 v[16:31], a[0:3], a[12:15], v[16:31]
	v_mfma_f32_32x32x16_bf16 v[0:15], a[4:7], a[12:15], v[0:15]
	s_and_b32 m0, s32, 7
	s_lshl_b32 m0, m0, 12
	s_add_i32 m0, m0, 0x18800
	s_nop 0
	global_load_lds_dwordx4 v[174:175], off
	s_nop 0
	s_nop 0
	s_nop 0
	s_nop 0
	ds_read_b128 a[0:3], v86 offset:32768
	ds_read_b128 a[4:7], v86 offset:36864
	ds_read_b128 a[8:11], v85
	ds_read_b128 a[12:15], v85 offset:4096
	s_waitcnt lgkmcnt(5)
	v_mfma_f32_32x32x16_bf16 v[48:63], a[16:19], a[24:27], v[48:63]
	v_mfma_f32_32x32x16_bf16 v[32:47], a[20:23], a[24:27], v[32:47]
	s_and_b32 m0, s32, 7
	s_lshl_b32 m0, m0, 12
	s_add_i32 m0, m0, 0x18c00
	s_nop 0
	global_load_lds_dwordx4 v[176:177], off
	s_waitcnt lgkmcnt(4)
	v_mfma_f32_32x32x16_bf16 v[16:31], a[16:19], a[28:31], v[16:31]
	v_mfma_f32_32x32x16_bf16 v[0:15], a[20:23], a[28:31], v[0:15]
	s_and_b32 m0, s32, 7
	s_lshl_b32 m0, m0, 11
	s_add_i32 m0, m0, 0x20000
	s_nop 0
	global_load_lds_dwordx4 v[178:179], off
	s_nop 0
	s_nop 0
	s_nop 0
	s_nop 0
	ds_read_b128 a[16:19], v88 offset:32768
	ds_read_b128 a[20:23], v88 offset:36864
	ds_read_b128 a[24:27], v87
	ds_read_b128 a[28:31], v87 offset:4096
	s_waitcnt lgkmcnt(5)
	v_mfma_f32_32x32x16_bf16 v[48:63], a[0:3], a[8:11], v[48:63]
	v_mfma_f32_32x32x16_bf16 v[32:47], a[4:7], a[8:11], v[32:47]
	s_and_b32 m0, s32, 7
	s_lshl_b32 m0, m0, 11
	s_add_i32 m0, m0, 0x20400
	s_nop 0
	global_load_lds_dwordx4 v[180:181], off
	s_waitcnt lgkmcnt(4)
	v_mfma_f32_32x32x16_bf16 v[16:31], a[0:3], a[12:15], v[16:31]
	v_mfma_f32_32x32x16_bf16 v[0:15], a[4:7], a[12:15], v[0:15]
	s_nop 0
	s_nop 0
	s_nop 0
	s_nop 0
	s_waitcnt lgkmcnt(1)
	v_mfma_f32_32x32x16_bf16 v[48:63], a[16:19], a[24:27], v[48:63]
	v_mfma_f32_32x32x16_bf16 v[32:47], a[20:23], a[24:27], v[32:47]
	s_waitcnt vmcnt(6)
	s_waitcnt lgkmcnt(0)
	s_barrier
	ds_read_b128 a[12:15], v81 offset:53248
	ds_read_b128 a[8:11], v81 offset:49152
	ds_read_b128 a[4:7], v89
	ds_read_b128 a[0:3], v91
	v_mfma_f32_32x32x16_bf16 v[16:31], a[16:19], a[28:31], v[16:31]
	v_lshl_add_u64 v[158:159], v[66:67], 0, s[30:31]
	s_nop 0
	v_lshl_add_u64 v[160:161], v[68:69], 0, s[30:31]
	s_nop 0
	s_nop 0
	s_nop 0
	v_lshl_add_u64 v[162:163], v[70:71], 0, s[30:31]
	s_nop 0
	v_mfma_f32_32x32x16_bf16 v[0:15], a[20:23], a[28:31], v[0:15]
	s_and_b32 m0, s32, 7
	s_lshl_b32 m0, m0, 12
	s_add_i32 m0, m0, 0x0
	s_nop 0
	global_load_lds_dwordx4 v[158:159], off
	s_nop 0
	s_nop 0
	s_nop 0
	s_nop 0
	v_lshl_add_u64 v[166:167], v[74:75], 0, s[30:31]
	s_nop 0
	s_nop 0
	s_nop 0
	v_lshl_add_u64 v[168:169], v[76:77], 0, s[30:31]
	s_nop 0
	s_mov_b64 s[30:31], 0x500
	s_nop 0
	s_nop 0
	s_nop 0
	s_nop 0
	s_nop 0
	ds_read_b128 a[16:19], v92
	ds_read_b128 a[20:23], v90
	ds_read_b128 a[24:27], v83 offset:49152
	ds_read_b128 a[28:31], v83 offset:53248
	s_waitcnt lgkmcnt(4)
	v_mfma_f32_32x32x16_bf16 v[48:63], a[0:3], a[8:11], v[48:63]
	s_nop 0
	v_lshl_add_u64 v[176:177], v[72:73], 0, s[30:31]
	v_mfma_f32_32x32x16_bf16 v[32:47], a[4:7], a[8:11], v[32:47]
	s_and_b32 m0, s32, 7
	s_lshl_b32 m0, m0, 12
	s_add_i32 m0, m0, 0x400
	s_nop 0
	global_load_lds_dwordx4 v[160:161], off
	v_mfma_f32_32x32x16_bf16 v[16:31], a[0:3], a[12:15], v[16:31]
	v_mfma_f32_32x32x16_bf16 v[0:15], a[4:7], a[12:15], v[0:15]
	s_and_b32 m0, s32, 7
	s_lshl_b32 m0, m0, 12
	s_add_i32 m0, m0, 0x800
	s_nop 0
	global_load_lds_dwordx4 v[162:163], off
	s_nop 0
	s_nop 0
	s_nop 0
	s_nop 0
	ds_read_b128 a[0:3], v94
	ds_read_b128 a[4:7], v93
	ds_read_b128 a[8:11], v85 offset:49152
	ds_read_b128 a[12:15], v85 offset:53248
	s_waitcnt lgkmcnt(5)
	v_mfma_f32_32x32x16_bf16 v[48:63], a[16:19], a[24:27], v[48:63]
	v_mfma_f32_32x32x16_bf16 v[32:47], a[20:23], a[24:27], v[32:47]
	s_and_b32 m0, s32, 7
	s_lshl_b32 m0, m0, 12
	s_add_i32 m0, m0, 0xc00
	s_nop 0
	global_load_lds_dwordx4 v[164:165], off
	s_waitcnt lgkmcnt(4)
	v_mfma_f32_32x32x16_bf16 v[16:31], a[16:19], a[28:31], v[16:31]
	v_mfma_f32_32x32x16_bf16 v[0:15], a[20:23], a[28:31], v[0:15]
	s_and_b32 m0, s32, 7
	s_lshl_b32 m0, m0, 11
	s_add_i32 m0, m0, 0x8000
	s_nop 0
	global_load_lds_dwordx4 v[166:167], off
	s_nop 0
	s_nop 0
	s_nop 0
	s_nop 0
	ds_read_b128 a[16:19], v96
	ds_read_b128 a[20:23], v95
	ds_read_b128 a[24:27], v87 offset:49152
	ds_read_b128 a[28:31], v87 offset:53248
	s_waitcnt lgkmcnt(5)
	v_mfma_f32_32x32x16_bf16 v[48:63], a[0:3], a[8:11], v[48:63]
	v_mfma_f32_32x32x16_bf16 v[32:47], a[4:7], a[8:11], v[32:47]
	s_and_b32 m0, s32, 7
	s_lshl_b32 m0, m0, 11
	s_add_i32 m0, m0, 0x8400
	s_nop 0
	global_load_lds_dwordx4 v[168:169], off
	s_waitcnt lgkmcnt(4)
	v_mfma_f32_32x32x16_bf16 v[16:31], a[0:3], a[12:15], v[16:31]
	v_mfma_f32_32x32x16_bf16 v[0:15], a[4:7], a[12:15], v[0:15]
	s_nop 0
	s_nop 0
	s_nop 0
	s_nop 0
	s_waitcnt lgkmcnt(1)
	v_mfma_f32_32x32x16_bf16 v[48:63], a[16:19], a[24:27], v[48:63]
	v_mfma_f32_32x32x16_bf16 v[32:47], a[20:23], a[24:27], v[32:47]
	s_waitcnt vmcnt(6)
	s_waitcnt lgkmcnt(0)
	s_barrier
	ds_read_b128 a[12:15], v100
	ds_read_b128 a[8:11], v99
	ds_read_b128 a[4:7], v98
	ds_read_b128 a[0:3], v97
	v_mfma_f32_32x32x16_bf16 v[16:31], a[16:19], a[28:31], v[16:31]
	v_lshl_add_u64 v[170:171], v[66:67], 0, s[30:31]
	s_nop 0
	v_lshl_add_u64 v[172:173], v[68:69], 0, s[30:31]
	s_nop 0
	s_nop 0
	s_nop 0
	v_lshl_add_u64 v[174:175], v[70:71], 0, s[30:31]
	s_nop 0
	v_mfma_f32_32x32x16_bf16 v[0:15], a[20:23], a[28:31], v[0:15]
	s_and_b32 m0, s32, 7
	s_lshl_b32 m0, m0, 12
	s_add_i32 m0, m0, 0xc000
	s_nop 0
	global_load_lds_dwordx4 v[170:171], off
	s_nop 0
	s_nop 0
	s_nop 0
	s_nop 0
	v_lshl_add_u64 v[178:179], v[74:75], 0, s[30:31]
	s_nop 0
	s_nop 0
	s_nop 0
	v_lshl_add_u64 v[180:181], v[76:77], 0, s[30:31]
	s_nop 0
	s_mov_b64 s[30:31], 0x580
	s_nop 0
	s_nop 0
	s_nop 0
	s_nop 0
	s_nop 0
	ds_read_b128 a[16:19], v101
	ds_read_b128 a[20:23], v102
	ds_read_b128 a[24:27], v103
	ds_read_b128 a[28:31], v104
	s_waitcnt lgkmcnt(4)
	v_mfma_f32_32x32x16_bf16 v[48:63], a[0:3], a[8:11], v[48:63]
	s_nop 0
	v_lshl_add_u64 v[164:165], v[72:73], 0, s[30:31]
	v_mfma_f32_32x32x16_bf16 v[32:47], a[4:7], a[8:11], v[32:47]
	s_and_b32 m0, s32, 7
	s_lshl_b32 m0, m0, 12
	s_add_i32 m0, m0, 0xc400
	s_nop 0
	global_load_lds_dwordx4 v[172:173], off
	v_mfma_f32_32x32x16_bf16 v[16:31], a[0:3], a[12:15], v[16:31]
	v_mfma_f32_32x32x16_bf16 v[0:15], a[4:7], a[12:15], v[0:15]
	s_and_b32 m0, s32, 7
	s_lshl_b32 m0, m0, 12
	s_add_i32 m0, m0, 0xc800
	s_nop 0
	global_load_lds_dwordx4 v[174:175], off
	s_nop 0
	s_nop 0
	s_nop 0
	s_nop 0
	ds_read_b128 a[0:3], v105
	ds_read_b128 a[4:7], v106
	ds_read_b128 a[8:11], v107
	ds_read_b128 a[12:15], v108
	s_waitcnt lgkmcnt(5)
	v_mfma_f32_32x32x16_bf16 v[48:63], a[16:19], a[24:27], v[48:63]
	v_mfma_f32_32x32x16_bf16 v[32:47], a[20:23], a[24:27], v[32:47]
	s_and_b32 m0, s32, 7
	s_lshl_b32 m0, m0, 12
	s_add_i32 m0, m0, 0xcc00
	s_nop 0
	global_load_lds_dwordx4 v[176:177], off
	s_waitcnt lgkmcnt(4)
	v_mfma_f32_32x32x16_bf16 v[16:31], a[16:19], a[28:31], v[16:31]
	v_mfma_f32_32x32x16_bf16 v[0:15], a[20:23], a[28:31], v[0:15]
	s_and_b32 m0, s32, 7
	s_lshl_b32 m0, m0, 11
	s_add_i32 m0, m0, 0x14000
	s_nop 0
	global_load_lds_dwordx4 v[178:179], off
	s_nop 0
	s_nop 0
	s_nop 0
	s_nop 0
	ds_read_b128 a[16:19], v109
	ds_read_b128 a[20:23], v110
	ds_read_b128 a[24:27], v111
	ds_read_b128 a[28:31], v112
	s_waitcnt lgkmcnt(5)
	v_mfma_f32_32x32x16_bf16 v[48:63], a[0:3], a[8:11], v[48:63]
	v_mfma_f32_32x32x16_bf16 v[32:47], a[4:7], a[8:11], v[32:47]
	s_and_b32 m0, s32, 7
	s_lshl_b32 m0, m0, 11
	s_add_i32 m0, m0, 0x14400
	s_nop 0
	global_load_lds_dwordx4 v[180:181], off
	s_waitcnt lgkmcnt(4)
	v_mfma_f32_32x32x16_bf16 v[16:31], a[0:3], a[12:15], v[16:31]
	v_mfma_f32_32x32x16_bf16 v[0:15], a[4:7], a[12:15], v[0:15]
	s_nop 0
	s_nop 0
	s_nop 0
	s_nop 0
	s_waitcnt lgkmcnt(1)
	v_mfma_f32_32x32x16_bf16 v[48:63], a[16:19], a[24:27], v[48:63]
	v_mfma_f32_32x32x16_bf16 v[32:47], a[20:23], a[24:27], v[32:47]
	s_waitcnt vmcnt(6)
	s_waitcnt lgkmcnt(0)
	s_barrier
	ds_read_b128 a[12:15], v81 offset:4096
	ds_read_b128 a[8:11], v81
	ds_read_b128 a[4:7], v82 offset:36864
	ds_read_b128 a[0:3], v82 offset:32768
	v_mfma_f32_32x32x16_bf16 v[16:31], a[16:19], a[28:31], v[16:31]
	v_lshl_add_u64 v[158:159], v[66:67], 0, s[30:31]
	s_nop 0
	v_lshl_add_u64 v[160:161], v[68:69], 0, s[30:31]
	s_nop 0
	s_nop 0
	s_nop 0
	v_lshl_add_u64 v[162:163], v[70:71], 0, s[30:31]
	s_nop 0
	v_mfma_f32_32x32x16_bf16 v[0:15], a[20:23], a[28:31], v[0:15]
	s_and_b32 m0, s32, 7
	s_lshl_b32 m0, m0, 12
	s_add_i32 m0, m0, 0x18000
	s_nop 0
	global_load_lds_dwordx4 v[158:159], off
	s_nop 0
	s_nop 0
	s_nop 0
	s_nop 0
	v_lshl_add_u64 v[166:167], v[74:75], 0, s[30:31]
	s_nop 0
	s_nop 0
	s_nop 0
	v_lshl_add_u64 v[168:169], v[76:77], 0, s[30:31]
	s_nop 0
	s_mov_b64 s[30:31], 0x600
	s_nop 0
	s_nop 0
	s_nop 0
	s_nop 0
	s_nop 0
	ds_read_b128 a[16:19], v84 offset:32768
	ds_read_b128 a[20:23], v84 offset:36864
	ds_read_b128 a[24:27], v83
	ds_read_b128 a[28:31], v83 offset:4096
	s_waitcnt lgkmcnt(4)
	v_mfma_f32_32x32x16_bf16 v[48:63], a[0:3], a[8:11], v[48:63]
	s_nop 0
	v_mfma_f32_32x32x16_bf16 v[32:47], a[4:7], a[8:11], v[32:47]
	s_and_b32 m0, s32, 7
	s_lshl_b32 m0, m0, 12
	s_add_i32 m0, m0, 0x18400
	s_nop 0
	global_load_lds_dwordx4 v[160:161], off
	v_mfma_f32_32x32x16_bf16 v[16:31], a[0:3], a[12:15], v[16:31]
	v_mfma_f32_32x32x16_bf16 v[0:15], a[4:7], a[12:15], v[0:15]
	s_and_b32 m0, s32, 7
	s_lshl_b32 m0, m0, 12
	s_add_i32 m0, m0, 0x18800
	s_nop 0
	global_load_lds_dwordx4 v[162:163], off
	s_nop 0
	s_nop 0
	s_nop 0
	s_nop 0
	ds_read_b128 a[0:3], v86 offset:32768
	ds_read_b128 a[4:7], v86 offset:36864
	ds_read_b128 a[8:11], v85
	ds_read_b128 a[12:15], v85 offset:4096
	s_waitcnt lgkmcnt(5)
	v_mfma_f32_32x32x16_bf16 v[48:63], a[16:19], a[24:27], v[48:63]
	v_mfma_f32_32x32x16_bf16 v[32:47], a[20:23], a[24:27], v[32:47]
	s_and_b32 m0, s32, 7
	s_lshl_b32 m0, m0, 12
	s_add_i32 m0, m0, 0x18c00
	s_nop 0
	global_load_lds_dwordx4 v[164:165], off
	s_waitcnt lgkmcnt(4)
	v_mfma_f32_32x32x16_bf16 v[16:31], a[16:19], a[28:31], v[16:31]
	v_mfma_f32_32x32x16_bf16 v[0:15], a[20:23], a[28:31], v[0:15]
	s_and_b32 m0, s32, 7
	s_lshl_b32 m0, m0, 11
	s_add_i32 m0, m0, 0x20000
	s_nop 0
	global_load_lds_dwordx4 v[166:167], off
	s_nop 0
	s_nop 0
	s_nop 0
	s_nop 0
	ds_read_b128 a[16:19], v88 offset:32768
	ds_read_b128 a[20:23], v88 offset:36864
	ds_read_b128 a[24:27], v87
	ds_read_b128 a[28:31], v87 offset:4096
	s_waitcnt lgkmcnt(5)
	v_mfma_f32_32x32x16_bf16 v[48:63], a[0:3], a[8:11], v[48:63]
	v_mfma_f32_32x32x16_bf16 v[32:47], a[4:7], a[8:11], v[32:47]
	s_and_b32 m0, s32, 7
	s_lshl_b32 m0, m0, 11
	s_add_i32 m0, m0, 0x20400
	s_nop 0
	global_load_lds_dwordx4 v[168:169], off
	s_waitcnt lgkmcnt(4)
	v_mfma_f32_32x32x16_bf16 v[16:31], a[0:3], a[12:15], v[16:31]
	v_mfma_f32_32x32x16_bf16 v[0:15], a[4:7], a[12:15], v[0:15]
	s_nop 0
	s_nop 0
	s_nop 0
	s_nop 0
	s_waitcnt lgkmcnt(1)
	v_mfma_f32_32x32x16_bf16 v[48:63], a[16:19], a[24:27], v[48:63]
	v_mfma_f32_32x32x16_bf16 v[32:47], a[20:23], a[24:27], v[32:47]
	s_waitcnt vmcnt(6)
	s_waitcnt lgkmcnt(0)
	s_barrier
	ds_read_b128 a[12:15], v81 offset:53248
	ds_read_b128 a[8:11], v81 offset:49152
	ds_read_b128 a[4:7], v89
	ds_read_b128 a[0:3], v91
	v_mfma_f32_32x32x16_bf16 v[16:31], a[16:19], a[28:31], v[16:31]
	v_lshl_add_u64 v[170:171], v[66:67], 0, s[30:31]
	s_nop 0
	v_lshl_add_u64 v[172:173], v[68:69], 0, s[30:31]
	s_nop 0
	s_nop 0
	s_nop 0
	v_lshl_add_u64 v[174:175], v[70:71], 0, s[30:31]
	s_nop 0
	v_mfma_f32_32x32x16_bf16 v[0:15], a[20:23], a[28:31], v[0:15]
	s_and_b32 m0, s32, 7
	s_lshl_b32 m0, m0, 12
	s_add_i32 m0, m0, 0x0
	s_nop 0
	global_load_lds_dwordx4 v[170:171], off
	s_nop 0
	v_lshl_add_u64 v[176:177], v[72:73], 0, s[30:31]
	s_nop 0
	s_nop 0
	s_nop 0
	v_lshl_add_u64 v[178:179], v[74:75], 0, s[30:31]
	s_nop 0
	s_nop 0
	s_nop 0
	v_lshl_add_u64 v[180:181], v[76:77], 0, s[30:31]
	s_nop 0
	s_mov_b64 s[30:31], 0x680
	s_nop 0
	s_nop 0
	s_nop 0
	s_nop 0
	s_nop 0
	ds_read_b128 a[16:19], v92
	ds_read_b128 a[20:23], v90
	ds_read_b128 a[24:27], v83 offset:49152
	ds_read_b128 a[28:31], v83 offset:53248
	s_waitcnt lgkmcnt(4)
	v_mfma_f32_32x32x16_bf16 v[48:63], a[0:3], a[8:11], v[48:63]
	s_nop 0
	v_mfma_f32_32x32x16_bf16 v[32:47], a[4:7], a[8:11], v[32:47]
	s_and_b32 m0, s32, 7
	s_lshl_b32 m0, m0, 12
	s_add_i32 m0, m0, 0x400
	s_nop 0
	global_load_lds_dwordx4 v[172:173], off
	v_mfma_f32_32x32x16_bf16 v[16:31], a[0:3], a[12:15], v[16:31]
	v_mfma_f32_32x32x16_bf16 v[0:15], a[4:7], a[12:15], v[0:15]
	s_and_b32 m0, s32, 7
	s_lshl_b32 m0, m0, 12
	s_add_i32 m0, m0, 0x800
	s_nop 0
	global_load_lds_dwordx4 v[174:175], off
	s_nop 0
	s_nop 0
	s_nop 0
	s_nop 0
	ds_read_b128 a[0:3], v94
	ds_read_b128 a[4:7], v93
	ds_read_b128 a[8:11], v85 offset:49152
	ds_read_b128 a[12:15], v85 offset:53248
	s_waitcnt lgkmcnt(5)
	v_mfma_f32_32x32x16_bf16 v[48:63], a[16:19], a[24:27], v[48:63]
	v_mfma_f32_32x32x16_bf16 v[32:47], a[20:23], a[24:27], v[32:47]
	s_and_b32 m0, s32, 7
	s_lshl_b32 m0, m0, 12
	s_add_i32 m0, m0, 0xc00
	s_nop 0
	global_load_lds_dwordx4 v[176:177], off
	s_waitcnt lgkmcnt(4)
	v_mfma_f32_32x32x16_bf16 v[16:31], a[16:19], a[28:31], v[16:31]
	v_mfma_f32_32x32x16_bf16 v[0:15], a[20:23], a[28:31], v[0:15]
	s_and_b32 m0, s32, 7
	s_lshl_b32 m0, m0, 11
	s_add_i32 m0, m0, 0x8000
	s_nop 0
	global_load_lds_dwordx4 v[178:179], off
	s_nop 0
	s_nop 0
	s_nop 0
	s_nop 0
	ds_read_b128 a[16:19], v96
	ds_read_b128 a[20:23], v95
	ds_read_b128 a[24:27], v87 offset:49152
	ds_read_b128 a[28:31], v87 offset:53248
	s_waitcnt lgkmcnt(5)
	v_mfma_f32_32x32x16_bf16 v[48:63], a[0:3], a[8:11], v[48:63]
	v_mfma_f32_32x32x16_bf16 v[32:47], a[4:7], a[8:11], v[32:47]
	s_and_b32 m0, s32, 7
	s_lshl_b32 m0, m0, 11
	s_add_i32 m0, m0, 0x8400
	s_nop 0
	global_load_lds_dwordx4 v[180:181], off
	s_waitcnt lgkmcnt(4)
	v_mfma_f32_32x32x16_bf16 v[16:31], a[0:3], a[12:15], v[16:31]
	v_mfma_f32_32x32x16_bf16 v[0:15], a[4:7], a[12:15], v[0:15]
	s_nop 0
	s_nop 0
	s_nop 0
	s_nop 0
	s_waitcnt lgkmcnt(1)
	v_mfma_f32_32x32x16_bf16 v[48:63], a[16:19], a[24:27], v[48:63]
	v_mfma_f32_32x32x16_bf16 v[32:47], a[20:23], a[24:27], v[32:47]
	s_waitcnt vmcnt(6)
	s_waitcnt lgkmcnt(0)
	s_barrier
	ds_read_b128 a[12:15], v100
	ds_read_b128 a[8:11], v99
	ds_read_b128 a[4:7], v98
	ds_read_b128 a[0:3], v97
	v_mfma_f32_32x32x16_bf16 v[16:31], a[16:19], a[28:31], v[16:31]
	v_lshl_add_u64 v[158:159], v[66:67], 0, s[30:31]
	s_nop 0
	v_lshl_add_u64 v[160:161], v[68:69], 0, s[30:31]
	s_nop 0
	s_nop 0
	s_nop 0
	v_lshl_add_u64 v[162:163], v[70:71], 0, s[30:31]
	s_nop 0
	v_mfma_f32_32x32x16_bf16 v[0:15], a[20:23], a[28:31], v[0:15]
	s_and_b32 m0, s32, 7
	s_lshl_b32 m0, m0, 12
	s_add_i32 m0, m0, 0xc000
	s_nop 0
	global_load_lds_dwordx4 v[158:159], off
	s_nop 0
	v_lshl_add_u64 v[164:165], v[72:73], 0, s[30:31]
	s_nop 0
	s_nop 0
	s_nop 0
	v_lshl_add_u64 v[166:167], v[74:75], 0, s[30:31]
	s_nop 0
	s_nop 0
	s_nop 0
	v_lshl_add_u64 v[168:169], v[76:77], 0, s[30:31]
	s_nop 0
	s_mov_b64 s[30:31], 0x700
	s_nop 0
	s_nop 0
	s_nop 0
	s_nop 0
	s_nop 0
	ds_read_b128 a[16:19], v101
	ds_read_b128 a[20:23], v102
	ds_read_b128 a[24:27], v103
	ds_read_b128 a[28:31], v104
	s_waitcnt lgkmcnt(4)
	v_mfma_f32_32x32x16_bf16 v[48:63], a[0:3], a[8:11], v[48:63]
	s_nop 0
	v_mfma_f32_32x32x16_bf16 v[32:47], a[4:7], a[8:11], v[32:47]
	s_and_b32 m0, s32, 7
	s_lshl_b32 m0, m0, 12
	s_add_i32 m0, m0, 0xc400
	s_nop 0
	global_load_lds_dwordx4 v[160:161], off
	v_mfma_f32_32x32x16_bf16 v[16:31], a[0:3], a[12:15], v[16:31]
	v_mfma_f32_32x32x16_bf16 v[0:15], a[4:7], a[12:15], v[0:15]
	s_and_b32 m0, s32, 7
	s_lshl_b32 m0, m0, 12
	s_add_i32 m0, m0, 0xc800
	s_nop 0
	global_load_lds_dwordx4 v[162:163], off
	s_nop 0
	s_nop 0
	s_nop 0
	s_nop 0
	ds_read_b128 a[0:3], v105
	ds_read_b128 a[4:7], v106
	ds_read_b128 a[8:11], v107
	ds_read_b128 a[12:15], v108
	s_waitcnt lgkmcnt(5)
	v_mfma_f32_32x32x16_bf16 v[48:63], a[16:19], a[24:27], v[48:63]
	v_mfma_f32_32x32x16_bf16 v[32:47], a[20:23], a[24:27], v[32:47]
	s_and_b32 m0, s32, 7
	s_lshl_b32 m0, m0, 12
	s_add_i32 m0, m0, 0xcc00
	s_nop 0
	global_load_lds_dwordx4 v[164:165], off
	s_waitcnt lgkmcnt(4)
	v_mfma_f32_32x32x16_bf16 v[16:31], a[16:19], a[28:31], v[16:31]
	v_mfma_f32_32x32x16_bf16 v[0:15], a[20:23], a[28:31], v[0:15]
	s_and_b32 m0, s32, 7
	s_lshl_b32 m0, m0, 11
	s_add_i32 m0, m0, 0x14000
	s_nop 0
	global_load_lds_dwordx4 v[166:167], off
	s_nop 0
	s_nop 0
	s_nop 0
	s_nop 0
	ds_read_b128 a[16:19], v109
	ds_read_b128 a[20:23], v110
	ds_read_b128 a[24:27], v111
	ds_read_b128 a[28:31], v112
	s_waitcnt lgkmcnt(5)
	v_mfma_f32_32x32x16_bf16 v[48:63], a[0:3], a[8:11], v[48:63]
	v_mfma_f32_32x32x16_bf16 v[32:47], a[4:7], a[8:11], v[32:47]
	s_and_b32 m0, s32, 7
	s_lshl_b32 m0, m0, 11
	s_add_i32 m0, m0, 0x14400
	s_nop 0
	global_load_lds_dwordx4 v[168:169], off
	s_waitcnt lgkmcnt(4)
	v_mfma_f32_32x32x16_bf16 v[16:31], a[0:3], a[12:15], v[16:31]
	v_mfma_f32_32x32x16_bf16 v[0:15], a[4:7], a[12:15], v[0:15]
	s_nop 0
	s_nop 0
	s_nop 0
	s_nop 0
	s_waitcnt lgkmcnt(1)
	v_mfma_f32_32x32x16_bf16 v[48:63], a[16:19], a[24:27], v[48:63]
	v_mfma_f32_32x32x16_bf16 v[32:47], a[20:23], a[24:27], v[32:47]
	s_waitcnt vmcnt(6)
	s_waitcnt lgkmcnt(0)
	s_barrier
	ds_read_b128 a[12:15], v81 offset:4096
	ds_read_b128 a[8:11], v81
	ds_read_b128 a[4:7], v82 offset:36864
	ds_read_b128 a[0:3], v82 offset:32768
	v_mfma_f32_32x32x16_bf16 v[16:31], a[16:19], a[28:31], v[16:31]
	v_lshl_add_u64 v[170:171], v[66:67], 0, s[30:31]
	s_nop 0
	v_lshl_add_u64 v[172:173], v[68:69], 0, s[30:31]
	s_nop 0
	s_nop 0
	s_nop 0
	v_lshl_add_u64 v[174:175], v[70:71], 0, s[30:31]
	s_nop 0
	v_mfma_f32_32x32x16_bf16 v[0:15], a[20:23], a[28:31], v[0:15]
	s_and_b32 m0, s32, 7
	s_lshl_b32 m0, m0, 12
	s_add_i32 m0, m0, 0x18000
	s_nop 0
	global_load_lds_dwordx4 v[170:171], off
	s_nop 0
	v_lshl_add_u64 v[176:177], v[72:73], 0, s[30:31]
	s_nop 0
	s_nop 0
	s_nop 0
	v_lshl_add_u64 v[178:179], v[74:75], 0, s[30:31]
	s_nop 0
	s_nop 0
	s_nop 0
	v_lshl_add_u64 v[180:181], v[76:77], 0, s[30:31]
	s_nop 0
	s_mov_b64 s[30:31], 0x780
	s_nop 0
	s_nop 0
	s_nop 0
	s_nop 0
	s_nop 0
	ds_read_b128 a[16:19], v84 offset:32768
	ds_read_b128 a[20:23], v84 offset:36864
	ds_read_b128 a[24:27], v83
	ds_read_b128 a[28:31], v83 offset:4096
	s_waitcnt lgkmcnt(4)
	v_mfma_f32_32x32x16_bf16 v[48:63], a[0:3], a[8:11], v[48:63]
	v_lshl_add_u64 v[158:159], v[66:67], 0, s[30:31]
	s_nop 0
	v_readlane_b32 s20, v214, 43
	v_mfma_f32_32x32x16_bf16 v[32:47], a[4:7], a[8:11], v[32:47]
	s_and_b32 m0, s32, 7
	s_lshl_b32 m0, m0, 12
	s_add_i32 m0, m0, 0x18400
	s_nop 0
	global_load_lds_dwordx4 v[172:173], off
	v_mfma_f32_32x32x16_bf16 v[16:31], a[0:3], a[12:15], v[16:31]
	v_mfma_f32_32x32x16_bf16 v[0:15], a[4:7], a[12:15], v[0:15]
	s_and_b32 m0, s32, 7
	s_lshl_b32 m0, m0, 12
	s_add_i32 m0, m0, 0x18800
	s_nop 0
	global_load_lds_dwordx4 v[174:175], off
	s_nop 0
	s_nop 0
	s_nop 0
	s_nop 0
	ds_read_b128 a[0:3], v86 offset:32768
	ds_read_b128 a[4:7], v86 offset:36864
	ds_read_b128 a[8:11], v85
	ds_read_b128 a[12:15], v85 offset:4096
	s_waitcnt lgkmcnt(5)
	v_mfma_f32_32x32x16_bf16 v[48:63], a[16:19], a[24:27], v[48:63]
	v_mfma_f32_32x32x16_bf16 v[32:47], a[20:23], a[24:27], v[32:47]
	s_and_b32 m0, s32, 7
	s_lshl_b32 m0, m0, 12
	s_add_i32 m0, m0, 0x18c00
	s_nop 0
	global_load_lds_dwordx4 v[176:177], off
	s_waitcnt lgkmcnt(4)
	v_mfma_f32_32x32x16_bf16 v[16:31], a[16:19], a[28:31], v[16:31]
	v_mfma_f32_32x32x16_bf16 v[0:15], a[20:23], a[28:31], v[0:15]
	s_and_b32 m0, s32, 7
	s_lshl_b32 m0, m0, 11
	s_add_i32 m0, m0, 0x20000
	s_nop 0
	global_load_lds_dwordx4 v[178:179], off
	s_nop 0
	s_nop 0
	s_nop 0
	s_nop 0
	ds_read_b128 a[16:19], v88 offset:32768
	ds_read_b128 a[20:23], v88 offset:36864
	ds_read_b128 a[24:27], v87
	ds_read_b128 a[28:31], v87 offset:4096
	s_waitcnt lgkmcnt(5)
	v_mfma_f32_32x32x16_bf16 v[48:63], a[0:3], a[8:11], v[48:63]
	v_mfma_f32_32x32x16_bf16 v[32:47], a[4:7], a[8:11], v[32:47]
	s_and_b32 m0, s32, 7
	s_lshl_b32 m0, m0, 11
	s_add_i32 m0, m0, 0x20400
	s_nop 0
	global_load_lds_dwordx4 v[180:181], off
	s_waitcnt lgkmcnt(4)
	v_mfma_f32_32x32x16_bf16 v[16:31], a[0:3], a[12:15], v[16:31]
	v_mfma_f32_32x32x16_bf16 v[0:15], a[4:7], a[12:15], v[0:15]
	s_nop 0
	s_nop 0
	s_nop 0
	s_nop 0
	s_waitcnt lgkmcnt(1)
	v_mfma_f32_32x32x16_bf16 v[48:63], a[16:19], a[24:27], v[48:63]
	v_mfma_f32_32x32x16_bf16 v[32:47], a[20:23], a[24:27], v[32:47]
	s_waitcnt vmcnt(6)
	s_waitcnt lgkmcnt(0)
	s_barrier
	ds_read_b128 a[12:15], v81 offset:53248
	ds_read_b128 a[8:11], v81 offset:49152
	ds_read_b128 a[4:7], v89
	ds_read_b128 a[0:3], v91
	s_nop 0
	v_lshl_add_u64 v[160:161], v[68:69], 0, s[30:31]
	s_nop 0
	v_mfma_f32_32x32x16_bf16 v[16:31], a[16:19], a[28:31], v[16:31]
	s_nop 0
	v_lshl_add_u64 v[162:163], v[70:71], 0, s[30:31]
	s_nop 0
	v_readlane_b32 s21, v214, 44
	s_nop 0
	v_lshl_add_u64 v[164:165], v[72:73], 0, s[30:31]
	s_nop 0
	v_mfma_f32_32x32x16_bf16 v[0:15], a[20:23], a[28:31], v[0:15]
	s_and_b32 m0, s32, 7
	s_lshl_b32 m0, m0, 12
	s_add_i32 m0, m0, 0x0
	s_nop 0
	global_load_lds_dwordx4 v[158:159], off
	s_nop 0
	v_lshl_add_u64 v[166:167], v[74:75], 0, s[30:31]
	s_nop 0
	s_lshl_b64 s[28:29], s[0:1], 21
	s_nop 0
	v_lshl_add_u64 v[168:169], v[76:77], 0, s[30:31]
	s_nop 0
	s_add_u32 s20, s20, s28
	s_nop 0
	s_nop 0
	s_nop 0
	s_nop 0
	s_nop 0
	ds_read_b128 a[16:19], v92
	ds_read_b128 a[20:23], v90
	ds_read_b128 a[24:27], v83 offset:49152
	ds_read_b128 a[28:31], v83 offset:53248
	s_waitcnt lgkmcnt(4)
	v_mfma_f32_32x32x16_bf16 v[48:63], a[0:3], a[8:11], v[48:63]
	s_addc_u32 s21, s21, s29
	v_readlane_b32 s23, v214, 41
	s_add_u32 s36, s23, s28
	v_readlane_b32 s23, v214, 42
	s_addc_u32 s37, s23, s29
	v_mfma_f32_32x32x16_bf16 v[32:47], a[4:7], a[8:11], v[32:47]
	s_and_b32 m0, s32, 7
	s_lshl_b32 m0, m0, 12
	s_add_i32 m0, m0, 0x400
	s_nop 0
	global_load_lds_dwordx4 v[160:161], off
	v_mfma_f32_32x32x16_bf16 v[16:31], a[0:3], a[12:15], v[16:31]
	v_mfma_f32_32x32x16_bf16 v[0:15], a[4:7], a[12:15], v[0:15]
	s_and_b32 m0, s32, 7
	s_lshl_b32 m0, m0, 12
	s_add_i32 m0, m0, 0x800
	s_nop 0
	global_load_lds_dwordx4 v[162:163], off
	s_nop 0
	s_nop 0
	s_nop 0
	s_nop 0
	ds_read_b128 a[0:3], v94
	ds_read_b128 a[4:7], v93
	ds_read_b128 a[8:11], v85 offset:49152
	ds_read_b128 a[12:15], v85 offset:53248
	s_waitcnt lgkmcnt(5)
	v_mfma_f32_32x32x16_bf16 v[48:63], a[16:19], a[24:27], v[48:63]
	v_mfma_f32_32x32x16_bf16 v[32:47], a[20:23], a[24:27], v[32:47]
	s_and_b32 m0, s32, 7
	s_lshl_b32 m0, m0, 12
	s_add_i32 m0, m0, 0xc00
	s_nop 0
	global_load_lds_dwordx4 v[164:165], off
	s_waitcnt lgkmcnt(4)
	v_mfma_f32_32x32x16_bf16 v[16:31], a[16:19], a[28:31], v[16:31]
	v_mfma_f32_32x32x16_bf16 v[0:15], a[20:23], a[28:31], v[0:15]
	s_and_b32 m0, s32, 7
	s_lshl_b32 m0, m0, 11
	s_add_i32 m0, m0, 0x8000
	s_nop 0
	global_load_lds_dwordx4 v[166:167], off
	s_nop 0
	s_nop 0
	s_nop 0
	s_nop 0
	ds_read_b128 a[16:19], v96
	ds_read_b128 a[20:23], v95
	ds_read_b128 a[24:27], v87 offset:49152
	ds_read_b128 a[28:31], v87 offset:53248
	s_waitcnt lgkmcnt(5)
	v_mfma_f32_32x32x16_bf16 v[48:63], a[0:3], a[8:11], v[48:63]
	v_mfma_f32_32x32x16_bf16 v[32:47], a[4:7], a[8:11], v[32:47]
	s_and_b32 m0, s32, 7
	s_lshl_b32 m0, m0, 11
	s_add_i32 m0, m0, 0x8400
	s_nop 0
	global_load_lds_dwordx4 v[168:169], off
	s_waitcnt lgkmcnt(4)
	v_mfma_f32_32x32x16_bf16 v[16:31], a[0:3], a[12:15], v[16:31]
	v_mfma_f32_32x32x16_bf16 v[0:15], a[4:7], a[12:15], v[0:15]
	s_nop 0
	s_nop 0
	s_nop 0
	s_nop 0
	s_waitcnt lgkmcnt(1)
	v_mfma_f32_32x32x16_bf16 v[48:63], a[16:19], a[24:27], v[48:63]
	v_mfma_f32_32x32x16_bf16 v[32:47], a[20:23], a[24:27], v[32:47]
	s_waitcnt vmcnt(6)
	s_waitcnt lgkmcnt(0)
	s_barrier
	ds_read_b128 a[12:15], v100
	ds_read_b128 a[8:11], v99
	ds_read_b128 a[4:7], v98
	ds_read_b128 a[0:3], v97
	v_mfma_f32_32x32x16_bf16 v[16:31], a[16:19], a[28:31], v[16:31]
	v_mfma_f32_32x32x16_bf16 v[0:15], a[20:23], a[28:31], v[0:15]
	s_nop 0
	s_nop 0
	s_nop 0
	s_nop 0
	ds_read_b128 a[16:19], v101
	ds_read_b128 a[20:23], v102
	ds_read_b128 a[24:27], v103
	ds_read_b128 a[28:31], v104
	s_waitcnt lgkmcnt(4)
	v_mfma_f32_32x32x16_bf16 v[48:63], a[0:3], a[8:11], v[48:63]
	v_mfma_f32_32x32x16_bf16 v[32:47], a[4:7], a[8:11], v[32:47]
	v_mfma_f32_32x32x16_bf16 v[16:31], a[0:3], a[12:15], v[16:31]
	v_mfma_f32_32x32x16_bf16 v[0:15], a[4:7], a[12:15], v[0:15]
	s_nop 0
	s_nop 0
	s_nop 0
	s_nop 0
	ds_read_b128 a[0:3], v105
	ds_read_b128 a[4:7], v106
	ds_read_b128 a[8:11], v107
	ds_read_b128 a[12:15], v108
	s_waitcnt lgkmcnt(5)
	v_mfma_f32_32x32x16_bf16 v[48:63], a[16:19], a[24:27], v[48:63]
	v_mfma_f32_32x32x16_bf16 v[32:47], a[20:23], a[24:27], v[32:47]
	s_waitcnt lgkmcnt(4)
	v_mfma_f32_32x32x16_bf16 v[16:31], a[16:19], a[28:31], v[16:31]
	v_mfma_f32_32x32x16_bf16 v[0:15], a[20:23], a[28:31], v[0:15]
	s_nop 0
	s_nop 0
	s_nop 0
	s_nop 0
	ds_read_b128 a[16:19], v109
	ds_read_b128 a[20:23], v110
	ds_read_b128 a[24:27], v111
	ds_read_b128 a[28:31], v112
	s_waitcnt lgkmcnt(5)
	v_mfma_f32_32x32x16_bf16 v[48:63], a[0:3], a[8:11], v[48:63]
	v_mfma_f32_32x32x16_bf16 v[32:47], a[4:7], a[8:11], v[32:47]
	s_waitcnt lgkmcnt(4)
	v_mfma_f32_32x32x16_bf16 v[16:31], a[0:3], a[12:15], v[16:31]
	v_mfma_f32_32x32x16_bf16 v[0:15], a[4:7], a[12:15], v[0:15]
	s_nop 0
	s_nop 0
	s_nop 0
	s_nop 0
	s_waitcnt lgkmcnt(1)
	v_mfma_f32_32x32x16_bf16 v[48:63], a[16:19], a[24:27], v[48:63]
	v_mfma_f32_32x32x16_bf16 v[32:47], a[20:23], a[24:27], v[32:47]
	s_waitcnt vmcnt(0)
	s_waitcnt lgkmcnt(0)
	s_barrier
	ds_read_b128 a[12:15], v81 offset:4096
	ds_read_b128 a[8:11], v81
	ds_read_b128 a[4:7], v82 offset:36864
	ds_read_b128 a[0:3], v82 offset:32768
	v_mfma_f32_32x32x16_bf16 v[16:31], a[16:19], a[28:31], v[16:31]
	v_mfma_f32_32x32x16_bf16 v[0:15], a[20:23], a[28:31], v[0:15]
	s_nop 0
	s_nop 0
	s_nop 0
	s_nop 0
	ds_read_b128 a[16:19], v84 offset:32768
	ds_read_b128 a[20:23], v84 offset:36864
	ds_read_b128 a[24:27], v83
	ds_read_b128 a[28:31], v83 offset:4096
	s_waitcnt lgkmcnt(4)
	v_mfma_f32_32x32x16_bf16 v[48:63], a[0:3], a[8:11], v[48:63]
	v_mfma_f32_32x32x16_bf16 v[32:47], a[4:7], a[8:11], v[32:47]
	v_mfma_f32_32x32x16_bf16 v[16:31], a[0:3], a[12:15], v[16:31]
	v_mfma_f32_32x32x16_bf16 v[0:15], a[4:7], a[12:15], v[0:15]
	s_nop 0
	s_nop 0
	s_nop 0
	s_nop 0
	ds_read_b128 a[0:3], v86 offset:32768
	ds_read_b128 a[4:7], v86 offset:36864
	ds_read_b128 a[8:11], v85
	ds_read_b128 a[12:15], v85 offset:4096
	s_waitcnt lgkmcnt(5)
	v_mfma_f32_32x32x16_bf16 v[48:63], a[16:19], a[24:27], v[48:63]
	v_mfma_f32_32x32x16_bf16 v[32:47], a[20:23], a[24:27], v[32:47]
	s_waitcnt lgkmcnt(4)
	v_mfma_f32_32x32x16_bf16 v[16:31], a[16:19], a[28:31], v[16:31]
	v_mfma_f32_32x32x16_bf16 v[0:15], a[20:23], a[28:31], v[0:15]
	s_nop 0
	s_nop 0
	s_nop 0
	s_nop 0
	s_waitcnt lgkmcnt(1)
	v_mfma_f32_32x32x16_bf16 v[48:63], a[0:3], a[8:11], v[48:63]
	v_mfma_f32_32x32x16_bf16 v[32:47], a[4:7], a[8:11], v[32:47]
	s_waitcnt lgkmcnt(0)
	v_mfma_f32_32x32x16_bf16 v[16:31], a[0:3], a[12:15], v[16:31]
	v_mfma_f32_32x32x16_bf16 v[0:15], a[4:7], a[12:15], v[0:15]
	ds_read_b128 v[66:69], v88 offset:32768
	ds_read_b128 v[70:73], v87
	ds_read_b128 v[74:77], v88 offset:36864
	ds_read_b128 v[82:85], v87 offset:4096
	s_waitcnt lgkmcnt(0)
	v_mfma_f32_32x32x16_bf16 v[48:63], v[66:69], v[70:73], v[48:63]
	v_mfma_f32_32x32x16_bf16 v[32:47], v[74:77], v[70:73], v[32:47]
	v_or_b32_e32 v70, s22, v80
	v_lshl_add_u32 v70, v78, 6, v70
	v_ashrrev_i32_e32 v71, 31, v70
	v_lshlrev_b64 v[72:73], 10, v[70:71]
	v_lshl_add_u64 v[86:87], s[36:37], 0, v[72:73]
	v_mfma_f32_32x32x16_bf16 v[16:31], v[66:69], v[82:85], v[16:31]
	v_lshlrev_b32_e32 v66, 6, v79
	v_or3_b32 v66, v66, v64, s2
	s_movk_i32 s2, 0xff
	v_cmp_lt_i32_e32 vcc, s2, v66
	v_mfma_f32_32x32x16_bf16 v[0:15], v[74:77], v[82:85], v[0:15]
	s_and_saveexec_b64 s[22:23], vcc
	s_xor_b64 s[28:29], exec, s[22:23]
	v_mov_b32_e32 v67, v65
	s_movk_i32 s22, 0xfc00
	v_lshl_add_u64 v[68:69], v[66:67], 2, v[86:87]
	s_mov_b32 s23, -1
	v_lshl_add_u64 v[68:69], v[68:69], 0, s[22:23]
	s_or_saveexec_b64 s[28:29], s[28:29]
	v_lshl_add_u64 v[90:91], s[20:21], 0, v[72:73]
	v_ashrrev_i32_e32 v67, 31, v66
	s_xor_b64 exec, exec, s[28:29]
	v_lshl_add_u64 v[68:69], v[66:67], 2, v[90:91]
	s_or_b64 exec, exec, s[28:29]
	s_lshl_b64 s[0:1], s[0:1], 19
	s_lshl_b64 s[22:23], s[0:1], 1
	v_readlane_b32 s0, v214, 37
	v_readlane_b32 s1, v214, 38
	s_add_u32 s0, s0, s22
	s_addc_u32 s1, s1, s23
	v_readlane_b32 s28, v214, 39
	v_readlane_b32 s29, v214, 40
	s_add_u32 s54, s28, s22
	v_and_b32_e32 v74, 0xdf, v70
	v_ashrrev_i32_e32 v71, 6, v70
	global_store_dwordx4 v[68:69], v[48:51], off
	v_add_u32_e32 v68, 0xffffff00, v66
	v_lshlrev_b32_e32 v69, 9, v66
	s_addc_u32 s55, s29, s23
	v_and_b32_e32 v71, -4, v71
	v_lshrrev_b32_e32 v92, 6, v68
	v_and_b32_e32 v72, 0x7800, v69
	v_lshlrev_b32_e32 v88, 1, v74
	s_and_saveexec_b64 s[22:23], vcc
	s_xor_b64 s[28:29], exec, s[22:23]
	s_cbranch_execz .LBB0_619
	v_add_u32_e32 v68, v92, v71
	v_ashrrev_i32_e32 v69, 31, v68
	v_lshlrev_b64 v[68:69], 15, v[68:69]
	v_lshl_add_u64 v[68:69], s[54:55], 0, v[68:69]
	v_mov_b32_e32 v73, v65
	v_lshl_add_u64 v[68:69], v[68:69], 0, v[72:73]
	v_mov_b32_e32 v89, v65
	v_bfe_u32 v73, v48, 16, 1
	v_lshl_add_u64 v[68:69], v[68:69], 0, v[88:89]
	v_add3_u32 v73, v48, v73, s27
	global_store_short_d16_hi v[68:69], v73, off
	v_bfe_u32 v73, v49, 16, 1
	v_add3_u32 v73, v49, v73, s27
	global_store_short_d16_hi v[68:69], v73, off offset:512
	v_bfe_u32 v73, v50, 16, 1
	v_add3_u32 v73, v50, v73, s27
	global_store_short_d16_hi v[68:69], v73, off offset:1024
	v_bfe_u32 v73, v51, 16, 1
	v_add3_u32 v73, v51, v73, s27
	global_store_short_d16_hi v[68:69], v73, off offset:1536

amdhsa.kernels:
  - .agpr_count:     36
    .args:
      - .offset:         0
        .size:           232
        .value_kind:     by_value
      - .offset:         232
        .size:           4
        .value_kind:     hidden_block_count_x
      - .offset:         236
        .size:           4
        .value_kind:     hidden_block_count_y
      - .offset:         240
        .size:           4
        .value_kind:     hidden_block_count_z
      - .offset:         244
        .size:           2
        .value_kind:     hidden_group_size_x
      - .offset:         246
        .size:           2
        .value_kind:     hidden_group_size_y
      - .offset:         248
        .size:           2
        .value_kind:     hidden_group_size_z
      - .offset:         250
        .size:           2
        .value_kind:     hidden_remainder_x
      - .offset:         252
        .size:           2
        .value_kind:     hidden_remainder_y
      - .offset:         254
        .size:           2
        .value_kind:     hidden_remainder_z
      - .offset:         272
        .size:           8
        .value_kind:     hidden_global_offset_x
      - .offset:         280
        .size:           8
        .value_kind:     hidden_global_offset_y
      - .offset:         288
        .size:           8
        .value_kind:     hidden_global_offset_z
      - .offset:         296
        .size:           2
        .value_kind:     hidden_grid_dims
      - .offset:         320
        .size:           8
        .value_kind:     hidden_multigrid_sync_arg
      - .offset:         352
        .size:           4
        .value_kind:     hidden_dynamic_lds_size
    .group_segment_fixed_size: 0
    .kernarg_segment_align: 8
    .kernarg_segment_size: 488
    .language:       OpenCL C
    .language_version:
      - 2
      - 0
    .max_flat_workgroup_size: 512
    .name:           _Z4mega6Params
    .private_segment_fixed_size: 0
    .sgpr_count:     106
    .sgpr_spill_count: 308
    .symbol:         _Z4mega6Params.kd
    .uniform_work_group_size: 1
    .uses_dynamic_stack: false
    .vgpr_count:     220
    .vgpr_spill_count: 0
    .wavefront_size: 64
